# GEMM unit seam: ALIGN_EPI barrier pair removed in all 15 GEMMs (halves keep their one-phase offset through the epilogue; one compensating barrier at unit-loop exit), on v53
# baseline (speedup 1.0000x reference)
; #define PG8_STAGE(bufoff, gbase, voff) do { _Pragma("unroll") for (int _i = 0; _i < 2; ++_i) \
;         __builtin_amdgcn_global_load_lds((const unsigned*)((const char*)(gbase) + (voff)[_i]), (LAS unsigned*)(lds + (bufoff) + ldsw + _i * 8192), 16, 0, 0); } while (0)
; #define PG8_LDA(dst, b, h) do { _Pragma("unroll") for (int m = 0; m < 4; ++m) _Pragma("unroll") for (int k = 0; k < 2; ++k) dst[m][k] = *(const LAS bf16x8*)(lds + PG8_SA(b, h) + aoff + m * 2048 + k * 1024); } while (0)
; #define PG8_LDB(dst, b, h) do { _Pragma("unroll") for (int n = 0; n < 2; ++n) _Pragma("unroll") for (int k = 0; k < 2; ++k) dst[n][k] = *(const LAS bf16x8*)(lds + PG8_SB(b, h) + boff + n * 2048 + k * 1024); } while (0)
; #define PG8_WAIT_V(n) asm volatile("s_waitcnt vmcnt(" #n ")" ::: "memory")
; #define PG8_WAIT_L(n) asm volatile("s_waitcnt lgkmcnt(" #n ")" ::: "memory")
; template <class Epi>
; __device__ __forceinline__ void gemm_phase(LAS unsigned char* lds, const Gemm g, const StaticOrder& S, const Epi& E, const int wid) {
;     ...
;         for (int t = 0; t < nt; t += 2) {
;             const bool last = (t == nt - 2);
;             const char* a1 = cA + (size_t)(t + 1) * kstep;
;             const char* a2 = last ? nA : cA + (size_t)(t + 2) * kstep; const char* b2 = last ? nB : cB + (size_t)(t + 2) * kstep;
;             const char* a3 = a2 + kstep; const char* b3 = b2 + kstep;
;             PG8_LDB(B0, 0, 0); PG8_LDB(B1, 0, 1); PG8_SCHED; PG8_LDA(At, 0, 0); PG8_STAGE(PG8_SA(1, 1), a1 + hsA, voffA);
;             PG8_WAIT_V(8); PG8_WAIT_L(0); PG8_BAR; PG8_MMA(0, 0, At, B0); PG8_MMA(0, 1, At, B1); PG8_BAR; PG8_SCHED;
;             PG8_LDA(At, 0, 1); PG8_STAGE(PG8_SB(0, 0), b2, voffB); PG8_STAGE(PG8_SB(0, 1), b2 + hsB, voffB); PG8_STAGE(PG8_SA(0, 0), a2, voffA);
;             PG8_WAIT_V(8); PG8_WAIT_L(0); PG8_BAR; PG8_MMA(1, 0, At, B0); PG8_MMA(1, 1, At, B1); PG8_BAR; PG8_SCHED;
;             PG8_LDB(B0, 1, 0); PG8_LDB(B1, 1, 1); PG8_SCHED; PG8_LDA(At, 1, 0); PG8_STAGE(PG8_SA(0, 1), a2 + hsA, voffA);
;             PG8_WAIT_V(8); PG8_WAIT_L(0); PG8_BAR; PG8_MMA(0, 0, At, B0); PG8_MMA(0, 1, At, B1); PG8_BAR; PG8_SCHED;
;             PG8_LDA(At, 1, 1); PG8_STAGE(PG8_SB(1, 0), b3, voffB); PG8_STAGE(PG8_SB(1, 1), b3 + hsB, voffB); PG8_STAGE(PG8_SA(1, 0), a3, voffA);
;             PG8_WAIT_V(8); PG8_WAIT_L(0); PG8_BAR; PG8_MMA(1, 0, At, B0); PG8_MMA(1, 1, At, B1); PG8_BAR; PG8_SCHED;
.LBB0_191:
	ds_read_b128 v[128:131], v171
	ds_read_b128 v[132:135], v171 offset:1024
	ds_read_b128 v[154:157], v171 offset:2048
	ds_read_b128 v[158:161], v171 offset:3072
	ds_read_b128 v[162:165], v172
	ds_read_b128 v[166:169], v172 offset:1024
	ds_read_b128 v[178:181], v172 offset:2048
	ds_read_b128 v[182:185], v172 offset:3072
	s_add_u32 s47, s34, 0xfffc0080
	s_addc_u32 s50, s35, -1
	s_cmp_eq_u32 s97, 12
	s_cselect_b32 s63, s27, s50
	s_cselect_b32 s62, s89, s47
	s_cselect_b32 s51, s25, s96
	s_cselect_b32 s50, s94, s95
	v_lshl_add_u64 v[218:219], s[34:35], 0, v[148:149]
	s_add_i32 m0, s66, 0xc000
	ds_read_b128 v[186:189], v173
	ds_read_b128 v[190:193], v173 offset:1024
	ds_read_b128 v[194:197], v173 offset:2048
	ds_read_b128 v[198:201], v173 offset:3072
	ds_read_b128 v[202:205], v173 offset:4096
	ds_read_b128 v[206:209], v173 offset:5120
	ds_read_b128 v[210:213], v173 offset:6144
	ds_read_b128 v[214:217], v173 offset:7168
	global_load_lds_dwordx4 v[218:219], off
	v_lshl_add_u64 v[218:219], s[34:35], 0, v[146:147]
	s_add_i32 m0, s66, 0xe000
	s_nop 0
	global_load_lds_dwordx4 v[218:219], off
	s_waitcnt vmcnt(8)
	s_waitcnt lgkmcnt(0)
	s_barrier
	s_setprio 1
	s_waitcnt lgkmcnt(0)
	v_mfma_f32_16x16x32_bf16 v[124:127], v[128:131], v[186:189], v[124:127]
	v_mfma_f32_16x16x32_bf16 v[120:123], v[154:157], v[186:189], v[120:123]
	v_mfma_f32_16x16x32_bf16 v[116:119], v[128:131], v[194:197], v[116:119]
	v_mfma_f32_16x16x32_bf16 v[104:107], v[154:157], v[194:197], v[104:107]
	v_mfma_f32_16x16x32_bf16 v[92:95], v[128:131], v[202:205], v[92:95]
	v_mfma_f32_16x16x32_bf16 v[88:91], v[154:157], v[202:205], v[88:91]
	v_mfma_f32_16x16x32_bf16 v[84:87], v[128:131], v[210:213], v[84:87]
	v_mfma_f32_16x16x32_bf16 v[68:71], v[154:157], v[210:213], v[68:71]
	v_mfma_f32_16x16x32_bf16 v[124:127], v[132:135], v[190:193], v[124:127]
	v_mfma_f32_16x16x32_bf16 v[120:123], v[158:161], v[190:193], v[120:123]
	v_mfma_f32_16x16x32_bf16 v[116:119], v[132:135], v[198:201], v[116:119]
	v_mfma_f32_16x16x32_bf16 v[104:107], v[158:161], v[198:201], v[104:107]
	v_mfma_f32_16x16x32_bf16 v[92:95], v[132:135], v[206:209], v[92:95]
	v_mfma_f32_16x16x32_bf16 v[88:91], v[158:161], v[206:209], v[88:91]
	v_mfma_f32_16x16x32_bf16 v[84:87], v[132:135], v[214:217], v[84:87]
	v_mfma_f32_16x16x32_bf16 v[68:71], v[158:161], v[214:217], v[68:71]
	s_setprio 0
	s_setprio 1
	v_mfma_f32_16x16x32_bf16 v[112:115], v[162:165], v[186:189], v[112:115]
	v_mfma_f32_16x16x32_bf16 v[108:111], v[178:181], v[186:189], v[108:111]
	v_mfma_f32_16x16x32_bf16 v[100:103], v[162:165], v[194:197], v[100:103]
	v_mfma_f32_16x16x32_bf16 v[96:99], v[178:181], v[194:197], v[96:99]
	v_mfma_f32_16x16x32_bf16 v[80:83], v[162:165], v[202:205], v[80:83]
	v_mfma_f32_16x16x32_bf16 v[76:79], v[178:181], v[202:205], v[76:79]
	v_mfma_f32_16x16x32_bf16 v[72:75], v[162:165], v[210:213], v[72:75]
	v_mfma_f32_16x16x32_bf16 v[64:67], v[178:181], v[210:213], v[64:67]
	v_mfma_f32_16x16x32_bf16 v[112:115], v[166:169], v[190:193], v[112:115]
	v_mfma_f32_16x16x32_bf16 v[108:111], v[182:185], v[190:193], v[108:111]
	v_mfma_f32_16x16x32_bf16 v[100:103], v[166:169], v[198:201], v[100:103]
	v_mfma_f32_16x16x32_bf16 v[96:99], v[182:185], v[198:201], v[96:99]
	v_mfma_f32_16x16x32_bf16 v[80:83], v[166:169], v[206:209], v[80:83]
	v_mfma_f32_16x16x32_bf16 v[76:79], v[182:185], v[206:209], v[76:79]
	v_mfma_f32_16x16x32_bf16 v[72:75], v[166:169], v[214:217], v[72:75]
	v_mfma_f32_16x16x32_bf16 v[64:67], v[182:185], v[214:217], v[64:67]
	s_setprio 0
	s_barrier
	s_add_i32 s47, s81, s68
	v_lshl_add_u64 v[218:219], s[50:51], 0, v[138:139]
	s_mov_b32 m0, s47
	ds_read_b128 v[186:189], v173 offset:16384
	ds_read_b128 v[190:193], v173 offset:17408
	ds_read_b128 v[194:197], v173 offset:18432
	ds_read_b128 v[198:201], v173 offset:19456
	ds_read_b128 v[202:205], v173 offset:20480
	ds_read_b128 v[206:209], v173 offset:21504
	ds_read_b128 v[210:213], v173 offset:22528
	ds_read_b128 v[214:217], v173 offset:23552
	global_load_lds_dwordx4 v[218:219], off
	s_add_i32 m0, s47, 0x2000
	s_add_u32 s70, s50, 0x40000
	v_lshl_add_u64 v[220:221], s[50:51], 0, v[142:143]
	s_addc_u32 s71, s51, 0
	s_add_i32 s47, s82, s68
	global_load_lds_dwordx4 v[220:221], off
	v_lshl_add_u64 v[222:223], s[70:71], 0, v[138:139]
	s_mov_b32 m0, s47
	v_lshl_add_u64 v[224:225], s[62:63], 0, v[140:141]
	global_load_lds_dwordx4 v[222:223], off
	v_lshl_add_u64 v[222:223], s[70:71], 0, v[142:143]
	s_add_i32 m0, s47, 0x2000
	s_nop 0
	global_load_lds_dwordx4 v[222:223], off
	v_lshl_add_u64 v[222:223], s[62:63], 0, v[136:137]
	s_mov_b32 m0, s66
	s_nop 0
	global_load_lds_dwordx4 v[222:223], off
	s_mov_b32 m0, s67
	s_nop 0
	global_load_lds_dwordx4 v[224:225], off
	s_waitcnt vmcnt(8)
	s_waitcnt lgkmcnt(0)
	s_barrier
; #define PG8_STAGE(bufoff, gbase, voff) do { _Pragma("unroll") for (int _i = 0; _i < 2; ++_i) \
;         __builtin_amdgcn_global_load_lds((const unsigned*)((const char*)(gbase) + (voff)[_i]), (LAS unsigned*)(lds + (bufoff) + ldsw + _i * 8192), 16, 0, 0); } while (0)
; #define PG8_LDA(dst, b, h) do { _Pragma("unroll") for (int m = 0; m < 4; ++m) _Pragma("unroll") for (int k = 0; k < 2; ++k) dst[m][k] = *(const LAS bf16x8*)(lds + PG8_SA(b, h) + aoff + m * 2048 + k * 1024); } while (0)
; #define PG8_LDB(dst, b, h) do { _Pragma("unroll") for (int n = 0; n < 2; ++n) _Pragma("unroll") for (int k = 0; k < 2; ++k) dst[n][k] = *(const LAS bf16x8*)(lds + PG8_SB(b, h) + boff + n * 2048 + k * 1024); } while (0)
; #define PG8_MMA(ai, bj, At, Bt) do { __builtin_amdgcn_s_setprio(1); _Pragma("unroll") for (int m = 0; m < 4; ++m) _Pragma("unroll") for (int n = 0; n < 2; ++n) _Pragma("unroll") for (int k = 0; k < 2; ++k) \
;         acc[ai][bj][m][n] = __builtin_amdgcn_mfma_f32_16x16x32_bf16(Bt[n][k], At[m][k], acc[ai][bj][m][n], 0, 0, 0); __builtin_amdgcn_s_setprio(0); } while (0)
; #define PG8_WAIT_V(n) asm volatile("s_waitcnt vmcnt(" #n ")" ::: "memory")
; #define PG8_BAR __builtin_amdgcn_s_barrier()
; template <class Epi>
; __device__ __forceinline__ void gemm_phase(LAS unsigned char* lds, const Gemm g, const StaticOrder& S, const Epi& E, const int wid) {
;     ...
;             PG8_LDB(B0, 0, 0); PG8_LDB(B1, 0, 1); PG8_SCHED; PG8_LDA(At, 0, 0); PG8_STAGE(PG8_SA(1, 1), a1 + hsA, voffA);
;             PG8_WAIT_V(8); PG8_WAIT_L(0); PG8_BAR; PG8_MMA(0, 0, At, B0); PG8_MMA(0, 1, At, B1); PG8_BAR; PG8_SCHED;
;             PG8_LDA(At, 0, 1); PG8_STAGE(PG8_SB(0, 0), b2, voffB); PG8_STAGE(PG8_SB(0, 1), b2 + hsB, voffB); PG8_STAGE(PG8_SA(0, 0), a2, voffA);
;             PG8_WAIT_V(8); PG8_WAIT_L(0); PG8_BAR; PG8_MMA(1, 0, At, B0); PG8_MMA(1, 1, At, B1); PG8_BAR; PG8_SCHED;
;             PG8_LDB(B0, 1, 0); PG8_LDB(B1, 1, 1); PG8_SCHED; PG8_LDA(At, 1, 0); PG8_STAGE(PG8_SA(0, 1), a2 + hsA, voffA);
;             PG8_WAIT_V(8); PG8_WAIT_L(0); PG8_BAR; PG8_MMA(0, 0, At, B0); PG8_MMA(0, 1, At, B1); PG8_BAR; PG8_SCHED;
;             PG8_LDA(At, 1, 1); PG8_STAGE(PG8_SB(1, 0), b3, voffB); PG8_STAGE(PG8_SB(1, 1), b3 + hsB, voffB); PG8_STAGE(PG8_SA(1, 0), a3, voffA);
;             PG8_WAIT_V(8); PG8_WAIT_L(0); PG8_BAR; PG8_MMA(1, 0, At, B0); PG8_MMA(1, 1, At, B1); PG8_BAR; PG8_SCHED;
	s_setprio 1
	s_waitcnt lgkmcnt(0)
	v_mfma_f32_16x16x32_bf16 v[60:63], v[128:131], v[186:189], v[60:63]
	v_mfma_f32_16x16x32_bf16 v[56:59], v[154:157], v[186:189], v[56:59]
	v_mfma_f32_16x16x32_bf16 v[44:47], v[128:131], v[194:197], v[44:47]
	v_mfma_f32_16x16x32_bf16 v[40:43], v[154:157], v[194:197], v[40:43]
	v_mfma_f32_16x16x32_bf16 v[28:31], v[128:131], v[202:205], v[28:31]
	v_mfma_f32_16x16x32_bf16 v[24:27], v[154:157], v[202:205], v[24:27]
	v_mfma_f32_16x16x32_bf16 v[12:15], v[128:131], v[210:213], v[12:15]
	v_mfma_f32_16x16x32_bf16 v[8:11], v[154:157], v[210:213], v[8:11]
	v_mfma_f32_16x16x32_bf16 v[60:63], v[132:135], v[190:193], v[60:63]
	v_mfma_f32_16x16x32_bf16 v[56:59], v[158:161], v[190:193], v[56:59]
	v_mfma_f32_16x16x32_bf16 v[44:47], v[132:135], v[198:201], v[44:47]
	v_mfma_f32_16x16x32_bf16 v[40:43], v[158:161], v[198:201], v[40:43]
	v_mfma_f32_16x16x32_bf16 v[28:31], v[132:135], v[206:209], v[28:31]
	v_mfma_f32_16x16x32_bf16 v[24:27], v[158:161], v[206:209], v[24:27]
	v_mfma_f32_16x16x32_bf16 v[12:15], v[132:135], v[214:217], v[12:15]
	v_mfma_f32_16x16x32_bf16 v[8:11], v[158:161], v[214:217], v[8:11]
	s_setprio 0
	s_setprio 1
	v_mfma_f32_16x16x32_bf16 v[52:55], v[162:165], v[186:189], v[52:55]
	v_mfma_f32_16x16x32_bf16 v[48:51], v[178:181], v[186:189], v[48:51]
	v_mfma_f32_16x16x32_bf16 v[36:39], v[162:165], v[194:197], v[36:39]
	v_mfma_f32_16x16x32_bf16 v[32:35], v[178:181], v[194:197], v[32:35]
	v_mfma_f32_16x16x32_bf16 v[20:23], v[162:165], v[202:205], v[20:23]
	v_mfma_f32_16x16x32_bf16 v[16:19], v[178:181], v[202:205], v[16:19]
	v_mfma_f32_16x16x32_bf16 v[4:7], v[162:165], v[210:213], v[4:7]
	v_mfma_f32_16x16x32_bf16 v[0:3], v[178:181], v[210:213], v[0:3]
	v_mfma_f32_16x16x32_bf16 v[52:55], v[166:169], v[190:193], v[52:55]
	v_mfma_f32_16x16x32_bf16 v[48:51], v[182:185], v[190:193], v[48:51]
	v_mfma_f32_16x16x32_bf16 v[36:39], v[166:169], v[198:201], v[36:39]
	v_mfma_f32_16x16x32_bf16 v[32:35], v[182:185], v[198:201], v[32:35]
	v_mfma_f32_16x16x32_bf16 v[20:23], v[166:169], v[206:209], v[20:23]
	v_mfma_f32_16x16x32_bf16 v[16:19], v[182:185], v[206:209], v[16:19]
	v_mfma_f32_16x16x32_bf16 v[4:7], v[166:169], v[214:217], v[4:7]
	v_mfma_f32_16x16x32_bf16 v[0:3], v[182:185], v[214:217], v[0:3]
	s_setprio 0
	s_barrier
	s_add_i32 s47, 0, 0x18000
	v_add_u32_e32 v144, s47, v170
	s_add_i32 s70, 0, 0x1c000
	ds_read_b128 v[128:131], v144
	ds_read_b128 v[132:135], v144 offset:1024
	ds_read_b128 v[154:157], v144 offset:2048
	ds_read_b128 v[158:161], v144 offset:3072
	v_add_u32_e32 v144, s70, v170
	ds_read_b128 v[162:165], v144
	ds_read_b128 v[166:169], v144 offset:1024
	ds_read_b128 v[178:181], v144 offset:2048
	ds_read_b128 v[182:185], v144 offset:3072
	s_add_u32 s62, s62, 0x40000
	s_addc_u32 s63, s63, 0
	s_mov_b32 m0, s74
	v_lshl_add_u64 v[226:227], s[62:63], 0, v[136:137]
	ds_read_b128 v[186:189], v173 offset:32768
	ds_read_b128 v[190:193], v173 offset:33792
	ds_read_b128 v[194:197], v173 offset:34816
	ds_read_b128 v[198:201], v173 offset:35840
	ds_read_b128 v[202:205], v173 offset:36864
	ds_read_b128 v[206:209], v173 offset:37888
	ds_read_b128 v[210:213], v173 offset:38912
	ds_read_b128 v[214:217], v173 offset:39936
	global_load_lds_dwordx4 v[226:227], off
	v_lshl_add_u64 v[226:227], s[62:63], 0, v[140:141]
	s_mov_b32 m0, s75
	s_nop 0
	global_load_lds_dwordx4 v[226:227], off
	s_waitcnt vmcnt(8)
	s_waitcnt lgkmcnt(0)
	s_barrier
	s_setprio 1
	s_waitcnt lgkmcnt(0)
	v_mfma_f32_16x16x32_bf16 v[124:127], v[128:131], v[186:189], v[124:127]
	v_mfma_f32_16x16x32_bf16 v[120:123], v[154:157], v[186:189], v[120:123]
	v_mfma_f32_16x16x32_bf16 v[116:119], v[128:131], v[194:197], v[116:119]
	v_mfma_f32_16x16x32_bf16 v[104:107], v[154:157], v[194:197], v[104:107]
	v_mfma_f32_16x16x32_bf16 v[92:95], v[128:131], v[202:205], v[92:95]
	v_mfma_f32_16x16x32_bf16 v[88:91], v[154:157], v[202:205], v[88:91]
	v_mfma_f32_16x16x32_bf16 v[84:87], v[128:131], v[210:213], v[84:87]
	v_mfma_f32_16x16x32_bf16 v[68:71], v[154:157], v[210:213], v[68:71]
	v_mfma_f32_16x16x32_bf16 v[124:127], v[132:135], v[190:193], v[124:127]
	v_mfma_f32_16x16x32_bf16 v[120:123], v[158:161], v[190:193], v[120:123]
	v_mfma_f32_16x16x32_bf16 v[116:119], v[132:135], v[198:201], v[116:119]
	v_mfma_f32_16x16x32_bf16 v[104:107], v[158:161], v[198:201], v[104:107]
	v_mfma_f32_16x16x32_bf16 v[92:95], v[132:135], v[206:209], v[92:95]
	v_mfma_f32_16x16x32_bf16 v[88:91], v[158:161], v[206:209], v[88:91]
	v_mfma_f32_16x16x32_bf16 v[84:87], v[132:135], v[214:217], v[84:87]
	v_mfma_f32_16x16x32_bf16 v[68:71], v[158:161], v[214:217], v[68:71]
	s_setprio 0
	s_setprio 1
	v_mfma_f32_16x16x32_bf16 v[112:115], v[162:165], v[186:189], v[112:115]
	v_mfma_f32_16x16x32_bf16 v[108:111], v[178:181], v[186:189], v[108:111]
	v_mfma_f32_16x16x32_bf16 v[100:103], v[162:165], v[194:197], v[100:103]
	v_mfma_f32_16x16x32_bf16 v[96:99], v[178:181], v[194:197], v[96:99]
	v_mfma_f32_16x16x32_bf16 v[80:83], v[162:165], v[202:205], v[80:83]
	v_mfma_f32_16x16x32_bf16 v[76:79], v[178:181], v[202:205], v[76:79]
	v_mfma_f32_16x16x32_bf16 v[72:75], v[162:165], v[210:213], v[72:75]
	v_mfma_f32_16x16x32_bf16 v[64:67], v[178:181], v[210:213], v[64:67]
	v_mfma_f32_16x16x32_bf16 v[112:115], v[166:169], v[190:193], v[112:115]
	v_mfma_f32_16x16x32_bf16 v[108:111], v[182:185], v[190:193], v[108:111]
	v_mfma_f32_16x16x32_bf16 v[100:103], v[166:169], v[198:201], v[100:103]
	v_mfma_f32_16x16x32_bf16 v[96:99], v[182:185], v[198:201], v[96:99]
	v_mfma_f32_16x16x32_bf16 v[80:83], v[166:169], v[206:209], v[80:83]
	v_mfma_f32_16x16x32_bf16 v[76:79], v[182:185], v[206:209], v[76:79]
	v_mfma_f32_16x16x32_bf16 v[72:75], v[166:169], v[214:217], v[72:75]
	v_mfma_f32_16x16x32_bf16 v[64:67], v[182:185], v[214:217], v[64:67]
	s_setprio 0
	s_barrier
; __device__ __forceinline__ int lane_id_asm() { int l; asm volatile("v_mbcnt_lo_u32_b32 %0, -1, 0\n\tv_mbcnt_hi_u32_b32 %0, -1, %0" : "=v"(l)); return l; }
; #define PG8_STAGE(bufoff, gbase, voff) do { _Pragma("unroll") for (int _i = 0; _i < 2; ++_i) \
;         __builtin_amdgcn_global_load_lds((const unsigned*)((const char*)(gbase) + (voff)[_i]), (LAS unsigned*)(lds + (bufoff) + ldsw + _i * 8192), 16, 0, 0); } while (0)
; #define PG8_LDA(dst, b, h) do { _Pragma("unroll") for (int m = 0; m < 4; ++m) _Pragma("unroll") for (int k = 0; k < 2; ++k) dst[m][k] = *(const LAS bf16x8*)(lds + PG8_SA(b, h) + aoff + m * 2048 + k * 1024); } while (0)
; #define PG8_LDB(dst, b, h) do { _Pragma("unroll") for (int n = 0; n < 2; ++n) _Pragma("unroll") for (int k = 0; k < 2; ++k) dst[n][k] = *(const LAS bf16x8*)(lds + PG8_SB(b, h) + boff + n * 2048 + k * 1024); } while (0)
; #define PG8_WAIT_V(n) asm volatile("s_waitcnt vmcnt(" #n ")" ::: "memory")
; #define PG8_WAIT_L(n) asm volatile("s_waitcnt lgkmcnt(" #n ")" ::: "memory")
; #define PG8_BAR __builtin_amdgcn_s_barrier()
; template <class Epi>
; __device__ __forceinline__ void gemm_phase(LAS unsigned char* lds, const Gemm g, const StaticOrder& S, const Epi& E, const int wid) {
;     ...
;             PG8_WAIT_V(8); PG8_WAIT_L(0); PG8_BAR; PG8_MMA(1, 0, At, B0); PG8_MMA(1, 1, At, B1); PG8_BAR; PG8_SCHED;
;             PG8_LDB(B0, 1, 0); PG8_LDB(B1, 1, 1); PG8_SCHED; PG8_LDA(At, 1, 0); PG8_STAGE(PG8_SA(0, 1), a2 + hsA, voffA);
;             PG8_WAIT_V(8); PG8_WAIT_L(0); PG8_BAR; PG8_MMA(0, 0, At, B0); PG8_MMA(0, 1, At, B1); PG8_BAR; PG8_SCHED;
;             PG8_LDA(At, 1, 1); PG8_STAGE(PG8_SB(1, 0), b3, voffB); PG8_STAGE(PG8_SB(1, 1), b3 + hsB, voffB); PG8_STAGE(PG8_SA(1, 0), a3, voffA);
;             PG8_WAIT_V(8); PG8_WAIT_L(0); PG8_BAR; PG8_MMA(1, 0, At, B0); PG8_MMA(1, 1, At, B1); PG8_BAR; PG8_SCHED;
;         }
;         if (wr == 0) PG8_BAR;
;     __device__ __forceinline__ void operator()(const Acc& acc, const pg8::Unit& u, int wid) const {
;         const int lane_ = lane_id_asm(), wr = wid >> 2, wc = wid & 3, fr = lane_ & 15, fq = lane_ >> 4;
;         const int row0 = u.pm * 256 + wr * 64 + fr, colL = wc * 32 + 8 * fq, pn = u.pn;
;         float scv[8];
; #pragma unroll
;         for (int i = 0; i < 8; ++i) scv[i] = ssq[row0 + (i >> 2) * 128 + (i & 3) * 16];
;         if (pn < 8) {
	s_add_i32 s47, s47, s68
	v_lshl_add_u64 v[218:219], v[218:219], 0, s[14:15]
	s_mov_b32 m0, s47
	ds_read_b128 v[186:189], v173 offset:49152
	ds_read_b128 v[190:193], v173 offset:50176
	ds_read_b128 v[194:197], v173 offset:51200
	ds_read_b128 v[198:201], v173 offset:52224
	ds_read_b128 v[202:205], v173 offset:53248
	ds_read_b128 v[206:209], v173 offset:54272
	ds_read_b128 v[210:213], v173 offset:55296
	ds_read_b128 v[214:217], v173 offset:56320
	global_load_lds_dwordx4 v[218:219], off
	s_add_i32 m0, s47, 0x2000
	s_add_u32 s50, s50, 0x40080
	v_lshl_add_u64 v[218:219], v[220:221], 0, s[14:15]
	s_addc_u32 s51, s51, 0
	s_add_i32 s47, s70, s68
	global_load_lds_dwordx4 v[218:219], off
	v_lshl_add_u64 v[218:219], s[50:51], 0, v[138:139]
	s_mov_b32 m0, s47
	s_nop 0
	global_load_lds_dwordx4 v[218:219], off
	v_lshl_add_u64 v[218:219], s[50:51], 0, v[142:143]
	s_add_i32 m0, s47, 0x2000
	s_nop 0
	global_load_lds_dwordx4 v[218:219], off
	v_lshl_add_u64 v[218:219], v[222:223], 0, s[14:15]
	s_mov_b32 m0, s76
	s_nop 0
	global_load_lds_dwordx4 v[218:219], off
	v_lshl_add_u64 v[218:219], v[224:225], 0, s[14:15]
	s_mov_b32 m0, s77
	s_nop 0
	global_load_lds_dwordx4 v[218:219], off
	s_waitcnt vmcnt(8)
	s_waitcnt lgkmcnt(0)
	s_barrier
	s_setprio 1
	s_waitcnt lgkmcnt(0)
	v_mfma_f32_16x16x32_bf16 v[60:63], v[128:131], v[186:189], v[60:63]
	v_mfma_f32_16x16x32_bf16 v[56:59], v[154:157], v[186:189], v[56:59]
	v_mfma_f32_16x16x32_bf16 v[44:47], v[128:131], v[194:197], v[44:47]
	v_mfma_f32_16x16x32_bf16 v[40:43], v[154:157], v[194:197], v[40:43]
	v_mfma_f32_16x16x32_bf16 v[28:31], v[128:131], v[202:205], v[28:31]
	v_mfma_f32_16x16x32_bf16 v[24:27], v[154:157], v[202:205], v[24:27]
	v_mfma_f32_16x16x32_bf16 v[12:15], v[128:131], v[210:213], v[12:15]
	v_mfma_f32_16x16x32_bf16 v[8:11], v[154:157], v[210:213], v[8:11]
	v_mfma_f32_16x16x32_bf16 v[60:63], v[132:135], v[190:193], v[60:63]
	v_mfma_f32_16x16x32_bf16 v[56:59], v[158:161], v[190:193], v[56:59]
	v_mfma_f32_16x16x32_bf16 v[44:47], v[132:135], v[198:201], v[44:47]
	v_mfma_f32_16x16x32_bf16 v[40:43], v[158:161], v[198:201], v[40:43]
	v_mfma_f32_16x16x32_bf16 v[28:31], v[132:135], v[206:209], v[28:31]
	v_mfma_f32_16x16x32_bf16 v[24:27], v[158:161], v[206:209], v[24:27]
	v_mfma_f32_16x16x32_bf16 v[12:15], v[132:135], v[214:217], v[12:15]
	v_mfma_f32_16x16x32_bf16 v[8:11], v[158:161], v[214:217], v[8:11]
	s_setprio 0
	s_setprio 1
	v_mfma_f32_16x16x32_bf16 v[52:55], v[162:165], v[186:189], v[52:55]
	v_mfma_f32_16x16x32_bf16 v[48:51], v[178:181], v[186:189], v[48:51]
	v_mfma_f32_16x16x32_bf16 v[36:39], v[162:165], v[194:197], v[36:39]
	v_mfma_f32_16x16x32_bf16 v[32:35], v[178:181], v[194:197], v[32:35]
	v_mfma_f32_16x16x32_bf16 v[20:23], v[162:165], v[202:205], v[20:23]
	v_mfma_f32_16x16x32_bf16 v[16:19], v[178:181], v[202:205], v[16:19]
	v_mfma_f32_16x16x32_bf16 v[4:7], v[162:165], v[210:213], v[4:7]
	v_mfma_f32_16x16x32_bf16 v[0:3], v[178:181], v[210:213], v[0:3]
	v_mfma_f32_16x16x32_bf16 v[52:55], v[166:169], v[190:193], v[52:55]
	v_mfma_f32_16x16x32_bf16 v[48:51], v[182:185], v[190:193], v[48:51]
	v_mfma_f32_16x16x32_bf16 v[36:39], v[166:169], v[198:201], v[36:39]
	v_mfma_f32_16x16x32_bf16 v[32:35], v[182:185], v[198:201], v[32:35]
	v_mfma_f32_16x16x32_bf16 v[20:23], v[166:169], v[206:209], v[20:23]
	v_mfma_f32_16x16x32_bf16 v[16:19], v[182:185], v[206:209], v[16:19]
	v_mfma_f32_16x16x32_bf16 v[4:7], v[166:169], v[214:217], v[4:7]
	v_mfma_f32_16x16x32_bf16 v[0:3], v[182:185], v[214:217], v[0:3]
	s_setprio 0
	s_barrier
	s_add_i32 s97, s97, 2
	s_add_u32 s95, s95, 0x100
	s_addc_u32 s96, s96, 0
	s_add_u32 s34, s34, 0x100
	s_addc_u32 s35, s35, 0
	s_cmp_gt_u32 s97, 13
	s_cbranch_scc0 .LBB0_191
.LBB0_194:
	s_lshl_b32 s4, s4, 8
	v_mbcnt_lo_u32_b32 v130, -1, 0
	v_mbcnt_hi_u32_b32 v130, -1, v130
	s_add_i32 s4, s4, s78
	v_and_b32_e32 v144, 15, v130
	v_or_b32_e32 v156, s4, v144
	v_ashrrev_i32_e32 v157, 31, v156
	v_lshl_add_u64 v[128:129], v[156:157], 2, s[54:55]
	flat_load_dword v131, v[128:129]
	flat_load_dword v132, v[128:129] offset:64
	flat_load_dword v133, v[128:129] offset:128
	flat_load_dword v134, v[128:129] offset:192
	flat_load_dword v135, v[128:129] offset:512
	flat_load_dword v158, v[128:129] offset:576
	flat_load_dword v159, v[128:129] offset:640
	flat_load_dword v160, v[128:129] offset:704
	v_ashrrev_i32_e32 v128, 1, v130
	v_and_b32_e32 v129, -8, v128
	v_add_u32_e32 v128, 0x80, v156
	v_add_u32_e32 v164, s69, v129
	v_ashrrev_i32_e32 v129, 31, v128
	v_lshlrev_b64 v[154:155], 12, v[128:129]
	v_lshlrev_b64 v[166:167], 12, v[156:157]
	s_mov_b64 s[34:35], -1
	s_cmp_gt_i32 s93, 7
	v_ashrrev_i32_e32 v165, 31, v164
	v_or_b32_e32 v162, 16, v156
	s_waitcnt vmcnt(0) lgkmcnt(0)
	v_fmamk_f32 v128, v131, 0x3a800000, v174
	v_fmamk_f32 v129, v132, 0x3a800000, v174
	v_fmamk_f32 v130, v133, 0x3a800000, v174
	v_fmamk_f32 v131, v134, 0x3a800000, v174
	v_fmamk_f32 v132, v135, 0x3a800000, v174
	v_fmamk_f32 v133, v158, 0x3a800000, v174
	v_fmamk_f32 v134, v159, 0x3a800000, v174
	v_fmamk_f32 v135, v160, 0x3a800000, v174
	v_rsq_f32_e32 v183, v128
	v_rsq_f32_e32 v182, v129
	v_rsq_f32_e32 v181, v130
	v_rsq_f32_e32 v180, v131
	v_rsq_f32_e32 v179, v132
	v_rsq_f32_e32 v178, v133
	v_rsq_f32_e32 v177, v134
	v_rsq_f32_e32 v157, v135
	v_or_b32_e32 v160, 32, v156
	v_or_b32_e32 v158, 48, v156
	s_cbranch_scc0 .LBB0_196
; __device__ __forceinline__ u32x4 pack8(f32x4 a, f32x4 b) { u32x4 w; w.x = pk2(a[0], a[1]); w.y = pk2(a[2], a[3]); w.z = pk2(b[0], b[1]); w.w = pk2(b[2], b[3]); return w; }
;     __device__ __forceinline__ void operator()(const Acc& acc, const pg8::Unit& u, int wid) const {
;     ...
;             const float lgh = __builtin_amdgcn_logf(1.f - __builtin_amdgcn_exp2f(-5.f - (float)((pn - 8) >> 1)));
; #pragma unroll
;             for (int ai = 0; ai < 2; ++ai)
; #pragma unroll
;                 for (int m = 0; m < 4; ++m) { const int row = row0 + ai * 128 + m * 16;
;                     const float sc = __builtin_amdgcn_rsqf(scv[ai * 4 + m] * (1.f / 1024.f) + EPS) * __builtin_amdgcn_exp2f(lgh * (float)(63 - (row & 63)));
;                     bf16_t* p = V + (size_t)row * 2048 + (pn - 8) * 256 + colL;
; #pragma unroll
;                     for (int bj = 0; bj < 2; ++bj) *(u32x4*)(p + bj * 128) = pack8(acc[ai][bj][m][0] * sc, acc[ai][bj][m][1] * sc); }
	s_add_i32 s4, s93, -8
	s_lshr_b32 s25, s4, 1
	v_cvt_f32_u32_e32 v128, s25
	v_xor_b32_e32 v130, 63, v144
	v_cvt_f32_ubyte0_e32 v130, v130
	s_lshl_b32 s4, s4, 9
	v_sub_f32_e32 v128, 0xc0a00000, v128
	v_exp_f32_e32 v128, v128
	v_lshlrev_b64 v[134:135], 1, v[164:165]
	v_ashrrev_i32_e32 v163, 31, v162
	v_ashrrev_i32_e32 v161, 31, v160
	v_sub_f32_e32 v128, 1.0, v128
	v_log_f32_e32 v159, v128
	v_lshl_add_u64 v[128:129], s[36:37], 0, v[166:167]
	v_lshl_add_u64 v[128:129], v[128:129], 0, s[4:5]
	v_lshl_add_u64 v[128:129], v[128:129], 0, v[134:135]
	v_mul_f32_e32 v130, v159, v130
	v_exp_f32_e32 v190, v130
	s_mov_b64 s[34:35], 0
	v_mul_f32_e32 v168, v183, v190
	v_pk_mul_f32 v[132:133], v[126:127], v[168:169] op_sel_hi:[1,0]
	v_pk_mul_f32 v[130:131], v[124:125], v[168:169] op_sel_hi:[1,0]
	v_pk_mul_f32 v[184:185], v[122:123], v[168:169] op_sel_hi:[1,0]
	v_pk_mul_f32 v[186:187], v[120:121], v[168:169] op_sel_hi:[1,0]
	v_cvt_pk_bf16_f32 v130, v130, v131
	v_cvt_pk_bf16_f32 v131, v132, v133
	v_cvt_pk_bf16_f32 v132, v186, v187
	v_cvt_pk_bf16_f32 v133, v184, v185
	flat_store_dwordx4 v[128:129], v[130:133]
	v_pk_mul_f32 v[184:185], v[110:111], v[168:169] op_sel_hi:[1,0]
	s_nop 0
	v_pk_mul_f32 v[132:133], v[114:115], v[168:169] op_sel_hi:[1,0]
	v_pk_mul_f32 v[130:131], v[112:113], v[168:169] op_sel_hi:[1,0]
	v_pk_mul_f32 v[168:169], v[108:109], v[168:169] op_sel_hi:[1,0]
	v_cvt_pk_bf16_f32 v130, v130, v131
	v_cvt_pk_bf16_f32 v131, v132, v133
	v_xor_b32_e32 v132, 47, v144
	v_cvt_f32_ubyte0_e32 v132, v132
	v_mul_f32_e32 v132, v159, v132
	v_exp_f32_e32 v191, v132
	v_cvt_pk_bf16_f32 v132, v168, v169
	v_cvt_pk_bf16_f32 v133, v184, v185
	flat_store_dwordx4 v[128:129], v[130:133] offset:256
	v_mul_f32_e32 v168, v191, v182
	v_pk_mul_f32 v[186:187], v[106:107], v[168:169] op_sel_hi:[1,0]
	v_lshlrev_b64 v[130:131], 12, v[162:163]
	v_lshl_add_u64 v[130:131], s[36:37], 0, v[130:131]
	v_lshl_add_u64 v[130:131], v[130:131], 0, s[4:5]
	v_lshl_add_u64 v[184:185], v[130:131], 0, v[134:135]
	v_pk_mul_f32 v[132:133], v[118:119], v[168:169] op_sel_hi:[1,0]
	v_pk_mul_f32 v[130:131], v[116:117], v[168:169] op_sel_hi:[1,0]
	v_pk_mul_f32 v[188:189], v[104:105], v[168:169] op_sel_hi:[1,0]
	v_cvt_pk_bf16_f32 v130, v130, v131
	v_cvt_pk_bf16_f32 v131, v132, v133
	v_cvt_pk_bf16_f32 v132, v188, v189
	v_cvt_pk_bf16_f32 v133, v186, v187
	flat_store_dwordx4 v[184:185], v[130:133]
	v_pk_mul_f32 v[186:187], v[98:99], v[168:169] op_sel_hi:[1,0]
	s_nop 0
	v_pk_mul_f32 v[132:133], v[102:103], v[168:169] op_sel_hi:[1,0]
	v_pk_mul_f32 v[130:131], v[100:101], v[168:169] op_sel_hi:[1,0]
	v_pk_mul_f32 v[168:169], v[96:97], v[168:169] op_sel_hi:[1,0]
	v_cvt_pk_bf16_f32 v130, v130, v131
	v_cvt_pk_bf16_f32 v131, v132, v133
	v_xor_b32_e32 v132, 31, v144
	v_cvt_f32_ubyte0_e32 v132, v132
	v_mul_f32_e32 v132, v159, v132
	v_exp_f32_e32 v163, v132
	v_cvt_pk_bf16_f32 v132, v168, v169
	v_cvt_pk_bf16_f32 v133, v186, v187
	flat_store_dwordx4 v[184:185], v[130:133] offset:256
	v_mul_f32_e32 v168, v163, v181
	v_pk_mul_f32 v[186:187], v[90:91], v[168:169] op_sel_hi:[1,0]
	v_lshlrev_b64 v[130:131], 12, v[160:161]
	v_lshl_add_u64 v[130:131], s[36:37], 0, v[130:131]
	v_lshl_add_u64 v[130:131], v[130:131], 0, s[4:5]
	v_lshl_add_u64 v[184:185], v[130:131], 0, v[134:135]
	v_pk_mul_f32 v[132:133], v[94:95], v[168:169] op_sel_hi:[1,0]
	v_pk_mul_f32 v[130:131], v[92:93], v[168:169] op_sel_hi:[1,0]
	v_pk_mul_f32 v[188:189], v[88:89], v[168:169] op_sel_hi:[1,0]
	v_cvt_pk_bf16_f32 v130, v130, v131
	v_cvt_pk_bf16_f32 v131, v132, v133
	v_cvt_pk_bf16_f32 v132, v188, v189
	v_cvt_pk_bf16_f32 v133, v186, v187
	flat_store_dwordx4 v[184:185], v[130:133]
	v_pk_mul_f32 v[186:187], v[78:79], v[168:169] op_sel_hi:[1,0]
	s_nop 0
	v_pk_mul_f32 v[132:133], v[82:83], v[168:169] op_sel_hi:[1,0]
	v_pk_mul_f32 v[130:131], v[80:81], v[168:169] op_sel_hi:[1,0]
	v_pk_mul_f32 v[168:169], v[76:77], v[168:169] op_sel_hi:[1,0]
	v_cvt_pk_bf16_f32 v130, v130, v131
	v_cvt_pk_bf16_f32 v131, v132, v133
	v_xor_b32_e32 v132, 15, v144
	v_cvt_f32_ubyte0_e32 v132, v132
	v_mul_f32_e32 v132, v159, v132
	v_exp_f32_e32 v161, v132
	v_cvt_pk_bf16_f32 v132, v168, v169
	v_cvt_pk_bf16_f32 v133, v186, v187
	v_ashrrev_i32_e32 v159, 31, v158
	flat_store_dwordx4 v[184:185], v[130:133] offset:256
	v_mul_f32_e32 v144, v161, v180
	v_pk_mul_f32 v[184:185], v[70:71], v[144:145] op_sel_hi:[1,0]
	v_lshlrev_b64 v[130:131], 12, v[158:159]
	v_lshl_add_u64 v[130:131], s[36:37], 0, v[130:131]
	v_lshl_add_u64 v[130:131], v[130:131], 0, s[4:5]
	v_lshl_add_u64 v[168:169], v[130:131], 0, v[134:135]
	v_pk_mul_f32 v[132:133], v[86:87], v[144:145] op_sel_hi:[1,0]
	v_pk_mul_f32 v[130:131], v[84:85], v[144:145] op_sel_hi:[1,0]
	v_pk_mul_f32 v[186:187], v[68:69], v[144:145] op_sel_hi:[1,0]
; __device__ __forceinline__ u32x4 pack8(f32x4 a, f32x4 b) { u32x4 w; w.x = pk2(a[0], a[1]); w.y = pk2(a[2], a[3]); w.z = pk2(b[0], b[1]); w.w = pk2(b[2], b[3]); return w; }
;     __device__ __forceinline__ void operator()(const Acc& acc, const pg8::Unit& u, int wid) const {
;     ...
;             for (int ai = 0; ai < 2; ++ai)
; #pragma unroll
;                 for (int m = 0; m < 4; ++m) { const int row = row0 + ai * 128 + m * 16;
;                     const float sc = __builtin_amdgcn_rsqf(scv[ai * 4 + m] * (1.f / 1024.f) + EPS) * __builtin_amdgcn_exp2f(lgh * (float)(63 - (row & 63)));
;                     bf16_t* p = V + (size_t)row * 2048 + (pn - 8) * 256 + colL;
; #pragma unroll
;                     for (int bj = 0; bj < 2; ++bj) *(u32x4*)(p + bj * 128) = pack8(acc[ai][bj][m][0] * sc, acc[ai][bj][m][1] * sc); }
	v_cvt_pk_bf16_f32 v130, v130, v131
	v_cvt_pk_bf16_f32 v131, v132, v133
	v_cvt_pk_bf16_f32 v132, v186, v187
	v_cvt_pk_bf16_f32 v133, v184, v185
	flat_store_dwordx4 v[168:169], v[130:133]
	v_pk_mul_f32 v[184:185], v[66:67], v[144:145] op_sel_hi:[1,0]
	v_pk_mul_f32 v[186:187], v[64:65], v[144:145] op_sel_hi:[1,0]
	v_pk_mul_f32 v[132:133], v[74:75], v[144:145] op_sel_hi:[1,0]
	v_pk_mul_f32 v[130:131], v[72:73], v[144:145] op_sel_hi:[1,0]
	v_mul_f32_e32 v144, v190, v179
	v_cvt_pk_bf16_f32 v130, v130, v131
	v_cvt_pk_bf16_f32 v131, v132, v133
	v_cvt_pk_bf16_f32 v132, v186, v187
	v_cvt_pk_bf16_f32 v133, v184, v185
	flat_store_dwordx4 v[168:169], v[130:133] offset:256
	v_pk_mul_f32 v[168:169], v[58:59], v[144:145] op_sel_hi:[1,0]
	v_pk_mul_f32 v[184:185], v[56:57], v[144:145] op_sel_hi:[1,0]
	v_lshl_add_u64 v[130:131], s[36:37], 0, v[154:155]
	v_lshl_add_u64 v[130:131], v[130:131], 0, s[4:5]
	v_lshl_add_u64 v[134:135], v[130:131], 0, v[134:135]
	v_pk_mul_f32 v[132:133], v[62:63], v[144:145] op_sel_hi:[1,0]
	v_pk_mul_f32 v[130:131], v[60:61], v[144:145] op_sel_hi:[1,0]
	s_nop 0
	v_cvt_pk_bf16_f32 v130, v130, v131
	v_cvt_pk_bf16_f32 v131, v132, v133
	v_cvt_pk_bf16_f32 v132, v184, v185
	v_cvt_pk_bf16_f32 v133, v168, v169
	flat_store_dwordx4 v[134:135], v[130:133]
	v_pk_mul_f32 v[168:169], v[50:51], v[144:145] op_sel_hi:[1,0]
	v_pk_mul_f32 v[184:185], v[48:49], v[144:145] op_sel_hi:[1,0]
	v_pk_mul_f32 v[132:133], v[54:55], v[144:145] op_sel_hi:[1,0]
	v_pk_mul_f32 v[130:131], v[52:53], v[144:145] op_sel_hi:[1,0]
	v_mul_f32_e32 v144, v161, v157
	v_cvt_pk_bf16_f32 v130, v130, v131
	v_cvt_pk_bf16_f32 v131, v132, v133
	v_cvt_pk_bf16_f32 v132, v184, v185
	v_cvt_pk_bf16_f32 v133, v168, v169
	flat_store_dwordx4 v[134:135], v[130:133] offset:256
	v_mul_f32_e32 v134, v191, v178
	v_pk_mul_f32 v[184:185], v[42:43], v[134:135] op_sel_hi:[1,0]
	v_pk_mul_f32 v[132:133], v[46:47], v[134:135] op_sel_hi:[1,0]
	v_pk_mul_f32 v[130:131], v[44:45], v[134:135] op_sel_hi:[1,0]
	v_pk_mul_f32 v[186:187], v[40:41], v[134:135] op_sel_hi:[1,0]
	v_cvt_pk_bf16_f32 v130, v130, v131
	v_cvt_pk_bf16_f32 v131, v132, v133
	v_cvt_pk_bf16_f32 v133, v184, v185
	v_add_co_u32_e32 v184, vcc, s83, v128
	v_cvt_pk_bf16_f32 v132, v186, v187
	s_nop 0
	v_addc_co_u32_e32 v185, vcc, 0, v129, vcc
	flat_store_dwordx4 v[184:185], v[130:133]
	v_pk_mul_f32 v[184:185], v[34:35], v[134:135] op_sel_hi:[1,0]
	v_lshl_add_u64 v[168:169], v[128:129], 0, s[18:19]
	v_pk_mul_f32 v[132:133], v[38:39], v[134:135] op_sel_hi:[1,0]
	v_pk_mul_f32 v[130:131], v[36:37], v[134:135] op_sel_hi:[1,0]
	v_pk_mul_f32 v[134:135], v[32:33], v[134:135] op_sel_hi:[1,0]
	v_cvt_pk_bf16_f32 v130, v130, v131
	v_cvt_pk_bf16_f32 v131, v132, v133
	v_cvt_pk_bf16_f32 v132, v134, v135
	v_cvt_pk_bf16_f32 v133, v184, v185
	v_mul_f32_e32 v134, v163, v177
	flat_store_dwordx4 v[168:169], v[130:133] offset:256
	v_pk_mul_f32 v[184:185], v[26:27], v[134:135] op_sel_hi:[1,0]
	v_pk_mul_f32 v[186:187], v[24:25], v[134:135] op_sel_hi:[1,0]
	v_pk_mul_f32 v[132:133], v[30:31], v[134:135] op_sel_hi:[1,0]
	v_pk_mul_f32 v[130:131], v[28:29], v[134:135] op_sel_hi:[1,0]
	v_lshl_add_u64 v[168:169], v[128:129], 0, s[20:21]
	v_cvt_pk_bf16_f32 v130, v130, v131
	v_cvt_pk_bf16_f32 v131, v132, v133
	v_cvt_pk_bf16_f32 v133, v184, v185
	v_add_co_u32_e32 v184, vcc, s90, v128
	v_cvt_pk_bf16_f32 v132, v186, v187
	s_nop 0
	v_addc_co_u32_e32 v185, vcc, 0, v129, vcc
	flat_store_dwordx4 v[184:185], v[130:133]
	v_pk_mul_f32 v[184:185], v[18:19], v[134:135] op_sel_hi:[1,0]
	s_nop 0
	v_pk_mul_f32 v[132:133], v[22:23], v[134:135] op_sel_hi:[1,0]
	v_pk_mul_f32 v[130:131], v[20:21], v[134:135] op_sel_hi:[1,0]
	v_pk_mul_f32 v[134:135], v[16:17], v[134:135] op_sel_hi:[1,0]
	v_cvt_pk_bf16_f32 v130, v130, v131
	v_cvt_pk_bf16_f32 v131, v132, v133
	v_cvt_pk_bf16_f32 v132, v134, v135
	v_cvt_pk_bf16_f32 v133, v184, v185
	flat_store_dwordx4 v[168:169], v[130:133] offset:256
	v_lshl_add_u64 v[168:169], v[128:129], 0, s[22:23]
	v_pk_mul_f32 v[134:135], v[10:11], v[144:145] op_sel_hi:[1,0]
	v_pk_mul_f32 v[132:133], v[14:15], v[144:145] op_sel_hi:[1,0]
	v_pk_mul_f32 v[130:131], v[12:13], v[144:145] op_sel_hi:[1,0]
	v_pk_mul_f32 v[184:185], v[8:9], v[144:145] op_sel_hi:[1,0]
	v_add_co_u32_e32 v128, vcc, s91, v128
	v_cvt_pk_bf16_f32 v130, v130, v131
	v_cvt_pk_bf16_f32 v131, v132, v133
	v_cvt_pk_bf16_f32 v132, v184, v185
	v_cvt_pk_bf16_f32 v133, v134, v135
	v_addc_co_u32_e32 v129, vcc, 0, v129, vcc
	flat_store_dwordx4 v[128:129], v[130:133]
	v_pk_mul_f32 v[128:129], v[4:5], v[144:145] op_sel_hi:[1,0]
	v_pk_mul_f32 v[134:135], v[2:3], v[144:145] op_sel_hi:[1,0]
	v_pk_mul_f32 v[130:131], v[6:7], v[144:145] op_sel_hi:[1,0]
	v_pk_mul_f32 v[132:133], v[0:1], v[144:145] op_sel_hi:[1,0]

; #define PG8_WAIT_V(n) asm volatile("s_waitcnt vmcnt(" #n ")" ::: "memory")
; #define PG8_BAR __builtin_amdgcn_s_barrier()
; template <class Epi>
; __device__ __forceinline__ void gemm_phase(LAS unsigned char* lds, const Gemm g, const StaticOrder& S, const Epi& E, const int wid) {
;     ...
;         E(acc, cur, wid);
;         if (!has_next) break;
; #pragma unroll
;         for (int a = 0; a < 2; ++a)
; #pragma unroll
;             for (int b = 0; b < 2; ++b)
; #pragma unroll
;                 for (int m = 0; m < 4; ++m)
; #pragma unroll
;                     for (int n = 0; n < 2; ++n) acc[a][b][m][n] = (f32x4){0.f, 0.f, 0.f, 0.f};
;         cur = nxt; cA = nA; cB = nB; ++ui;
;         if (wr == 1) PG8_BAR;
;     }
;     PG8_WAIT_V(0);
;     PG8_BAR;
.LBB0_198:
	s_nop 1
	v_cvt_pk_bf16_f32 v0, v128, v129
	v_cvt_pk_bf16_f32 v1, v130, v131
	v_cvt_pk_bf16_f32 v2, v132, v133
	v_cvt_pk_bf16_f32 v3, v134, v135
	s_andn2_b64 vcc, exec, s[0:1]
	s_mov_b64 s[0:1], -1
	flat_store_dwordx4 v[168:169], v[0:3] offset:256
	s_cbranch_vccnz .LBB0_183
	s_branch .LBB0_182
.LBB0_201:
	s_and_b64 vcc, exec, s[16:17]
	s_cbranch_vccz .Lna_0
	s_barrier

;     __device__ __forceinline__ void operator()(const Acc& acc, const pg8::Unit& u, int wid) const {
;         const int lane_ = lane_id_asm(), wr = wid >> 2, wc = wid & 3, fr = lane_ & 15, fq = lane_ >> 4;
;         const int row0 = u.pm * 256 + wr * 64 + fr, col0 = u.pn * 256 + wc * 32 + 8 * fq, head = u.pn >> 1;
;         f32x4 g4[2][2];
; #pragma unroll
;         for (int bj = 0; bj < 2; ++bj) { g4[bj][0] = *(const f32x4*)(gn + col0 + bj * 128); g4[bj][1] = *(const f32x4*)(gn + col0 + bj * 128 + 4); }
; #pragma unroll
;         for (int ai = 0; ai < 2; ++ai)
; #pragma unroll
;             for (int mp = 0; mp < 2; ++mp) {
;                 float scv[2]; f32x4 rq[2][4]; u32x4 ov[2][2];
; #pragma unroll
;                 for (int mm = 0; mm < 2; ++mm) { const int row = row0 + ai * 128 + (2 * mp + mm) * 16;
;                     scv[mm] = ssq[row];
;                     const f32x4* rp = (const f32x4*)(rssq + (size_t)row * 64 + head * 16);
; #pragma unroll
;                     for (int i = 0; i < 4; ++i) rq[mm][i] = rp[i];
; #pragma unroll
;                     for (int bj = 0; bj < 2; ++bj) ov[mm][bj] = *(const u32x4*)(Y + (size_t)row * 2048 + col0 + bj * 128); }
; #pragma unroll
;                 for (int mm = 0; mm < 2; ++mm) { const int m = 2 * mp + mm, row = row0 + ai * 128 + m * 16;
;                     const float sc = __builtin_amdgcn_rsqf(scv[mm] * (1.f / 1024.f) + EPS);
;                     const f32x4 pa = (rq[mm][0] + rq[mm][1]) + (rq[mm][2] + rq[mm][3]);
;                     const float rg = __builtin_amdgcn_rsqf(((pa[0] + pa[1]) + (pa[2] + pa[3])) * (1.f / 512.f) + EPS);
; #pragma unroll
;                     for (int bj = 0; bj < 2; ++bj) {
;                         const u32x4 w = ov[mm][bj];
;                         f32x4 o0 = (f32x4){bflo(w.x), bfhi(w.x), bflo(w.y), bfhi(w.y)}, o1 = (f32x4){bflo(w.z), bfhi(w.z), bflo(w.w), bfhi(w.w)};
;                         f32x4 a0 = acc[ai][bj][m][0] * sc, a1 = acc[ai][bj][m][1] * sc;
; #pragma unroll
;                         for (int e = 0; e < 4; ++e) { a0[e] = a0[e] * __builtin_amdgcn_rcpf(1.f + __builtin_amdgcn_exp2f(-1.4426950408889634f * a0[e])); a1[e] = a1[e] * __builtin_amdgcn_rcpf(1.f + __builtin_amdgcn_exp2f(-1.4426950408889634f * a1[e])); }
;                         o0 = a0 * o0 * g4[bj][0] * rg; o1 = a1 * o1 * g4[bj][1] * rg;
.LBB0_334:
	s_lshl_b32 s11, s22, 8
	s_add_i32 s11, s11, s66
	v_mbcnt_lo_u32_b32 v50, -1, 0
	v_mbcnt_hi_u32_b32 v50, -1, v50
	s_lshl_b32 s15, s20, 8
	v_and_or_b32 v186, v50, 15, s11
	s_lshl_b32 s11, s20, 3
	s_and_b32 s20, s11, -16
	s_ashr_i32 s21, s20, 31
	s_or_b32 s15, s15, s69
	s_lshl_b64 s[20:21], s[20:21], 2
	s_add_u32 s20, s60, s20
	v_ashrrev_i32_e32 v187, 31, v186
	v_ashrrev_i32_e32 v48, 1, v50
	s_addc_u32 s21, s61, s21
	v_lshl_add_u64 v[188:189], v[186:187], 2, s[54:55]
	v_lshlrev_b64 v[50:51], 8, v[186:187]
	v_lshl_add_u64 v[50:51], s[20:21], 0, v[50:51]
	flat_load_dword v199, v[188:189]
	flat_load_dwordx4 v[200:203], v[50:51]
	flat_load_dwordx4 v[204:207], v[50:51] offset:16
	flat_load_dwordx4 v[208:211], v[50:51] offset:32
	flat_load_dwordx4 v[212:215], v[50:51] offset:48
	v_and_b32_e32 v48, -8, v48
	v_add_u32_e32 v48, s15, v48
	v_ashrrev_i32_e32 v49, 31, v48
	v_lshlrev_b64 v[184:185], 1, v[48:49]
	v_lshl_add_u64 v[190:191], s[36:37], 0, v[184:185]
	v_lshlrev_b64 v[224:225], 12, v[186:187]
	v_lshl_add_u64 v[144:145], v[190:191], 0, v[224:225]
	flat_load_dwordx4 v[216:219], v[144:145]
	v_lshl_add_u64 v[48:49], v[48:49], 2, s[48:49]
	v_or_b32_e32 v50, 16, v186
	flat_load_dwordx4 v[64:67], v[48:49]
	v_ashrrev_i32_e32 v51, 31, v50
	v_lshlrev_b64 v[146:147], 8, v[50:51]
	v_lshlrev_b64 v[192:193], 12, v[50:51]
	flat_load_dwordx4 v[68:71], v[48:49] offset:16
	flat_load_dwordx4 v[56:59], v[48:49] offset:512
	s_nop 0
	flat_load_dwordx4 v[48:51], v[48:49] offset:528
	v_lshl_add_u64 v[146:147], s[20:21], 0, v[146:147]
	flat_load_dword v187, v[188:189] offset:64
	flat_load_dwordx4 v[160:163], v[146:147] offset:16
	flat_load_dwordx4 v[152:155], v[146:147] offset:32
	v_lshl_add_u64 v[226:227], v[190:191], 0, v[192:193]
	flat_load_dwordx4 v[220:223], v[144:145] offset:256
	flat_load_dwordx4 v[164:167], v[146:147]
	flat_load_dwordx4 v[156:159], v[146:147] offset:48
	flat_load_dwordx4 v[148:151], v[226:227]
	s_nop 0
	flat_load_dwordx4 v[144:147], v[226:227] offset:256
	s_andn2_b64 vcc, exec, s[0:1]
	s_mov_b64 s[0:1], -1
	s_waitcnt vmcnt(0) lgkmcnt(0)
	v_fmamk_f32 v199, v199, 0x3a800000, v198
	v_rsq_f32_e32 v226, v199
	v_pk_add_f32 v[202:203], v[202:203], v[206:207]
	v_pk_add_f32 v[200:201], v[200:201], v[204:205]
	v_pk_add_f32 v[204:205], v[210:211], v[214:215]
	v_pk_add_f32 v[206:207], v[208:209], v[212:213]
	v_pk_add_f32 v[202:203], v[202:203], v[204:205]
	v_pk_add_f32 v[200:201], v[200:201], v[206:207]
	v_pk_mul_f32 v[140:141], v[140:141], v[226:227] op_sel_hi:[1,0]
	v_pk_mov_b32 v[212:213], v[200:201], v[202:203] op_sel:[1,0]
	v_mov_b32_e32 v201, v203
	v_pk_add_f32 v[200:201], v[212:213], v[200:201]
	v_pk_mul_f32 v[136:137], v[136:137], v[226:227] op_sel_hi:[1,0]
	v_pk_mul_f32 v[142:143], v[142:143], v[226:227] op_sel_hi:[1,0]
	v_add_f32_e32 v199, v200, v201
	v_mul_f32_e32 v200, 0xbfb8aa3b, v140
	v_mul_f32_e32 v201, 0xbfb8aa3b, v136
	v_mul_f32_e32 v202, 0xbfb8aa3b, v141
	v_mul_f32_e32 v212, 0xbfb8aa3b, v142
	v_exp_f32_e32 v214, v200
	v_exp_f32_e32 v201, v201
	v_exp_f32_e32 v202, v202
	v_exp_f32_e32 v212, v212
	v_fmamk_f32 v199, v199, 0x3b000000, v198
	v_pk_mul_f32 v[138:139], v[138:139], v[226:227] op_sel_hi:[1,0]
	v_mul_f32_e32 v215, 0xbfb8aa3b, v143
	v_rsq_f32_e32 v200, v199
	v_add_f32_e32 v199, 1.0, v214
	v_add_f32_e32 v201, 1.0, v201
	v_lshlrev_b32_e32 v204, 16, v216
	v_and_b32_e32 v205, 0xffff0000, v216
	v_mul_f32_e32 v203, 0xbfb8aa3b, v137
	v_mul_f32_e32 v213, 0xbfb8aa3b, v138
	v_add_f32_e32 v214, 1.0, v202
	v_add_f32_e32 v216, 1.0, v212
	v_rcp_f32_e32 v202, v199
	v_rcp_f32_e32 v212, v201
	v_exp_f32_e32 v199, v215
	v_mul_f32_e32 v201, 0xbfb8aa3b, v139
	v_exp_f32_e32 v203, v203
	v_exp_f32_e32 v213, v213
	v_exp_f32_e32 v201, v201
	v_add_f32_e32 v199, 1.0, v199
	v_lshlrev_b32_e32 v208, 16, v218
	v_and_b32_e32 v209, 0xffff0000, v218
	v_add_f32_e32 v218, 1.0, v203
	v_add_f32_e32 v213, 1.0, v213
	v_rcp_f32_e32 v215, v199
	v_add_f32_e32 v199, 1.0, v201
	v_lshlrev_b32_e32 v206, 16, v217
	v_and_b32_e32 v207, 0xffff0000, v217
	v_rcp_f32_e32 v203, v214
	v_rcp_f32_e32 v214, v216
	v_rcp_f32_e32 v216, v213
	v_rcp_f32_e32 v217, v199
	v_rcp_f32_e32 v213, v218
	v_lshlrev_b32_e32 v210, 16, v219
	v_and_b32_e32 v211, 0xffff0000, v219
	v_pk_mul_f32 v[142:143], v[142:143], v[214:215]
	v_pk_mul_f32 v[140:141], v[140:141], v[202:203]
	v_pk_mul_f32 v[138:139], v[138:139], v[216:217]
	v_pk_mul_f32 v[136:137], v[136:137], v[212:213]
	v_pk_mul_f32 v[140:141], v[140:141], v[204:205]
	v_pk_mul_f32 v[142:143], v[142:143], v[206:207]
	v_pk_mul_f32 v[136:137], v[136:137], v[208:209]
	v_pk_mul_f32 v[138:139], v[138:139], v[210:211]
	v_pk_mul_f32 v[132:133], v[132:133], v[226:227] op_sel_hi:[1,0]
	v_pk_mul_f32 v[142:143], v[66:67], v[142:143]
	v_pk_mul_f32 v[140:141], v[64:65], v[140:141]
	v_pk_mul_f32 v[138:139], v[70:71], v[138:139]
	v_pk_mul_f32 v[136:137], v[68:69], v[136:137]
	v_mul_f32_e32 v199, 0xbfb8aa3b, v132
	v_pk_mul_f32 v[128:129], v[128:129], v[226:227] op_sel_hi:[1,0]
	v_pk_mul_f32 v[142:143], v[200:201], v[142:143] op_sel_hi:[0,1]
	v_pk_mul_f32 v[140:141], v[200:201], v[140:141] op_sel_hi:[0,1]
	v_pk_mul_f32 v[202:203], v[200:201], v[138:139] op_sel_hi:[0,1]
	v_pk_mul_f32 v[138:139], v[200:201], v[136:137] op_sel_hi:[0,1]
	v_exp_f32_e32 v199, v199
	v_mul_f32_e32 v201, 0xbfb8aa3b, v128
	v_exp_f32_e32 v201, v201
	v_pk_mul_f32 v[134:135], v[134:135], v[226:227] op_sel_hi:[1,0]
	v_add_f32_e32 v199, 1.0, v199
	v_mul_f32_e32 v204, 0xbfb8aa3b, v133
	v_pk_mul_f32 v[130:131], v[130:131], v[226:227] op_sel_hi:[1,0]
	v_exp_f32_e32 v205, v204
	v_rcp_f32_e32 v204, v199
	v_add_f32_e32 v199, 1.0, v201
	v_mul_f32_e32 v201, 0xbfb8aa3b, v134
	v_exp_f32_e32 v201, v201
; __device__ __forceinline__ u32x4 pack8(f32x4 a, f32x4 b) { u32x4 w; w.x = pk2(a[0], a[1]); w.y = pk2(a[2], a[3]); w.z = pk2(b[0], b[1]); w.w = pk2(b[2], b[3]); return w; }
;     __device__ __forceinline__ void operator()(const Acc& acc, const pg8::Unit& u, int wid) const {
;     ...
;                 for (int mm = 0; mm < 2; ++mm) { const int m = 2 * mp + mm, row = row0 + ai * 128 + m * 16;
;                     const float sc = __builtin_amdgcn_rsqf(scv[mm] * (1.f / 1024.f) + EPS);
;                     const f32x4 pa = (rq[mm][0] + rq[mm][1]) + (rq[mm][2] + rq[mm][3]);
;                     const float rg = __builtin_amdgcn_rsqf(((pa[0] + pa[1]) + (pa[2] + pa[3])) * (1.f / 512.f) + EPS);
; #pragma unroll
;                     for (int bj = 0; bj < 2; ++bj) {
;                         const u32x4 w = ov[mm][bj];
;                         f32x4 o0 = (f32x4){bflo(w.x), bfhi(w.x), bflo(w.y), bfhi(w.y)}, o1 = (f32x4){bflo(w.z), bfhi(w.z), bflo(w.w), bfhi(w.w)};
;                         f32x4 a0 = acc[ai][bj][m][0] * sc, a1 = acc[ai][bj][m][1] * sc;
; #pragma unroll
;                         for (int e = 0; e < 4; ++e) { a0[e] = a0[e] * __builtin_amdgcn_rcpf(1.f + __builtin_amdgcn_exp2f(-1.4426950408889634f * a0[e])); a1[e] = a1[e] * __builtin_amdgcn_rcpf(1.f + __builtin_amdgcn_exp2f(-1.4426950408889634f * a1[e])); }
;                         o0 = a0 * o0 * g4[bj][0] * rg; o1 = a1 * o1 * g4[bj][1] * rg;
;                         *(u32x4*)(Y + (size_t)row * 2048 + col0 + bj * 128) = pack8(o0, o1);
;                     } }
	v_mul_f32_e32 v207, 0xbfb8aa3b, v130
	v_exp_f32_e32 v207, v207
	v_rcp_f32_e32 v206, v199
	v_add_f32_e32 v201, 1.0, v201
	v_add_f32_e32 v199, 1.0, v205
	v_rcp_f32_e32 v208, v201
	v_add_f32_e32 v201, 1.0, v207
	v_mul_f32_e32 v207, 0xbfb8aa3b, v135
	v_rcp_f32_e32 v205, v199
	v_mul_f32_e32 v199, 0xbfb8aa3b, v129
	v_exp_f32_e32 v207, v207
	v_mul_f32_e32 v209, 0xbfb8aa3b, v131
	v_exp_f32_e32 v199, v199
	v_exp_f32_e32 v211, v209
	v_rcp_f32_e32 v210, v201
	v_add_f32_e32 v201, 1.0, v207
	v_add_f32_e32 v199, 1.0, v199
	v_rcp_f32_e32 v209, v201
	v_add_f32_e32 v201, 1.0, v211
	v_rcp_f32_e32 v211, v201
	v_rcp_f32_e32 v207, v199
	v_cvt_pk_bf16_f32 v136, v140, v141
	v_lshl_add_u64 v[140:141], s[36:37], 0, v[224:225]
	v_cvt_pk_bf16_f32 v137, v142, v143
	v_cvt_pk_bf16_f32 v138, v138, v139
	v_cvt_pk_bf16_f32 v139, v202, v203
	v_lshl_add_u64 v[140:141], v[140:141], 0, v[184:185]
	flat_store_dwordx4 v[140:141], v[136:139]
	v_lshlrev_b32_e32 v142, 16, v222
	v_and_b32_e32 v143, 0xffff0000, v222
	v_lshlrev_b32_e32 v136, 16, v220
	v_and_b32_e32 v137, 0xffff0000, v220
	v_lshlrev_b32_e32 v138, 16, v221
	v_and_b32_e32 v139, 0xffff0000, v221
	v_lshlrev_b32_e32 v202, 16, v223
	v_and_b32_e32 v203, 0xffff0000, v223
	v_pk_mul_f32 v[134:135], v[134:135], v[208:209]
	v_pk_mul_f32 v[132:133], v[132:133], v[204:205]
	v_pk_mul_f32 v[130:131], v[130:131], v[210:211]
	v_pk_mul_f32 v[128:129], v[128:129], v[206:207]
	v_pk_mul_f32 v[132:133], v[132:133], v[136:137]
	v_pk_mul_f32 v[134:135], v[134:135], v[138:139]
	v_pk_mul_f32 v[128:129], v[128:129], v[142:143]
	v_pk_mul_f32 v[130:131], v[130:131], v[202:203]
	v_pk_mul_f32 v[134:135], v[58:59], v[134:135]
	v_pk_mul_f32 v[132:133], v[56:57], v[132:133]
	v_pk_mul_f32 v[130:131], v[50:51], v[130:131]
	v_pk_mul_f32 v[128:129], v[48:49], v[128:129]
	v_pk_mul_f32 v[134:135], v[200:201], v[134:135] op_sel_hi:[0,1]
	v_pk_mul_f32 v[132:133], v[200:201], v[132:133] op_sel_hi:[0,1]
	v_pk_mul_f32 v[136:137], v[200:201], v[130:131] op_sel_hi:[0,1]
	v_pk_mul_f32 v[130:131], v[200:201], v[128:129] op_sel_hi:[0,1]
	v_cvt_pk_bf16_f32 v128, v132, v133
	v_cvt_pk_bf16_f32 v129, v134, v135
	v_cvt_pk_bf16_f32 v130, v130, v131
	v_cvt_pk_bf16_f32 v131, v136, v137
	flat_store_dwordx4 v[140:141], v[128:131] offset:256
	v_pk_add_f32 v[132:133], v[154:155], v[158:159]
	v_pk_add_f32 v[136:137], v[152:153], v[156:157]
	v_fmamk_f32 v128, v187, 0x3a800000, v198
	v_rsq_f32_e32 v134, v128
	v_pk_add_f32 v[128:129], v[166:167], v[162:163]
	v_pk_add_f32 v[130:131], v[164:165], v[160:161]
	v_pk_add_f32 v[128:129], v[128:129], v[132:133]
	v_pk_add_f32 v[130:131], v[130:131], v[136:137]
	v_pk_mul_f32 v[124:125], v[124:125], v[134:135] op_sel_hi:[1,0]
	v_pk_mov_b32 v[132:133], v[130:131], v[128:129] op_sel:[1,0]
	v_mov_b32_e32 v131, v129
	v_pk_add_f32 v[128:129], v[132:133], v[130:131]
	v_pk_mul_f32 v[120:121], v[120:121], v[134:135] op_sel_hi:[1,0]
	v_add_f32_e32 v128, v128, v129
	v_mul_f32_e32 v129, 0xbfb8aa3b, v124
	v_exp_f32_e32 v129, v129
	v_pk_mul_f32 v[126:127], v[126:127], v[134:135] op_sel_hi:[1,0]
	v_pk_mul_f32 v[122:123], v[122:123], v[134:135] op_sel_hi:[1,0]
	v_mul_f32_e32 v135, 0xbfb8aa3b, v120
	v_exp_f32_e32 v135, v135
	v_add_f32_e32 v129, 1.0, v129
	v_mul_f32_e32 v140, 0xbfb8aa3b, v125
	v_exp_f32_e32 v141, v140
	v_rcp_f32_e32 v140, v129
	v_add_f32_e32 v129, 1.0, v135
	v_mul_f32_e32 v135, 0xbfb8aa3b, v126
	v_exp_f32_e32 v135, v135
	v_mul_f32_e32 v143, 0xbfb8aa3b, v122
	v_exp_f32_e32 v143, v143
	v_lshlrev_b32_e32 v130, 16, v148
	v_add_f32_e32 v135, 1.0, v135
	v_and_b32_e32 v131, 0xffff0000, v148
	v_rcp_f32_e32 v142, v129
	v_add_f32_e32 v129, 1.0, v141
	v_rcp_f32_e32 v148, v135
	v_add_f32_e32 v135, 1.0, v143
	v_mul_f32_e32 v143, 0xbfb8aa3b, v127
	v_lshlrev_b32_e32 v132, 16, v149
	v_and_b32_e32 v133, 0xffff0000, v149
	v_rcp_f32_e32 v141, v129
	v_mul_f32_e32 v129, 0xbfb8aa3b, v121
	v_exp_f32_e32 v143, v143
	v_mul_f32_e32 v149, 0xbfb8aa3b, v123
	v_lshlrev_b32_e32 v138, 16, v151
	v_and_b32_e32 v139, 0xffff0000, v151
	v_exp_f32_e32 v129, v129
	v_exp_f32_e32 v151, v149
	v_lshlrev_b32_e32 v136, 16, v150
	v_and_b32_e32 v137, 0xffff0000, v150
	v_rcp_f32_e32 v150, v135
	v_add_f32_e32 v135, 1.0, v143
	v_add_f32_e32 v129, 1.0, v129
	v_rcp_f32_e32 v149, v135
	v_add_f32_e32 v135, 1.0, v151
	v_rcp_f32_e32 v151, v135
	v_rcp_f32_e32 v143, v129
	v_fmamk_f32 v128, v128, 0x3b000000, v198
	v_rsq_f32_e32 v128, v128
	v_pk_mul_f32 v[126:127], v[126:127], v[148:149]
	v_pk_mul_f32 v[124:125], v[124:125], v[140:141]
	v_pk_mul_f32 v[122:123], v[122:123], v[150:151]
	v_pk_mul_f32 v[120:121], v[120:121], v[142:143]
	v_pk_mul_f32 v[124:125], v[124:125], v[130:131]
	v_pk_mul_f32 v[126:127], v[126:127], v[132:133]
	v_pk_mul_f32 v[120:121], v[120:121], v[136:137]
	v_pk_mul_f32 v[122:123], v[122:123], v[138:139]
	v_pk_mul_f32 v[126:127], v[66:67], v[126:127]
	v_pk_mul_f32 v[124:125], v[64:65], v[124:125]
	v_pk_mul_f32 v[122:123], v[70:71], v[122:123]
	v_pk_mul_f32 v[120:121], v[68:69], v[120:121]
	v_pk_mul_f32 v[116:117], v[116:117], v[134:135] op_sel_hi:[1,0]
	v_pk_mul_f32 v[126:127], v[128:129], v[126:127] op_sel_hi:[0,1]
	v_pk_mul_f32 v[124:125], v[128:129], v[124:125] op_sel_hi:[0,1]
	v_pk_mul_f32 v[130:131], v[128:129], v[122:123] op_sel_hi:[0,1]
	v_pk_mul_f32 v[122:123], v[128:129], v[120:121] op_sel_hi:[0,1]
	v_mul_f32_e32 v129, 0xbfb8aa3b, v116
	v_pk_mul_f32 v[112:113], v[112:113], v[134:135] op_sel_hi:[1,0]
	v_exp_f32_e32 v129, v129
	v_pk_mul_f32 v[118:119], v[118:119], v[134:135] op_sel_hi:[1,0]
	v_pk_mul_f32 v[114:115], v[114:115], v[134:135] op_sel_hi:[1,0]
	v_mul_f32_e32 v134, 0xbfb8aa3b, v112
	v_exp_f32_e32 v135, v134
	v_mul_f32_e32 v134, 0xbfb8aa3b, v117
	v_exp_f32_e32 v143, v134
; __device__ __forceinline__ u32x4 pack8(f32x4 a, f32x4 b) { u32x4 w; w.x = pk2(a[0], a[1]); w.y = pk2(a[2], a[3]); w.z = pk2(b[0], b[1]); w.w = pk2(b[2], b[3]); return w; }
;     __device__ __forceinline__ void operator()(const Acc& acc, const pg8::Unit& u, int wid) const {
;     ...
;                 float scv[2]; f32x4 rq[2][4]; u32x4 ov[2][2];
; #pragma unroll
;                 for (int mm = 0; mm < 2; ++mm) { const int row = row0 + ai * 128 + (2 * mp + mm) * 16;
;                     scv[mm] = ssq[row];
;                     const f32x4* rp = (const f32x4*)(rssq + (size_t)row * 64 + head * 16);
; #pragma unroll
;                     for (int i = 0; i < 4; ++i) rq[mm][i] = rp[i];
; #pragma unroll
;                     for (int bj = 0; bj < 2; ++bj) ov[mm][bj] = *(const u32x4*)(Y + (size_t)row * 2048 + col0 + bj * 128); }
; #pragma unroll
;                 for (int mm = 0; mm < 2; ++mm) { const int m = 2 * mp + mm, row = row0 + ai * 128 + m * 16;
;                     const float sc = __builtin_amdgcn_rsqf(scv[mm] * (1.f / 1024.f) + EPS);
;                     const f32x4 pa = (rq[mm][0] + rq[mm][1]) + (rq[mm][2] + rq[mm][3]);
;                     const float rg = __builtin_amdgcn_rsqf(((pa[0] + pa[1]) + (pa[2] + pa[3])) * (1.f / 512.f) + EPS);
; #pragma unroll
;                     for (int bj = 0; bj < 2; ++bj) {
;                         const u32x4 w = ov[mm][bj];
;                         f32x4 o0 = (f32x4){bflo(w.x), bfhi(w.x), bflo(w.y), bfhi(w.y)}, o1 = (f32x4){bflo(w.z), bfhi(w.z), bflo(w.w), bfhi(w.w)};
;                         f32x4 a0 = acc[ai][bj][m][0] * sc, a1 = acc[ai][bj][m][1] * sc;
; #pragma unroll
;                         for (int e = 0; e < 4; ++e) { a0[e] = a0[e] * __builtin_amdgcn_rcpf(1.f + __builtin_amdgcn_exp2f(-1.4426950408889634f * a0[e])); a1[e] = a1[e] * __builtin_amdgcn_rcpf(1.f + __builtin_amdgcn_exp2f(-1.4426950408889634f * a1[e])); }
;                         o0 = a0 * o0 * g4[bj][0] * rg; o1 = a1 * o1 * g4[bj][1] * rg;
;                         *(u32x4*)(Y + (size_t)row * 2048 + col0 + bj * 128) = pack8(o0, o1);
;                     } }
	v_add_f32_e32 v129, 1.0, v129
	v_rcp_f32_e32 v134, v129
	v_add_f32_e32 v129, 1.0, v135
	v_rcp_f32_e32 v142, v129
	v_add_f32_e32 v129, 1.0, v143
	v_mul_f32_e32 v143, 0xbfb8aa3b, v118
	v_cvt_pk_bf16_f32 v121, v126, v127
	v_lshlrev_b32_e32 v126, 16, v144
	v_and_b32_e32 v127, 0xffff0000, v144
	v_exp_f32_e32 v143, v143
	v_mul_f32_e32 v144, 0xbfb8aa3b, v114
	v_lshlrev_b32_e32 v136, 16, v145
	v_and_b32_e32 v137, 0xffff0000, v145
	v_exp_f32_e32 v145, v144
	v_add_f32_e32 v143, 1.0, v143
	v_rcp_f32_e32 v144, v143
	v_lshlrev_b32_e32 v138, 16, v146
	v_add_f32_e32 v143, 1.0, v145
	v_mul_f32_e32 v145, 0xbfb8aa3b, v119
	v_and_b32_e32 v139, 0xffff0000, v146
	v_rcp_f32_e32 v135, v129
	v_mul_f32_e32 v129, 0xbfb8aa3b, v113
	v_exp_f32_e32 v145, v145
	v_mul_f32_e32 v146, 0xbfb8aa3b, v115
	v_lshlrev_b32_e32 v140, 16, v147
	v_and_b32_e32 v141, 0xffff0000, v147
	v_exp_f32_e32 v129, v129
	v_exp_f32_e32 v147, v146
	v_rcp_f32_e32 v146, v143
	v_add_f32_e32 v143, 1.0, v145
	v_add_f32_e32 v129, 1.0, v129
	v_rcp_f32_e32 v145, v143
	v_add_f32_e32 v143, 1.0, v147
	v_rcp_f32_e32 v147, v143
	v_rcp_f32_e32 v143, v129
	v_cvt_pk_bf16_f32 v120, v124, v125
	v_lshl_add_u64 v[124:125], s[36:37], 0, v[192:193]
	v_pk_mul_f32 v[118:119], v[118:119], v[144:145]
	v_pk_mul_f32 v[116:117], v[116:117], v[134:135]
	v_pk_mul_f32 v[114:115], v[114:115], v[146:147]
	v_pk_mul_f32 v[112:113], v[112:113], v[142:143]
	v_cvt_pk_bf16_f32 v122, v122, v123
	v_cvt_pk_bf16_f32 v123, v130, v131
	v_lshl_add_u64 v[124:125], v[124:125], 0, v[184:185]
	v_pk_mul_f32 v[116:117], v[116:117], v[126:127]
	v_pk_mul_f32 v[118:119], v[118:119], v[136:137]
	v_pk_mul_f32 v[112:113], v[112:113], v[138:139]
	v_pk_mul_f32 v[114:115], v[114:115], v[140:141]
	flat_store_dwordx4 v[124:125], v[120:123]
	v_pk_mul_f32 v[118:119], v[58:59], v[118:119]
	v_pk_mul_f32 v[116:117], v[56:57], v[116:117]
	v_or_b32_e32 v120, 32, v186
	v_pk_mul_f32 v[114:115], v[50:51], v[114:115]
	v_pk_mul_f32 v[112:113], v[48:49], v[112:113]
	v_ashrrev_i32_e32 v121, 31, v120
	v_pk_mul_f32 v[118:119], v[128:129], v[118:119] op_sel_hi:[0,1]
	v_pk_mul_f32 v[116:117], v[128:129], v[116:117] op_sel_hi:[0,1]
	v_pk_mul_f32 v[126:127], v[128:129], v[114:115] op_sel_hi:[0,1]
	v_pk_mul_f32 v[114:115], v[128:129], v[112:113] op_sel_hi:[0,1]
	v_lshlrev_b64 v[162:163], 12, v[120:121]
	v_cvt_pk_bf16_f32 v112, v116, v117
	v_cvt_pk_bf16_f32 v113, v118, v119
	v_cvt_pk_bf16_f32 v114, v114, v115
	v_cvt_pk_bf16_f32 v115, v126, v127
	v_lshl_add_u64 v[122:123], v[190:191], 0, v[162:163]
	flat_store_dwordx4 v[124:125], v[112:115] offset:256
	flat_load_dwordx4 v[130:133], v[122:123]
	s_nop 0
	v_lshlrev_b64 v[112:113], 8, v[120:121]
	v_lshl_add_u64 v[112:113], s[20:21], 0, v[112:113]
	flat_load_dword v164, v[188:189] offset:128
	flat_load_dwordx4 v[134:137], v[112:113]
	flat_load_dwordx4 v[138:141], v[112:113] offset:16
	flat_load_dwordx4 v[142:145], v[112:113] offset:32
	flat_load_dwordx4 v[146:149], v[112:113] offset:48
	flat_load_dwordx4 v[150:153], v[122:123] offset:256
	flat_load_dword v165, v[188:189] offset:192
	v_or_b32_e32 v112, 48, v186
	v_ashrrev_i32_e32 v113, 31, v112
	v_lshlrev_b64 v[114:115], 8, v[112:113]
	v_lshl_add_u64 v[114:115], s[20:21], 0, v[114:115]
	flat_load_dwordx4 v[154:157], v[114:115]
	flat_load_dwordx4 v[158:161], v[114:115] offset:16
	flat_load_dwordx4 v[120:123], v[114:115] offset:32
	flat_load_dwordx4 v[124:127], v[114:115] offset:48
	v_lshlrev_b64 v[128:129], 12, v[112:113]
	v_lshl_add_u64 v[112:113], v[190:191], 0, v[128:129]
	flat_load_dwordx4 v[116:119], v[112:113]
	s_nop 0
	flat_load_dwordx4 v[112:115], v[112:113] offset:256
	s_waitcnt vmcnt(0) lgkmcnt(0)
	v_fmamk_f32 v164, v164, 0x3a800000, v198
	v_rsq_f32_e32 v164, v164
	v_pk_add_f32 v[136:137], v[136:137], v[140:141]
	v_pk_add_f32 v[134:135], v[134:135], v[138:139]
	v_pk_add_f32 v[138:139], v[144:145], v[148:149]
	v_pk_add_f32 v[140:141], v[142:143], v[146:147]
	v_pk_add_f32 v[136:137], v[136:137], v[138:139]
	v_pk_add_f32 v[134:135], v[134:135], v[140:141]
	v_pk_mul_f32 v[108:109], v[108:109], v[164:165] op_sel_hi:[1,0]
	v_pk_mov_b32 v[138:139], v[134:135], v[136:137] op_sel:[1,0]
	v_mov_b32_e32 v135, v137
	v_pk_add_f32 v[134:135], v[138:139], v[134:135]
	v_pk_mul_f32 v[104:105], v[104:105], v[164:165] op_sel_hi:[1,0]
	v_add_f32_e32 v134, v134, v135
	v_mul_f32_e32 v135, 0xbfb8aa3b, v108
	v_exp_f32_e32 v135, v135
	v_mul_f32_e32 v140, 0xbfb8aa3b, v104
	v_exp_f32_e32 v141, v140
	v_mul_f32_e32 v140, 0xbfb8aa3b, v109
	v_exp_f32_e32 v143, v140
	v_add_f32_e32 v135, 1.0, v135
	v_pk_mul_f32 v[110:111], v[110:111], v[164:165] op_sel_hi:[1,0]
	v_rcp_f32_e32 v140, v135
	v_add_f32_e32 v135, 1.0, v141
	v_pk_mul_f32 v[106:107], v[106:107], v[164:165] op_sel_hi:[1,0]
	v_rcp_f32_e32 v142, v135
	v_add_f32_e32 v135, 1.0, v143
	v_mul_f32_e32 v143, 0xbfb8aa3b, v110
	v_exp_f32_e32 v143, v143
	v_mul_f32_e32 v144, 0xbfb8aa3b, v106
	v_exp_f32_e32 v145, v144
	v_rcp_f32_e32 v141, v135
	v_add_f32_e32 v143, 1.0, v143
	v_rcp_f32_e32 v144, v143
	v_add_f32_e32 v143, 1.0, v145
	v_mul_f32_e32 v145, 0xbfb8aa3b, v111
	v_mul_f32_e32 v135, 0xbfb8aa3b, v105
	v_exp_f32_e32 v145, v145
	v_mul_f32_e32 v146, 0xbfb8aa3b, v107
	v_exp_f32_e32 v135, v135
	v_exp_f32_e32 v147, v146
	v_rcp_f32_e32 v146, v143
	v_add_f32_e32 v143, 1.0, v145
	v_add_f32_e32 v135, 1.0, v135
	v_rcp_f32_e32 v145, v143
	v_add_f32_e32 v143, 1.0, v147
	v_rcp_f32_e32 v147, v143
	v_rcp_f32_e32 v143, v135
	v_fmamk_f32 v134, v134, 0x3b000000, v198
	v_rsq_f32_e32 v134, v134
	v_lshlrev_b32_e32 v136, 16, v130
	v_and_b32_e32 v137, 0xffff0000, v130
	v_lshlrev_b32_e32 v130, 16, v131
	v_and_b32_e32 v131, 0xffff0000, v131
	v_lshlrev_b32_e32 v138, 16, v132
; __device__ __forceinline__ u32x4 pack8(f32x4 a, f32x4 b) { u32x4 w; w.x = pk2(a[0], a[1]); w.y = pk2(a[2], a[3]); w.z = pk2(b[0], b[1]); w.w = pk2(b[2], b[3]); return w; }
;     __device__ __forceinline__ void operator()(const Acc& acc, const pg8::Unit& u, int wid) const {
;     ...
;                 for (int mm = 0; mm < 2; ++mm) { const int m = 2 * mp + mm, row = row0 + ai * 128 + m * 16;
;                     const float sc = __builtin_amdgcn_rsqf(scv[mm] * (1.f / 1024.f) + EPS);
;                     const f32x4 pa = (rq[mm][0] + rq[mm][1]) + (rq[mm][2] + rq[mm][3]);
;                     const float rg = __builtin_amdgcn_rsqf(((pa[0] + pa[1]) + (pa[2] + pa[3])) * (1.f / 512.f) + EPS);
; #pragma unroll
;                     for (int bj = 0; bj < 2; ++bj) {
;                         const u32x4 w = ov[mm][bj];
;                         f32x4 o0 = (f32x4){bflo(w.x), bfhi(w.x), bflo(w.y), bfhi(w.y)}, o1 = (f32x4){bflo(w.z), bfhi(w.z), bflo(w.w), bfhi(w.w)};
;                         f32x4 a0 = acc[ai][bj][m][0] * sc, a1 = acc[ai][bj][m][1] * sc;
; #pragma unroll
;                         for (int e = 0; e < 4; ++e) { a0[e] = a0[e] * __builtin_amdgcn_rcpf(1.f + __builtin_amdgcn_exp2f(-1.4426950408889634f * a0[e])); a1[e] = a1[e] * __builtin_amdgcn_rcpf(1.f + __builtin_amdgcn_exp2f(-1.4426950408889634f * a1[e])); }
;                         o0 = a0 * o0 * g4[bj][0] * rg; o1 = a1 * o1 * g4[bj][1] * rg;
;                         *(u32x4*)(Y + (size_t)row * 2048 + col0 + bj * 128) = pack8(o0, o1);
;                     } }
	v_and_b32_e32 v139, 0xffff0000, v132
	v_lshlrev_b32_e32 v132, 16, v133
	v_and_b32_e32 v133, 0xffff0000, v133
	v_pk_mul_f32 v[110:111], v[110:111], v[144:145]
	v_pk_mul_f32 v[108:109], v[108:109], v[140:141]
	v_pk_mul_f32 v[106:107], v[106:107], v[146:147]
	v_pk_mul_f32 v[104:105], v[104:105], v[142:143]
	v_pk_mul_f32 v[102:103], v[102:103], v[164:165] op_sel_hi:[1,0]
	v_pk_mul_f32 v[108:109], v[108:109], v[136:137]
	v_pk_mul_f32 v[110:111], v[110:111], v[130:131]
	v_pk_mul_f32 v[104:105], v[104:105], v[138:139]
	v_pk_mul_f32 v[106:107], v[106:107], v[132:133]
	v_pk_mul_f32 v[98:99], v[98:99], v[164:165] op_sel_hi:[1,0]
	v_pk_mul_f32 v[96:97], v[96:97], v[164:165] op_sel_hi:[1,0]
	v_mul_f32_e32 v137, 0xbfb8aa3b, v102
	v_pk_mul_f32 v[110:111], v[66:67], v[110:111]
	v_pk_mul_f32 v[108:109], v[64:65], v[108:109]
	v_pk_mul_f32 v[106:107], v[70:71], v[106:107]
	v_pk_mul_f32 v[104:105], v[68:69], v[104:105]
	v_pk_mul_f32 v[100:101], v[100:101], v[164:165] op_sel_hi:[1,0]
	v_mul_f32_e32 v133, 0xbfb8aa3b, v96
	v_exp_f32_e32 v137, v137
	v_mul_f32_e32 v138, 0xbfb8aa3b, v98
	v_pk_mul_f32 v[110:111], v[134:135], v[110:111] op_sel_hi:[0,1]
	v_pk_mul_f32 v[108:109], v[134:135], v[108:109] op_sel_hi:[0,1]
	v_pk_mul_f32 v[130:131], v[134:135], v[106:107] op_sel_hi:[0,1]
	v_pk_mul_f32 v[106:107], v[134:135], v[104:105] op_sel_hi:[0,1]
	v_exp_f32_e32 v133, v133
	v_mul_f32_e32 v135, 0xbfb8aa3b, v101
	v_exp_f32_e32 v139, v138
	v_exp_f32_e32 v135, v135
	v_add_f32_e32 v137, 1.0, v137
	v_add_f32_e32 v133, 1.0, v133
	v_rcp_f32_e32 v138, v137
	v_add_f32_e32 v137, 1.0, v139
	v_mul_f32_e32 v139, 0xbfb8aa3b, v103
	v_mul_f32_e32 v132, 0xbfb8aa3b, v100
	v_rcp_f32_e32 v136, v133
	v_add_f32_e32 v133, 1.0, v135
	v_mul_f32_e32 v135, 0xbfb8aa3b, v97
	v_exp_f32_e32 v139, v139
	v_mul_f32_e32 v140, 0xbfb8aa3b, v99
	v_exp_f32_e32 v132, v132
	v_exp_f32_e32 v135, v135
	v_exp_f32_e32 v141, v140
	v_rcp_f32_e32 v140, v137
	v_add_f32_e32 v137, 1.0, v139
	v_add_f32_e32 v132, 1.0, v132
	v_add_f32_e32 v135, 1.0, v135
	v_rcp_f32_e32 v139, v137
	v_add_f32_e32 v137, 1.0, v141
	v_rcp_f32_e32 v132, v132
	v_rcp_f32_e32 v133, v133
	v_rcp_f32_e32 v141, v137
	v_rcp_f32_e32 v137, v135
	v_cvt_pk_bf16_f32 v104, v108, v109
	v_lshl_add_u64 v[108:109], s[36:37], 0, v[162:163]
	v_cvt_pk_bf16_f32 v105, v110, v111
	v_cvt_pk_bf16_f32 v106, v106, v107
	v_cvt_pk_bf16_f32 v107, v130, v131
	v_lshl_add_u64 v[108:109], v[108:109], 0, v[184:185]
	flat_store_dwordx4 v[108:109], v[104:107]
	v_lshlrev_b32_e32 v110, 16, v152
	v_and_b32_e32 v111, 0xffff0000, v152
	v_lshlrev_b32_e32 v104, 16, v150
	v_and_b32_e32 v105, 0xffff0000, v150
	v_lshlrev_b32_e32 v106, 16, v151
	v_and_b32_e32 v107, 0xffff0000, v151
	v_lshlrev_b32_e32 v130, 16, v153
	v_and_b32_e32 v131, 0xffff0000, v153
	v_pk_mul_f32 v[102:103], v[102:103], v[138:139]
	v_pk_mul_f32 v[100:101], v[100:101], v[132:133]
	v_pk_mul_f32 v[98:99], v[98:99], v[140:141]
	v_pk_mul_f32 v[96:97], v[96:97], v[136:137]
	v_pk_mul_f32 v[100:101], v[100:101], v[104:105]
	v_pk_mul_f32 v[102:103], v[102:103], v[106:107]
	v_pk_mul_f32 v[96:97], v[96:97], v[110:111]
	v_pk_mul_f32 v[98:99], v[98:99], v[130:131]
	v_pk_mul_f32 v[102:103], v[58:59], v[102:103]
	v_pk_mul_f32 v[100:101], v[56:57], v[100:101]
	v_pk_mul_f32 v[98:99], v[50:51], v[98:99]
	v_pk_mul_f32 v[96:97], v[48:49], v[96:97]
	v_pk_mul_f32 v[102:103], v[134:135], v[102:103] op_sel_hi:[0,1]
	v_pk_mul_f32 v[100:101], v[134:135], v[100:101] op_sel_hi:[0,1]
	v_pk_mul_f32 v[104:105], v[134:135], v[98:99] op_sel_hi:[0,1]
	v_pk_mul_f32 v[98:99], v[134:135], v[96:97] op_sel_hi:[0,1]
	v_cvt_pk_bf16_f32 v96, v100, v101
	v_cvt_pk_bf16_f32 v97, v102, v103
	v_cvt_pk_bf16_f32 v98, v98, v99
	v_cvt_pk_bf16_f32 v99, v104, v105
	flat_store_dwordx4 v[108:109], v[96:99] offset:256
	v_pk_add_f32 v[100:101], v[154:155], v[158:159]
	v_pk_add_f32 v[102:103], v[122:123], v[126:127]
	v_pk_add_f32 v[98:99], v[156:157], v[160:161]
	v_pk_add_f32 v[104:105], v[120:121], v[124:125]
	v_fmamk_f32 v96, v165, 0x3a800000, v198
	v_pk_add_f32 v[98:99], v[98:99], v[102:103]
	v_pk_add_f32 v[100:101], v[100:101], v[104:105]
	v_rsq_f32_e32 v96, v96
	v_pk_mov_b32 v[102:103], v[100:101], v[98:99] op_sel:[1,0]
	v_mov_b32_e32 v101, v99
	v_pk_add_f32 v[98:99], v[102:103], v[100:101]
	v_lshlrev_b32_e32 v100, 16, v116
	v_add_f32_e32 v97, v98, v99
	v_fmamk_f32 v97, v97, 0x3b000000, v198
	v_pk_mul_f32 v[92:93], v[92:93], v[96:97] op_sel_hi:[1,0]
	v_rsq_f32_e32 v98, v97
	v_mul_f32_e32 v97, 0xbfb8aa3b, v92
	v_exp_f32_e32 v97, v97
	v_mul_f32_e32 v108, 0xbfb8aa3b, v93
	v_exp_f32_e32 v109, v108
	v_and_b32_e32 v101, 0xffff0000, v116
	v_pk_mul_f32 v[88:89], v[88:89], v[96:97] op_sel_hi:[1,0]
	v_pk_mul_f32 v[94:95], v[94:95], v[96:97] op_sel_hi:[1,0]
	v_mul_f32_e32 v99, 0xbfb8aa3b, v88
	v_exp_f32_e32 v99, v99
	v_pk_mul_f32 v[90:91], v[90:91], v[96:97] op_sel_hi:[1,0]
	v_add_f32_e32 v97, 1.0, v97
	v_rcp_f32_e32 v108, v97
	v_add_f32_e32 v97, 1.0, v99
	v_mul_f32_e32 v99, 0xbfb8aa3b, v94
	v_exp_f32_e32 v99, v99
	v_mul_f32_e32 v111, 0xbfb8aa3b, v90
	v_exp_f32_e32 v111, v111
	v_rcp_f32_e32 v110, v97
	v_add_f32_e32 v97, 1.0, v109
	v_rcp_f32_e32 v109, v97
	v_mul_f32_e32 v97, 0xbfb8aa3b, v89
	v_add_f32_e32 v99, 1.0, v99
	v_exp_f32_e32 v97, v97
	v_rcp_f32_e32 v116, v99
	v_add_f32_e32 v99, 1.0, v111
	v_mul_f32_e32 v111, 0xbfb8aa3b, v95
	v_lshlrev_b32_e32 v102, 16, v117
	v_and_b32_e32 v103, 0xffff0000, v117
	v_exp_f32_e32 v111, v111
	v_mul_f32_e32 v117, 0xbfb8aa3b, v91
	v_lshlrev_b32_e32 v106, 16, v119
	v_and_b32_e32 v107, 0xffff0000, v119
	v_exp_f32_e32 v119, v117
	v_add_f32_e32 v97, 1.0, v97
	v_lshlrev_b32_e32 v104, 16, v118
	v_and_b32_e32 v105, 0xffff0000, v118
	v_rcp_f32_e32 v118, v99
; __device__ __forceinline__ u32x4 pack8(f32x4 a, f32x4 b) { u32x4 w; w.x = pk2(a[0], a[1]); w.y = pk2(a[2], a[3]); w.z = pk2(b[0], b[1]); w.w = pk2(b[2], b[3]); return w; }
;     __device__ __forceinline__ void operator()(const Acc& acc, const pg8::Unit& u, int wid) const {
;     ...
;                 float scv[2]; f32x4 rq[2][4]; u32x4 ov[2][2];
; #pragma unroll
;                 for (int mm = 0; mm < 2; ++mm) { const int row = row0 + ai * 128 + (2 * mp + mm) * 16;
;                     scv[mm] = ssq[row];
;                     const f32x4* rp = (const f32x4*)(rssq + (size_t)row * 64 + head * 16);
; #pragma unroll
;                     for (int i = 0; i < 4; ++i) rq[mm][i] = rp[i];
; #pragma unroll
;                     for (int bj = 0; bj < 2; ++bj) ov[mm][bj] = *(const u32x4*)(Y + (size_t)row * 2048 + col0 + bj * 128); }
; #pragma unroll
;                 for (int mm = 0; mm < 2; ++mm) { const int m = 2 * mp + mm, row = row0 + ai * 128 + m * 16;
;                     const float sc = __builtin_amdgcn_rsqf(scv[mm] * (1.f / 1024.f) + EPS);
;                     const f32x4 pa = (rq[mm][0] + rq[mm][1]) + (rq[mm][2] + rq[mm][3]);
;                     const float rg = __builtin_amdgcn_rsqf(((pa[0] + pa[1]) + (pa[2] + pa[3])) * (1.f / 512.f) + EPS);
; #pragma unroll
;                     for (int bj = 0; bj < 2; ++bj) {
;                         const u32x4 w = ov[mm][bj];
;                         f32x4 o0 = (f32x4){bflo(w.x), bfhi(w.x), bflo(w.y), bfhi(w.y)}, o1 = (f32x4){bflo(w.z), bfhi(w.z), bflo(w.w), bfhi(w.w)};
;                         f32x4 a0 = acc[ai][bj][m][0] * sc, a1 = acc[ai][bj][m][1] * sc;
; #pragma unroll
;                         for (int e = 0; e < 4; ++e) { a0[e] = a0[e] * __builtin_amdgcn_rcpf(1.f + __builtin_amdgcn_exp2f(-1.4426950408889634f * a0[e])); a1[e] = a1[e] * __builtin_amdgcn_rcpf(1.f + __builtin_amdgcn_exp2f(-1.4426950408889634f * a1[e])); }
;                         o0 = a0 * o0 * g4[bj][0] * rg; o1 = a1 * o1 * g4[bj][1] * rg;
;                         *(u32x4*)(Y + (size_t)row * 2048 + col0 + bj * 128) = pack8(o0, o1);
;                     } }
	v_add_f32_e32 v99, 1.0, v111
	v_pk_mul_f32 v[84:85], v[84:85], v[96:97] op_sel_hi:[1,0]
	v_rcp_f32_e32 v117, v99
	v_add_f32_e32 v99, 1.0, v119
	v_rcp_f32_e32 v111, v97
	v_mul_f32_e32 v97, 0xbfb8aa3b, v84
	v_rcp_f32_e32 v119, v99
	v_exp_f32_e32 v97, v97
	v_pk_mul_f32 v[94:95], v[94:95], v[116:117]
	v_pk_mul_f32 v[92:93], v[92:93], v[108:109]
	v_pk_mul_f32 v[90:91], v[90:91], v[118:119]
	v_pk_mul_f32 v[88:89], v[88:89], v[110:111]
	v_pk_mul_f32 v[86:87], v[86:87], v[96:97] op_sel_hi:[1,0]
	v_pk_mul_f32 v[92:93], v[92:93], v[100:101]
	v_pk_mul_f32 v[94:95], v[94:95], v[102:103]
	v_pk_mul_f32 v[88:89], v[88:89], v[104:105]
	v_pk_mul_f32 v[90:91], v[90:91], v[106:107]
	v_pk_mul_f32 v[82:83], v[82:83], v[96:97] op_sel_hi:[1,0]
	v_pk_mul_f32 v[80:81], v[80:81], v[96:97] op_sel_hi:[1,0]
	v_mul_f32_e32 v103, 0xbfb8aa3b, v86
	v_pk_mul_f32 v[94:95], v[66:67], v[94:95]
	v_pk_mul_f32 v[92:93], v[64:65], v[92:93]
	v_pk_mul_f32 v[90:91], v[70:71], v[90:91]
	v_pk_mul_f32 v[88:89], v[68:69], v[88:89]
	v_add_f32_e32 v96, 1.0, v97
	v_mul_f32_e32 v97, 0xbfb8aa3b, v80
	v_exp_f32_e32 v103, v103
	v_mul_f32_e32 v104, 0xbfb8aa3b, v82
	v_pk_mul_f32 v[94:95], v[98:99], v[94:95] op_sel_hi:[0,1]
	v_pk_mul_f32 v[92:93], v[98:99], v[92:93] op_sel_hi:[0,1]
	v_pk_mul_f32 v[100:101], v[98:99], v[90:91] op_sel_hi:[0,1]
	v_pk_mul_f32 v[90:91], v[98:99], v[88:89] op_sel_hi:[0,1]
	v_exp_f32_e32 v97, v97
	v_mul_f32_e32 v99, 0xbfb8aa3b, v85
	v_exp_f32_e32 v105, v104
	v_exp_f32_e32 v99, v99
	v_add_f32_e32 v103, 1.0, v103
	v_add_f32_e32 v97, 1.0, v97
	v_rcp_f32_e32 v104, v103
	v_add_f32_e32 v103, 1.0, v105
	v_mul_f32_e32 v105, 0xbfb8aa3b, v87
	v_rcp_f32_e32 v102, v97
	v_add_f32_e32 v97, 1.0, v99
	v_mul_f32_e32 v99, 0xbfb8aa3b, v81
	v_exp_f32_e32 v105, v105
	v_mul_f32_e32 v106, 0xbfb8aa3b, v83
	v_exp_f32_e32 v99, v99
	v_exp_f32_e32 v107, v106
	v_rcp_f32_e32 v106, v103
	v_add_f32_e32 v103, 1.0, v105
	v_add_f32_e32 v99, 1.0, v99
	v_rcp_f32_e32 v105, v103
	v_add_f32_e32 v103, 1.0, v107
	v_rcp_f32_e32 v96, v96
	v_rcp_f32_e32 v97, v97
	v_rcp_f32_e32 v107, v103
	v_rcp_f32_e32 v103, v99
	v_cvt_pk_bf16_f32 v88, v92, v93
	v_lshl_add_u64 v[92:93], s[36:37], 0, v[128:129]
	v_cvt_pk_bf16_f32 v89, v94, v95
	v_cvt_pk_bf16_f32 v90, v90, v91
	v_cvt_pk_bf16_f32 v91, v100, v101
	v_lshl_add_u64 v[92:93], v[92:93], 0, v[184:185]
	flat_store_dwordx4 v[92:93], v[88:91]
	v_lshlrev_b32_e32 v94, 16, v114
	v_and_b32_e32 v95, 0xffff0000, v114
	v_lshlrev_b32_e32 v88, 16, v112
	v_and_b32_e32 v89, 0xffff0000, v112
	v_lshlrev_b32_e32 v90, 16, v113
	v_and_b32_e32 v91, 0xffff0000, v113
	v_lshlrev_b32_e32 v100, 16, v115
	v_and_b32_e32 v101, 0xffff0000, v115
	v_pk_mul_f32 v[86:87], v[86:87], v[104:105]
	v_pk_mul_f32 v[84:85], v[84:85], v[96:97]
	v_pk_mul_f32 v[82:83], v[82:83], v[106:107]
	v_pk_mul_f32 v[80:81], v[80:81], v[102:103]
	v_pk_mul_f32 v[84:85], v[84:85], v[88:89]
	v_pk_mul_f32 v[86:87], v[86:87], v[90:91]
	v_pk_mul_f32 v[80:81], v[80:81], v[94:95]
	v_pk_mul_f32 v[82:83], v[82:83], v[100:101]
	v_pk_mul_f32 v[86:87], v[58:59], v[86:87]
	v_pk_mul_f32 v[84:85], v[56:57], v[84:85]
	v_pk_mul_f32 v[82:83], v[50:51], v[82:83]
	v_pk_mul_f32 v[80:81], v[48:49], v[80:81]
	v_pk_mul_f32 v[86:87], v[98:99], v[86:87] op_sel_hi:[0,1]
	v_pk_mul_f32 v[84:85], v[98:99], v[84:85] op_sel_hi:[0,1]
	v_pk_mul_f32 v[88:89], v[98:99], v[82:83] op_sel_hi:[0,1]
	v_pk_mul_f32 v[82:83], v[98:99], v[80:81] op_sel_hi:[0,1]
	v_cvt_pk_bf16_f32 v80, v84, v85
	v_cvt_pk_bf16_f32 v81, v86, v87
	v_cvt_pk_bf16_f32 v82, v82, v83
	v_cvt_pk_bf16_f32 v83, v88, v89
	flat_store_dwordx4 v[92:93], v[80:83] offset:256
	s_nop 1
	v_add_u32_e32 v80, 0x80, v186
	v_ashrrev_i32_e32 v81, 31, v80
	v_lshlrev_b64 v[82:83], 8, v[80:81]
	v_lshl_add_u64 v[82:83], s[20:21], 0, v[82:83]
	flat_load_dword v132, v[188:189] offset:512
	flat_load_dwordx4 v[94:97], v[82:83]
	flat_load_dwordx4 v[98:101], v[82:83] offset:16
	flat_load_dwordx4 v[102:105], v[82:83] offset:32
	flat_load_dwordx4 v[106:109], v[82:83] offset:48
	v_lshlrev_b64 v[130:131], 12, v[80:81]
	v_lshl_add_u64 v[80:81], v[190:191], 0, v[130:131]
	flat_load_dwordx4 v[110:113], v[80:81]
	flat_load_dword v133, v[188:189] offset:576
	v_add_u32_e32 v82, 0x90, v186
	v_ashrrev_i32_e32 v83, 31, v82
	v_lshlrev_b64 v[84:85], 8, v[82:83]
	v_lshl_add_u64 v[84:85], s[20:21], 0, v[84:85]
	flat_load_dwordx4 v[114:117], v[80:81] offset:256
	flat_load_dwordx4 v[118:121], v[84:85]
	flat_load_dwordx4 v[122:125], v[84:85] offset:16
	flat_load_dwordx4 v[88:91], v[84:85] offset:32
	v_lshlrev_b64 v[92:93], 12, v[82:83]
	v_lshl_add_u64 v[80:81], v[190:191], 0, v[92:93]
	flat_load_dwordx4 v[126:129], v[84:85] offset:48
	s_nop 0
	flat_load_dwordx4 v[84:87], v[80:81]
	s_nop 0
	flat_load_dwordx4 v[80:83], v[80:81] offset:256
	s_waitcnt vmcnt(0) lgkmcnt(0)
; __device__ __forceinline__ u32x4 pack8(f32x4 a, f32x4 b) { u32x4 w; w.x = pk2(a[0], a[1]); w.y = pk2(a[2], a[3]); w.z = pk2(b[0], b[1]); w.w = pk2(b[2], b[3]); return w; }
;     __device__ __forceinline__ void operator()(const Acc& acc, const pg8::Unit& u, int wid) const {
;     ...
;                 for (int mm = 0; mm < 2; ++mm) { const int m = 2 * mp + mm, row = row0 + ai * 128 + m * 16;
;                     const float sc = __builtin_amdgcn_rsqf(scv[mm] * (1.f / 1024.f) + EPS);
;                     const f32x4 pa = (rq[mm][0] + rq[mm][1]) + (rq[mm][2] + rq[mm][3]);
;                     const float rg = __builtin_amdgcn_rsqf(((pa[0] + pa[1]) + (pa[2] + pa[3])) * (1.f / 512.f) + EPS);
; #pragma unroll
;                     for (int bj = 0; bj < 2; ++bj) {
;                         const u32x4 w = ov[mm][bj];
;                         f32x4 o0 = (f32x4){bflo(w.x), bfhi(w.x), bflo(w.y), bfhi(w.y)}, o1 = (f32x4){bflo(w.z), bfhi(w.z), bflo(w.w), bfhi(w.w)};
;                         f32x4 a0 = acc[ai][bj][m][0] * sc, a1 = acc[ai][bj][m][1] * sc;
; #pragma unroll
;                         for (int e = 0; e < 4; ++e) { a0[e] = a0[e] * __builtin_amdgcn_rcpf(1.f + __builtin_amdgcn_exp2f(-1.4426950408889634f * a0[e])); a1[e] = a1[e] * __builtin_amdgcn_rcpf(1.f + __builtin_amdgcn_exp2f(-1.4426950408889634f * a1[e])); }
;                         o0 = a0 * o0 * g4[bj][0] * rg; o1 = a1 * o1 * g4[bj][1] * rg;
;                         *(u32x4*)(Y + (size_t)row * 2048 + col0 + bj * 128) = pack8(o0, o1);
;                     } }
	v_fmamk_f32 v132, v132, 0x3a800000, v198
	v_rsq_f32_e32 v132, v132
	v_pk_add_f32 v[96:97], v[96:97], v[100:101]
	v_pk_add_f32 v[94:95], v[94:95], v[98:99]
	v_pk_add_f32 v[98:99], v[104:105], v[108:109]
	v_pk_add_f32 v[100:101], v[102:103], v[106:107]
	v_pk_add_f32 v[96:97], v[96:97], v[98:99]
	v_pk_add_f32 v[94:95], v[94:95], v[100:101]
	v_pk_mul_f32 v[76:77], v[76:77], v[132:133] op_sel_hi:[1,0]
	v_pk_mov_b32 v[98:99], v[94:95], v[96:97] op_sel:[1,0]
	v_mov_b32_e32 v95, v97
	v_pk_add_f32 v[94:95], v[98:99], v[94:95]
	v_pk_mul_f32 v[72:73], v[72:73], v[132:133] op_sel_hi:[1,0]
	v_add_f32_e32 v94, v94, v95
	v_mul_f32_e32 v95, 0xbfb8aa3b, v76
	v_exp_f32_e32 v95, v95
	v_mul_f32_e32 v104, 0xbfb8aa3b, v72
	v_exp_f32_e32 v105, v104
	v_mul_f32_e32 v104, 0xbfb8aa3b, v77
	v_exp_f32_e32 v107, v104
	v_add_f32_e32 v95, 1.0, v95
	v_pk_mul_f32 v[78:79], v[78:79], v[132:133] op_sel_hi:[1,0]
	v_rcp_f32_e32 v104, v95
	v_add_f32_e32 v95, 1.0, v105
	v_pk_mul_f32 v[74:75], v[74:75], v[132:133] op_sel_hi:[1,0]
	v_rcp_f32_e32 v106, v95
	v_add_f32_e32 v95, 1.0, v107
	v_mul_f32_e32 v107, 0xbfb8aa3b, v78
	v_exp_f32_e32 v107, v107
	v_mul_f32_e32 v108, 0xbfb8aa3b, v74
	v_exp_f32_e32 v109, v108
	v_lshlrev_b32_e32 v96, 16, v110
	v_add_f32_e32 v107, 1.0, v107
	v_rcp_f32_e32 v108, v107
	v_add_f32_e32 v107, 1.0, v109
	v_mul_f32_e32 v109, 0xbfb8aa3b, v79
	v_and_b32_e32 v97, 0xffff0000, v110
	v_rcp_f32_e32 v105, v95
	v_mul_f32_e32 v95, 0xbfb8aa3b, v73
	v_exp_f32_e32 v109, v109
	v_mul_f32_e32 v110, 0xbfb8aa3b, v75
	v_lshlrev_b32_e32 v98, 16, v111
	v_and_b32_e32 v99, 0xffff0000, v111
	v_exp_f32_e32 v95, v95
	v_exp_f32_e32 v111, v110
	v_rcp_f32_e32 v110, v107
	v_add_f32_e32 v107, 1.0, v109
	v_add_f32_e32 v95, 1.0, v95
	v_rcp_f32_e32 v109, v107
	v_add_f32_e32 v107, 1.0, v111
	v_rcp_f32_e32 v111, v107
	v_rcp_f32_e32 v107, v95
	v_fmamk_f32 v94, v94, 0x3b000000, v198
	v_rsq_f32_e32 v94, v94
	v_lshlrev_b32_e32 v100, 16, v112
	v_and_b32_e32 v101, 0xffff0000, v112
	v_lshlrev_b32_e32 v102, 16, v113
	v_and_b32_e32 v103, 0xffff0000, v113
	v_pk_mul_f32 v[78:79], v[78:79], v[108:109]
	v_pk_mul_f32 v[76:77], v[76:77], v[104:105]
	v_pk_mul_f32 v[74:75], v[74:75], v[110:111]
	v_pk_mul_f32 v[72:73], v[72:73], v[106:107]
	v_pk_mul_f32 v[76:77], v[76:77], v[96:97]
	v_pk_mul_f32 v[78:79], v[78:79], v[98:99]
	v_pk_mul_f32 v[72:73], v[72:73], v[100:101]
	v_pk_mul_f32 v[74:75], v[74:75], v[102:103]
	v_pk_mul_f32 v[78:79], v[66:67], v[78:79]
	v_pk_mul_f32 v[76:77], v[64:65], v[76:77]
	v_pk_mul_f32 v[74:75], v[70:71], v[74:75]
	v_pk_mul_f32 v[72:73], v[68:69], v[72:73]
	v_pk_mul_f32 v[60:61], v[60:61], v[132:133] op_sel_hi:[1,0]
	v_pk_mul_f32 v[78:79], v[94:95], v[78:79] op_sel_hi:[0,1]
	v_pk_mul_f32 v[76:77], v[94:95], v[76:77] op_sel_hi:[0,1]
	v_pk_mul_f32 v[96:97], v[94:95], v[74:75] op_sel_hi:[0,1]
	v_pk_mul_f32 v[74:75], v[94:95], v[72:73] op_sel_hi:[0,1]
	v_mul_f32_e32 v95, 0xbfb8aa3b, v60
	v_pk_mul_f32 v[52:53], v[52:53], v[132:133] op_sel_hi:[1,0]
	v_exp_f32_e32 v95, v95
	v_mul_f32_e32 v98, 0xbfb8aa3b, v52
	v_exp_f32_e32 v99, v98
	v_mul_f32_e32 v98, 0xbfb8aa3b, v61
	v_exp_f32_e32 v101, v98
	v_add_f32_e32 v95, 1.0, v95
	v_pk_mul_f32 v[62:63], v[62:63], v[132:133] op_sel_hi:[1,0]
	v_rcp_f32_e32 v98, v95
	v_add_f32_e32 v95, 1.0, v99
	v_pk_mul_f32 v[54:55], v[54:55], v[132:133] op_sel_hi:[1,0]
	v_rcp_f32_e32 v100, v95
	v_add_f32_e32 v95, 1.0, v101
	v_mul_f32_e32 v101, 0xbfb8aa3b, v62
	v_exp_f32_e32 v101, v101
	v_mul_f32_e32 v102, 0xbfb8aa3b, v54
	v_exp_f32_e32 v103, v102
	v_rcp_f32_e32 v99, v95
	v_add_f32_e32 v101, 1.0, v101
	v_rcp_f32_e32 v102, v101
	v_add_f32_e32 v101, 1.0, v103
	v_mul_f32_e32 v103, 0xbfb8aa3b, v63
	v_mul_f32_e32 v95, 0xbfb8aa3b, v53
	v_exp_f32_e32 v103, v103
	v_mul_f32_e32 v104, 0xbfb8aa3b, v55
	v_exp_f32_e32 v95, v95
	v_exp_f32_e32 v105, v104
	v_rcp_f32_e32 v104, v101
	v_add_f32_e32 v101, 1.0, v103
	v_add_f32_e32 v95, 1.0, v95
	v_rcp_f32_e32 v103, v101
	v_add_f32_e32 v101, 1.0, v105
	v_rcp_f32_e32 v105, v101
	v_rcp_f32_e32 v101, v95
	v_cvt_pk_bf16_f32 v72, v76, v77
	v_lshl_add_u64 v[76:77], s[36:37], 0, v[130:131]
	v_cvt_pk_bf16_f32 v73, v78, v79
	v_cvt_pk_bf16_f32 v74, v74, v75
	v_cvt_pk_bf16_f32 v75, v96, v97
	v_lshl_add_u64 v[76:77], v[76:77], 0, v[184:185]
	flat_store_dwordx4 v[76:77], v[72:75]
	v_lshlrev_b32_e32 v78, 16, v116
	v_and_b32_e32 v79, 0xffff0000, v116
	v_lshlrev_b32_e32 v72, 16, v114
	v_and_b32_e32 v73, 0xffff0000, v114
	v_lshlrev_b32_e32 v74, 16, v115
	v_and_b32_e32 v75, 0xffff0000, v115
	v_lshlrev_b32_e32 v96, 16, v117
	v_and_b32_e32 v97, 0xffff0000, v117
	v_pk_mul_f32 v[62:63], v[62:63], v[102:103]
	v_pk_mul_f32 v[60:61], v[60:61], v[98:99]
	v_pk_mul_f32 v[54:55], v[54:55], v[104:105]
	v_pk_mul_f32 v[52:53], v[52:53], v[100:101]
	v_pk_mul_f32 v[60:61], v[60:61], v[72:73]
	v_pk_mul_f32 v[62:63], v[62:63], v[74:75]
	v_pk_mul_f32 v[52:53], v[52:53], v[78:79]
	v_pk_mul_f32 v[54:55], v[54:55], v[96:97]
	v_pk_mul_f32 v[62:63], v[58:59], v[62:63]
	v_pk_mul_f32 v[60:61], v[56:57], v[60:61]
	v_pk_mul_f32 v[54:55], v[50:51], v[54:55]
	v_pk_mul_f32 v[52:53], v[48:49], v[52:53]
	v_pk_mul_f32 v[62:63], v[94:95], v[62:63] op_sel_hi:[0,1]
	v_pk_mul_f32 v[60:61], v[94:95], v[60:61] op_sel_hi:[0,1]
	v_pk_mul_f32 v[72:73], v[94:95], v[54:55] op_sel_hi:[0,1]
	v_pk_mul_f32 v[54:55], v[94:95], v[52:53] op_sel_hi:[0,1]
	v_cvt_pk_bf16_f32 v52, v60, v61
	v_cvt_pk_bf16_f32 v53, v62, v63
	v_cvt_pk_bf16_f32 v54, v54, v55
	v_cvt_pk_bf16_f32 v55, v72, v73
	flat_store_dwordx4 v[76:77], v[52:55] offset:256
	v_pk_add_f32 v[60:61], v[118:119], v[122:123]
	v_pk_add_f32 v[62:63], v[90:91], v[128:129]
	v_fmamk_f32 v52, v133, 0x3a800000, v198
	v_rsq_f32_e32 v54, v52
; __device__ __forceinline__ u32x4 pack8(f32x4 a, f32x4 b) { u32x4 w; w.x = pk2(a[0], a[1]); w.y = pk2(a[2], a[3]); w.z = pk2(b[0], b[1]); w.w = pk2(b[2], b[3]); return w; }
;     __device__ __forceinline__ void operator()(const Acc& acc, const pg8::Unit& u, int wid) const {
;     ...
;                 float scv[2]; f32x4 rq[2][4]; u32x4 ov[2][2];
; #pragma unroll
;                 for (int mm = 0; mm < 2; ++mm) { const int row = row0 + ai * 128 + (2 * mp + mm) * 16;
;                     scv[mm] = ssq[row];
;                     const f32x4* rp = (const f32x4*)(rssq + (size_t)row * 64 + head * 16);
; #pragma unroll
;                     for (int i = 0; i < 4; ++i) rq[mm][i] = rp[i];
; #pragma unroll
;                     for (int bj = 0; bj < 2; ++bj) ov[mm][bj] = *(const u32x4*)(Y + (size_t)row * 2048 + col0 + bj * 128); }
; #pragma unroll
;                 for (int mm = 0; mm < 2; ++mm) { const int m = 2 * mp + mm, row = row0 + ai * 128 + m * 16;
;                     const float sc = __builtin_amdgcn_rsqf(scv[mm] * (1.f / 1024.f) + EPS);
;                     const f32x4 pa = (rq[mm][0] + rq[mm][1]) + (rq[mm][2] + rq[mm][3]);
;                     const float rg = __builtin_amdgcn_rsqf(((pa[0] + pa[1]) + (pa[2] + pa[3])) * (1.f / 512.f) + EPS);
; #pragma unroll
;                     for (int bj = 0; bj < 2; ++bj) {
;                         const u32x4 w = ov[mm][bj];
;                         f32x4 o0 = (f32x4){bflo(w.x), bfhi(w.x), bflo(w.y), bfhi(w.y)}, o1 = (f32x4){bflo(w.z), bfhi(w.z), bflo(w.w), bfhi(w.w)};
;                         f32x4 a0 = acc[ai][bj][m][0] * sc, a1 = acc[ai][bj][m][1] * sc;
; #pragma unroll
;                         for (int e = 0; e < 4; ++e) { a0[e] = a0[e] * __builtin_amdgcn_rcpf(1.f + __builtin_amdgcn_exp2f(-1.4426950408889634f * a0[e])); a1[e] = a1[e] * __builtin_amdgcn_rcpf(1.f + __builtin_amdgcn_exp2f(-1.4426950408889634f * a1[e])); }
;                         o0 = a0 * o0 * g4[bj][0] * rg; o1 = a1 * o1 * g4[bj][1] * rg;
;                         *(u32x4*)(Y + (size_t)row * 2048 + col0 + bj * 128) = pack8(o0, o1);
;                     } }
	v_pk_add_f32 v[52:53], v[120:121], v[124:125]
	v_pk_add_f32 v[72:73], v[88:89], v[126:127]
	v_pk_add_f32 v[52:53], v[52:53], v[62:63]
	v_pk_add_f32 v[60:61], v[60:61], v[72:73]
	v_pk_mul_f32 v[44:45], v[44:45], v[54:55] op_sel_hi:[1,0]
	v_pk_mov_b32 v[62:63], v[60:61], v[52:53] op_sel:[1,0]
	v_mov_b32_e32 v61, v53
	v_pk_add_f32 v[52:53], v[62:63], v[60:61]
	v_pk_mul_f32 v[40:41], v[40:41], v[54:55] op_sel_hi:[1,0]
	v_add_f32_e32 v52, v52, v53
	v_mul_f32_e32 v53, 0xbfb8aa3b, v44
	v_exp_f32_e32 v53, v53
	v_pk_mul_f32 v[46:47], v[46:47], v[54:55] op_sel_hi:[1,0]
	v_pk_mul_f32 v[42:43], v[42:43], v[54:55] op_sel_hi:[1,0]
	v_mul_f32_e32 v55, 0xbfb8aa3b, v40
	v_exp_f32_e32 v55, v55
	v_add_f32_e32 v53, 1.0, v53
	v_mul_f32_e32 v76, 0xbfb8aa3b, v45
	v_exp_f32_e32 v77, v76
	v_rcp_f32_e32 v76, v53
	v_add_f32_e32 v53, 1.0, v55
	v_mul_f32_e32 v55, 0xbfb8aa3b, v46
	v_exp_f32_e32 v55, v55
	v_mul_f32_e32 v79, 0xbfb8aa3b, v42
	v_exp_f32_e32 v79, v79
	v_lshlrev_b32_e32 v60, 16, v84
	v_add_f32_e32 v55, 1.0, v55
	v_and_b32_e32 v61, 0xffff0000, v84
	v_rcp_f32_e32 v78, v53
	v_add_f32_e32 v53, 1.0, v77
	v_rcp_f32_e32 v84, v55
	v_add_f32_e32 v55, 1.0, v79
	v_mul_f32_e32 v79, 0xbfb8aa3b, v47
	v_lshlrev_b32_e32 v62, 16, v85
	v_and_b32_e32 v63, 0xffff0000, v85
	v_rcp_f32_e32 v77, v53
	v_mul_f32_e32 v53, 0xbfb8aa3b, v41
	v_exp_f32_e32 v79, v79
	v_mul_f32_e32 v85, 0xbfb8aa3b, v43
	v_lshlrev_b32_e32 v74, 16, v87
	v_and_b32_e32 v75, 0xffff0000, v87
	v_exp_f32_e32 v53, v53
	v_exp_f32_e32 v87, v85
	v_lshlrev_b32_e32 v72, 16, v86
	v_and_b32_e32 v73, 0xffff0000, v86
	v_rcp_f32_e32 v86, v55
	v_add_f32_e32 v55, 1.0, v79
	v_add_f32_e32 v53, 1.0, v53
	v_rcp_f32_e32 v85, v55
	v_add_f32_e32 v55, 1.0, v87
	v_rcp_f32_e32 v87, v55
	v_rcp_f32_e32 v79, v53
	v_fmamk_f32 v52, v52, 0x3b000000, v198
	v_rsq_f32_e32 v52, v52
	v_pk_mul_f32 v[46:47], v[46:47], v[84:85]
	v_pk_mul_f32 v[44:45], v[44:45], v[76:77]
	v_pk_mul_f32 v[42:43], v[42:43], v[86:87]
	v_pk_mul_f32 v[40:41], v[40:41], v[78:79]
	v_pk_mul_f32 v[44:45], v[44:45], v[60:61]
	v_pk_mul_f32 v[46:47], v[46:47], v[62:63]
	v_pk_mul_f32 v[40:41], v[40:41], v[72:73]
	v_pk_mul_f32 v[42:43], v[42:43], v[74:75]
	v_pk_mul_f32 v[46:47], v[66:67], v[46:47]
	v_pk_mul_f32 v[44:45], v[64:65], v[44:45]
	v_pk_mul_f32 v[42:43], v[70:71], v[42:43]
	v_pk_mul_f32 v[40:41], v[68:69], v[40:41]
	v_pk_mul_f32 v[36:37], v[36:37], v[54:55] op_sel_hi:[1,0]
	v_pk_mul_f32 v[46:47], v[52:53], v[46:47] op_sel_hi:[0,1]
	v_pk_mul_f32 v[44:45], v[52:53], v[44:45] op_sel_hi:[0,1]
	v_pk_mul_f32 v[60:61], v[52:53], v[42:43] op_sel_hi:[0,1]
	v_pk_mul_f32 v[42:43], v[52:53], v[40:41] op_sel_hi:[0,1]
	v_mul_f32_e32 v53, 0xbfb8aa3b, v36
	v_pk_mul_f32 v[32:33], v[32:33], v[54:55] op_sel_hi:[1,0]
	v_exp_f32_e32 v53, v53
	v_pk_mul_f32 v[38:39], v[38:39], v[54:55] op_sel_hi:[1,0]
	v_pk_mul_f32 v[34:35], v[34:35], v[54:55] op_sel_hi:[1,0]
	v_mul_f32_e32 v54, 0xbfb8aa3b, v32
	v_exp_f32_e32 v55, v54
	v_mul_f32_e32 v54, 0xbfb8aa3b, v37
	v_exp_f32_e32 v79, v54
	v_add_f32_e32 v53, 1.0, v53
	v_rcp_f32_e32 v54, v53
	v_add_f32_e32 v53, 1.0, v55
	v_rcp_f32_e32 v78, v53
	v_add_f32_e32 v53, 1.0, v79
	v_mul_f32_e32 v79, 0xbfb8aa3b, v38
	v_cvt_pk_bf16_f32 v41, v46, v47
	v_lshlrev_b32_e32 v46, 16, v80
	v_and_b32_e32 v47, 0xffff0000, v80
	v_exp_f32_e32 v79, v79
	v_mul_f32_e32 v80, 0xbfb8aa3b, v34
	v_lshlrev_b32_e32 v72, 16, v81
	v_and_b32_e32 v73, 0xffff0000, v81
	v_exp_f32_e32 v81, v80
	v_add_f32_e32 v79, 1.0, v79
	v_rcp_f32_e32 v80, v79
	v_lshlrev_b32_e32 v74, 16, v82
	v_add_f32_e32 v79, 1.0, v81
	v_mul_f32_e32 v81, 0xbfb8aa3b, v39
	v_and_b32_e32 v75, 0xffff0000, v82
	v_rcp_f32_e32 v55, v53
	v_mul_f32_e32 v53, 0xbfb8aa3b, v33
	v_exp_f32_e32 v81, v81
	v_mul_f32_e32 v82, 0xbfb8aa3b, v35
	v_lshlrev_b32_e32 v76, 16, v83
	v_and_b32_e32 v77, 0xffff0000, v83
	v_exp_f32_e32 v53, v53
	v_exp_f32_e32 v83, v82
	v_rcp_f32_e32 v82, v79
	v_add_f32_e32 v79, 1.0, v81
	v_add_f32_e32 v53, 1.0, v53
	v_rcp_f32_e32 v81, v79
	v_add_f32_e32 v79, 1.0, v83
	v_rcp_f32_e32 v83, v79
	v_rcp_f32_e32 v79, v53
	v_cvt_pk_bf16_f32 v40, v44, v45
	v_lshl_add_u64 v[44:45], s[36:37], 0, v[92:93]
	v_pk_mul_f32 v[38:39], v[38:39], v[80:81]
	v_pk_mul_f32 v[36:37], v[36:37], v[54:55]
	v_pk_mul_f32 v[34:35], v[34:35], v[82:83]
	v_pk_mul_f32 v[32:33], v[32:33], v[78:79]
	v_cvt_pk_bf16_f32 v42, v42, v43
	v_cvt_pk_bf16_f32 v43, v60, v61
	v_lshl_add_u64 v[44:45], v[44:45], 0, v[184:185]
	v_pk_mul_f32 v[36:37], v[36:37], v[46:47]
	v_pk_mul_f32 v[38:39], v[38:39], v[72:73]
	v_pk_mul_f32 v[32:33], v[32:33], v[74:75]
	v_pk_mul_f32 v[34:35], v[34:35], v[76:77]
	flat_store_dwordx4 v[44:45], v[40:43]
	v_pk_mul_f32 v[38:39], v[58:59], v[38:39]
	v_pk_mul_f32 v[36:37], v[56:57], v[36:37]
	v_add_u32_e32 v40, 0xa0, v186
	v_pk_mul_f32 v[34:35], v[50:51], v[34:35]
	v_pk_mul_f32 v[32:33], v[48:49], v[32:33]
	v_ashrrev_i32_e32 v41, 31, v40
	v_pk_mul_f32 v[38:39], v[52:53], v[38:39] op_sel_hi:[0,1]
	v_pk_mul_f32 v[36:37], v[52:53], v[36:37] op_sel_hi:[0,1]
	v_pk_mul_f32 v[46:47], v[52:53], v[34:35] op_sel_hi:[0,1]
	v_pk_mul_f32 v[34:35], v[52:53], v[32:33] op_sel_hi:[0,1]
	v_lshlrev_b64 v[100:101], 12, v[40:41]
	v_cvt_pk_bf16_f32 v32, v36, v37
	v_cvt_pk_bf16_f32 v33, v38, v39
	v_cvt_pk_bf16_f32 v34, v34, v35
	v_cvt_pk_bf16_f32 v35, v46, v47
	v_lshl_add_u64 v[42:43], v[190:191], 0, v[100:101]
	flat_store_dwordx4 v[44:45], v[32:35] offset:256
	flat_load_dwordx4 v[60:63], v[42:43]
	s_nop 0
	v_lshlrev_b64 v[32:33], 8, v[40:41]
	v_lshl_add_u64 v[32:33], s[20:21], 0, v[32:33]
	flat_load_dword v54, v[188:189] offset:640
	flat_load_dwordx4 v[72:75], v[32:33]
	flat_load_dwordx4 v[76:79], v[32:33] offset:16
	flat_load_dwordx4 v[80:83], v[32:33] offset:32
	flat_load_dwordx4 v[84:87], v[32:33] offset:48
	flat_load_dwordx4 v[88:91], v[42:43] offset:256
	v_add_u32_e32 v32, 0xb0, v186
	v_ashrrev_i32_e32 v33, 31, v32
	v_lshlrev_b64 v[34:35], 8, v[32:33]
	v_lshl_add_u64 v[34:35], s[20:21], 0, v[34:35]
	flat_load_dword v102, v[188:189] offset:704
	flat_load_dwordx4 v[92:95], v[34:35]
	flat_load_dwordx4 v[96:99], v[34:35] offset:16
	flat_load_dwordx4 v[40:43], v[34:35] offset:32
	flat_load_dwordx4 v[44:47], v[34:35] offset:48
	v_lshlrev_b64 v[52:53], 12, v[32:33]
	v_lshl_add_u64 v[32:33], v[190:191], 0, v[52:53]
	flat_load_dwordx4 v[36:39], v[32:33]
	s_nop 0
	flat_load_dwordx4 v[32:35], v[32:33] offset:256
	s_waitcnt vmcnt(0) lgkmcnt(0)
; __device__ __forceinline__ u32x4 pack8(f32x4 a, f32x4 b) { u32x4 w; w.x = pk2(a[0], a[1]); w.y = pk2(a[2], a[3]); w.z = pk2(b[0], b[1]); w.w = pk2(b[2], b[3]); return w; }
;     __device__ __forceinline__ void operator()(const Acc& acc, const pg8::Unit& u, int wid) const {
;     ...
;                 for (int mm = 0; mm < 2; ++mm) { const int m = 2 * mp + mm, row = row0 + ai * 128 + m * 16;
;                     const float sc = __builtin_amdgcn_rsqf(scv[mm] * (1.f / 1024.f) + EPS);
;                     const f32x4 pa = (rq[mm][0] + rq[mm][1]) + (rq[mm][2] + rq[mm][3]);
;                     const float rg = __builtin_amdgcn_rsqf(((pa[0] + pa[1]) + (pa[2] + pa[3])) * (1.f / 512.f) + EPS);
; #pragma unroll
;                     for (int bj = 0; bj < 2; ++bj) {
;                         const u32x4 w = ov[mm][bj];
;                         f32x4 o0 = (f32x4){bflo(w.x), bfhi(w.x), bflo(w.y), bfhi(w.y)}, o1 = (f32x4){bflo(w.z), bfhi(w.z), bflo(w.w), bfhi(w.w)};
;                         f32x4 a0 = acc[ai][bj][m][0] * sc, a1 = acc[ai][bj][m][1] * sc;
; #pragma unroll
;                         for (int e = 0; e < 4; ++e) { a0[e] = a0[e] * __builtin_amdgcn_rcpf(1.f + __builtin_amdgcn_exp2f(-1.4426950408889634f * a0[e])); a1[e] = a1[e] * __builtin_amdgcn_rcpf(1.f + __builtin_amdgcn_exp2f(-1.4426950408889634f * a1[e])); }
;                         o0 = a0 * o0 * g4[bj][0] * rg; o1 = a1 * o1 * g4[bj][1] * rg;
;                         *(u32x4*)(Y + (size_t)row * 2048 + col0 + bj * 128) = pack8(o0, o1);
;                     } }
	v_fmamk_f32 v54, v54, 0x3a800000, v198
	v_rsq_f32_e32 v54, v54
	v_pk_add_f32 v[74:75], v[74:75], v[78:79]
	v_pk_add_f32 v[72:73], v[72:73], v[76:77]
	v_pk_add_f32 v[76:77], v[82:83], v[86:87]
	v_pk_add_f32 v[78:79], v[80:81], v[84:85]
	v_pk_add_f32 v[74:75], v[74:75], v[76:77]
	v_pk_add_f32 v[72:73], v[72:73], v[78:79]
	s_nop 0
	v_pk_mov_b32 v[76:77], v[72:73], v[74:75] op_sel:[1,0]
	v_mov_b32_e32 v73, v75
	v_pk_add_f32 v[72:73], v[76:77], v[72:73]
	v_lshlrev_b32_e32 v74, 16, v60
	v_add_f32_e32 v55, v72, v73
	v_fmamk_f32 v55, v55, 0x3b000000, v198
	v_pk_mul_f32 v[28:29], v[28:29], v[54:55] op_sel_hi:[1,0]
	v_rsq_f32_e32 v72, v55
	v_mul_f32_e32 v55, 0xbfb8aa3b, v28
	v_exp_f32_e32 v55, v55
	v_mul_f32_e32 v78, 0xbfb8aa3b, v29
	v_exp_f32_e32 v79, v78
	v_and_b32_e32 v75, 0xffff0000, v60
	v_pk_mul_f32 v[24:25], v[24:25], v[54:55] op_sel_hi:[1,0]
	v_pk_mul_f32 v[30:31], v[30:31], v[54:55] op_sel_hi:[1,0]
	v_mul_f32_e32 v73, 0xbfb8aa3b, v24
	v_exp_f32_e32 v73, v73
	v_pk_mul_f32 v[26:27], v[26:27], v[54:55] op_sel_hi:[1,0]
	v_add_f32_e32 v55, 1.0, v55
	v_rcp_f32_e32 v78, v55
	v_add_f32_e32 v55, 1.0, v73
	v_mul_f32_e32 v73, 0xbfb8aa3b, v30
	v_exp_f32_e32 v73, v73
	v_mul_f32_e32 v81, 0xbfb8aa3b, v26
	v_exp_f32_e32 v81, v81
	v_rcp_f32_e32 v80, v55
	v_add_f32_e32 v73, 1.0, v73
	v_add_f32_e32 v55, 1.0, v79
	v_rcp_f32_e32 v82, v73
	v_add_f32_e32 v73, 1.0, v81
	v_mul_f32_e32 v81, 0xbfb8aa3b, v31
	v_rcp_f32_e32 v79, v55
	v_mul_f32_e32 v55, 0xbfb8aa3b, v25
	v_exp_f32_e32 v81, v81
	v_mul_f32_e32 v83, 0xbfb8aa3b, v27
	v_exp_f32_e32 v55, v55
	v_exp_f32_e32 v85, v83
	v_rcp_f32_e32 v84, v73
	v_add_f32_e32 v73, 1.0, v81
	v_add_f32_e32 v55, 1.0, v55
	v_rcp_f32_e32 v83, v73
	v_add_f32_e32 v73, 1.0, v85
	v_rcp_f32_e32 v85, v73
	v_rcp_f32_e32 v81, v55
	v_pk_mul_f32 v[20:21], v[20:21], v[54:55] op_sel_hi:[1,0]
	v_lshlrev_b32_e32 v60, 16, v61
	v_mul_f32_e32 v55, 0xbfb8aa3b, v20
	v_exp_f32_e32 v55, v55
	v_and_b32_e32 v61, 0xffff0000, v61
	v_lshlrev_b32_e32 v76, 16, v62
	v_and_b32_e32 v77, 0xffff0000, v62
	v_lshlrev_b32_e32 v62, 16, v63
	v_and_b32_e32 v63, 0xffff0000, v63
	v_pk_mul_f32 v[30:31], v[30:31], v[82:83]
	v_pk_mul_f32 v[28:29], v[28:29], v[78:79]
	v_pk_mul_f32 v[26:27], v[26:27], v[84:85]
	v_pk_mul_f32 v[24:25], v[24:25], v[80:81]
	v_pk_mul_f32 v[28:29], v[28:29], v[74:75]
	v_pk_mul_f32 v[30:31], v[30:31], v[60:61]
	v_pk_mul_f32 v[24:25], v[24:25], v[76:77]
	v_pk_mul_f32 v[26:27], v[26:27], v[62:63]
	v_pk_mul_f32 v[30:31], v[66:67], v[30:31]
	v_pk_mul_f32 v[28:29], v[64:65], v[28:29]
	v_pk_mul_f32 v[26:27], v[70:71], v[26:27]
	v_pk_mul_f32 v[24:25], v[68:69], v[24:25]
	v_pk_mul_f32 v[22:23], v[22:23], v[54:55] op_sel_hi:[1,0]
	v_pk_mul_f32 v[30:31], v[72:73], v[30:31] op_sel_hi:[0,1]
	v_pk_mul_f32 v[28:29], v[72:73], v[28:29] op_sel_hi:[0,1]
	v_pk_mul_f32 v[60:61], v[72:73], v[26:27] op_sel_hi:[0,1]
	v_pk_mul_f32 v[26:27], v[72:73], v[24:25] op_sel_hi:[0,1]
	v_pk_mul_f32 v[18:19], v[18:19], v[54:55] op_sel_hi:[1,0]
	v_pk_mul_f32 v[16:17], v[16:17], v[54:55] op_sel_hi:[1,0]
	v_mul_f32_e32 v73, 0xbfb8aa3b, v22
	v_add_f32_e32 v54, 1.0, v55
	v_mul_f32_e32 v55, 0xbfb8aa3b, v16
	v_exp_f32_e32 v73, v73
	v_mul_f32_e32 v74, 0xbfb8aa3b, v18
	v_exp_f32_e32 v55, v55
	v_mul_f32_e32 v62, 0xbfb8aa3b, v21
	v_exp_f32_e32 v75, v74
	v_exp_f32_e32 v63, v62
	v_add_f32_e32 v73, 1.0, v73
	v_add_f32_e32 v55, 1.0, v55
	v_rcp_f32_e32 v74, v73
	v_add_f32_e32 v73, 1.0, v75
	v_mul_f32_e32 v75, 0xbfb8aa3b, v23
	v_rcp_f32_e32 v62, v55
	v_add_f32_e32 v55, 1.0, v63
	v_mul_f32_e32 v63, 0xbfb8aa3b, v17
	v_exp_f32_e32 v75, v75
	v_mul_f32_e32 v76, 0xbfb8aa3b, v19
	v_exp_f32_e32 v63, v63
	v_exp_f32_e32 v77, v76
	v_rcp_f32_e32 v76, v73
	v_add_f32_e32 v73, 1.0, v75
	v_add_f32_e32 v63, 1.0, v63
	v_rcp_f32_e32 v75, v73
	v_add_f32_e32 v73, 1.0, v77
	v_rcp_f32_e32 v54, v54
	v_rcp_f32_e32 v55, v55
	v_rcp_f32_e32 v77, v73
	v_rcp_f32_e32 v63, v63
	v_cvt_pk_bf16_f32 v24, v28, v29
	v_lshl_add_u64 v[28:29], s[36:37], 0, v[100:101]
	v_cvt_pk_bf16_f32 v25, v30, v31
	v_cvt_pk_bf16_f32 v26, v26, v27
	v_cvt_pk_bf16_f32 v27, v60, v61
	v_lshl_add_u64 v[28:29], v[28:29], 0, v[184:185]
	flat_store_dwordx4 v[28:29], v[24:27]
	v_lshlrev_b32_e32 v30, 16, v90
	v_and_b32_e32 v31, 0xffff0000, v90
	v_lshlrev_b32_e32 v24, 16, v88
	v_and_b32_e32 v25, 0xffff0000, v88
	v_lshlrev_b32_e32 v26, 16, v89
	v_and_b32_e32 v27, 0xffff0000, v89
	v_lshlrev_b32_e32 v60, 16, v91
	v_and_b32_e32 v61, 0xffff0000, v91
	v_pk_mul_f32 v[22:23], v[22:23], v[74:75]
	v_pk_mul_f32 v[20:21], v[20:21], v[54:55]
	v_pk_mul_f32 v[18:19], v[18:19], v[76:77]
	v_pk_mul_f32 v[16:17], v[16:17], v[62:63]
	v_pk_mul_f32 v[20:21], v[20:21], v[24:25]
	v_pk_mul_f32 v[22:23], v[22:23], v[26:27]
	v_pk_mul_f32 v[16:17], v[16:17], v[30:31]
	v_pk_mul_f32 v[18:19], v[18:19], v[60:61]
	v_pk_mul_f32 v[22:23], v[58:59], v[22:23]
	v_pk_mul_f32 v[20:21], v[56:57], v[20:21]
	v_pk_mul_f32 v[18:19], v[50:51], v[18:19]
	v_pk_mul_f32 v[16:17], v[48:49], v[16:17]
	v_pk_mul_f32 v[22:23], v[72:73], v[22:23] op_sel_hi:[0,1]
	v_pk_mul_f32 v[20:21], v[72:73], v[20:21] op_sel_hi:[0,1]
	v_pk_mul_f32 v[24:25], v[72:73], v[18:19] op_sel_hi:[0,1]
	v_pk_mul_f32 v[18:19], v[72:73], v[16:17] op_sel_hi:[0,1]
	v_cvt_pk_bf16_f32 v16, v20, v21
	v_cvt_pk_bf16_f32 v17, v22, v23
	v_cvt_pk_bf16_f32 v18, v18, v19
	v_cvt_pk_bf16_f32 v19, v24, v25
	flat_store_dwordx4 v[28:29], v[16:19] offset:256
; #define PG8_WAIT_V(n) asm volatile("s_waitcnt vmcnt(" #n ")" ::: "memory")
; #define PG8_BAR __builtin_amdgcn_s_barrier()
; __device__ __forceinline__ u32x4 pack8(f32x4 a, f32x4 b) { u32x4 w; w.x = pk2(a[0], a[1]); w.y = pk2(a[2], a[3]); w.z = pk2(b[0], b[1]); w.w = pk2(b[2], b[3]); return w; }
; template <class Epi>
; __device__ __forceinline__ void gemm_phase(LAS unsigned char* lds, const Gemm g, const StaticOrder& S, const Epi& E, const int wid) {
;     ...
;         if (!has_next) break;
; #pragma unroll
;         for (int a = 0; a < 2; ++a)
; #pragma unroll
;             for (int b = 0; b < 2; ++b)
; #pragma unroll
;                 for (int m = 0; m < 4; ++m)
; #pragma unroll
;                     for (int n = 0; n < 2; ++n) acc[a][b][m][n] = (f32x4){0.f, 0.f, 0.f, 0.f};
;         cur = nxt; cA = nA; cB = nB; ++ui;
;         if (wr == 1) PG8_BAR;
;     }
;     PG8_WAIT_V(0);
;     PG8_BAR;
;     __device__ __forceinline__ void operator()(const Acc& acc, const pg8::Unit& u, int wid) const {
;     ...
;                 for (int mm = 0; mm < 2; ++mm) { const int m = 2 * mp + mm, row = row0 + ai * 128 + m * 16;
;                     const float sc = __builtin_amdgcn_rsqf(scv[mm] * (1.f / 1024.f) + EPS);
;                     const f32x4 pa = (rq[mm][0] + rq[mm][1]) + (rq[mm][2] + rq[mm][3]);
;                     const float rg = __builtin_amdgcn_rsqf(((pa[0] + pa[1]) + (pa[2] + pa[3])) * (1.f / 512.f) + EPS);
; #pragma unroll
;                     for (int bj = 0; bj < 2; ++bj) {
;                         const u32x4 w = ov[mm][bj];
;                         f32x4 o0 = (f32x4){bflo(w.x), bfhi(w.x), bflo(w.y), bfhi(w.y)}, o1 = (f32x4){bflo(w.z), bfhi(w.z), bflo(w.w), bfhi(w.w)};
;                         f32x4 a0 = acc[ai][bj][m][0] * sc, a1 = acc[ai][bj][m][1] * sc;
; #pragma unroll
;                         for (int e = 0; e < 4; ++e) { a0[e] = a0[e] * __builtin_amdgcn_rcpf(1.f + __builtin_amdgcn_exp2f(-1.4426950408889634f * a0[e])); a1[e] = a1[e] * __builtin_amdgcn_rcpf(1.f + __builtin_amdgcn_exp2f(-1.4426950408889634f * a1[e])); }
;                         o0 = a0 * o0 * g4[bj][0] * rg; o1 = a1 * o1 * g4[bj][1] * rg;
;                         *(u32x4*)(Y + (size_t)row * 2048 + col0 + bj * 128) = pack8(o0, o1);
;                     } }
	v_pk_add_f32 v[20:21], v[92:93], v[96:97]
	v_pk_add_f32 v[22:23], v[42:43], v[46:47]
	v_pk_add_f32 v[18:19], v[94:95], v[98:99]
	v_pk_add_f32 v[24:25], v[40:41], v[44:45]
	v_fmamk_f32 v16, v102, 0x3a800000, v198
	v_pk_add_f32 v[18:19], v[18:19], v[22:23]
	v_pk_add_f32 v[20:21], v[20:21], v[24:25]
	v_rsq_f32_e32 v16, v16
	v_pk_mov_b32 v[22:23], v[20:21], v[18:19] op_sel:[1,0]
	v_mov_b32_e32 v21, v19
	v_pk_add_f32 v[18:19], v[22:23], v[20:21]
	v_lshlrev_b32_e32 v20, 16, v36
	v_add_f32_e32 v17, v18, v19
	v_fmamk_f32 v17, v17, 0x3b000000, v198
	v_pk_mul_f32 v[12:13], v[12:13], v[16:17] op_sel_hi:[1,0]
	v_rsq_f32_e32 v18, v17
	v_mul_f32_e32 v17, 0xbfb8aa3b, v12
	v_exp_f32_e32 v17, v17
	v_mul_f32_e32 v28, 0xbfb8aa3b, v13
	v_exp_f32_e32 v29, v28
	v_and_b32_e32 v21, 0xffff0000, v36
	v_pk_mul_f32 v[8:9], v[8:9], v[16:17] op_sel_hi:[1,0]
	v_pk_mul_f32 v[14:15], v[14:15], v[16:17] op_sel_hi:[1,0]
	v_mul_f32_e32 v19, 0xbfb8aa3b, v8
	v_exp_f32_e32 v19, v19
	v_pk_mul_f32 v[10:11], v[10:11], v[16:17] op_sel_hi:[1,0]
	v_add_f32_e32 v17, 1.0, v17
	v_rcp_f32_e32 v28, v17
	v_add_f32_e32 v17, 1.0, v19
	v_mul_f32_e32 v19, 0xbfb8aa3b, v14
	v_exp_f32_e32 v19, v19
	v_mul_f32_e32 v31, 0xbfb8aa3b, v10
	v_exp_f32_e32 v31, v31
	v_rcp_f32_e32 v30, v17
	v_add_f32_e32 v17, 1.0, v29
	v_rcp_f32_e32 v29, v17
	v_mul_f32_e32 v17, 0xbfb8aa3b, v9
	v_add_f32_e32 v19, 1.0, v19
	v_exp_f32_e32 v17, v17
	v_rcp_f32_e32 v36, v19
	v_add_f32_e32 v19, 1.0, v31
	v_mul_f32_e32 v31, 0xbfb8aa3b, v15
	v_lshlrev_b32_e32 v22, 16, v37
	v_and_b32_e32 v23, 0xffff0000, v37
	v_exp_f32_e32 v31, v31
	v_mul_f32_e32 v37, 0xbfb8aa3b, v11
	v_lshlrev_b32_e32 v26, 16, v39
	v_and_b32_e32 v27, 0xffff0000, v39
	v_exp_f32_e32 v39, v37
	v_add_f32_e32 v17, 1.0, v17
	v_lshlrev_b32_e32 v24, 16, v38
	v_and_b32_e32 v25, 0xffff0000, v38
	v_rcp_f32_e32 v38, v19
	v_add_f32_e32 v19, 1.0, v31
	v_pk_mul_f32 v[4:5], v[4:5], v[16:17] op_sel_hi:[1,0]
	v_rcp_f32_e32 v37, v19
	v_add_f32_e32 v19, 1.0, v39
	v_rcp_f32_e32 v31, v17
	v_mul_f32_e32 v17, 0xbfb8aa3b, v4
	v_rcp_f32_e32 v39, v19
	v_exp_f32_e32 v17, v17
	v_pk_mul_f32 v[14:15], v[14:15], v[36:37]
	v_pk_mul_f32 v[12:13], v[12:13], v[28:29]
	v_pk_mul_f32 v[10:11], v[10:11], v[38:39]
	v_pk_mul_f32 v[8:9], v[8:9], v[30:31]
	v_pk_mul_f32 v[6:7], v[6:7], v[16:17] op_sel_hi:[1,0]
	v_pk_mul_f32 v[12:13], v[12:13], v[20:21]
	v_pk_mul_f32 v[14:15], v[14:15], v[22:23]
	v_pk_mul_f32 v[8:9], v[8:9], v[24:25]
	v_pk_mul_f32 v[10:11], v[10:11], v[26:27]
	v_pk_mul_f32 v[2:3], v[2:3], v[16:17] op_sel_hi:[1,0]
	v_pk_mul_f32 v[0:1], v[0:1], v[16:17] op_sel_hi:[1,0]
	v_mul_f32_e32 v23, 0xbfb8aa3b, v6
	v_pk_mul_f32 v[14:15], v[66:67], v[14:15]
	v_pk_mul_f32 v[12:13], v[64:65], v[12:13]
	v_pk_mul_f32 v[10:11], v[70:71], v[10:11]
	v_pk_mul_f32 v[8:9], v[68:69], v[8:9]
	v_add_f32_e32 v16, 1.0, v17
	v_mul_f32_e32 v17, 0xbfb8aa3b, v0
	v_exp_f32_e32 v23, v23
	v_mul_f32_e32 v24, 0xbfb8aa3b, v2
	v_pk_mul_f32 v[14:15], v[18:19], v[14:15] op_sel_hi:[0,1]
	v_pk_mul_f32 v[12:13], v[18:19], v[12:13] op_sel_hi:[0,1]
	v_pk_mul_f32 v[20:21], v[18:19], v[10:11] op_sel_hi:[0,1]
	v_pk_mul_f32 v[10:11], v[18:19], v[8:9] op_sel_hi:[0,1]
	v_exp_f32_e32 v17, v17
	v_mul_f32_e32 v19, 0xbfb8aa3b, v5
	v_exp_f32_e32 v25, v24
	v_exp_f32_e32 v19, v19
	v_add_f32_e32 v23, 1.0, v23
	v_add_f32_e32 v17, 1.0, v17
	v_rcp_f32_e32 v24, v23
	v_add_f32_e32 v23, 1.0, v25
	v_mul_f32_e32 v25, 0xbfb8aa3b, v7
	v_rcp_f32_e32 v22, v17
	v_add_f32_e32 v17, 1.0, v19
	v_mul_f32_e32 v19, 0xbfb8aa3b, v1
	v_exp_f32_e32 v25, v25
	v_mul_f32_e32 v26, 0xbfb8aa3b, v3
	v_exp_f32_e32 v19, v19
	v_exp_f32_e32 v27, v26
	v_rcp_f32_e32 v26, v23
	v_add_f32_e32 v23, 1.0, v25
	v_add_f32_e32 v19, 1.0, v19
	v_rcp_f32_e32 v25, v23
	v_add_f32_e32 v23, 1.0, v27
	v_rcp_f32_e32 v16, v16
	v_rcp_f32_e32 v17, v17
	v_rcp_f32_e32 v27, v23
	v_rcp_f32_e32 v23, v19
	v_cvt_pk_bf16_f32 v8, v12, v13
	v_lshl_add_u64 v[12:13], s[36:37], 0, v[52:53]
	v_cvt_pk_bf16_f32 v9, v14, v15
	v_cvt_pk_bf16_f32 v10, v10, v11
	v_cvt_pk_bf16_f32 v11, v20, v21
	v_lshl_add_u64 v[12:13], v[12:13], 0, v[184:185]
	flat_store_dwordx4 v[12:13], v[8:11]
	v_lshlrev_b32_e32 v14, 16, v34
	v_and_b32_e32 v15, 0xffff0000, v34
	v_lshlrev_b32_e32 v8, 16, v32
	v_and_b32_e32 v9, 0xffff0000, v32
	v_lshlrev_b32_e32 v10, 16, v33
	v_and_b32_e32 v11, 0xffff0000, v33
	v_lshlrev_b32_e32 v20, 16, v35
	v_and_b32_e32 v21, 0xffff0000, v35
	v_pk_mul_f32 v[6:7], v[6:7], v[24:25]
	v_pk_mul_f32 v[4:5], v[4:5], v[16:17]
	v_pk_mul_f32 v[2:3], v[2:3], v[26:27]
	v_pk_mul_f32 v[0:1], v[0:1], v[22:23]
	v_pk_mul_f32 v[4:5], v[4:5], v[8:9]
	v_pk_mul_f32 v[6:7], v[6:7], v[10:11]
	v_pk_mul_f32 v[0:1], v[0:1], v[14:15]
	v_pk_mul_f32 v[2:3], v[2:3], v[20:21]
	v_pk_mul_f32 v[6:7], v[58:59], v[6:7]
	v_pk_mul_f32 v[4:5], v[56:57], v[4:5]
	v_pk_mul_f32 v[2:3], v[50:51], v[2:3]
	v_pk_mul_f32 v[0:1], v[48:49], v[0:1]
	v_pk_mul_f32 v[6:7], v[18:19], v[6:7] op_sel_hi:[0,1]
	v_pk_mul_f32 v[4:5], v[18:19], v[4:5] op_sel_hi:[0,1]
	v_pk_mul_f32 v[8:9], v[18:19], v[2:3] op_sel_hi:[0,1]
	v_pk_mul_f32 v[2:3], v[18:19], v[0:1] op_sel_hi:[0,1]
	v_cvt_pk_bf16_f32 v0, v4, v5
	v_cvt_pk_bf16_f32 v1, v6, v7
	v_cvt_pk_bf16_f32 v2, v2, v3
	v_cvt_pk_bf16_f32 v3, v8, v9
	flat_store_dwordx4 v[12:13], v[0:3] offset:256
	s_cbranch_vccnz .LBB0_323
	s_branch .LBB0_322
.LBB0_337:
	s_and_b64 vcc, exec, s[8:9]
	s_cbranch_vccz .Lna_1
	s_barrier

; #define PG8_STAGE(bufoff, gbase, voff) do { _Pragma("unroll") for (int _i = 0; _i < 2; ++_i) \
;         __builtin_amdgcn_global_load_lds((const unsigned*)((const char*)(gbase) + (voff)[_i]), (LAS unsigned*)(lds + (bufoff) + ldsw + _i * 8192), 16, 0, 0); } while (0)
; #define PG8_LDA(dst, b, h) do { _Pragma("unroll") for (int m = 0; m < 4; ++m) _Pragma("unroll") for (int k = 0; k < 2; ++k) dst[m][k] = *(const LAS bf16x8*)(lds + PG8_SA(b, h) + aoff + m * 2048 + k * 1024); } while (0)
; #define PG8_LDB(dst, b, h) do { _Pragma("unroll") for (int n = 0; n < 2; ++n) _Pragma("unroll") for (int k = 0; k < 2; ++k) dst[n][k] = *(const LAS bf16x8*)(lds + PG8_SB(b, h) + boff + n * 2048 + k * 1024); } while (0)
; #define PG8_MMA(ai, bj, At, Bt) do { __builtin_amdgcn_s_setprio(1); _Pragma("unroll") for (int m = 0; m < 4; ++m) _Pragma("unroll") for (int n = 0; n < 2; ++n) _Pragma("unroll") for (int k = 0; k < 2; ++k) \
;         acc[ai][bj][m][n] = __builtin_amdgcn_mfma_f32_16x16x32_bf16(Bt[n][k], At[m][k], acc[ai][bj][m][n], 0, 0, 0); __builtin_amdgcn_s_setprio(0); } while (0)
; #define PG8_WAIT_V(n) asm volatile("s_waitcnt vmcnt(" #n ")" ::: "memory")
; #define PG8_BAR __builtin_amdgcn_s_barrier()
; template <class Epi>
; __device__ __forceinline__ void gemm_phase(LAS unsigned char* lds, const Gemm g, const StaticOrder& S, const Epi& E, const int wid) {
;     ...
;             PG8_LDB(B0, 0, 0); PG8_LDB(B1, 0, 1); PG8_SCHED; PG8_LDA(At, 0, 0); PG8_STAGE(PG8_SA(1, 1), a1 + hsA, voffA);
;             PG8_WAIT_V(8); PG8_WAIT_L(0); PG8_BAR; PG8_MMA(0, 0, At, B0); PG8_MMA(0, 1, At, B1); PG8_BAR; PG8_SCHED;
;             PG8_LDA(At, 0, 1); PG8_STAGE(PG8_SB(0, 0), b2, voffB); PG8_STAGE(PG8_SB(0, 1), b2 + hsB, voffB); PG8_STAGE(PG8_SA(0, 0), a2, voffA);
;             PG8_WAIT_V(8); PG8_WAIT_L(0); PG8_BAR; PG8_MMA(1, 0, At, B0); PG8_MMA(1, 1, At, B1); PG8_BAR; PG8_SCHED;
;             PG8_LDB(B0, 1, 0); PG8_LDB(B1, 1, 1); PG8_SCHED; PG8_LDA(At, 1, 0); PG8_STAGE(PG8_SA(0, 1), a2 + hsA, voffA);
;             PG8_WAIT_V(8); PG8_WAIT_L(0); PG8_BAR; PG8_MMA(0, 0, At, B0); PG8_MMA(0, 1, At, B1); PG8_BAR; PG8_SCHED;
;             PG8_LDA(At, 1, 1); PG8_STAGE(PG8_SB(1, 0), b3, voffB); PG8_STAGE(PG8_SB(1, 1), b3 + hsB, voffB); PG8_STAGE(PG8_SA(1, 0), a3, voffA);
;             PG8_WAIT_V(8); PG8_WAIT_L(0); PG8_BAR; PG8_MMA(1, 0, At, B0); PG8_MMA(1, 1, At, B1); PG8_BAR; PG8_SCHED;
.LBB0_401:
	ds_read_b128 v[120:123], v246
	ds_read_b128 v[124:127], v246 offset:1024
	ds_read_b128 v[132:135], v246 offset:2048
	ds_read_b128 v[136:139], v246 offset:3072
	ds_read_b128 v[144:147], v247
	ds_read_b128 v[148:151], v247 offset:1024
	ds_read_b128 v[152:155], v247 offset:2048
	ds_read_b128 v[156:159], v247 offset:3072
	s_add_u32 s28, s26, 0xfff80080
	s_addc_u32 s29, s27, -1
	s_cmp_eq_u32 s81, 28
	s_cselect_b32 s31, s1, s29
	s_cselect_b32 s30, s19, s28
	s_cselect_b32 s29, s17, s80
	s_cselect_b32 s28, s78, s79
	v_lshl_add_u64 v[208:209], s[26:27], 0, v[202:203]
	s_add_i32 m0, s25, 0xc000
	ds_read_b128 v[160:163], v248
	ds_read_b128 v[164:167], v248 offset:1024
	ds_read_b128 v[168:171], v248 offset:2048
	ds_read_b128 v[172:175], v248 offset:3072
	ds_read_b128 v[176:179], v248 offset:4096
	ds_read_b128 v[180:183], v248 offset:5120
	ds_read_b128 v[184:187], v248 offset:6144
	ds_read_b128 v[188:191], v248 offset:7168
	global_load_lds_dwordx4 v[208:209], off
	v_lshl_add_u64 v[208:209], s[26:27], 0, v[200:201]
	s_add_i32 m0, s25, 0xe000
	s_nop 0
	global_load_lds_dwordx4 v[208:209], off
	s_waitcnt vmcnt(8)
	s_waitcnt lgkmcnt(0)
	s_barrier
	s_setprio 1
	s_waitcnt lgkmcnt(0)
	v_mfma_f32_16x16x32_bf16 v[140:143], v[120:123], v[160:163], v[140:143]
	v_mfma_f32_16x16x32_bf16 v[128:131], v[132:135], v[160:163], v[128:131]
	v_mfma_f32_16x16x32_bf16 v[108:111], v[120:123], v[168:171], v[108:111]
	v_mfma_f32_16x16x32_bf16 v[104:107], v[132:135], v[168:171], v[104:107]
	v_mfma_f32_16x16x32_bf16 v[92:95], v[120:123], v[176:179], v[92:95]
	v_mfma_f32_16x16x32_bf16 v[88:91], v[132:135], v[176:179], v[88:91]
	v_mfma_f32_16x16x32_bf16 v[76:79], v[120:123], v[184:187], v[76:79]
	v_mfma_f32_16x16x32_bf16 v[72:75], v[132:135], v[184:187], v[72:75]
	v_mfma_f32_16x16x32_bf16 v[140:143], v[124:127], v[164:167], v[140:143]
	v_mfma_f32_16x16x32_bf16 v[128:131], v[136:139], v[164:167], v[128:131]
	v_mfma_f32_16x16x32_bf16 v[108:111], v[124:127], v[172:175], v[108:111]
	v_mfma_f32_16x16x32_bf16 v[104:107], v[136:139], v[172:175], v[104:107]
	v_mfma_f32_16x16x32_bf16 v[92:95], v[124:127], v[180:183], v[92:95]
	v_mfma_f32_16x16x32_bf16 v[88:91], v[136:139], v[180:183], v[88:91]
	v_mfma_f32_16x16x32_bf16 v[76:79], v[124:127], v[188:191], v[76:79]
	v_mfma_f32_16x16x32_bf16 v[72:75], v[136:139], v[188:191], v[72:75]
	s_setprio 0
	s_setprio 1
	v_mfma_f32_16x16x32_bf16 v[116:119], v[144:147], v[160:163], v[116:119]
	v_mfma_f32_16x16x32_bf16 v[112:115], v[152:155], v[160:163], v[112:115]
	v_mfma_f32_16x16x32_bf16 v[100:103], v[144:147], v[168:171], v[100:103]
	v_mfma_f32_16x16x32_bf16 v[96:99], v[152:155], v[168:171], v[96:99]
	v_mfma_f32_16x16x32_bf16 v[84:87], v[144:147], v[176:179], v[84:87]
	v_mfma_f32_16x16x32_bf16 v[80:83], v[152:155], v[176:179], v[80:83]
	v_mfma_f32_16x16x32_bf16 v[68:71], v[144:147], v[184:187], v[68:71]
	v_mfma_f32_16x16x32_bf16 v[64:67], v[152:155], v[184:187], v[64:67]
	v_mfma_f32_16x16x32_bf16 v[116:119], v[148:151], v[164:167], v[116:119]
	v_mfma_f32_16x16x32_bf16 v[112:115], v[156:159], v[164:167], v[112:115]
	v_mfma_f32_16x16x32_bf16 v[100:103], v[148:151], v[172:175], v[100:103]
	v_mfma_f32_16x16x32_bf16 v[96:99], v[156:159], v[172:175], v[96:99]
	v_mfma_f32_16x16x32_bf16 v[84:87], v[148:151], v[180:183], v[84:87]
	v_mfma_f32_16x16x32_bf16 v[80:83], v[156:159], v[180:183], v[80:83]
	v_mfma_f32_16x16x32_bf16 v[68:71], v[148:151], v[188:191], v[68:71]
	v_mfma_f32_16x16x32_bf16 v[64:67], v[156:159], v[188:191], v[64:67]
	s_setprio 0
	s_barrier
	s_add_i32 s47, s76, s68
	v_lshl_add_u64 v[208:209], s[28:29], 0, v[194:195]
	s_mov_b32 m0, s47
	ds_read_b128 v[160:163], v248 offset:16384
	ds_read_b128 v[164:167], v248 offset:17408
	ds_read_b128 v[168:171], v248 offset:18432
	ds_read_b128 v[172:175], v248 offset:19456
	ds_read_b128 v[176:179], v248 offset:20480
	ds_read_b128 v[180:183], v248 offset:21504
	ds_read_b128 v[184:187], v248 offset:22528
	ds_read_b128 v[188:191], v248 offset:23552
	global_load_lds_dwordx4 v[208:209], off
	s_add_i32 m0, s47, 0x2000
	s_add_u32 s50, s28, 0x80000
	v_lshl_add_u64 v[210:211], s[28:29], 0, v[198:199]
	s_addc_u32 s51, s29, 0
	s_add_i32 s47, s77, s68
	global_load_lds_dwordx4 v[210:211], off
	v_lshl_add_u64 v[212:213], s[50:51], 0, v[194:195]
	s_mov_b32 m0, s47
	v_lshl_add_u64 v[214:215], s[30:31], 0, v[196:197]
	global_load_lds_dwordx4 v[212:213], off
	v_lshl_add_u64 v[212:213], s[50:51], 0, v[198:199]
	s_add_i32 m0, s47, 0x2000
	s_nop 0
	global_load_lds_dwordx4 v[212:213], off
	v_lshl_add_u64 v[212:213], s[30:31], 0, v[192:193]
	s_mov_b32 m0, s25
	s_nop 0
	global_load_lds_dwordx4 v[212:213], off
	s_mov_b32 m0, s60
	s_nop 0
	global_load_lds_dwordx4 v[214:215], off
	s_waitcnt vmcnt(8)
	s_waitcnt lgkmcnt(0)
	s_barrier
; #define PG8_STAGE(bufoff, gbase, voff) do { _Pragma("unroll") for (int _i = 0; _i < 2; ++_i) \
;         __builtin_amdgcn_global_load_lds((const unsigned*)((const char*)(gbase) + (voff)[_i]), (LAS unsigned*)(lds + (bufoff) + ldsw + _i * 8192), 16, 0, 0); } while (0)
; #define PG8_LDA(dst, b, h) do { _Pragma("unroll") for (int m = 0; m < 4; ++m) _Pragma("unroll") for (int k = 0; k < 2; ++k) dst[m][k] = *(const LAS bf16x8*)(lds + PG8_SA(b, h) + aoff + m * 2048 + k * 1024); } while (0)
; #define PG8_LDB(dst, b, h) do { _Pragma("unroll") for (int n = 0; n < 2; ++n) _Pragma("unroll") for (int k = 0; k < 2; ++k) dst[n][k] = *(const LAS bf16x8*)(lds + PG8_SB(b, h) + boff + n * 2048 + k * 1024); } while (0)
; #define PG8_MMA(ai, bj, At, Bt) do { __builtin_amdgcn_s_setprio(1); _Pragma("unroll") for (int m = 0; m < 4; ++m) _Pragma("unroll") for (int n = 0; n < 2; ++n) _Pragma("unroll") for (int k = 0; k < 2; ++k) \
;         acc[ai][bj][m][n] = __builtin_amdgcn_mfma_f32_16x16x32_bf16(Bt[n][k], At[m][k], acc[ai][bj][m][n], 0, 0, 0); __builtin_amdgcn_s_setprio(0); } while (0)
; #define PG8_WAIT_V(n) asm volatile("s_waitcnt vmcnt(" #n ")" ::: "memory")
; #define PG8_BAR __builtin_amdgcn_s_barrier()
; template <class Epi>
; __device__ __forceinline__ void gemm_phase(LAS unsigned char* lds, const Gemm g, const StaticOrder& S, const Epi& E, const int wid) {
;     ...
;             PG8_LDB(B0, 0, 0); PG8_LDB(B1, 0, 1); PG8_SCHED; PG8_LDA(At, 0, 0); PG8_STAGE(PG8_SA(1, 1), a1 + hsA, voffA);
;             PG8_WAIT_V(8); PG8_WAIT_L(0); PG8_BAR; PG8_MMA(0, 0, At, B0); PG8_MMA(0, 1, At, B1); PG8_BAR; PG8_SCHED;
;             PG8_LDA(At, 0, 1); PG8_STAGE(PG8_SB(0, 0), b2, voffB); PG8_STAGE(PG8_SB(0, 1), b2 + hsB, voffB); PG8_STAGE(PG8_SA(0, 0), a2, voffA);
;             PG8_WAIT_V(8); PG8_WAIT_L(0); PG8_BAR; PG8_MMA(1, 0, At, B0); PG8_MMA(1, 1, At, B1); PG8_BAR; PG8_SCHED;
;             PG8_LDB(B0, 1, 0); PG8_LDB(B1, 1, 1); PG8_SCHED; PG8_LDA(At, 1, 0); PG8_STAGE(PG8_SA(0, 1), a2 + hsA, voffA);
;             PG8_WAIT_V(8); PG8_WAIT_L(0); PG8_BAR; PG8_MMA(0, 0, At, B0); PG8_MMA(0, 1, At, B1); PG8_BAR; PG8_SCHED;
;             PG8_LDA(At, 1, 1); PG8_STAGE(PG8_SB(1, 0), b3, voffB); PG8_STAGE(PG8_SB(1, 1), b3 + hsB, voffB); PG8_STAGE(PG8_SA(1, 0), a3, voffA);
;             PG8_WAIT_V(8); PG8_WAIT_L(0); PG8_BAR; PG8_MMA(1, 0, At, B0); PG8_MMA(1, 1, At, B1); PG8_BAR; PG8_SCHED;
	s_setprio 1
	s_waitcnt lgkmcnt(0)
	v_mfma_f32_16x16x32_bf16 v[60:63], v[120:123], v[160:163], v[60:63]
	v_mfma_f32_16x16x32_bf16 v[56:59], v[132:135], v[160:163], v[56:59]
	v_mfma_f32_16x16x32_bf16 v[44:47], v[120:123], v[168:171], v[44:47]
	v_mfma_f32_16x16x32_bf16 v[40:43], v[132:135], v[168:171], v[40:43]
	v_mfma_f32_16x16x32_bf16 v[28:31], v[120:123], v[176:179], v[28:31]
	v_mfma_f32_16x16x32_bf16 v[24:27], v[132:135], v[176:179], v[24:27]
	v_mfma_f32_16x16x32_bf16 v[12:15], v[120:123], v[184:187], v[12:15]
	v_mfma_f32_16x16x32_bf16 v[8:11], v[132:135], v[184:187], v[8:11]
	v_mfma_f32_16x16x32_bf16 v[60:63], v[124:127], v[164:167], v[60:63]
	v_mfma_f32_16x16x32_bf16 v[56:59], v[136:139], v[164:167], v[56:59]
	v_mfma_f32_16x16x32_bf16 v[44:47], v[124:127], v[172:175], v[44:47]
	v_mfma_f32_16x16x32_bf16 v[40:43], v[136:139], v[172:175], v[40:43]
	v_mfma_f32_16x16x32_bf16 v[28:31], v[124:127], v[180:183], v[28:31]
	v_mfma_f32_16x16x32_bf16 v[24:27], v[136:139], v[180:183], v[24:27]
	v_mfma_f32_16x16x32_bf16 v[12:15], v[124:127], v[188:191], v[12:15]
	v_mfma_f32_16x16x32_bf16 v[8:11], v[136:139], v[188:191], v[8:11]
	s_setprio 0
	s_setprio 1
	v_mfma_f32_16x16x32_bf16 v[52:55], v[144:147], v[160:163], v[52:55]
	v_mfma_f32_16x16x32_bf16 v[48:51], v[152:155], v[160:163], v[48:51]
	v_mfma_f32_16x16x32_bf16 v[36:39], v[144:147], v[168:171], v[36:39]
	v_mfma_f32_16x16x32_bf16 v[32:35], v[152:155], v[168:171], v[32:35]
	v_mfma_f32_16x16x32_bf16 v[20:23], v[144:147], v[176:179], v[20:23]
	v_mfma_f32_16x16x32_bf16 v[16:19], v[152:155], v[176:179], v[16:19]
	v_mfma_f32_16x16x32_bf16 v[4:7], v[144:147], v[184:187], v[4:7]
	v_mfma_f32_16x16x32_bf16 v[0:3], v[152:155], v[184:187], v[0:3]
	v_mfma_f32_16x16x32_bf16 v[52:55], v[148:151], v[164:167], v[52:55]
	v_mfma_f32_16x16x32_bf16 v[48:51], v[156:159], v[164:167], v[48:51]
	v_mfma_f32_16x16x32_bf16 v[36:39], v[148:151], v[172:175], v[36:39]
	v_mfma_f32_16x16x32_bf16 v[32:35], v[156:159], v[172:175], v[32:35]
	v_mfma_f32_16x16x32_bf16 v[20:23], v[148:151], v[180:183], v[20:23]
	v_mfma_f32_16x16x32_bf16 v[16:19], v[156:159], v[180:183], v[16:19]
	v_mfma_f32_16x16x32_bf16 v[4:7], v[148:151], v[188:191], v[4:7]
	v_mfma_f32_16x16x32_bf16 v[0:3], v[156:159], v[188:191], v[0:3]
	s_setprio 0
	s_barrier
	s_add_i32 s47, 0, 0x18000
	s_add_i32 s50, 0, 0x1c000
	v_add_u32_e32 v136, s47, v245
	v_add_u32_e32 v156, s50, v245
	ds_read_b128 v[120:123], v136
	ds_read_b128 v[124:127], v136 offset:1024
	ds_read_b128 v[132:135], v136 offset:2048
	ds_read_b128 v[136:139], v136 offset:3072
	ds_read_b128 v[144:147], v156
	ds_read_b128 v[148:151], v156 offset:1024
	ds_read_b128 v[152:155], v156 offset:2048
	ds_read_b128 v[156:159], v156 offset:3072
	s_add_u32 s30, s30, 0x80000
	s_addc_u32 s31, s31, 0
	s_mov_b32 m0, s61
	v_lshl_add_u64 v[216:217], s[30:31], 0, v[192:193]
	ds_read_b128 v[160:163], v248 offset:32768
	ds_read_b128 v[164:167], v248 offset:33792
	ds_read_b128 v[168:171], v248 offset:34816
	ds_read_b128 v[172:175], v248 offset:35840
	ds_read_b128 v[176:179], v248 offset:36864
	ds_read_b128 v[180:183], v248 offset:37888
	ds_read_b128 v[184:187], v248 offset:38912
	ds_read_b128 v[188:191], v248 offset:39936
	global_load_lds_dwordx4 v[216:217], off
	v_lshl_add_u64 v[216:217], s[30:31], 0, v[196:197]
	s_mov_b32 m0, s62
	s_nop 0
	global_load_lds_dwordx4 v[216:217], off
	s_waitcnt vmcnt(8)
	s_waitcnt lgkmcnt(0)
	s_barrier
	s_setprio 1
	s_waitcnt lgkmcnt(0)
	v_mfma_f32_16x16x32_bf16 v[140:143], v[120:123], v[160:163], v[140:143]
	v_mfma_f32_16x16x32_bf16 v[128:131], v[132:135], v[160:163], v[128:131]
	v_mfma_f32_16x16x32_bf16 v[108:111], v[120:123], v[168:171], v[108:111]
	v_mfma_f32_16x16x32_bf16 v[104:107], v[132:135], v[168:171], v[104:107]
	v_mfma_f32_16x16x32_bf16 v[92:95], v[120:123], v[176:179], v[92:95]
	v_mfma_f32_16x16x32_bf16 v[88:91], v[132:135], v[176:179], v[88:91]
	v_mfma_f32_16x16x32_bf16 v[76:79], v[120:123], v[184:187], v[76:79]
	v_mfma_f32_16x16x32_bf16 v[72:75], v[132:135], v[184:187], v[72:75]
	v_mfma_f32_16x16x32_bf16 v[140:143], v[124:127], v[164:167], v[140:143]
	v_mfma_f32_16x16x32_bf16 v[128:131], v[136:139], v[164:167], v[128:131]
	v_mfma_f32_16x16x32_bf16 v[108:111], v[124:127], v[172:175], v[108:111]
	v_mfma_f32_16x16x32_bf16 v[104:107], v[136:139], v[172:175], v[104:107]
	v_mfma_f32_16x16x32_bf16 v[92:95], v[124:127], v[180:183], v[92:95]
	v_mfma_f32_16x16x32_bf16 v[88:91], v[136:139], v[180:183], v[88:91]
	v_mfma_f32_16x16x32_bf16 v[76:79], v[124:127], v[188:191], v[76:79]
	v_mfma_f32_16x16x32_bf16 v[72:75], v[136:139], v[188:191], v[72:75]
	s_setprio 0
	s_setprio 1
	v_mfma_f32_16x16x32_bf16 v[116:119], v[144:147], v[160:163], v[116:119]
	v_mfma_f32_16x16x32_bf16 v[112:115], v[152:155], v[160:163], v[112:115]
	v_mfma_f32_16x16x32_bf16 v[100:103], v[144:147], v[168:171], v[100:103]
	v_mfma_f32_16x16x32_bf16 v[96:99], v[152:155], v[168:171], v[96:99]
	v_mfma_f32_16x16x32_bf16 v[84:87], v[144:147], v[176:179], v[84:87]
	v_mfma_f32_16x16x32_bf16 v[80:83], v[152:155], v[176:179], v[80:83]
	v_mfma_f32_16x16x32_bf16 v[68:71], v[144:147], v[184:187], v[68:71]
	v_mfma_f32_16x16x32_bf16 v[64:67], v[152:155], v[184:187], v[64:67]
	v_mfma_f32_16x16x32_bf16 v[116:119], v[148:151], v[164:167], v[116:119]
	v_mfma_f32_16x16x32_bf16 v[112:115], v[156:159], v[164:167], v[112:115]
	v_mfma_f32_16x16x32_bf16 v[100:103], v[148:151], v[172:175], v[100:103]
	v_mfma_f32_16x16x32_bf16 v[96:99], v[156:159], v[172:175], v[96:99]
	v_mfma_f32_16x16x32_bf16 v[84:87], v[148:151], v[180:183], v[84:87]
	v_mfma_f32_16x16x32_bf16 v[80:83], v[156:159], v[180:183], v[80:83]
	v_mfma_f32_16x16x32_bf16 v[68:71], v[148:151], v[188:191], v[68:71]
	v_mfma_f32_16x16x32_bf16 v[64:67], v[156:159], v[188:191], v[64:67]
	s_setprio 0
	s_barrier
; #define PG8_STAGE(bufoff, gbase, voff) do { _Pragma("unroll") for (int _i = 0; _i < 2; ++_i) \
;         __builtin_amdgcn_global_load_lds((const unsigned*)((const char*)(gbase) + (voff)[_i]), (LAS unsigned*)(lds + (bufoff) + ldsw + _i * 8192), 16, 0, 0); } while (0)
; #define PG8_LDA(dst, b, h) do { _Pragma("unroll") for (int m = 0; m < 4; ++m) _Pragma("unroll") for (int k = 0; k < 2; ++k) dst[m][k] = *(const LAS bf16x8*)(lds + PG8_SA(b, h) + aoff + m * 2048 + k * 1024); } while (0)
; #define PG8_LDB(dst, b, h) do { _Pragma("unroll") for (int n = 0; n < 2; ++n) _Pragma("unroll") for (int k = 0; k < 2; ++k) dst[n][k] = *(const LAS bf16x8*)(lds + PG8_SB(b, h) + boff + n * 2048 + k * 1024); } while (0)
; #define PG8_MMA(ai, bj, At, Bt) do { __builtin_amdgcn_s_setprio(1); _Pragma("unroll") for (int m = 0; m < 4; ++m) _Pragma("unroll") for (int n = 0; n < 2; ++n) _Pragma("unroll") for (int k = 0; k < 2; ++k) \
;         acc[ai][bj][m][n] = __builtin_amdgcn_mfma_f32_16x16x32_bf16(Bt[n][k], At[m][k], acc[ai][bj][m][n], 0, 0, 0); __builtin_amdgcn_s_setprio(0); } while (0)
; #define PG8_WAIT_V(n) asm volatile("s_waitcnt vmcnt(" #n ")" ::: "memory")
; #define PG8_WAIT_L(n) asm volatile("s_waitcnt lgkmcnt(" #n ")" ::: "memory")
; #define PG8_BAR __builtin_amdgcn_s_barrier()
; #define PG8_SCHED __builtin_amdgcn_sched_barrier(0)
; template <class Epi>
; __device__ __forceinline__ void gemm_phase(LAS unsigned char* lds, const Gemm g, const StaticOrder& S, const Epi& E, const int wid) {
;     ...
;             PG8_LDB(B0, 1, 0); PG8_LDB(B1, 1, 1); PG8_SCHED; PG8_LDA(At, 1, 0); PG8_STAGE(PG8_SA(0, 1), a2 + hsA, voffA);
;             PG8_WAIT_V(8); PG8_WAIT_L(0); PG8_BAR; PG8_MMA(0, 0, At, B0); PG8_MMA(0, 1, At, B1); PG8_BAR; PG8_SCHED;
;             PG8_LDA(At, 1, 1); PG8_STAGE(PG8_SB(1, 0), b3, voffB); PG8_STAGE(PG8_SB(1, 1), b3 + hsB, voffB); PG8_STAGE(PG8_SA(1, 0), a3, voffA);
;             PG8_WAIT_V(8); PG8_WAIT_L(0); PG8_BAR; PG8_MMA(1, 0, At, B0); PG8_MMA(1, 1, At, B1); PG8_BAR; PG8_SCHED;
;         }
	s_add_i32 s30, s47, s68
	v_lshl_add_u64 v[208:209], v[208:209], 0, s[8:9]
	s_mov_b32 m0, s30
	ds_read_b128 v[160:163], v248 offset:49152
	ds_read_b128 v[164:167], v248 offset:50176
	ds_read_b128 v[168:171], v248 offset:51200
	ds_read_b128 v[172:175], v248 offset:52224
	ds_read_b128 v[176:179], v248 offset:53248
	ds_read_b128 v[180:183], v248 offset:54272
	ds_read_b128 v[184:187], v248 offset:55296
	ds_read_b128 v[188:191], v248 offset:56320
	global_load_lds_dwordx4 v[208:209], off
	s_add_i32 m0, s30, 0x2000
	s_add_u32 s28, s28, 0x80080
	v_lshl_add_u64 v[208:209], v[210:211], 0, s[8:9]
	s_addc_u32 s29, s29, 0
	s_add_i32 s30, s50, s68
	global_load_lds_dwordx4 v[208:209], off
	v_lshl_add_u64 v[208:209], s[28:29], 0, v[194:195]
	s_mov_b32 m0, s30
	s_nop 0
	global_load_lds_dwordx4 v[208:209], off
	v_lshl_add_u64 v[208:209], s[28:29], 0, v[198:199]
	s_add_i32 m0, s30, 0x2000
	s_nop 0
	global_load_lds_dwordx4 v[208:209], off
	v_lshl_add_u64 v[208:209], v[212:213], 0, s[8:9]
	s_mov_b32 m0, s64
	s_nop 0
	global_load_lds_dwordx4 v[208:209], off
	v_lshl_add_u64 v[208:209], v[214:215], 0, s[8:9]
	s_mov_b32 m0, s65
	s_nop 0
	global_load_lds_dwordx4 v[208:209], off
	s_waitcnt vmcnt(8)
	s_waitcnt lgkmcnt(0)
	s_barrier
	s_setprio 1
	s_waitcnt lgkmcnt(0)
	v_mfma_f32_16x16x32_bf16 v[60:63], v[120:123], v[160:163], v[60:63]
	v_mfma_f32_16x16x32_bf16 v[56:59], v[132:135], v[160:163], v[56:59]
	v_mfma_f32_16x16x32_bf16 v[44:47], v[120:123], v[168:171], v[44:47]
	v_mfma_f32_16x16x32_bf16 v[40:43], v[132:135], v[168:171], v[40:43]
	v_mfma_f32_16x16x32_bf16 v[28:31], v[120:123], v[176:179], v[28:31]
	v_mfma_f32_16x16x32_bf16 v[24:27], v[132:135], v[176:179], v[24:27]
	v_mfma_f32_16x16x32_bf16 v[12:15], v[120:123], v[184:187], v[12:15]
	v_mfma_f32_16x16x32_bf16 v[8:11], v[132:135], v[184:187], v[8:11]
	v_mfma_f32_16x16x32_bf16 v[60:63], v[124:127], v[164:167], v[60:63]
	v_mfma_f32_16x16x32_bf16 v[56:59], v[136:139], v[164:167], v[56:59]
	v_mfma_f32_16x16x32_bf16 v[44:47], v[124:127], v[172:175], v[44:47]
	v_mfma_f32_16x16x32_bf16 v[40:43], v[136:139], v[172:175], v[40:43]
	v_mfma_f32_16x16x32_bf16 v[28:31], v[124:127], v[180:183], v[28:31]
	v_mfma_f32_16x16x32_bf16 v[24:27], v[136:139], v[180:183], v[24:27]
	v_mfma_f32_16x16x32_bf16 v[12:15], v[124:127], v[188:191], v[12:15]
	v_mfma_f32_16x16x32_bf16 v[8:11], v[136:139], v[188:191], v[8:11]
	s_setprio 0
	s_setprio 1
	v_mfma_f32_16x16x32_bf16 v[52:55], v[144:147], v[160:163], v[52:55]
	v_mfma_f32_16x16x32_bf16 v[48:51], v[152:155], v[160:163], v[48:51]
	v_mfma_f32_16x16x32_bf16 v[36:39], v[144:147], v[168:171], v[36:39]
	v_mfma_f32_16x16x32_bf16 v[32:35], v[152:155], v[168:171], v[32:35]
	v_mfma_f32_16x16x32_bf16 v[20:23], v[144:147], v[176:179], v[20:23]
	v_mfma_f32_16x16x32_bf16 v[16:19], v[152:155], v[176:179], v[16:19]
	v_mfma_f32_16x16x32_bf16 v[4:7], v[144:147], v[184:187], v[4:7]
	v_mfma_f32_16x16x32_bf16 v[0:3], v[152:155], v[184:187], v[0:3]
	v_mfma_f32_16x16x32_bf16 v[52:55], v[148:151], v[164:167], v[52:55]
	v_mfma_f32_16x16x32_bf16 v[48:51], v[156:159], v[164:167], v[48:51]
	v_mfma_f32_16x16x32_bf16 v[36:39], v[148:151], v[172:175], v[36:39]
	v_mfma_f32_16x16x32_bf16 v[32:35], v[156:159], v[172:175], v[32:35]
	v_mfma_f32_16x16x32_bf16 v[20:23], v[148:151], v[180:183], v[20:23]
	v_mfma_f32_16x16x32_bf16 v[16:19], v[156:159], v[180:183], v[16:19]
	v_mfma_f32_16x16x32_bf16 v[4:7], v[148:151], v[188:191], v[4:7]
	v_mfma_f32_16x16x32_bf16 v[0:3], v[156:159], v[188:191], v[0:3]
	s_setprio 0
	s_barrier
	s_add_i32 s81, s81, 2
	s_add_u32 s79, s79, 0x100
	s_addc_u32 s80, s80, 0
	s_add_u32 s26, s26, 0x100
	s_addc_u32 s27, s27, 0
	s_cmp_gt_u32 s81, 29
	s_cbranch_scc0 .LBB0_401
; __device__ __forceinline__ int lane_id_asm() { int l; asm volatile("v_mbcnt_lo_u32_b32 %0, -1, 0\n\tv_mbcnt_hi_u32_b32 %0, -1, %0" : "=v"(l)); return l; }
; #define PG8_BAR __builtin_amdgcn_s_barrier()
; template <class Epi>
; __device__ __forceinline__ void gemm_phase(LAS unsigned char* lds, const Gemm g, const StaticOrder& S, const Epi& E, const int wid) {
;     ...
;         if (wr == 0) PG8_BAR;
;         E(acc, cur, wid);
;     __device__ __forceinline__ void operator()(const Acc& acc, const pg8::Unit& u, int wid) const {
;         const int lane_ = lane_id_asm(), wr = wid >> 2, wc = wid & 3, fr = lane_ & 15, fq = lane_ >> 4;
;         const int row0 = u.pm * 256 + wr * 64 + fr, col0 = u.pn * 256 + wc * 32 + 8 * fq;
;         float r2[8];
; #pragma unroll
;         for (int i = 0; i < 8; ++i) r2[i] = ssq2 ? ssq2[row0 + (i >> 2) * 128 + (i & 3) * 16] : 0.f;
;         u32x4 bv[2][4][2];
; #pragma unroll
;         for (int ai = 0; ai < 2; ++ai)
; #pragma unroll
;             for (int m = 0; m < 4; ++m)
; #pragma unroll
;                 for (int bj = 0; bj < 2; ++bj) bv[ai][m][bj] = *(const u32x4*)(base + (size_t)(row0 + ai * 128 + m * 16) * 1024 + col0 + bj * 128);
; #pragma unroll
;         for (int ai = 0; ai < 2; ++ai) {
; #pragma unroll
;             for (int m = 0; m < 4; ++m) {
;                 const int row = row0 + ai * 128 + m * 16; float sq = 0.f;
;                 const float rr = ssq2 ? __builtin_amdgcn_rcpf(r2[ai * 4 + m] * (1.f / 1024.f) + EPS) : 1.f;
; #pragma unroll
;                 for (int bj = 0; bj < 2; ++bj) {
;                     const u32x4 b4 = bv[ai][m][bj];
;                     const f32x4 o0 = (f32x4){bflo(b4.x), bfhi(b4.x), bflo(b4.y), bfhi(b4.y)} + acc[ai][bj][m][0] * rr;
;                     const f32x4 o1 = (f32x4){bflo(b4.z), bfhi(b4.z), bflo(b4.w), bfhi(b4.w)} + acc[ai][bj][m][1] * rr;
;                     *(u32x4*)(hb + (size_t)row * 1024 + col0 + bj * 128) = pack8(o0, o1);
;                     sq += (o0[0] * o0[0] + o0[1] * o0[1]) + (o0[2] * o0[2] + o0[3] * o0[3]) + (o1[0] * o1[0] + o1[1] * o1[1]) + (o1[2] * o1[2] + o1[3] * o1[3]);
;                 }
;                 if (ssq_out) { sq += __shfl_xor(sq, 16); sq += __shfl_xor(sq, 32); if (fq == 0) atomicAdd(ssq_out + row, sq); }
;             }
;         }
.LBB0_404:
	v_mbcnt_lo_u32_b32 v250, -1, 0
	v_mbcnt_hi_u32_b32 v250, -1, v250
	s_lshl_b32 s0, s0, 8
	v_ashrrev_i32_e32 v120, 1, v250
	s_lshl_b32 s1, s24, 8
	v_and_b32_e32 v120, -8, v120
	s_or_b32 s0, s0, s69
	s_add_i32 s1, s1, s66
	v_add_u32_e32 v208, s0, v120
	v_and_or_b32 v238, v250, 15, s1
	v_ashrrev_i32_e32 v209, 31, v208
	v_lshlrev_b64 v[240:241], 1, v[208:209]
	v_ashrrev_i32_e32 v239, 31, v238
	v_lshl_add_u64 v[120:121], s[42:43], 0, v[240:241]
	v_lshlrev_b64 v[242:243], 11, v[238:239]
	v_lshl_add_u64 v[122:123], v[120:121], 0, v[242:243]
	flat_load_dwordx4 v[188:191], v[122:123]
	flat_load_dwordx4 v[184:187], v[122:123] offset:256
	v_or_b32_e32 v234, 16, v238
	v_ashrrev_i32_e32 v235, 31, v234
	v_or_b32_e32 v230, 32, v238
	v_lshlrev_b64 v[236:237], 11, v[234:235]
	v_ashrrev_i32_e32 v231, 31, v230
	v_or_b32_e32 v226, 48, v238
	v_add_u32_e32 v220, 0x80, v238
	v_lshl_add_u64 v[122:123], v[120:121], 0, v[236:237]
	v_lshlrev_b64 v[232:233], 11, v[230:231]
	v_ashrrev_i32_e32 v227, 31, v226
	v_ashrrev_i32_e32 v221, 31, v220
	flat_load_dwordx4 v[180:183], v[122:123]
	flat_load_dwordx4 v[176:179], v[122:123] offset:256
	v_lshl_add_u64 v[122:123], v[120:121], 0, v[232:233]
	v_lshlrev_b64 v[228:229], 11, v[226:227]
	v_add_u32_e32 v218, 0x90, v238
	flat_load_dwordx4 v[172:175], v[122:123]
	flat_load_dwordx4 v[168:171], v[122:123] offset:256
	v_lshl_add_u64 v[122:123], v[120:121], 0, v[228:229]
	v_lshlrev_b64 v[224:225], 11, v[220:221]
	v_ashrrev_i32_e32 v219, 31, v218
	v_add_u32_e32 v214, 0xa0, v238
	v_add_u32_e32 v210, 0xb0, v238
	flat_load_dwordx4 v[164:167], v[122:123]
	flat_load_dwordx4 v[160:163], v[122:123] offset:256
	v_lshl_add_u64 v[122:123], v[120:121], 0, v[224:225]
	v_lshlrev_b64 v[222:223], 11, v[218:219]
	v_ashrrev_i32_e32 v215, 31, v214
	v_ashrrev_i32_e32 v211, 31, v210
	flat_load_dwordx4 v[156:159], v[122:123]
	flat_load_dwordx4 v[152:155], v[122:123] offset:256
	v_lshl_add_u64 v[122:123], v[120:121], 0, v[222:223]
	v_lshlrev_b64 v[216:217], 11, v[214:215]
	v_lshlrev_b64 v[212:213], 11, v[210:211]
	flat_load_dwordx4 v[148:151], v[122:123]
	flat_load_dwordx4 v[144:147], v[122:123] offset:256
	v_lshl_add_u64 v[122:123], v[120:121], 0, v[216:217]
	v_lshl_add_u64 v[120:121], v[120:121], 0, v[212:213]
	flat_load_dwordx4 v[136:139], v[122:123]
	flat_load_dwordx4 v[124:127], v[122:123] offset:256
	flat_load_dwordx4 v[132:135], v[120:121]
	s_nop 0
	flat_load_dwordx4 v[120:123], v[120:121] offset:256
	v_cmp_gt_u32_e32 vcc, 16, v250
	v_lshl_add_u64 v[242:243], s[42:43], 0, v[242:243]
	v_lshl_add_u64 v[240:241], v[242:243], 0, v[240:241]
	s_waitcnt vmcnt(0) lgkmcnt(0)
	v_lshlrev_b32_e32 v250, 16, v188
	v_and_b32_e32 v251, 0xffff0000, v188
	v_lshlrev_b32_e32 v188, 16, v189
	v_and_b32_e32 v189, 0xffff0000, v189
	v_pk_add_f32 v[142:143], v[142:143], v[188:189]
	v_lshlrev_b32_e32 v188, 16, v190
	v_and_b32_e32 v189, 0xffff0000, v190
	v_lshlrev_b32_e32 v190, 16, v191
	v_and_b32_e32 v191, 0xffff0000, v191
	v_pk_add_f32 v[140:141], v[140:141], v[250:251]
	v_pk_add_f32 v[190:191], v[130:131], v[190:191]
	v_pk_add_f32 v[188:189], v[128:129], v[188:189]
	v_cvt_pk_bf16_f32 v128, v140, v141
	v_cvt_pk_bf16_f32 v129, v142, v143
	v_cvt_pk_bf16_f32 v130, v188, v189
	v_cvt_pk_bf16_f32 v131, v190, v191
	flat_store_dwordx4 v[240:241], v[128:131]
	s_nop 1
	v_lshlrev_b32_e32 v128, 16, v184
	v_and_b32_e32 v129, 0xffff0000, v184
	v_lshlrev_b32_e32 v130, 16, v185
	v_and_b32_e32 v131, 0xffff0000, v185
	v_pk_add_f32 v[118:119], v[118:119], v[130:131]
	v_pk_add_f32 v[116:117], v[116:117], v[128:129]
	v_lshlrev_b32_e32 v128, 16, v186
	v_and_b32_e32 v129, 0xffff0000, v186
	v_lshlrev_b32_e32 v130, 16, v187
	v_and_b32_e32 v131, 0xffff0000, v187
	v_pk_add_f32 v[130:131], v[114:115], v[130:131]
	v_pk_add_f32 v[128:129], v[112:113], v[128:129]
	v_cvt_pk_bf16_f32 v112, v116, v117
	v_cvt_pk_bf16_f32 v113, v118, v119
	v_cvt_pk_bf16_f32 v114, v128, v129
	v_cvt_pk_bf16_f32 v115, v130, v131
	flat_store_dwordx4 v[240:241], v[112:115] offset:256
	s_nop 1
	v_mul_f32_e32 v114, v141, v141
	v_mul_f32_e32 v115, v143, v143
	v_fmac_f32_e32 v114, v140, v140
	v_fmac_f32_e32 v115, v142, v142
	v_mul_f32_e32 v113, v189, v189
	v_add_f32_e32 v114, v114, v115
	v_mul_f32_e32 v115, v117, v117
	v_mul_f32_e32 v112, v191, v191
	v_fmac_f32_e32 v113, v188, v188
	v_fmac_f32_e32 v115, v116, v116
	v_mul_f32_e32 v116, v119, v119
	v_fmac_f32_e32 v112, v190, v190
	v_add_f32_e32 v113, v113, v114
	v_mul_f32_e32 v114, v129, v129
	v_fmac_f32_e32 v116, v118, v118
	v_add_f32_e32 v112, v112, v113
	v_mul_f32_e32 v113, v131, v131
	v_fmac_f32_e32 v114, v128, v128
	v_add_f32_e32 v115, v115, v116
	v_fmac_f32_e32 v113, v130, v130
	v_add_f32_e32 v114, v114, v115
	v_add_f32_e32 v113, v113, v114
	v_and_b32_e32 v114, 64, v249
	v_add_f32_e32 v113, v112, v113
	v_xor_b32_e32 v112, 16, v249
	v_add_u32_e32 v115, 64, v114
	v_cmp_lt_i32_e64 s[0:1], v112, v115
	s_nop 1
	v_cndmask_b32_e64 v112, v249, v112, s[0:1]
	v_lshlrev_b32_e32 v112, 2, v112
	ds_bpermute_b32 v114, v112, v113
	s_waitcnt lgkmcnt(0)
	v_add_f32_e32 v114, v113, v114
	v_xor_b32_e32 v113, 32, v249
	v_cmp_lt_i32_e64 s[0:1], v113, v115
	s_nop 1
	v_cndmask_b32_e64 v113, v249, v113, s[0:1]
	v_lshlrev_b32_e32 v113, 2, v113
	ds_bpermute_b32 v115, v113, v114
	s_and_saveexec_b64 s[0:1], vcc
	s_cbranch_execz .LBB0_406
	v_lshl_add_u64 v[116:117], v[238:239], 2, s[48:49]
	s_waitcnt lgkmcnt(0)
	v_add_f32_e32 v114, v114, v115
	flat_atomic_add_f32 v[116:117], v114

; #define PG8_WAIT_V(n) asm volatile("s_waitcnt vmcnt(" #n ")" ::: "memory")
; #define PG8_BAR __builtin_amdgcn_s_barrier()
; template <class Epi>
; __device__ __forceinline__ void gemm_phase(LAS unsigned char* lds, const Gemm g, const StaticOrder& S, const Epi& E, const int wid) {
;     ...
;         if (!has_next) break;
; #pragma unroll
;         for (int a = 0; a < 2; ++a)
; #pragma unroll
;             for (int b = 0; b < 2; ++b)
; #pragma unroll
;                 for (int m = 0; m < 4; ++m)
; #pragma unroll
;                     for (int n = 0; n < 2; ++n) acc[a][b][m][n] = (f32x4){0.f, 0.f, 0.f, 0.f};
;         cur = nxt; cA = nA; cB = nB; ++ui;
;         if (wr == 1) PG8_BAR;
;     }
;     PG8_WAIT_V(0);
;     PG8_BAR;
.LBB0_420:
	s_or_b64 exec, exec, s[0:1]
	s_andn2_b64 vcc, exec, s[4:5]
	s_mov_b64 s[0:1], -1
	s_cbranch_vccnz .LBB0_393
	s_branch .LBB0_392
.LBB0_423:
	s_and_b64 vcc, exec, s[10:11]
	s_cbranch_vccz .Lna_2
	s_barrier

; __device__ __forceinline__ int lane_id_asm() { int l; asm volatile("v_mbcnt_lo_u32_b32 %0, -1, 0\n\tv_mbcnt_hi_u32_b32 %0, -1, %0" : "=v"(l)); return l; }
; #define PG8_BAR __builtin_amdgcn_s_barrier()
; __device__ __forceinline__ u32x4 pack8(f32x4 a, f32x4 b) { u32x4 w; w.x = pk2(a[0], a[1]); w.y = pk2(a[2], a[3]); w.z = pk2(b[0], b[1]); w.w = pk2(b[2], b[3]); return w; }
; template <class Epi>
; __device__ __forceinline__ void gemm_phase(LAS unsigned char* lds, const Gemm g, const StaticOrder& S, const Epi& E, const int wid) {
;     ...
;         if (wr == 0) PG8_BAR;
;         E(acc, cur, wid);
;     __device__ __forceinline__ void operator()(const Acc& acc, const pg8::Unit& u, int wid) const {
;         const int lane_ = lane_id_asm(), wr = wid >> 2, wc = wid & 3, fr = lane_ & 15, fq = lane_ >> 4;
;         const int row0 = u.pm * 256 + wr * 64 + fr, col0 = u.pn * 256 + wc * 32 + 8 * fq;
;         float scv[8];
; #pragma unroll
;         for (int i = 0; i < 8; ++i) scv[i] = ssq ? ssq[row0 + (i >> 2) * 128 + (i & 3) * 16] : 0.f;
; #pragma unroll
;         for (int ai = 0; ai < 2; ++ai)
; #pragma unroll
;             for (int m = 0; m < 4; ++m) {
;                 const int row = row0 + ai * 128 + m * 16;
;                 const float sc = ssq ? __builtin_amdgcn_rsqf(scv[ai * 4 + m] * inv_n + EPS) : 1.f;
; #pragma unroll
;                 for (int bj = 0; bj < 2; ++bj) {
;                     f32x4 v0 = acc[ai][bj][m][0] * sc, v1 = acc[ai][bj][m][1] * sc;
;                     if (ACT == 1) {
; #pragma unroll
;                         for (int e = 0; e < 4; ++e) { float a = fmaxf(v0[e], 0.f), b = fmaxf(v1[e], 0.f); v0[e] = a * a; v1[e] = b * b; }
;                     }
;                     *(u32x4*)(O + (size_t)row * ldc + col0 + bj * 128) = pack8(v0, v1);
.LBB0_488:
	s_lshl_b32 s4, s34, 8
	v_mbcnt_lo_u32_b32 v149, -1, 0
	v_mbcnt_hi_u32_b32 v149, -1, v149
	s_add_i32 s4, s4, s77
	v_and_or_b32 v148, v149, 15, s4
	v_ashrrev_i32_e32 v149, 1, v149
	s_lshl_b32 s4, s89, 8
	v_and_b32_e32 v149, -8, v149
	s_or_b32 s4, s4, s69
	v_add_u32_e32 v150, s4, v149
	v_mov_b32_e32 v149, 0
	v_mov_b32_e32 v151, 0
	v_lshlrev_b64 v[152:153], 13, v[148:149]
	v_lshl_add_u64 v[152:153], s[44:45], 0, v[152:153]
	v_lshlrev_b64 v[150:151], 1, v[150:151]
	v_lshl_add_u64 v[152:153], v[152:153], 0, v[150:151]
	v_max_f32_e32 v124, 0, v124
	v_max_f32_e32 v125, 0, v125
	v_max_f32_e32 v126, 0, v126
	v_max_f32_e32 v127, 0, v127
	v_max_f32_e32 v120, 0, v120
	v_max_f32_e32 v121, 0, v121
	v_max_f32_e32 v122, 0, v122
	v_max_f32_e32 v123, 0, v123
	v_pk_mul_f32 v[124:125], v[124:125], v[124:125]
	v_pk_mul_f32 v[126:127], v[126:127], v[126:127]
	v_pk_mul_f32 v[120:121], v[120:121], v[120:121]
	v_pk_mul_f32 v[122:123], v[122:123], v[122:123]
	v_cvt_pk_bf16_f32 v124, v124, v125
	v_cvt_pk_bf16_f32 v125, v126, v127
	v_cvt_pk_bf16_f32 v126, v120, v121
	v_cvt_pk_bf16_f32 v127, v122, v123
	flat_store_dwordx4 v[152:153], v[124:127]
	v_max_f32_e32 v116, 0, v116
	v_max_f32_e32 v117, 0, v117
	v_max_f32_e32 v118, 0, v118
	v_max_f32_e32 v119, 0, v119
	v_max_f32_e32 v112, 0, v112
	v_max_f32_e32 v113, 0, v113
	v_max_f32_e32 v114, 0, v114
	v_max_f32_e32 v115, 0, v115
	v_pk_mul_f32 v[116:117], v[116:117], v[116:117]
	v_pk_mul_f32 v[118:119], v[118:119], v[118:119]
	v_pk_mul_f32 v[112:113], v[112:113], v[112:113]
	v_pk_mul_f32 v[114:115], v[114:115], v[114:115]
	v_cvt_pk_bf16_f32 v116, v116, v117
	v_cvt_pk_bf16_f32 v117, v118, v119
	v_cvt_pk_bf16_f32 v118, v112, v113
	v_cvt_pk_bf16_f32 v119, v114, v115
	flat_store_dwordx4 v[152:153], v[116:119] offset:256
	v_add_co_u32_e32 v150, vcc, 0x20000, v152
	s_nop 1
	v_addc_co_u32_e32 v151, vcc, 0, v153, vcc
	v_max_f32_e32 v108, 0, v108
	v_max_f32_e32 v109, 0, v109
	v_max_f32_e32 v110, 0, v110
	v_max_f32_e32 v111, 0, v111
	v_max_f32_e32 v104, 0, v104
	v_max_f32_e32 v105, 0, v105
	v_max_f32_e32 v106, 0, v106
	v_max_f32_e32 v107, 0, v107
	v_pk_mul_f32 v[108:109], v[108:109], v[108:109]
	v_pk_mul_f32 v[110:111], v[110:111], v[110:111]
	v_pk_mul_f32 v[104:105], v[104:105], v[104:105]
	v_pk_mul_f32 v[106:107], v[106:107], v[106:107]
	v_cvt_pk_bf16_f32 v108, v108, v109
	v_cvt_pk_bf16_f32 v109, v110, v111
	v_cvt_pk_bf16_f32 v110, v104, v105
	v_cvt_pk_bf16_f32 v111, v106, v107
	flat_store_dwordx4 v[150:151], v[108:111]
	v_max_f32_e32 v100, 0, v100
	v_max_f32_e32 v101, 0, v101
	v_max_f32_e32 v102, 0, v102
	v_max_f32_e32 v103, 0, v103
	v_max_f32_e32 v96, 0, v96
	v_max_f32_e32 v97, 0, v97
	v_max_f32_e32 v98, 0, v98
	v_max_f32_e32 v99, 0, v99
	v_pk_mul_f32 v[100:101], v[100:101], v[100:101]
	v_pk_mul_f32 v[102:103], v[102:103], v[102:103]
	v_pk_mul_f32 v[96:97], v[96:97], v[96:97]
	v_pk_mul_f32 v[98:99], v[98:99], v[98:99]
	v_cvt_pk_bf16_f32 v100, v100, v101
	v_cvt_pk_bf16_f32 v101, v102, v103
	v_cvt_pk_bf16_f32 v102, v96, v97
	v_cvt_pk_bf16_f32 v103, v98, v99
	flat_store_dwordx4 v[150:151], v[100:103] offset:256
	v_add_co_u32_e32 v150, vcc, 0x40000, v152
	s_nop 1
	v_addc_co_u32_e32 v151, vcc, 0, v153, vcc
	v_max_f32_e32 v92, 0, v92
	v_max_f32_e32 v93, 0, v93
	v_max_f32_e32 v94, 0, v94
	v_max_f32_e32 v95, 0, v95
	v_max_f32_e32 v88, 0, v88
	v_max_f32_e32 v89, 0, v89
	v_max_f32_e32 v90, 0, v90
	v_max_f32_e32 v91, 0, v91
	v_pk_mul_f32 v[92:93], v[92:93], v[92:93]
	v_pk_mul_f32 v[94:95], v[94:95], v[94:95]
	v_pk_mul_f32 v[88:89], v[88:89], v[88:89]
	v_pk_mul_f32 v[90:91], v[90:91], v[90:91]
	v_cvt_pk_bf16_f32 v92, v92, v93
	v_cvt_pk_bf16_f32 v93, v94, v95
	v_cvt_pk_bf16_f32 v94, v88, v89
	v_cvt_pk_bf16_f32 v95, v90, v91
	flat_store_dwordx4 v[150:151], v[92:95]
	v_max_f32_e32 v84, 0, v84
	v_max_f32_e32 v85, 0, v85
	v_max_f32_e32 v86, 0, v86
	v_max_f32_e32 v87, 0, v87
	v_max_f32_e32 v80, 0, v80
	v_max_f32_e32 v81, 0, v81
	v_max_f32_e32 v82, 0, v82
	v_max_f32_e32 v83, 0, v83
	v_pk_mul_f32 v[84:85], v[84:85], v[84:85]
	v_pk_mul_f32 v[86:87], v[86:87], v[86:87]
	v_pk_mul_f32 v[80:81], v[80:81], v[80:81]
	v_pk_mul_f32 v[82:83], v[82:83], v[82:83]
	v_cvt_pk_bf16_f32 v84, v84, v85
	v_cvt_pk_bf16_f32 v85, v86, v87
	v_cvt_pk_bf16_f32 v86, v80, v81
	v_cvt_pk_bf16_f32 v87, v82, v83
	flat_store_dwordx4 v[150:151], v[84:87] offset:256
	v_add_co_u32_e32 v150, vcc, 0x60000, v152
	s_nop 1
	v_addc_co_u32_e32 v151, vcc, 0, v153, vcc
	v_max_f32_e32 v76, 0, v76
	v_max_f32_e32 v77, 0, v77
	v_max_f32_e32 v78, 0, v78
	v_max_f32_e32 v79, 0, v79
	v_max_f32_e32 v72, 0, v72
	v_max_f32_e32 v73, 0, v73
	v_max_f32_e32 v74, 0, v74
	v_max_f32_e32 v75, 0, v75
	v_pk_mul_f32 v[76:77], v[76:77], v[76:77]
	v_pk_mul_f32 v[78:79], v[78:79], v[78:79]
	v_pk_mul_f32 v[72:73], v[72:73], v[72:73]
	v_pk_mul_f32 v[74:75], v[74:75], v[74:75]
	v_cvt_pk_bf16_f32 v76, v76, v77
	v_cvt_pk_bf16_f32 v77, v78, v79
	v_cvt_pk_bf16_f32 v78, v72, v73
	v_cvt_pk_bf16_f32 v79, v74, v75
	flat_store_dwordx4 v[150:151], v[76:79]
	v_max_f32_e32 v68, 0, v68
	v_max_f32_e32 v69, 0, v69
	v_max_f32_e32 v70, 0, v70
	v_max_f32_e32 v71, 0, v71
	v_max_f32_e32 v64, 0, v64
	v_max_f32_e32 v65, 0, v65
	v_max_f32_e32 v66, 0, v66
	v_max_f32_e32 v67, 0, v67
	v_pk_mul_f32 v[68:69], v[68:69], v[68:69]
; #define PG8_BAR __builtin_amdgcn_s_barrier()
; __device__ __forceinline__ u32x4 pack8(f32x4 a, f32x4 b) { u32x4 w; w.x = pk2(a[0], a[1]); w.y = pk2(a[2], a[3]); w.z = pk2(b[0], b[1]); w.w = pk2(b[2], b[3]); return w; }
; template <class Epi>
; __device__ __forceinline__ void gemm_phase(LAS unsigned char* lds, const Gemm g, const StaticOrder& S, const Epi& E, const int wid) {
;     ...
;         if (!has_next) break;
; #pragma unroll
;         for (int a = 0; a < 2; ++a)
; #pragma unroll
;             for (int b = 0; b < 2; ++b)
; #pragma unroll
;                 for (int m = 0; m < 4; ++m)
; #pragma unroll
;                     for (int n = 0; n < 2; ++n) acc[a][b][m][n] = (f32x4){0.f, 0.f, 0.f, 0.f};
;         cur = nxt; cA = nA; cB = nB; ++ui;
;         if (wr == 1) PG8_BAR;
;     }
;     __device__ __forceinline__ void operator()(const Acc& acc, const pg8::Unit& u, int wid) const {
;     ...
;         for (int ai = 0; ai < 2; ++ai)
; #pragma unroll
;             for (int m = 0; m < 4; ++m) {
;                 const int row = row0 + ai * 128 + m * 16;
;                 const float sc = ssq ? __builtin_amdgcn_rsqf(scv[ai * 4 + m] * inv_n + EPS) : 1.f;
; #pragma unroll
;                 for (int bj = 0; bj < 2; ++bj) {
;                     f32x4 v0 = acc[ai][bj][m][0] * sc, v1 = acc[ai][bj][m][1] * sc;
;                     if (ACT == 1) {
; #pragma unroll
;                         for (int e = 0; e < 4; ++e) { float a = fmaxf(v0[e], 0.f), b = fmaxf(v1[e], 0.f); v0[e] = a * a; v1[e] = b * b; }
;                     }
;                     *(u32x4*)(O + (size_t)row * ldc + col0 + bj * 128) = pack8(v0, v1);
	v_pk_mul_f32 v[70:71], v[70:71], v[70:71]
	v_pk_mul_f32 v[64:65], v[64:65], v[64:65]
	v_pk_mul_f32 v[66:67], v[66:67], v[66:67]
	v_cvt_pk_bf16_f32 v68, v68, v69
	v_cvt_pk_bf16_f32 v69, v70, v71
	v_cvt_pk_bf16_f32 v70, v64, v65
	v_cvt_pk_bf16_f32 v71, v66, v67
	flat_store_dwordx4 v[150:151], v[68:71] offset:256
	v_add_co_u32_e32 v150, vcc, 0x100000, v152
	s_nop 1
	v_addc_co_u32_e32 v151, vcc, 0, v153, vcc
	v_max_f32_e32 v60, 0, v60
	v_max_f32_e32 v61, 0, v61
	v_max_f32_e32 v62, 0, v62
	v_max_f32_e32 v63, 0, v63
	v_max_f32_e32 v56, 0, v56
	v_max_f32_e32 v57, 0, v57
	v_max_f32_e32 v58, 0, v58
	v_max_f32_e32 v59, 0, v59
	v_pk_mul_f32 v[60:61], v[60:61], v[60:61]
	v_pk_mul_f32 v[62:63], v[62:63], v[62:63]
	v_pk_mul_f32 v[56:57], v[56:57], v[56:57]
	v_pk_mul_f32 v[58:59], v[58:59], v[58:59]
	v_cvt_pk_bf16_f32 v60, v60, v61
	v_cvt_pk_bf16_f32 v61, v62, v63
	v_cvt_pk_bf16_f32 v62, v56, v57
	v_cvt_pk_bf16_f32 v63, v58, v59
	flat_store_dwordx4 v[150:151], v[60:63]
	v_max_f32_e32 v52, 0, v52
	v_max_f32_e32 v53, 0, v53
	v_max_f32_e32 v54, 0, v54
	v_max_f32_e32 v55, 0, v55
	v_max_f32_e32 v48, 0, v48
	v_max_f32_e32 v49, 0, v49
	v_max_f32_e32 v50, 0, v50
	v_max_f32_e32 v51, 0, v51
	v_pk_mul_f32 v[52:53], v[52:53], v[52:53]
	v_pk_mul_f32 v[54:55], v[54:55], v[54:55]
	v_pk_mul_f32 v[48:49], v[48:49], v[48:49]
	v_pk_mul_f32 v[50:51], v[50:51], v[50:51]
	v_cvt_pk_bf16_f32 v52, v52, v53
	v_cvt_pk_bf16_f32 v53, v54, v55
	v_cvt_pk_bf16_f32 v54, v48, v49
	v_cvt_pk_bf16_f32 v55, v50, v51
	flat_store_dwordx4 v[150:151], v[52:55] offset:256
	v_add_co_u32_e32 v150, vcc, 0x120000, v152
	s_nop 1
	v_addc_co_u32_e32 v151, vcc, 0, v153, vcc
	v_max_f32_e32 v44, 0, v44
	v_max_f32_e32 v45, 0, v45
	v_max_f32_e32 v46, 0, v46
	v_max_f32_e32 v47, 0, v47
	v_max_f32_e32 v40, 0, v40
	v_max_f32_e32 v41, 0, v41
	v_max_f32_e32 v42, 0, v42
	v_max_f32_e32 v43, 0, v43
	v_pk_mul_f32 v[44:45], v[44:45], v[44:45]
	v_pk_mul_f32 v[46:47], v[46:47], v[46:47]
	v_pk_mul_f32 v[40:41], v[40:41], v[40:41]
	v_pk_mul_f32 v[42:43], v[42:43], v[42:43]
	v_cvt_pk_bf16_f32 v44, v44, v45
	v_cvt_pk_bf16_f32 v45, v46, v47
	v_cvt_pk_bf16_f32 v46, v40, v41
	v_cvt_pk_bf16_f32 v47, v42, v43
	flat_store_dwordx4 v[150:151], v[44:47]
	v_max_f32_e32 v36, 0, v36
	v_max_f32_e32 v37, 0, v37
	v_max_f32_e32 v38, 0, v38
	v_max_f32_e32 v39, 0, v39
	v_max_f32_e32 v32, 0, v32
	v_max_f32_e32 v33, 0, v33
	v_max_f32_e32 v34, 0, v34
	v_max_f32_e32 v35, 0, v35
	v_pk_mul_f32 v[36:37], v[36:37], v[36:37]
	v_pk_mul_f32 v[38:39], v[38:39], v[38:39]
	v_pk_mul_f32 v[32:33], v[32:33], v[32:33]
	v_pk_mul_f32 v[34:35], v[34:35], v[34:35]
	v_cvt_pk_bf16_f32 v36, v36, v37
	v_cvt_pk_bf16_f32 v37, v38, v39
	v_cvt_pk_bf16_f32 v38, v32, v33
	v_cvt_pk_bf16_f32 v39, v34, v35
	flat_store_dwordx4 v[150:151], v[36:39] offset:256
	v_add_co_u32_e32 v150, vcc, 0x140000, v152
	s_nop 1
	v_addc_co_u32_e32 v151, vcc, 0, v153, vcc
	v_max_f32_e32 v28, 0, v28
	v_max_f32_e32 v29, 0, v29
	v_max_f32_e32 v30, 0, v30
	v_max_f32_e32 v31, 0, v31
	v_max_f32_e32 v24, 0, v24
	v_max_f32_e32 v25, 0, v25
	v_max_f32_e32 v26, 0, v26
	v_max_f32_e32 v27, 0, v27
	v_pk_mul_f32 v[28:29], v[28:29], v[28:29]
	v_pk_mul_f32 v[30:31], v[30:31], v[30:31]
	v_pk_mul_f32 v[24:25], v[24:25], v[24:25]
	v_pk_mul_f32 v[26:27], v[26:27], v[26:27]
	v_cvt_pk_bf16_f32 v28, v28, v29
	v_cvt_pk_bf16_f32 v29, v30, v31
	v_cvt_pk_bf16_f32 v30, v24, v25
	v_cvt_pk_bf16_f32 v31, v26, v27
	flat_store_dwordx4 v[150:151], v[28:31]
	v_max_f32_e32 v20, 0, v20
	v_max_f32_e32 v21, 0, v21
	v_max_f32_e32 v22, 0, v22
	v_max_f32_e32 v23, 0, v23
	v_max_f32_e32 v16, 0, v16
	v_max_f32_e32 v17, 0, v17
	v_max_f32_e32 v18, 0, v18
	v_max_f32_e32 v19, 0, v19
	v_pk_mul_f32 v[20:21], v[20:21], v[20:21]
	v_pk_mul_f32 v[22:23], v[22:23], v[22:23]
	v_pk_mul_f32 v[16:17], v[16:17], v[16:17]
	v_pk_mul_f32 v[18:19], v[18:19], v[18:19]
	v_cvt_pk_bf16_f32 v20, v20, v21
	v_cvt_pk_bf16_f32 v21, v22, v23
	v_cvt_pk_bf16_f32 v22, v16, v17
	v_cvt_pk_bf16_f32 v23, v18, v19
	flat_store_dwordx4 v[150:151], v[20:23] offset:256
	v_add_co_u32_e32 v150, vcc, 0x160000, v152
	s_nop 1
	v_addc_co_u32_e32 v151, vcc, 0, v153, vcc
	v_max_f32_e32 v12, 0, v12
	v_max_f32_e32 v13, 0, v13
	v_max_f32_e32 v14, 0, v14
	v_max_f32_e32 v15, 0, v15
	v_max_f32_e32 v8, 0, v8
	v_max_f32_e32 v9, 0, v9
	v_max_f32_e32 v10, 0, v10
	v_max_f32_e32 v11, 0, v11
	v_pk_mul_f32 v[12:13], v[12:13], v[12:13]
	v_pk_mul_f32 v[14:15], v[14:15], v[14:15]
	v_pk_mul_f32 v[8:9], v[8:9], v[8:9]
	v_pk_mul_f32 v[10:11], v[10:11], v[10:11]
	v_cvt_pk_bf16_f32 v12, v12, v13
	v_cvt_pk_bf16_f32 v13, v14, v15
	v_cvt_pk_bf16_f32 v14, v8, v9
	v_cvt_pk_bf16_f32 v15, v10, v11
	flat_store_dwordx4 v[150:151], v[12:15]
	v_max_f32_e32 v4, 0, v4
	v_max_f32_e32 v5, 0, v5
	v_max_f32_e32 v6, 0, v6
	v_max_f32_e32 v7, 0, v7
	v_max_f32_e32 v0, 0, v0
	v_max_f32_e32 v1, 0, v1
	v_max_f32_e32 v2, 0, v2
	v_max_f32_e32 v3, 0, v3
	v_pk_mul_f32 v[4:5], v[4:5], v[4:5]
	v_pk_mul_f32 v[6:7], v[6:7], v[6:7]
	v_pk_mul_f32 v[0:1], v[0:1], v[0:1]
	v_pk_mul_f32 v[2:3], v[2:3], v[2:3]
	v_cvt_pk_bf16_f32 v4, v4, v5
	v_cvt_pk_bf16_f32 v5, v6, v7
	v_cvt_pk_bf16_f32 v6, v0, v1
	v_cvt_pk_bf16_f32 v7, v2, v3
	s_andn2_b64 vcc, exec, s[6:7]
	s_mov_b64 s[6:7], -1
	flat_store_dwordx4 v[150:151], v[4:7] offset:256
	s_cbranch_vccnz .LBB0_477
	s_branch .LBB0_476

; #define PG8_STAGE(bufoff, gbase, voff) do { _Pragma("unroll") for (int _i = 0; _i < 2; ++_i) \
;         __builtin_amdgcn_global_load_lds((const unsigned*)((const char*)(gbase) + (voff)[_i]), (LAS unsigned*)(lds + (bufoff) + ldsw + _i * 8192), 16, 0, 0); } while (0)
; #define PG8_LDA(dst, b, h) do { _Pragma("unroll") for (int m = 0; m < 4; ++m) _Pragma("unroll") for (int k = 0; k < 2; ++k) dst[m][k] = *(const LAS bf16x8*)(lds + PG8_SA(b, h) + aoff + m * 2048 + k * 1024); } while (0)
; #define PG8_LDB(dst, b, h) do { _Pragma("unroll") for (int n = 0; n < 2; ++n) _Pragma("unroll") for (int k = 0; k < 2; ++k) dst[n][k] = *(const LAS bf16x8*)(lds + PG8_SB(b, h) + boff + n * 2048 + k * 1024); } while (0)
; #define PG8_MMA(ai, bj, At, Bt) do { __builtin_amdgcn_s_setprio(1); _Pragma("unroll") for (int m = 0; m < 4; ++m) _Pragma("unroll") for (int n = 0; n < 2; ++n) _Pragma("unroll") for (int k = 0; k < 2; ++k) \
;         acc[ai][bj][m][n] = __builtin_amdgcn_mfma_f32_16x16x32_bf16(Bt[n][k], At[m][k], acc[ai][bj][m][n], 0, 0, 0); __builtin_amdgcn_s_setprio(0); } while (0)
; #define PG8_WAIT_V(n) asm volatile("s_waitcnt vmcnt(" #n ")" ::: "memory")
; #define PG8_WAIT_L(n) asm volatile("s_waitcnt lgkmcnt(" #n ")" ::: "memory")
; #define PG8_BAR __builtin_amdgcn_s_barrier()
; #define PG8_SCHED __builtin_amdgcn_sched_barrier(0)
; template <class Epi>
; __device__ __forceinline__ void gemm_phase(LAS unsigned char* lds, const Gemm g, const StaticOrder& S, const Epi& E, const int wid) {
;     ...
;             PG8_LDB(B0, 0, 0); PG8_LDB(B1, 0, 1); PG8_SCHED; PG8_LDA(At, 0, 0); PG8_STAGE(PG8_SA(1, 1), a1 + hsA, voffA);
;             PG8_WAIT_V(8); PG8_WAIT_L(0); PG8_BAR; PG8_MMA(0, 0, At, B0); PG8_MMA(0, 1, At, B1); PG8_BAR; PG8_SCHED;
;             PG8_LDA(At, 0, 1); PG8_STAGE(PG8_SB(0, 0), b2, voffB); PG8_STAGE(PG8_SB(0, 1), b2 + hsB, voffB); PG8_STAGE(PG8_SA(0, 0), a2, voffA);
;             PG8_WAIT_V(8); PG8_WAIT_L(0); PG8_BAR; PG8_MMA(1, 0, At, B0); PG8_MMA(1, 1, At, B1); PG8_BAR; PG8_SCHED;
;             PG8_LDB(B0, 1, 0); PG8_LDB(B1, 1, 1); PG8_SCHED; PG8_LDA(At, 1, 0); PG8_STAGE(PG8_SA(0, 1), a2 + hsA, voffA);
;             PG8_WAIT_V(8); PG8_WAIT_L(0); PG8_BAR; PG8_MMA(0, 0, At, B0); PG8_MMA(0, 1, At, B1); PG8_BAR; PG8_SCHED;
;             PG8_LDA(At, 1, 1); PG8_STAGE(PG8_SB(1, 0), b3, voffB); PG8_STAGE(PG8_SB(1, 1), b3 + hsB, voffB); PG8_STAGE(PG8_SA(1, 0), a3, voffA);
.LBB0_555:
	ds_read_b128 v[124:127], v241
	ds_read_b128 v[132:135], v241 offset:1024
	ds_read_b128 v[136:139], v241 offset:2048
	ds_read_b128 v[140:143], v241 offset:3072
	ds_read_b128 v[144:147], v242
	ds_read_b128 v[148:151], v242 offset:1024
	ds_read_b128 v[152:155], v242 offset:2048
	ds_read_b128 v[156:159], v242 offset:3072
	s_add_u32 s4, s28, 0xfff00080
	s_addc_u32 s5, s29, -1
	s_cmp_eq_u32 s81, 60
	s_cselect_b32 s35, s1, s5
	s_cselect_b32 s34, s21, s4
	s_cselect_b32 s31, s19, s80
	s_cselect_b32 s30, s78, s79
	v_lshl_add_u64 v[204:205], s[28:29], 0, v[202:203]
	s_add_i32 m0, s27, 0xc000
	ds_read_b128 v[160:163], v243
	ds_read_b128 v[164:167], v243 offset:1024
	ds_read_b128 v[168:171], v243 offset:2048
	ds_read_b128 v[172:175], v243 offset:3072
	ds_read_b128 v[176:179], v243 offset:4096
	ds_read_b128 v[180:183], v243 offset:5120
	ds_read_b128 v[184:187], v243 offset:6144
	ds_read_b128 v[188:191], v243 offset:7168
	global_load_lds_dwordx4 v[204:205], off
	v_lshl_add_u64 v[204:205], s[28:29], 0, v[200:201]
	s_add_i32 m0, s27, 0xe000
	s_nop 0
	global_load_lds_dwordx4 v[204:205], off
	s_waitcnt vmcnt(8)
	s_waitcnt lgkmcnt(0)
	s_barrier
	s_setprio 1
	s_waitcnt lgkmcnt(0)
	v_mfma_f32_16x16x32_bf16 v[128:131], v[124:127], v[160:163], v[128:131]
	v_mfma_f32_16x16x32_bf16 v[120:123], v[136:139], v[160:163], v[120:123]
	v_mfma_f32_16x16x32_bf16 v[108:111], v[124:127], v[168:171], v[108:111]
	v_mfma_f32_16x16x32_bf16 v[104:107], v[136:139], v[168:171], v[104:107]
	v_mfma_f32_16x16x32_bf16 v[92:95], v[124:127], v[176:179], v[92:95]
	v_mfma_f32_16x16x32_bf16 v[88:91], v[136:139], v[176:179], v[88:91]
	v_mfma_f32_16x16x32_bf16 v[76:79], v[124:127], v[184:187], v[76:79]
	v_mfma_f32_16x16x32_bf16 v[72:75], v[136:139], v[184:187], v[72:75]
	v_mfma_f32_16x16x32_bf16 v[128:131], v[132:135], v[164:167], v[128:131]
	v_mfma_f32_16x16x32_bf16 v[120:123], v[140:143], v[164:167], v[120:123]
	v_mfma_f32_16x16x32_bf16 v[108:111], v[132:135], v[172:175], v[108:111]
	v_mfma_f32_16x16x32_bf16 v[104:107], v[140:143], v[172:175], v[104:107]
	v_mfma_f32_16x16x32_bf16 v[92:95], v[132:135], v[180:183], v[92:95]
	v_mfma_f32_16x16x32_bf16 v[88:91], v[140:143], v[180:183], v[88:91]
	v_mfma_f32_16x16x32_bf16 v[76:79], v[132:135], v[188:191], v[76:79]
	v_mfma_f32_16x16x32_bf16 v[72:75], v[140:143], v[188:191], v[72:75]
	s_setprio 0
	s_setprio 1
	v_mfma_f32_16x16x32_bf16 v[116:119], v[144:147], v[160:163], v[116:119]
	v_mfma_f32_16x16x32_bf16 v[112:115], v[152:155], v[160:163], v[112:115]
	v_mfma_f32_16x16x32_bf16 v[100:103], v[144:147], v[168:171], v[100:103]
	v_mfma_f32_16x16x32_bf16 v[96:99], v[152:155], v[168:171], v[96:99]
	v_mfma_f32_16x16x32_bf16 v[84:87], v[144:147], v[176:179], v[84:87]
	v_mfma_f32_16x16x32_bf16 v[80:83], v[152:155], v[176:179], v[80:83]
	v_mfma_f32_16x16x32_bf16 v[68:71], v[144:147], v[184:187], v[68:71]
	v_mfma_f32_16x16x32_bf16 v[64:67], v[152:155], v[184:187], v[64:67]
	v_mfma_f32_16x16x32_bf16 v[116:119], v[148:151], v[164:167], v[116:119]
	v_mfma_f32_16x16x32_bf16 v[112:115], v[156:159], v[164:167], v[112:115]
	v_mfma_f32_16x16x32_bf16 v[100:103], v[148:151], v[172:175], v[100:103]
	v_mfma_f32_16x16x32_bf16 v[96:99], v[156:159], v[172:175], v[96:99]
	v_mfma_f32_16x16x32_bf16 v[84:87], v[148:151], v[180:183], v[84:87]
	v_mfma_f32_16x16x32_bf16 v[80:83], v[156:159], v[180:183], v[80:83]
	v_mfma_f32_16x16x32_bf16 v[68:71], v[148:151], v[188:191], v[68:71]
	v_mfma_f32_16x16x32_bf16 v[64:67], v[156:159], v[188:191], v[64:67]
	s_setprio 0
	s_barrier
	s_add_i32 s4, s76, s68
	v_lshl_add_u64 v[204:205], s[30:31], 0, v[194:195]
	s_mov_b32 m0, s4
	ds_read_b128 v[160:163], v243 offset:16384
	ds_read_b128 v[164:167], v243 offset:17408
	ds_read_b128 v[168:171], v243 offset:18432
	ds_read_b128 v[172:175], v243 offset:19456
	ds_read_b128 v[176:179], v243 offset:20480
	ds_read_b128 v[180:183], v243 offset:21504
	ds_read_b128 v[184:187], v243 offset:22528
	ds_read_b128 v[188:191], v243 offset:23552
	global_load_lds_dwordx4 v[204:205], off
	s_add_i32 m0, s4, 0x2000
	s_add_u32 s4, s30, 0x100000
	v_lshl_add_u64 v[206:207], s[30:31], 0, v[198:199]
	s_addc_u32 s5, s31, 0
	s_add_i32 s47, s77, s68
	global_load_lds_dwordx4 v[206:207], off
	v_lshl_add_u64 v[208:209], s[4:5], 0, v[194:195]
	s_mov_b32 m0, s47
	v_lshl_add_u64 v[210:211], s[34:35], 0, v[196:197]
	global_load_lds_dwordx4 v[208:209], off
	v_lshl_add_u64 v[208:209], s[4:5], 0, v[198:199]
	s_add_i32 m0, s47, 0x2000
	s_nop 0
	global_load_lds_dwordx4 v[208:209], off
	v_lshl_add_u64 v[208:209], s[34:35], 0, v[192:193]
	s_mov_b32 m0, s27
	s_nop 0
	global_load_lds_dwordx4 v[208:209], off
	s_mov_b32 m0, s38
	s_nop 0
	global_load_lds_dwordx4 v[210:211], off
	s_waitcnt vmcnt(8)
	s_waitcnt lgkmcnt(0)
	s_barrier
; #define PG8_STAGE(bufoff, gbase, voff) do { _Pragma("unroll") for (int _i = 0; _i < 2; ++_i) \
;         __builtin_amdgcn_global_load_lds((const unsigned*)((const char*)(gbase) + (voff)[_i]), (LAS unsigned*)(lds + (bufoff) + ldsw + _i * 8192), 16, 0, 0); } while (0)
; #define PG8_LDA(dst, b, h) do { _Pragma("unroll") for (int m = 0; m < 4; ++m) _Pragma("unroll") for (int k = 0; k < 2; ++k) dst[m][k] = *(const LAS bf16x8*)(lds + PG8_SA(b, h) + aoff + m * 2048 + k * 1024); } while (0)
; #define PG8_LDB(dst, b, h) do { _Pragma("unroll") for (int n = 0; n < 2; ++n) _Pragma("unroll") for (int k = 0; k < 2; ++k) dst[n][k] = *(const LAS bf16x8*)(lds + PG8_SB(b, h) + boff + n * 2048 + k * 1024); } while (0)
; #define PG8_MMA(ai, bj, At, Bt) do { __builtin_amdgcn_s_setprio(1); _Pragma("unroll") for (int m = 0; m < 4; ++m) _Pragma("unroll") for (int n = 0; n < 2; ++n) _Pragma("unroll") for (int k = 0; k < 2; ++k) \
;         acc[ai][bj][m][n] = __builtin_amdgcn_mfma_f32_16x16x32_bf16(Bt[n][k], At[m][k], acc[ai][bj][m][n], 0, 0, 0); __builtin_amdgcn_s_setprio(0); } while (0)
; #define PG8_WAIT_V(n) asm volatile("s_waitcnt vmcnt(" #n ")" ::: "memory")
; #define PG8_BAR __builtin_amdgcn_s_barrier()
; template <class Epi>
; __device__ __forceinline__ void gemm_phase(LAS unsigned char* lds, const Gemm g, const StaticOrder& S, const Epi& E, const int wid) {
;     ...
;             PG8_LDB(B0, 0, 0); PG8_LDB(B1, 0, 1); PG8_SCHED; PG8_LDA(At, 0, 0); PG8_STAGE(PG8_SA(1, 1), a1 + hsA, voffA);
;             PG8_WAIT_V(8); PG8_WAIT_L(0); PG8_BAR; PG8_MMA(0, 0, At, B0); PG8_MMA(0, 1, At, B1); PG8_BAR; PG8_SCHED;
;             PG8_LDA(At, 0, 1); PG8_STAGE(PG8_SB(0, 0), b2, voffB); PG8_STAGE(PG8_SB(0, 1), b2 + hsB, voffB); PG8_STAGE(PG8_SA(0, 0), a2, voffA);
;             PG8_WAIT_V(8); PG8_WAIT_L(0); PG8_BAR; PG8_MMA(1, 0, At, B0); PG8_MMA(1, 1, At, B1); PG8_BAR; PG8_SCHED;
;             PG8_LDB(B0, 1, 0); PG8_LDB(B1, 1, 1); PG8_SCHED; PG8_LDA(At, 1, 0); PG8_STAGE(PG8_SA(0, 1), a2 + hsA, voffA);
;             PG8_WAIT_V(8); PG8_WAIT_L(0); PG8_BAR; PG8_MMA(0, 0, At, B0); PG8_MMA(0, 1, At, B1); PG8_BAR; PG8_SCHED;
;             PG8_LDA(At, 1, 1); PG8_STAGE(PG8_SB(1, 0), b3, voffB); PG8_STAGE(PG8_SB(1, 1), b3 + hsB, voffB); PG8_STAGE(PG8_SA(1, 0), a3, voffA);
;             PG8_WAIT_V(8); PG8_WAIT_L(0); PG8_BAR; PG8_MMA(1, 0, At, B0); PG8_MMA(1, 1, At, B1); PG8_BAR; PG8_SCHED;
	s_setprio 1
	s_waitcnt lgkmcnt(0)
	v_mfma_f32_16x16x32_bf16 v[60:63], v[124:127], v[160:163], v[60:63]
	v_mfma_f32_16x16x32_bf16 v[56:59], v[136:139], v[160:163], v[56:59]
	v_mfma_f32_16x16x32_bf16 v[44:47], v[124:127], v[168:171], v[44:47]
	v_mfma_f32_16x16x32_bf16 v[40:43], v[136:139], v[168:171], v[40:43]
	v_mfma_f32_16x16x32_bf16 v[28:31], v[124:127], v[176:179], v[28:31]
	v_mfma_f32_16x16x32_bf16 v[24:27], v[136:139], v[176:179], v[24:27]
	v_mfma_f32_16x16x32_bf16 v[12:15], v[124:127], v[184:187], v[12:15]
	v_mfma_f32_16x16x32_bf16 v[8:11], v[136:139], v[184:187], v[8:11]
	v_mfma_f32_16x16x32_bf16 v[60:63], v[132:135], v[164:167], v[60:63]
	v_mfma_f32_16x16x32_bf16 v[56:59], v[140:143], v[164:167], v[56:59]
	v_mfma_f32_16x16x32_bf16 v[44:47], v[132:135], v[172:175], v[44:47]
	v_mfma_f32_16x16x32_bf16 v[40:43], v[140:143], v[172:175], v[40:43]
	v_mfma_f32_16x16x32_bf16 v[28:31], v[132:135], v[180:183], v[28:31]
	v_mfma_f32_16x16x32_bf16 v[24:27], v[140:143], v[180:183], v[24:27]
	v_mfma_f32_16x16x32_bf16 v[12:15], v[132:135], v[188:191], v[12:15]
	v_mfma_f32_16x16x32_bf16 v[8:11], v[140:143], v[188:191], v[8:11]
	s_setprio 0
	s_setprio 1
	v_mfma_f32_16x16x32_bf16 v[52:55], v[144:147], v[160:163], v[52:55]
	v_mfma_f32_16x16x32_bf16 v[48:51], v[152:155], v[160:163], v[48:51]
	v_mfma_f32_16x16x32_bf16 v[36:39], v[144:147], v[168:171], v[36:39]
	v_mfma_f32_16x16x32_bf16 v[32:35], v[152:155], v[168:171], v[32:35]
	v_mfma_f32_16x16x32_bf16 v[20:23], v[144:147], v[176:179], v[20:23]
	v_mfma_f32_16x16x32_bf16 v[16:19], v[152:155], v[176:179], v[16:19]
	v_mfma_f32_16x16x32_bf16 v[4:7], v[144:147], v[184:187], v[4:7]
	v_mfma_f32_16x16x32_bf16 v[0:3], v[152:155], v[184:187], v[0:3]
	v_mfma_f32_16x16x32_bf16 v[52:55], v[148:151], v[164:167], v[52:55]
	v_mfma_f32_16x16x32_bf16 v[48:51], v[156:159], v[164:167], v[48:51]
	v_mfma_f32_16x16x32_bf16 v[36:39], v[148:151], v[172:175], v[36:39]
	v_mfma_f32_16x16x32_bf16 v[32:35], v[156:159], v[172:175], v[32:35]
	v_mfma_f32_16x16x32_bf16 v[20:23], v[148:151], v[180:183], v[20:23]
	v_mfma_f32_16x16x32_bf16 v[16:19], v[156:159], v[180:183], v[16:19]
	v_mfma_f32_16x16x32_bf16 v[4:7], v[148:151], v[188:191], v[4:7]
	v_mfma_f32_16x16x32_bf16 v[0:3], v[156:159], v[188:191], v[0:3]
	s_setprio 0
	s_barrier
	s_add_i32 s47, 0, 0x18000
	s_add_i32 s50, 0, 0x1c000
	v_add_u32_e32 v140, s47, v240
	v_add_u32_e32 v156, s50, v240
	ds_read_b128 v[124:127], v140
	ds_read_b128 v[132:135], v140 offset:1024
	ds_read_b128 v[136:139], v140 offset:2048
	ds_read_b128 v[140:143], v140 offset:3072
	ds_read_b128 v[144:147], v156
	ds_read_b128 v[148:151], v156 offset:1024
	ds_read_b128 v[152:155], v156 offset:2048
	ds_read_b128 v[156:159], v156 offset:3072
	s_add_u32 s4, s34, 0x100000
	s_addc_u32 s5, s35, 0
	s_mov_b32 m0, s39
	v_lshl_add_u64 v[212:213], s[4:5], 0, v[192:193]
	ds_read_b128 v[160:163], v243 offset:32768
	ds_read_b128 v[164:167], v243 offset:33792
	ds_read_b128 v[168:171], v243 offset:34816
	ds_read_b128 v[172:175], v243 offset:35840
	ds_read_b128 v[176:179], v243 offset:36864
	ds_read_b128 v[180:183], v243 offset:37888
	ds_read_b128 v[184:187], v243 offset:38912
	ds_read_b128 v[188:191], v243 offset:39936
	global_load_lds_dwordx4 v[212:213], off
	v_lshl_add_u64 v[212:213], s[4:5], 0, v[196:197]
	s_mov_b32 m0, s62
	s_nop 0
	global_load_lds_dwordx4 v[212:213], off
	s_waitcnt vmcnt(8)
	s_waitcnt lgkmcnt(0)
	s_barrier
	s_setprio 1
	s_waitcnt lgkmcnt(0)
	v_mfma_f32_16x16x32_bf16 v[128:131], v[124:127], v[160:163], v[128:131]
	v_mfma_f32_16x16x32_bf16 v[120:123], v[136:139], v[160:163], v[120:123]
	v_mfma_f32_16x16x32_bf16 v[108:111], v[124:127], v[168:171], v[108:111]
	v_mfma_f32_16x16x32_bf16 v[104:107], v[136:139], v[168:171], v[104:107]
	v_mfma_f32_16x16x32_bf16 v[92:95], v[124:127], v[176:179], v[92:95]
	v_mfma_f32_16x16x32_bf16 v[88:91], v[136:139], v[176:179], v[88:91]
	v_mfma_f32_16x16x32_bf16 v[76:79], v[124:127], v[184:187], v[76:79]
	v_mfma_f32_16x16x32_bf16 v[72:75], v[136:139], v[184:187], v[72:75]
	v_mfma_f32_16x16x32_bf16 v[128:131], v[132:135], v[164:167], v[128:131]
	v_mfma_f32_16x16x32_bf16 v[120:123], v[140:143], v[164:167], v[120:123]
	v_mfma_f32_16x16x32_bf16 v[108:111], v[132:135], v[172:175], v[108:111]
	v_mfma_f32_16x16x32_bf16 v[104:107], v[140:143], v[172:175], v[104:107]
	v_mfma_f32_16x16x32_bf16 v[92:95], v[132:135], v[180:183], v[92:95]
	v_mfma_f32_16x16x32_bf16 v[88:91], v[140:143], v[180:183], v[88:91]
	v_mfma_f32_16x16x32_bf16 v[76:79], v[132:135], v[188:191], v[76:79]
	v_mfma_f32_16x16x32_bf16 v[72:75], v[140:143], v[188:191], v[72:75]
	s_setprio 0
	s_setprio 1
	v_mfma_f32_16x16x32_bf16 v[116:119], v[144:147], v[160:163], v[116:119]
	v_mfma_f32_16x16x32_bf16 v[112:115], v[152:155], v[160:163], v[112:115]
	v_mfma_f32_16x16x32_bf16 v[100:103], v[144:147], v[168:171], v[100:103]
	v_mfma_f32_16x16x32_bf16 v[96:99], v[152:155], v[168:171], v[96:99]
	v_mfma_f32_16x16x32_bf16 v[84:87], v[144:147], v[176:179], v[84:87]
	v_mfma_f32_16x16x32_bf16 v[80:83], v[152:155], v[176:179], v[80:83]
	v_mfma_f32_16x16x32_bf16 v[68:71], v[144:147], v[184:187], v[68:71]
	v_mfma_f32_16x16x32_bf16 v[64:67], v[152:155], v[184:187], v[64:67]
	v_mfma_f32_16x16x32_bf16 v[116:119], v[148:151], v[164:167], v[116:119]
	v_mfma_f32_16x16x32_bf16 v[112:115], v[156:159], v[164:167], v[112:115]
	v_mfma_f32_16x16x32_bf16 v[100:103], v[148:151], v[172:175], v[100:103]
	v_mfma_f32_16x16x32_bf16 v[96:99], v[156:159], v[172:175], v[96:99]
	v_mfma_f32_16x16x32_bf16 v[84:87], v[148:151], v[180:183], v[84:87]
	v_mfma_f32_16x16x32_bf16 v[80:83], v[156:159], v[180:183], v[80:83]
	v_mfma_f32_16x16x32_bf16 v[68:71], v[148:151], v[188:191], v[68:71]
	v_mfma_f32_16x16x32_bf16 v[64:67], v[156:159], v[188:191], v[64:67]
	s_setprio 0
	s_barrier
; #define PG8_STAGE(bufoff, gbase, voff) do { _Pragma("unroll") for (int _i = 0; _i < 2; ++_i) \
;         __builtin_amdgcn_global_load_lds((const unsigned*)((const char*)(gbase) + (voff)[_i]), (LAS unsigned*)(lds + (bufoff) + ldsw + _i * 8192), 16, 0, 0); } while (0)
; #define PG8_LDA(dst, b, h) do { _Pragma("unroll") for (int m = 0; m < 4; ++m) _Pragma("unroll") for (int k = 0; k < 2; ++k) dst[m][k] = *(const LAS bf16x8*)(lds + PG8_SA(b, h) + aoff + m * 2048 + k * 1024); } while (0)
; #define PG8_MMA(ai, bj, At, Bt) do { __builtin_amdgcn_s_setprio(1); _Pragma("unroll") for (int m = 0; m < 4; ++m) _Pragma("unroll") for (int n = 0; n < 2; ++n) _Pragma("unroll") for (int k = 0; k < 2; ++k) \
;         acc[ai][bj][m][n] = __builtin_amdgcn_mfma_f32_16x16x32_bf16(Bt[n][k], At[m][k], acc[ai][bj][m][n], 0, 0, 0); __builtin_amdgcn_s_setprio(0); } while (0)
; #define PG8_WAIT_V(n) asm volatile("s_waitcnt vmcnt(" #n ")" ::: "memory")
; #define PG8_WAIT_L(n) asm volatile("s_waitcnt lgkmcnt(" #n ")" ::: "memory")
; #define PG8_BAR __builtin_amdgcn_s_barrier()
; #define PG8_SCHED __builtin_amdgcn_sched_barrier(0)
; template <class Epi>
; __device__ __forceinline__ void gemm_phase(LAS unsigned char* lds, const Gemm g, const StaticOrder& S, const Epi& E, const int wid) {
;     ...
;         for (int t = 0; t < nt; t += 2) {
;     ...
;             PG8_LDA(At, 1, 1); PG8_STAGE(PG8_SB(1, 0), b3, voffB); PG8_STAGE(PG8_SB(1, 1), b3 + hsB, voffB); PG8_STAGE(PG8_SA(1, 0), a3, voffA);
;             PG8_WAIT_V(8); PG8_WAIT_L(0); PG8_BAR; PG8_MMA(1, 0, At, B0); PG8_MMA(1, 1, At, B1); PG8_BAR; PG8_SCHED;
;         }
	s_add_i32 s4, s47, s68
	v_lshl_add_u64 v[204:205], v[204:205], 0, s[10:11]
	s_mov_b32 m0, s4
	ds_read_b128 v[160:163], v243 offset:49152
	ds_read_b128 v[164:167], v243 offset:50176
	ds_read_b128 v[168:171], v243 offset:51200
	ds_read_b128 v[172:175], v243 offset:52224
	ds_read_b128 v[176:179], v243 offset:53248
	ds_read_b128 v[180:183], v243 offset:54272
	ds_read_b128 v[184:187], v243 offset:55296
	ds_read_b128 v[188:191], v243 offset:56320
	global_load_lds_dwordx4 v[204:205], off
	s_add_i32 m0, s4, 0x2000
	s_add_u32 s4, s30, 0x100080
	v_lshl_add_u64 v[204:205], v[206:207], 0, s[10:11]
	s_addc_u32 s5, s31, 0
	s_add_i32 s30, s50, s68
	global_load_lds_dwordx4 v[204:205], off
	v_lshl_add_u64 v[204:205], s[4:5], 0, v[194:195]
	s_mov_b32 m0, s30
	s_nop 0
	global_load_lds_dwordx4 v[204:205], off
	v_lshl_add_u64 v[204:205], s[4:5], 0, v[198:199]
	s_add_i32 m0, s30, 0x2000
	s_nop 0
	global_load_lds_dwordx4 v[204:205], off
	v_lshl_add_u64 v[204:205], v[208:209], 0, s[10:11]
	s_mov_b32 m0, s64
	s_nop 0
	global_load_lds_dwordx4 v[204:205], off
	v_lshl_add_u64 v[204:205], v[210:211], 0, s[10:11]
	s_mov_b32 m0, s65
	s_nop 0
	global_load_lds_dwordx4 v[204:205], off
	s_waitcnt vmcnt(8)
	s_waitcnt lgkmcnt(0)
	s_barrier
	s_setprio 1
	s_waitcnt lgkmcnt(0)
	v_mfma_f32_16x16x32_bf16 v[60:63], v[124:127], v[160:163], v[60:63]
	v_mfma_f32_16x16x32_bf16 v[56:59], v[136:139], v[160:163], v[56:59]
	v_mfma_f32_16x16x32_bf16 v[44:47], v[124:127], v[168:171], v[44:47]
	v_mfma_f32_16x16x32_bf16 v[40:43], v[136:139], v[168:171], v[40:43]
	v_mfma_f32_16x16x32_bf16 v[28:31], v[124:127], v[176:179], v[28:31]
	v_mfma_f32_16x16x32_bf16 v[24:27], v[136:139], v[176:179], v[24:27]
	v_mfma_f32_16x16x32_bf16 v[12:15], v[124:127], v[184:187], v[12:15]
	v_mfma_f32_16x16x32_bf16 v[8:11], v[136:139], v[184:187], v[8:11]
	v_mfma_f32_16x16x32_bf16 v[60:63], v[132:135], v[164:167], v[60:63]
	v_mfma_f32_16x16x32_bf16 v[56:59], v[140:143], v[164:167], v[56:59]
	v_mfma_f32_16x16x32_bf16 v[44:47], v[132:135], v[172:175], v[44:47]
	v_mfma_f32_16x16x32_bf16 v[40:43], v[140:143], v[172:175], v[40:43]
	v_mfma_f32_16x16x32_bf16 v[28:31], v[132:135], v[180:183], v[28:31]
	v_mfma_f32_16x16x32_bf16 v[24:27], v[140:143], v[180:183], v[24:27]
	v_mfma_f32_16x16x32_bf16 v[12:15], v[132:135], v[188:191], v[12:15]
	v_mfma_f32_16x16x32_bf16 v[8:11], v[140:143], v[188:191], v[8:11]
	s_setprio 0
	s_setprio 1
	v_mfma_f32_16x16x32_bf16 v[52:55], v[144:147], v[160:163], v[52:55]
	v_mfma_f32_16x16x32_bf16 v[48:51], v[152:155], v[160:163], v[48:51]
	v_mfma_f32_16x16x32_bf16 v[36:39], v[144:147], v[168:171], v[36:39]
	v_mfma_f32_16x16x32_bf16 v[32:35], v[152:155], v[168:171], v[32:35]
	v_mfma_f32_16x16x32_bf16 v[20:23], v[144:147], v[176:179], v[20:23]
	v_mfma_f32_16x16x32_bf16 v[16:19], v[152:155], v[176:179], v[16:19]
	v_mfma_f32_16x16x32_bf16 v[4:7], v[144:147], v[184:187], v[4:7]
	v_mfma_f32_16x16x32_bf16 v[0:3], v[152:155], v[184:187], v[0:3]
	v_mfma_f32_16x16x32_bf16 v[52:55], v[148:151], v[164:167], v[52:55]
	v_mfma_f32_16x16x32_bf16 v[48:51], v[156:159], v[164:167], v[48:51]
	v_mfma_f32_16x16x32_bf16 v[36:39], v[148:151], v[172:175], v[36:39]
	v_mfma_f32_16x16x32_bf16 v[32:35], v[156:159], v[172:175], v[32:35]
	v_mfma_f32_16x16x32_bf16 v[20:23], v[148:151], v[180:183], v[20:23]
	v_mfma_f32_16x16x32_bf16 v[16:19], v[156:159], v[180:183], v[16:19]
	v_mfma_f32_16x16x32_bf16 v[4:7], v[148:151], v[188:191], v[4:7]
	v_mfma_f32_16x16x32_bf16 v[0:3], v[156:159], v[188:191], v[0:3]
	s_setprio 0
	s_barrier
	s_add_i32 s81, s81, 2
	s_add_u32 s79, s79, 0x100
	s_addc_u32 s80, s80, 0
	s_add_u32 s28, s28, 0x100
	s_addc_u32 s29, s29, 0
	s_cmp_gt_u32 s81, 61
	s_cbranch_scc0 .LBB0_555
; #define PG8_BAR __builtin_amdgcn_s_barrier()
; __device__ __forceinline__ u32x4 pack8(f32x4 a, f32x4 b) { u32x4 w; w.x = pk2(a[0], a[1]); w.y = pk2(a[2], a[3]); w.z = pk2(b[0], b[1]); w.w = pk2(b[2], b[3]); return w; }
; template <class Epi>
; __device__ __forceinline__ void gemm_phase(LAS unsigned char* lds, const Gemm g, const StaticOrder& S, const Epi& E, const int wid) {
;     ...
;         if (wr == 0) PG8_BAR;
;         E(acc, cur, wid);
;     __device__ __forceinline__ void operator()(const Acc& acc, const pg8::Unit& u, int wid) const {
;     ...
;         float r2[8];
; #pragma unroll
;         for (int i = 0; i < 8; ++i) r2[i] = ssq2 ? ssq2[row0 + (i >> 2) * 128 + (i & 3) * 16] : 0.f;
;         u32x4 bv[2][4][2];
; #pragma unroll
;         for (int ai = 0; ai < 2; ++ai)
; #pragma unroll
;             for (int m = 0; m < 4; ++m)
; #pragma unroll
;                 for (int bj = 0; bj < 2; ++bj) bv[ai][m][bj] = *(const u32x4*)(base + (size_t)(row0 + ai * 128 + m * 16) * 1024 + col0 + bj * 128);
; #pragma unroll
;         for (int ai = 0; ai < 2; ++ai) {
; #pragma unroll
;             for (int m = 0; m < 4; ++m) {
;                 const int row = row0 + ai * 128 + m * 16; float sq = 0.f;
;                 const float rr = ssq2 ? __builtin_amdgcn_rcpf(r2[ai * 4 + m] * (1.f / 1024.f) + EPS) : 1.f;
; #pragma unroll
;                 for (int bj = 0; bj < 2; ++bj) {
;                     const u32x4 b4 = bv[ai][m][bj];
;                     const f32x4 o0 = (f32x4){bflo(b4.x), bfhi(b4.x), bflo(b4.y), bfhi(b4.y)} + acc[ai][bj][m][0] * rr;
;                     const f32x4 o1 = (f32x4){bflo(b4.z), bfhi(b4.z), bflo(b4.w), bfhi(b4.w)} + acc[ai][bj][m][1] * rr;
;                     *(u32x4*)(hb + (size_t)row * 1024 + col0 + bj * 128) = pack8(o0, o1);
;                     sq += (o0[0] * o0[0] + o0[1] * o0[1]) + (o0[2] * o0[2] + o0[3] * o0[3]) + (o1[0] * o1[0] + o1[1] * o1[1]) + (o1[2] * o1[2] + o1[3] * o1[3]);
;                 }
;                 if (ssq_out) { sq += __shfl_xor(sq, 16); sq += __shfl_xor(sq, 32); if (fq == 0) atomicAdd(ssq_out + row, sq); }
.LBB0_558:
	s_lshl_b32 s1, s26, 8
	s_add_i32 s1, s1, s66
	v_mbcnt_lo_u32_b32 v208, -1, 0
	v_mbcnt_hi_u32_b32 v208, -1, v208
	s_lshl_b32 s0, s0, 8
	v_and_or_b32 v234, v208, 15, s1
	v_ashrrev_i32_e32 v124, 1, v208
	v_ashrrev_i32_e32 v235, 31, v234
	v_and_b32_e32 v126, -8, v124
	v_lshl_add_u64 v[124:125], v[234:235], 2, s[48:49]
	flat_load_dword v127, v[124:125]
	s_or_b32 s0, s0, s69
	v_add_u32_e32 v204, s0, v126
	v_ashrrev_i32_e32 v205, 31, v204
	v_lshlrev_b64 v[236:237], 1, v[204:205]
	v_lshl_add_u64 v[136:137], s[42:43], 0, v[236:237]
	v_lshlrev_b64 v[238:239], 11, v[234:235]
	flat_load_dword v253, v[124:125] offset:64
	flat_load_dword v252, v[124:125] offset:128
	flat_load_dword v251, v[124:125] offset:192
	flat_load_dword v250, v[124:125] offset:512
	flat_load_dword v249, v[124:125] offset:576
	flat_load_dword v248, v[124:125] offset:640
	flat_load_dword v247, v[124:125] offset:704
	v_lshl_add_u64 v[124:125], v[136:137], 0, v[238:239]
	flat_load_dwordx4 v[188:191], v[124:125]
	flat_load_dwordx4 v[184:187], v[124:125] offset:256
	v_or_b32_e32 v230, 16, v234
	v_ashrrev_i32_e32 v231, 31, v230
	v_or_b32_e32 v226, 32, v234
	v_lshlrev_b64 v[232:233], 11, v[230:231]
	v_ashrrev_i32_e32 v227, 31, v226
	v_or_b32_e32 v222, 48, v234
	v_add_u32_e32 v214, 0x80, v234
	v_lshl_add_u64 v[124:125], v[136:137], 0, v[232:233]
	v_lshlrev_b64 v[228:229], 11, v[226:227]
	v_ashrrev_i32_e32 v223, 31, v222
	v_ashrrev_i32_e32 v215, 31, v214
	flat_load_dwordx4 v[180:183], v[124:125]
	flat_load_dwordx4 v[176:179], v[124:125] offset:256
	v_lshl_add_u64 v[124:125], v[136:137], 0, v[228:229]
	v_lshlrev_b64 v[224:225], 11, v[222:223]
	v_add_u32_e32 v216, 0x90, v234
	flat_load_dwordx4 v[172:175], v[124:125]
	flat_load_dwordx4 v[168:171], v[124:125] offset:256
	v_lshl_add_u64 v[124:125], v[136:137], 0, v[224:225]
	v_lshlrev_b64 v[220:221], 11, v[214:215]
	v_ashrrev_i32_e32 v217, 31, v216
	flat_load_dwordx4 v[164:167], v[124:125]
	flat_load_dwordx4 v[160:163], v[124:125] offset:256
	v_lshl_add_u64 v[124:125], v[136:137], 0, v[220:221]
	v_lshlrev_b64 v[218:219], 11, v[216:217]
	v_add_u32_e32 v210, 0xa0, v234
	v_add_u32_e32 v206, 0xb0, v234
	flat_load_dwordx4 v[156:159], v[124:125]
	flat_load_dwordx4 v[152:155], v[124:125] offset:256
	v_lshl_add_u64 v[124:125], v[136:137], 0, v[218:219]
	v_ashrrev_i32_e32 v211, 31, v210
	v_ashrrev_i32_e32 v207, 31, v206
	flat_load_dwordx4 v[148:151], v[124:125]
	flat_load_dwordx4 v[144:147], v[124:125] offset:256
	v_lshlrev_b64 v[124:125], 11, v[210:211]
	v_lshlrev_b64 v[138:139], 11, v[206:207]
	v_lshl_add_u64 v[124:125], v[136:137], 0, v[124:125]
	v_lshl_add_u64 v[136:137], v[136:137], 0, v[138:139]
	v_cmp_gt_u32_e32 vcc, 16, v208
	s_waitcnt vmcnt(0) lgkmcnt(0)
	v_fmamk_f32 v209, v127, 0x3a800000, v245
	flat_load_dwordx4 v[132:135], v[124:125]
	s_nop 0
	flat_load_dwordx4 v[124:127], v[124:125] offset:256
	s_nop 0
	flat_load_dwordx4 v[140:143], v[136:137]
	s_nop 0
	flat_load_dwordx4 v[136:139], v[136:137] offset:256
	v_rcp_f32_e32 v208, v209
	v_lshlrev_b32_e32 v212, 16, v188
	v_and_b32_e32 v213, 0xffff0000, v188
	v_lshlrev_b32_e32 v188, 16, v189
	v_and_b32_e32 v189, 0xffff0000, v189
	v_pk_fma_f32 v[130:131], v[130:131], v[208:209], v[188:189] op_sel_hi:[1,0,1]
	v_lshlrev_b32_e32 v188, 16, v190
	v_and_b32_e32 v189, 0xffff0000, v190
	v_lshlrev_b32_e32 v190, 16, v191
	v_and_b32_e32 v191, 0xffff0000, v191
	v_pk_fma_f32 v[128:129], v[128:129], v[208:209], v[212:213] op_sel_hi:[1,0,1]
	v_pk_fma_f32 v[190:191], v[122:123], v[208:209], v[190:191] op_sel_hi:[1,0,1]
	v_pk_fma_f32 v[188:189], v[120:121], v[208:209], v[188:189] op_sel_hi:[1,0,1]
	v_lshl_add_u64 v[212:213], s[42:43], 0, v[238:239]
	v_cvt_pk_bf16_f32 v120, v128, v129
	v_cvt_pk_bf16_f32 v121, v130, v131
	v_cvt_pk_bf16_f32 v122, v188, v189
	v_cvt_pk_bf16_f32 v123, v190, v191
	v_lshl_add_u64 v[212:213], v[212:213], 0, v[236:237]
	flat_store_dwordx4 v[212:213], v[120:123]
	s_nop 1
	v_lshlrev_b32_e32 v120, 16, v184
	v_and_b32_e32 v121, 0xffff0000, v184
	v_lshlrev_b32_e32 v122, 16, v185
	v_and_b32_e32 v123, 0xffff0000, v185
	v_pk_fma_f32 v[118:119], v[118:119], v[208:209], v[122:123] op_sel_hi:[1,0,1]
	v_pk_fma_f32 v[116:117], v[116:117], v[208:209], v[120:121] op_sel_hi:[1,0,1]
	v_lshlrev_b32_e32 v120, 16, v186
	v_and_b32_e32 v121, 0xffff0000, v186
	v_lshlrev_b32_e32 v122, 16, v187
	v_and_b32_e32 v123, 0xffff0000, v187
	v_pk_fma_f32 v[122:123], v[114:115], v[208:209], v[122:123] op_sel_hi:[1,0,1]
	v_pk_fma_f32 v[120:121], v[112:113], v[208:209], v[120:121] op_sel_hi:[1,0,1]
	v_cvt_pk_bf16_f32 v112, v116, v117
	v_cvt_pk_bf16_f32 v113, v118, v119
	v_cvt_pk_bf16_f32 v114, v120, v121
	v_cvt_pk_bf16_f32 v115, v122, v123
	flat_store_dwordx4 v[212:213], v[112:115] offset:256
	s_nop 1
	v_mul_f32_e32 v114, v129, v129
	v_mul_f32_e32 v115, v131, v131
	v_fmac_f32_e32 v114, v128, v128
	v_fmac_f32_e32 v115, v130, v130
	v_mul_f32_e32 v113, v189, v189
	v_add_f32_e32 v114, v114, v115
	v_mul_f32_e32 v115, v117, v117
	v_mul_f32_e32 v112, v191, v191
	v_fmac_f32_e32 v113, v188, v188
	v_fmac_f32_e32 v115, v116, v116
	v_mul_f32_e32 v116, v119, v119
	v_fmac_f32_e32 v112, v190, v190
	v_add_f32_e32 v113, v113, v114
	v_mul_f32_e32 v114, v121, v121
	v_fmac_f32_e32 v116, v118, v118
	v_add_f32_e32 v112, v112, v113
	v_mul_f32_e32 v113, v123, v123
	v_fmac_f32_e32 v114, v120, v120
	v_add_f32_e32 v115, v115, v116
	v_fmac_f32_e32 v113, v122, v122
	v_add_f32_e32 v114, v114, v115
	v_add_f32_e32 v113, v113, v114
	v_and_b32_e32 v114, 64, v246
	v_add_f32_e32 v113, v112, v113
	v_xor_b32_e32 v112, 16, v246
	v_add_u32_e32 v115, 64, v114
	v_cmp_lt_i32_e64 s[0:1], v112, v115
	s_nop 1
	v_cndmask_b32_e64 v112, v246, v112, s[0:1]
	v_lshlrev_b32_e32 v112, 2, v112
	ds_bpermute_b32 v114, v112, v113
	s_waitcnt lgkmcnt(0)
	v_add_f32_e32 v114, v113, v114
	v_xor_b32_e32 v113, 32, v246
	v_cmp_lt_i32_e64 s[0:1], v113, v115
	s_nop 1
	v_cndmask_b32_e64 v113, v246, v113, s[0:1]
	v_lshlrev_b32_e32 v113, 2, v113
	ds_bpermute_b32 v115, v113, v114
	s_and_saveexec_b64 s[0:1], vcc
	s_cbranch_execz .LBB0_560
	v_lshl_add_u64 v[116:117], v[234:235], 2, s[60:61]
	s_waitcnt lgkmcnt(0)
	v_add_f32_e32 v114, v114, v115
	flat_atomic_add_f32 v[116:117], v114

; #define PG8_BAR __builtin_amdgcn_s_barrier()
; template <class Epi>
; __device__ __forceinline__ void gemm_phase(LAS unsigned char* lds, const Gemm g, const StaticOrder& S, const Epi& E, const int wid) {
;     ...
;         if (!has_next) break;
; #pragma unroll
;         for (int a = 0; a < 2; ++a)
; #pragma unroll
;             for (int b = 0; b < 2; ++b)
; #pragma unroll
;                 for (int m = 0; m < 4; ++m)
; #pragma unroll
;                     for (int n = 0; n < 2; ++n) acc[a][b][m][n] = (f32x4){0.f, 0.f, 0.f, 0.f};
;         cur = nxt; cA = nA; cB = nB; ++ui;
;         if (wr == 1) PG8_BAR;
;     }
.LBB0_574:
	s_or_b64 exec, exec, s[0:1]
	s_andn2_b64 vcc, exec, s[6:7]
	s_mov_b64 s[0:1], -1
	s_cbranch_vccnz .LBB0_547
	s_branch .LBB0_546

; __device__ __forceinline__ int lane_id_asm() { int l; asm volatile("v_mbcnt_lo_u32_b32 %0, -1, 0\n\tv_mbcnt_hi_u32_b32 %0, -1, %0" : "=v"(l)); return l; }
; #define PG8_BAR __builtin_amdgcn_s_barrier()
; __device__ __forceinline__ u32x4 pack8(f32x4 a, f32x4 b) { u32x4 w; w.x = pk2(a[0], a[1]); w.y = pk2(a[2], a[3]); w.z = pk2(b[0], b[1]); w.w = pk2(b[2], b[3]); return w; }
; template <class Epi>
; __device__ __forceinline__ void gemm_phase(LAS unsigned char* lds, const Gemm g, const StaticOrder& S, const Epi& E, const int wid) {
;     ...
;         if (wr == 0) PG8_BAR;
;         E(acc, cur, wid);
;         if (!has_next) break;
; #pragma unroll
;         for (int a = 0; a < 2; ++a)
; #pragma unroll
;             for (int b = 0; b < 2; ++b)
; #pragma unroll
;                 for (int m = 0; m < 4; ++m)
; #pragma unroll
;                     for (int n = 0; n < 2; ++n) acc[a][b][m][n] = (f32x4){0.f, 0.f, 0.f, 0.f};
;         cur = nxt; cA = nA; cB = nB; ++ui;
;         if (wr == 1) PG8_BAR;
;     __device__ __forceinline__ void operator()(const Acc& acc, const pg8::Unit& u, int wid) const {
;         const int lane_ = lane_id_asm(), wr = wid >> 2, wc = wid & 3, fr = lane_ & 15, fq = lane_ >> 4;
;         const int row0 = u.pm * 256 + wr * 64 + fr, col0 = u.pn * 256 + wc * 32 + 8 * fq;
; #pragma unroll
;         for (int ai = 0; ai < 2; ++ai)
; #pragma unroll
;             for (int m = 0; m < 4; ++m)
; #pragma unroll
;                 for (int bj = 0; bj < 2; ++bj) *(u32x4*)(O + (size_t)(row0 + ai * 128 + m * 16) * 1024 + col0 + bj * 128) = pack8(acc[ai][bj][m][0], acc[ai][bj][m][1]);
.LBB0_642:
	s_lshl_b32 s4, s18, 8
	v_mbcnt_lo_u32_b32 v145, -1, 0
	v_mbcnt_hi_u32_b32 v145, -1, v145
	s_add_i32 s4, s4, s83
	v_and_or_b32 v144, v145, 15, s4
	s_lshl_b32 s4, s93, 8
	v_ashrrev_i32_e32 v145, 1, v145
	s_or_b32 s4, s4, s69
	v_and_b32_e32 v145, -8, v145
	v_add_u32_e32 v146, s4, v145
	v_ashrrev_i32_e32 v145, 31, v144
	v_ashrrev_i32_e32 v147, 31, v146
	v_lshlrev_b64 v[148:149], 11, v[144:145]
	v_cvt_pk_bf16_f32 v124, v124, v125
	v_cvt_pk_bf16_f32 v125, v126, v127
	v_cvt_pk_bf16_f32 v126, v120, v121
	v_cvt_pk_bf16_f32 v127, v122, v123
	v_lshl_add_u64 v[120:121], s[48:49], 0, v[148:149]
	v_lshlrev_b64 v[122:123], 1, v[146:147]
	v_lshl_add_u64 v[120:121], v[120:121], 0, v[122:123]
	v_cvt_pk_bf16_f32 v108, v108, v109
	v_cvt_pk_bf16_f32 v109, v110, v111
	v_cvt_pk_bf16_f32 v110, v104, v105
	v_or_b32_e32 v104, 16, v144
	s_mov_b64 s[4:5], 0x40000
	v_cvt_pk_bf16_f32 v111, v106, v107
	v_ashrrev_i32_e32 v105, 31, v104
	v_cvt_pk_bf16_f32 v60, v60, v61
	v_cvt_pk_bf16_f32 v61, v62, v63
	v_cvt_pk_bf16_f32 v62, v56, v57
	v_lshl_add_u64 v[56:57], v[120:121], 0, s[4:5]
	s_mov_b32 s4, 0x40000
	flat_store_dwordx4 v[120:121], v[108:111] offset:256
	v_cvt_pk_bf16_f32 v63, v58, v59
	v_add_co_u32_e32 v58, vcc, s4, v120
	v_lshlrev_b64 v[108:109], 11, v[104:105]
	v_cvt_pk_bf16_f32 v44, v44, v45
	v_cvt_pk_bf16_f32 v45, v46, v47
	v_cvt_pk_bf16_f32 v46, v40, v41
	v_cvt_pk_bf16_f32 v47, v42, v43
	s_mov_b64 s[4:5], 0x48000
	v_lshl_add_u64 v[108:109], s[48:49], 0, v[108:109]
	v_cvt_pk_bf16_f32 v92, v92, v93
	v_cvt_pk_bf16_f32 v93, v94, v95
	v_cvt_pk_bf16_f32 v94, v88, v89
	v_or_b32_e32 v88, 32, v144
	v_addc_co_u32_e32 v59, vcc, 0, v121, vcc
	flat_store_dwordx4 v[56:57], v[44:47] offset:256
	v_lshl_add_u64 v[108:109], v[108:109], 0, v[122:123]
	v_cvt_pk_bf16_f32 v95, v90, v91
	v_lshl_add_u64 v[44:45], v[120:121], 0, s[4:5]
	s_mov_b32 s4, 0x48000
	v_ashrrev_i32_e32 v89, 31, v88
	v_add_co_u32_e32 v46, vcc, s4, v120
	v_cvt_pk_bf16_f32 v28, v28, v29
	v_cvt_pk_bf16_f32 v29, v30, v31
	v_cvt_pk_bf16_f32 v30, v24, v25
	v_cvt_pk_bf16_f32 v31, v26, v27
	s_mov_b64 s[4:5], 0x50000
	flat_store_dwordx4 v[108:109], v[92:95] offset:256
	v_addc_co_u32_e32 v47, vcc, 0, v121, vcc
	s_nop 0
	v_lshlrev_b64 v[92:93], 11, v[88:89]
	flat_store_dwordx4 v[44:45], v[28:31] offset:256
	v_lshl_add_u64 v[92:93], s[48:49], 0, v[92:93]
	v_cvt_pk_bf16_f32 v76, v76, v77
	v_lshl_add_u64 v[28:29], v[120:121], 0, s[4:5]
	s_mov_b32 s4, 0x50000
	v_cvt_pk_bf16_f32 v77, v78, v79
	v_cvt_pk_bf16_f32 v78, v72, v73
	v_or_b32_e32 v72, 48, v144
	v_add_co_u32_e32 v30, vcc, s4, v120
	v_cvt_pk_bf16_f32 v12, v12, v13
	v_cvt_pk_bf16_f32 v13, v14, v15
	v_cvt_pk_bf16_f32 v14, v8, v9
	v_cvt_pk_bf16_f32 v15, v10, v11
	s_mov_b64 s[4:5], 0x58000
	v_lshl_add_u64 v[92:93], v[92:93], 0, v[122:123]
	v_cvt_pk_bf16_f32 v79, v74, v75
	v_ashrrev_i32_e32 v73, 31, v72
	v_addc_co_u32_e32 v31, vcc, 0, v121, vcc
	flat_store_dwordx4 v[28:29], v[12:15] offset:256
	flat_store_dwordx4 v[92:93], v[76:79] offset:256
	v_cvt_pk_bf16_f32 v104, v116, v117
	v_lshl_add_u64 v[12:13], v[120:121], 0, s[4:5]
	s_mov_b32 s4, 0x58000
	v_lshlrev_b64 v[76:77], 11, v[72:73]
	v_add_co_u32_e32 v14, vcc, s4, v120
	v_lshl_add_u64 v[76:77], s[48:49], 0, v[76:77]
	s_nop 0
	v_addc_co_u32_e32 v15, vcc, 0, v121, vcc
	v_cvt_pk_bf16_f32 v105, v118, v119
	v_cvt_pk_bf16_f32 v106, v112, v113
	v_cvt_pk_bf16_f32 v107, v114, v115
	v_cvt_pk_bf16_f32 v88, v100, v101
	v_cvt_pk_bf16_f32 v89, v102, v103
	v_cvt_pk_bf16_f32 v90, v96, v97
	v_cvt_pk_bf16_f32 v91, v98, v99
	v_cvt_pk_bf16_f32 v72, v84, v85
	v_cvt_pk_bf16_f32 v73, v86, v87
	v_cvt_pk_bf16_f32 v74, v80, v81
	v_cvt_pk_bf16_f32 v75, v82, v83
	v_lshl_add_u64 v[76:77], v[76:77], 0, v[122:123]
	v_cvt_pk_bf16_f32 v68, v68, v69
	v_cvt_pk_bf16_f32 v69, v70, v71
	v_cvt_pk_bf16_f32 v70, v64, v65
	v_cvt_pk_bf16_f32 v71, v66, v67
	v_cvt_pk_bf16_f32 v40, v52, v53
	v_cvt_pk_bf16_f32 v41, v54, v55
	v_cvt_pk_bf16_f32 v42, v48, v49
	v_cvt_pk_bf16_f32 v43, v50, v51
	v_cvt_pk_bf16_f32 v24, v36, v37
	v_cvt_pk_bf16_f32 v25, v38, v39
	v_cvt_pk_bf16_f32 v26, v32, v33
	v_cvt_pk_bf16_f32 v27, v34, v35
	v_cvt_pk_bf16_f32 v8, v20, v21
	v_cvt_pk_bf16_f32 v9, v22, v23
	v_cvt_pk_bf16_f32 v10, v16, v17
	v_cvt_pk_bf16_f32 v11, v18, v19
	v_cvt_pk_bf16_f32 v4, v4, v5
	v_cvt_pk_bf16_f32 v5, v6, v7
	v_cvt_pk_bf16_f32 v6, v0, v1
	v_cvt_pk_bf16_f32 v7, v2, v3
	s_andn2_b64 vcc, exec, s[6:7]
	s_mov_b64 s[6:7], -1
	flat_store_dwordx4 v[120:121], v[124:127]
	flat_store_dwordx4 v[108:109], v[104:107]
	flat_store_dwordx4 v[92:93], v[88:91]
	flat_store_dwordx4 v[76:77], v[72:75]
	flat_store_dwordx4 v[76:77], v[68:71] offset:256
	flat_store_dwordx4 v[58:59], v[60:63]
	flat_store_dwordx4 v[46:47], v[40:43]
	flat_store_dwordx4 v[30:31], v[24:27]
	flat_store_dwordx4 v[14:15], v[8:11]
	flat_store_dwordx4 v[12:13], v[4:7] offset:256
	s_cbranch_vccnz .LBB0_631
	s_branch .LBB0_630

; #define PG8_STAGE(bufoff, gbase, voff) do { _Pragma("unroll") for (int _i = 0; _i < 2; ++_i) \
;         __builtin_amdgcn_global_load_lds((const unsigned*)((const char*)(gbase) + (voff)[_i]), (LAS unsigned*)(lds + (bufoff) + ldsw + _i * 8192), 16, 0, 0); } while (0)
; #define PG8_LDA(dst, b, h) do { _Pragma("unroll") for (int m = 0; m < 4; ++m) _Pragma("unroll") for (int k = 0; k < 2; ++k) dst[m][k] = *(const LAS bf16x8*)(lds + PG8_SA(b, h) + aoff + m * 2048 + k * 1024); } while (0)
; #define PG8_LDB(dst, b, h) do { _Pragma("unroll") for (int n = 0; n < 2; ++n) _Pragma("unroll") for (int k = 0; k < 2; ++k) dst[n][k] = *(const LAS bf16x8*)(lds + PG8_SB(b, h) + boff + n * 2048 + k * 1024); } while (0)
; #define PG8_MMA(ai, bj, At, Bt) do { __builtin_amdgcn_s_setprio(1); _Pragma("unroll") for (int m = 0; m < 4; ++m) _Pragma("unroll") for (int n = 0; n < 2; ++n) _Pragma("unroll") for (int k = 0; k < 2; ++k) \
;         acc[ai][bj][m][n] = __builtin_amdgcn_mfma_f32_16x16x32_bf16(Bt[n][k], At[m][k], acc[ai][bj][m][n], 0, 0, 0); __builtin_amdgcn_s_setprio(0); } while (0)
; #define PG8_WAIT_V(n) asm volatile("s_waitcnt vmcnt(" #n ")" ::: "memory")
; #define PG8_WAIT_L(n) asm volatile("s_waitcnt lgkmcnt(" #n ")" ::: "memory")
; template <class Epi>
; __device__ __forceinline__ void gemm_phase(LAS unsigned char* lds, const Gemm g, const StaticOrder& S, const Epi& E, const int wid) {
;     ...
;         const bool has_next = S.next(ui + 1, nxt);
;         const char* nA = has_next ? (const char*)g.A + (size_t)nxt.pm * tsA : cA; const char* nB = has_next ? (const char*)g.Bt + (size_t)nxt.pn * tsB : cB;
; #pragma unroll 1
;         for (int t = 0; t < nt; t += 2) {
;             const bool last = (t == nt - 2);
;             const char* a1 = cA + (size_t)(t + 1) * kstep;
;             const char* a2 = last ? nA : cA + (size_t)(t + 2) * kstep; const char* b2 = last ? nB : cB + (size_t)(t + 2) * kstep;
;             const char* a3 = a2 + kstep; const char* b3 = b2 + kstep;
;             PG8_LDB(B0, 0, 0); PG8_LDB(B1, 0, 1); PG8_SCHED; PG8_LDA(At, 0, 0); PG8_STAGE(PG8_SA(1, 1), a1 + hsA, voffA);
;             PG8_WAIT_V(8); PG8_WAIT_L(0); PG8_BAR; PG8_MMA(0, 0, At, B0); PG8_MMA(0, 1, At, B1); PG8_BAR; PG8_SCHED;
;             PG8_LDA(At, 0, 1); PG8_STAGE(PG8_SB(0, 0), b2, voffB); PG8_STAGE(PG8_SB(0, 1), b2 + hsB, voffB); PG8_STAGE(PG8_SA(0, 0), a2, voffA);
.LBB0_665:
	ds_read_b128 v[128:131], v183
	ds_read_b128 v[132:135], v183 offset:1024
	ds_read_b128 v[136:139], v183 offset:2048
	ds_read_b128 v[140:143], v183 offset:3072
	ds_read_b128 v[144:147], v184
	ds_read_b128 v[148:151], v184 offset:1024
	ds_read_b128 v[168:171], v184 offset:2048
	ds_read_b128 v[172:175], v184 offset:3072
	s_add_u32 s4, s28, 0xfffc0080
	s_addc_u32 s5, s29, -1
	s_cmp_eq_u32 s81, 12
	s_cselect_b32 s35, s9, s5
	s_cselect_b32 s34, s11, s4
	s_cselect_b32 s31, s21, s80
	s_cselect_b32 s30, s23, s79
	v_lshl_add_u64 v[180:181], s[28:29], 0, v[162:163]
	s_add_i32 m0, s38, 0xc000
	ds_read_b128 v[176:179], v185
	ds_read_b128 v[188:191], v185 offset:1024
	ds_read_b128 v[192:195], v185 offset:2048
	ds_read_b128 v[196:199], v185 offset:3072
	ds_read_b128 v[200:203], v185 offset:4096
	ds_read_b128 v[204:207], v185 offset:5120
	ds_read_b128 v[208:211], v185 offset:6144
	ds_read_b128 v[212:215], v185 offset:7168
	global_load_lds_dwordx4 v[180:181], off
	v_lshl_add_u64 v[180:181], s[28:29], 0, v[160:161]
	s_add_i32 m0, s38, 0xe000
	s_nop 0
	global_load_lds_dwordx4 v[180:181], off
	s_waitcnt vmcnt(8)
	s_waitcnt lgkmcnt(0)
	s_barrier
	s_setprio 1
	s_waitcnt lgkmcnt(0)
	v_mfma_f32_16x16x32_bf16 v[124:127], v[128:131], v[176:179], v[124:127]
	v_mfma_f32_16x16x32_bf16 v[120:123], v[136:139], v[176:179], v[120:123]
	v_mfma_f32_16x16x32_bf16 v[108:111], v[128:131], v[192:195], v[108:111]
	v_mfma_f32_16x16x32_bf16 v[104:107], v[136:139], v[192:195], v[104:107]
	v_mfma_f32_16x16x32_bf16 v[92:95], v[128:131], v[200:203], v[92:95]
	v_mfma_f32_16x16x32_bf16 v[88:91], v[136:139], v[200:203], v[88:91]
	v_mfma_f32_16x16x32_bf16 v[76:79], v[128:131], v[208:211], v[76:79]
	v_mfma_f32_16x16x32_bf16 v[72:75], v[136:139], v[208:211], v[72:75]
	v_mfma_f32_16x16x32_bf16 v[124:127], v[132:135], v[188:191], v[124:127]
	v_mfma_f32_16x16x32_bf16 v[120:123], v[140:143], v[188:191], v[120:123]
	v_mfma_f32_16x16x32_bf16 v[108:111], v[132:135], v[196:199], v[108:111]
	v_mfma_f32_16x16x32_bf16 v[104:107], v[140:143], v[196:199], v[104:107]
	v_mfma_f32_16x16x32_bf16 v[92:95], v[132:135], v[204:207], v[92:95]
	v_mfma_f32_16x16x32_bf16 v[88:91], v[140:143], v[204:207], v[88:91]
	v_mfma_f32_16x16x32_bf16 v[76:79], v[132:135], v[212:215], v[76:79]
	v_mfma_f32_16x16x32_bf16 v[72:75], v[140:143], v[212:215], v[72:75]
	s_setprio 0
	s_setprio 1
	v_mfma_f32_16x16x32_bf16 v[116:119], v[144:147], v[176:179], v[116:119]
	v_mfma_f32_16x16x32_bf16 v[112:115], v[168:171], v[176:179], v[112:115]
	v_mfma_f32_16x16x32_bf16 v[100:103], v[144:147], v[192:195], v[100:103]
	v_mfma_f32_16x16x32_bf16 v[96:99], v[168:171], v[192:195], v[96:99]
	v_mfma_f32_16x16x32_bf16 v[84:87], v[144:147], v[200:203], v[84:87]
	v_mfma_f32_16x16x32_bf16 v[80:83], v[168:171], v[200:203], v[80:83]
	v_mfma_f32_16x16x32_bf16 v[68:71], v[144:147], v[208:211], v[68:71]
	v_mfma_f32_16x16x32_bf16 v[64:67], v[168:171], v[208:211], v[64:67]
	v_mfma_f32_16x16x32_bf16 v[116:119], v[148:151], v[188:191], v[116:119]
	v_mfma_f32_16x16x32_bf16 v[112:115], v[172:175], v[188:191], v[112:115]
	v_mfma_f32_16x16x32_bf16 v[100:103], v[148:151], v[196:199], v[100:103]
	v_mfma_f32_16x16x32_bf16 v[96:99], v[172:175], v[196:199], v[96:99]
	v_mfma_f32_16x16x32_bf16 v[84:87], v[148:151], v[204:207], v[84:87]
	v_mfma_f32_16x16x32_bf16 v[80:83], v[172:175], v[204:207], v[80:83]
	v_mfma_f32_16x16x32_bf16 v[68:71], v[148:151], v[212:215], v[68:71]
	v_mfma_f32_16x16x32_bf16 v[64:67], v[172:175], v[212:215], v[64:67]
	s_setprio 0
	s_barrier
	s_add_i32 s4, s77, s68
	v_lshl_add_u64 v[180:181], s[30:31], 0, v[154:155]
	s_mov_b32 m0, s4
	ds_read_b128 v[176:179], v185 offset:16384
	ds_read_b128 v[188:191], v185 offset:17408
	ds_read_b128 v[192:195], v185 offset:18432
	ds_read_b128 v[196:199], v185 offset:19456
	ds_read_b128 v[200:203], v185 offset:20480
	ds_read_b128 v[204:207], v185 offset:21504
	ds_read_b128 v[208:211], v185 offset:22528
	ds_read_b128 v[212:215], v185 offset:23552
	global_load_lds_dwordx4 v[180:181], off
	s_add_i32 m0, s4, 0x2000
	s_add_u32 s4, s30, 0x40000
	v_lshl_add_u64 v[216:217], s[30:31], 0, v[158:159]
	s_addc_u32 s5, s31, 0
	s_add_i32 s47, s78, s68
	global_load_lds_dwordx4 v[216:217], off
	v_lshl_add_u64 v[218:219], s[4:5], 0, v[154:155]
	s_mov_b32 m0, s47
	v_lshl_add_u64 v[220:221], s[34:35], 0, v[156:157]
	global_load_lds_dwordx4 v[218:219], off
	v_lshl_add_u64 v[218:219], s[4:5], 0, v[158:159]
	s_add_i32 m0, s47, 0x2000
	s_nop 0
	global_load_lds_dwordx4 v[218:219], off
	v_lshl_add_u64 v[218:219], s[34:35], 0, v[152:153]
	s_mov_b32 m0, s38
	s_nop 0
	global_load_lds_dwordx4 v[218:219], off
	s_mov_b32 m0, s39
	s_nop 0
	global_load_lds_dwordx4 v[220:221], off
	s_waitcnt vmcnt(8)
	s_waitcnt lgkmcnt(0)
	s_barrier
; #define PG8_STAGE(bufoff, gbase, voff) do { _Pragma("unroll") for (int _i = 0; _i < 2; ++_i) \
;         __builtin_amdgcn_global_load_lds((const unsigned*)((const char*)(gbase) + (voff)[_i]), (LAS unsigned*)(lds + (bufoff) + ldsw + _i * 8192), 16, 0, 0); } while (0)
; #define PG8_LDA(dst, b, h) do { _Pragma("unroll") for (int m = 0; m < 4; ++m) _Pragma("unroll") for (int k = 0; k < 2; ++k) dst[m][k] = *(const LAS bf16x8*)(lds + PG8_SA(b, h) + aoff + m * 2048 + k * 1024); } while (0)
; #define PG8_LDB(dst, b, h) do { _Pragma("unroll") for (int n = 0; n < 2; ++n) _Pragma("unroll") for (int k = 0; k < 2; ++k) dst[n][k] = *(const LAS bf16x8*)(lds + PG8_SB(b, h) + boff + n * 2048 + k * 1024); } while (0)
; #define PG8_MMA(ai, bj, At, Bt) do { __builtin_amdgcn_s_setprio(1); _Pragma("unroll") for (int m = 0; m < 4; ++m) _Pragma("unroll") for (int n = 0; n < 2; ++n) _Pragma("unroll") for (int k = 0; k < 2; ++k) \
;         acc[ai][bj][m][n] = __builtin_amdgcn_mfma_f32_16x16x32_bf16(Bt[n][k], At[m][k], acc[ai][bj][m][n], 0, 0, 0); __builtin_amdgcn_s_setprio(0); } while (0)
; #define PG8_WAIT_V(n) asm volatile("s_waitcnt vmcnt(" #n ")" ::: "memory")
; #define PG8_WAIT_L(n) asm volatile("s_waitcnt lgkmcnt(" #n ")" ::: "memory")
; #define PG8_BAR __builtin_amdgcn_s_barrier()
; #define PG8_SCHED __builtin_amdgcn_sched_barrier(0)
; template <class Epi>
; __device__ __forceinline__ void gemm_phase(LAS unsigned char* lds, const Gemm g, const StaticOrder& S, const Epi& E, const int wid) {
;     ...
;             PG8_WAIT_V(8); PG8_WAIT_L(0); PG8_BAR; PG8_MMA(1, 0, At, B0); PG8_MMA(1, 1, At, B1); PG8_BAR; PG8_SCHED;
;             PG8_LDB(B0, 1, 0); PG8_LDB(B1, 1, 1); PG8_SCHED; PG8_LDA(At, 1, 0); PG8_STAGE(PG8_SA(0, 1), a2 + hsA, voffA);
;             PG8_WAIT_V(8); PG8_WAIT_L(0); PG8_BAR; PG8_MMA(0, 0, At, B0); PG8_MMA(0, 1, At, B1); PG8_BAR; PG8_SCHED;
;             PG8_LDA(At, 1, 1); PG8_STAGE(PG8_SB(1, 0), b3, voffB); PG8_STAGE(PG8_SB(1, 1), b3 + hsB, voffB); PG8_STAGE(PG8_SA(1, 0), a3, voffA);
;             PG8_WAIT_V(8); PG8_WAIT_L(0); PG8_BAR; PG8_MMA(1, 0, At, B0); PG8_MMA(1, 1, At, B1); PG8_BAR; PG8_SCHED;
	s_setprio 1
	s_waitcnt lgkmcnt(0)
	v_mfma_f32_16x16x32_bf16 v[60:63], v[128:131], v[176:179], v[60:63]
	v_mfma_f32_16x16x32_bf16 v[56:59], v[136:139], v[176:179], v[56:59]
	v_mfma_f32_16x16x32_bf16 v[44:47], v[128:131], v[192:195], v[44:47]
	v_mfma_f32_16x16x32_bf16 v[40:43], v[136:139], v[192:195], v[40:43]
	v_mfma_f32_16x16x32_bf16 v[28:31], v[128:131], v[200:203], v[28:31]
	v_mfma_f32_16x16x32_bf16 v[24:27], v[136:139], v[200:203], v[24:27]
	v_mfma_f32_16x16x32_bf16 v[12:15], v[128:131], v[208:211], v[12:15]
	v_mfma_f32_16x16x32_bf16 v[8:11], v[136:139], v[208:211], v[8:11]
	v_mfma_f32_16x16x32_bf16 v[60:63], v[132:135], v[188:191], v[60:63]
	v_mfma_f32_16x16x32_bf16 v[56:59], v[140:143], v[188:191], v[56:59]
	v_mfma_f32_16x16x32_bf16 v[44:47], v[132:135], v[196:199], v[44:47]
	v_mfma_f32_16x16x32_bf16 v[40:43], v[140:143], v[196:199], v[40:43]
	v_mfma_f32_16x16x32_bf16 v[28:31], v[132:135], v[204:207], v[28:31]
	v_mfma_f32_16x16x32_bf16 v[24:27], v[140:143], v[204:207], v[24:27]
	v_mfma_f32_16x16x32_bf16 v[12:15], v[132:135], v[212:215], v[12:15]
	v_mfma_f32_16x16x32_bf16 v[8:11], v[140:143], v[212:215], v[8:11]
	s_setprio 0
	s_setprio 1
	v_mfma_f32_16x16x32_bf16 v[52:55], v[144:147], v[176:179], v[52:55]
	v_mfma_f32_16x16x32_bf16 v[48:51], v[168:171], v[176:179], v[48:51]
	v_mfma_f32_16x16x32_bf16 v[36:39], v[144:147], v[192:195], v[36:39]
	v_mfma_f32_16x16x32_bf16 v[32:35], v[168:171], v[192:195], v[32:35]
	v_mfma_f32_16x16x32_bf16 v[20:23], v[144:147], v[200:203], v[20:23]
	v_mfma_f32_16x16x32_bf16 v[16:19], v[168:171], v[200:203], v[16:19]
	v_mfma_f32_16x16x32_bf16 v[4:7], v[144:147], v[208:211], v[4:7]
	v_mfma_f32_16x16x32_bf16 v[0:3], v[168:171], v[208:211], v[0:3]
	v_mfma_f32_16x16x32_bf16 v[52:55], v[148:151], v[188:191], v[52:55]
	v_mfma_f32_16x16x32_bf16 v[48:51], v[172:175], v[188:191], v[48:51]
	v_mfma_f32_16x16x32_bf16 v[36:39], v[148:151], v[196:199], v[36:39]
	v_mfma_f32_16x16x32_bf16 v[32:35], v[172:175], v[196:199], v[32:35]
	v_mfma_f32_16x16x32_bf16 v[20:23], v[148:151], v[204:207], v[20:23]
	v_mfma_f32_16x16x32_bf16 v[16:19], v[172:175], v[204:207], v[16:19]
	v_mfma_f32_16x16x32_bf16 v[4:7], v[148:151], v[212:215], v[4:7]
	v_mfma_f32_16x16x32_bf16 v[0:3], v[172:175], v[212:215], v[0:3]
	s_setprio 0
	s_barrier
	s_add_i32 s47, 0, 0x18000
	s_add_i32 s50, 0, 0x1c000
	v_add_u32_e32 v140, s47, v182
	v_add_u32_e32 v172, s50, v182
	ds_read_b128 v[128:131], v140
	ds_read_b128 v[132:135], v140 offset:1024
	ds_read_b128 v[136:139], v140 offset:2048
	ds_read_b128 v[140:143], v140 offset:3072
	ds_read_b128 v[144:147], v172
	ds_read_b128 v[148:151], v172 offset:1024
	ds_read_b128 v[168:171], v172 offset:2048
	ds_read_b128 v[172:175], v172 offset:3072
	s_add_u32 s4, s34, 0x40000
	s_addc_u32 s5, s35, 0
	s_mov_b32 m0, s62
	v_lshl_add_u64 v[222:223], s[4:5], 0, v[152:153]
	ds_read_b128 v[176:179], v185 offset:32768
	ds_read_b128 v[188:191], v185 offset:33792
	ds_read_b128 v[192:195], v185 offset:34816
	ds_read_b128 v[196:199], v185 offset:35840
	ds_read_b128 v[200:203], v185 offset:36864
	ds_read_b128 v[204:207], v185 offset:37888
	ds_read_b128 v[208:211], v185 offset:38912
	ds_read_b128 v[212:215], v185 offset:39936
	global_load_lds_dwordx4 v[222:223], off
	v_lshl_add_u64 v[222:223], s[4:5], 0, v[156:157]
	s_mov_b32 m0, s63
	s_nop 0
	global_load_lds_dwordx4 v[222:223], off
	s_waitcnt vmcnt(8)
	s_waitcnt lgkmcnt(0)
	s_barrier
	s_setprio 1
	s_waitcnt lgkmcnt(0)
	v_mfma_f32_16x16x32_bf16 v[124:127], v[128:131], v[176:179], v[124:127]
	v_mfma_f32_16x16x32_bf16 v[120:123], v[136:139], v[176:179], v[120:123]
	v_mfma_f32_16x16x32_bf16 v[108:111], v[128:131], v[192:195], v[108:111]
	v_mfma_f32_16x16x32_bf16 v[104:107], v[136:139], v[192:195], v[104:107]
	v_mfma_f32_16x16x32_bf16 v[92:95], v[128:131], v[200:203], v[92:95]
	v_mfma_f32_16x16x32_bf16 v[88:91], v[136:139], v[200:203], v[88:91]
	v_mfma_f32_16x16x32_bf16 v[76:79], v[128:131], v[208:211], v[76:79]
	v_mfma_f32_16x16x32_bf16 v[72:75], v[136:139], v[208:211], v[72:75]
	v_mfma_f32_16x16x32_bf16 v[124:127], v[132:135], v[188:191], v[124:127]
	v_mfma_f32_16x16x32_bf16 v[120:123], v[140:143], v[188:191], v[120:123]
	v_mfma_f32_16x16x32_bf16 v[108:111], v[132:135], v[196:199], v[108:111]
	v_mfma_f32_16x16x32_bf16 v[104:107], v[140:143], v[196:199], v[104:107]
	v_mfma_f32_16x16x32_bf16 v[92:95], v[132:135], v[204:207], v[92:95]
	v_mfma_f32_16x16x32_bf16 v[88:91], v[140:143], v[204:207], v[88:91]
	v_mfma_f32_16x16x32_bf16 v[76:79], v[132:135], v[212:215], v[76:79]
	v_mfma_f32_16x16x32_bf16 v[72:75], v[140:143], v[212:215], v[72:75]
	s_setprio 0
	s_setprio 1
	v_mfma_f32_16x16x32_bf16 v[116:119], v[144:147], v[176:179], v[116:119]
	v_mfma_f32_16x16x32_bf16 v[112:115], v[168:171], v[176:179], v[112:115]
	v_mfma_f32_16x16x32_bf16 v[100:103], v[144:147], v[192:195], v[100:103]
	v_mfma_f32_16x16x32_bf16 v[96:99], v[168:171], v[192:195], v[96:99]
	v_mfma_f32_16x16x32_bf16 v[84:87], v[144:147], v[200:203], v[84:87]
	v_mfma_f32_16x16x32_bf16 v[80:83], v[168:171], v[200:203], v[80:83]
	v_mfma_f32_16x16x32_bf16 v[68:71], v[144:147], v[208:211], v[68:71]
	v_mfma_f32_16x16x32_bf16 v[64:67], v[168:171], v[208:211], v[64:67]
	v_mfma_f32_16x16x32_bf16 v[116:119], v[148:151], v[188:191], v[116:119]
	v_mfma_f32_16x16x32_bf16 v[112:115], v[172:175], v[188:191], v[112:115]
	v_mfma_f32_16x16x32_bf16 v[100:103], v[148:151], v[196:199], v[100:103]
	v_mfma_f32_16x16x32_bf16 v[96:99], v[172:175], v[196:199], v[96:99]
	v_mfma_f32_16x16x32_bf16 v[84:87], v[148:151], v[204:207], v[84:87]
	v_mfma_f32_16x16x32_bf16 v[80:83], v[172:175], v[204:207], v[80:83]
	v_mfma_f32_16x16x32_bf16 v[68:71], v[148:151], v[212:215], v[68:71]
	v_mfma_f32_16x16x32_bf16 v[64:67], v[172:175], v[212:215], v[64:67]
	s_setprio 0
	s_barrier
; #define PG8_STAGE(bufoff, gbase, voff) do { _Pragma("unroll") for (int _i = 0; _i < 2; ++_i) \
;         __builtin_amdgcn_global_load_lds((const unsigned*)((const char*)(gbase) + (voff)[_i]), (LAS unsigned*)(lds + (bufoff) + ldsw + _i * 8192), 16, 0, 0); } while (0)
; #define PG8_LDA(dst, b, h) do { _Pragma("unroll") for (int m = 0; m < 4; ++m) _Pragma("unroll") for (int k = 0; k < 2; ++k) dst[m][k] = *(const LAS bf16x8*)(lds + PG8_SA(b, h) + aoff + m * 2048 + k * 1024); } while (0)
; #define PG8_MMA(ai, bj, At, Bt) do { __builtin_amdgcn_s_setprio(1); _Pragma("unroll") for (int m = 0; m < 4; ++m) _Pragma("unroll") for (int n = 0; n < 2; ++n) _Pragma("unroll") for (int k = 0; k < 2; ++k) \
;         acc[ai][bj][m][n] = __builtin_amdgcn_mfma_f32_16x16x32_bf16(Bt[n][k], At[m][k], acc[ai][bj][m][n], 0, 0, 0); __builtin_amdgcn_s_setprio(0); } while (0)
; #define PG8_WAIT_V(n) asm volatile("s_waitcnt vmcnt(" #n ")" ::: "memory")
; #define PG8_WAIT_L(n) asm volatile("s_waitcnt lgkmcnt(" #n ")" ::: "memory")
; #define PG8_BAR __builtin_amdgcn_s_barrier()
; #define PG8_SCHED __builtin_amdgcn_sched_barrier(0)
; template <class Epi>
; __device__ __forceinline__ void gemm_phase(LAS unsigned char* lds, const Gemm g, const StaticOrder& S, const Epi& E, const int wid) {
;     ...
;             PG8_LDA(At, 1, 1); PG8_STAGE(PG8_SB(1, 0), b3, voffB); PG8_STAGE(PG8_SB(1, 1), b3 + hsB, voffB); PG8_STAGE(PG8_SA(1, 0), a3, voffA);
;             PG8_WAIT_V(8); PG8_WAIT_L(0); PG8_BAR; PG8_MMA(1, 0, At, B0); PG8_MMA(1, 1, At, B1); PG8_BAR; PG8_SCHED;
;         }
	s_add_i32 s4, s47, s68
	v_lshl_add_u64 v[180:181], v[180:181], 0, s[16:17]
	s_mov_b32 m0, s4
	ds_read_b128 v[176:179], v185 offset:49152
	ds_read_b128 v[188:191], v185 offset:50176
	ds_read_b128 v[192:195], v185 offset:51200
	ds_read_b128 v[196:199], v185 offset:52224
	ds_read_b128 v[200:203], v185 offset:53248
	ds_read_b128 v[204:207], v185 offset:54272
	ds_read_b128 v[208:211], v185 offset:55296
	ds_read_b128 v[212:215], v185 offset:56320
	global_load_lds_dwordx4 v[180:181], off
	s_add_i32 m0, s4, 0x2000
	s_add_u32 s4, s30, 0x40080
	v_lshl_add_u64 v[180:181], v[216:217], 0, s[16:17]
	s_addc_u32 s5, s31, 0
	s_add_i32 s30, s50, s68
	global_load_lds_dwordx4 v[180:181], off
	v_lshl_add_u64 v[180:181], s[4:5], 0, v[154:155]
	s_mov_b32 m0, s30
	s_nop 0
	global_load_lds_dwordx4 v[180:181], off
	v_lshl_add_u64 v[180:181], s[4:5], 0, v[158:159]
	s_add_i32 m0, s30, 0x2000
	s_nop 0
	global_load_lds_dwordx4 v[180:181], off
	v_lshl_add_u64 v[180:181], v[218:219], 0, s[16:17]
	s_mov_b32 m0, s65
	s_nop 0
	global_load_lds_dwordx4 v[180:181], off
	v_lshl_add_u64 v[180:181], v[220:221], 0, s[16:17]
	s_mov_b32 m0, s66
	s_nop 0
	global_load_lds_dwordx4 v[180:181], off
	s_waitcnt vmcnt(8)
	s_waitcnt lgkmcnt(0)
	s_barrier
	s_setprio 1
	s_waitcnt lgkmcnt(0)
	v_mfma_f32_16x16x32_bf16 v[60:63], v[128:131], v[176:179], v[60:63]
	v_mfma_f32_16x16x32_bf16 v[56:59], v[136:139], v[176:179], v[56:59]
	v_mfma_f32_16x16x32_bf16 v[44:47], v[128:131], v[192:195], v[44:47]
	v_mfma_f32_16x16x32_bf16 v[40:43], v[136:139], v[192:195], v[40:43]
	v_mfma_f32_16x16x32_bf16 v[28:31], v[128:131], v[200:203], v[28:31]
	v_mfma_f32_16x16x32_bf16 v[24:27], v[136:139], v[200:203], v[24:27]
	v_mfma_f32_16x16x32_bf16 v[12:15], v[128:131], v[208:211], v[12:15]
	v_mfma_f32_16x16x32_bf16 v[8:11], v[136:139], v[208:211], v[8:11]
	v_mfma_f32_16x16x32_bf16 v[60:63], v[132:135], v[188:191], v[60:63]
	v_mfma_f32_16x16x32_bf16 v[56:59], v[140:143], v[188:191], v[56:59]
	v_mfma_f32_16x16x32_bf16 v[44:47], v[132:135], v[196:199], v[44:47]
	v_mfma_f32_16x16x32_bf16 v[40:43], v[140:143], v[196:199], v[40:43]
	v_mfma_f32_16x16x32_bf16 v[28:31], v[132:135], v[204:207], v[28:31]
	v_mfma_f32_16x16x32_bf16 v[24:27], v[140:143], v[204:207], v[24:27]
	v_mfma_f32_16x16x32_bf16 v[12:15], v[132:135], v[212:215], v[12:15]
	v_mfma_f32_16x16x32_bf16 v[8:11], v[140:143], v[212:215], v[8:11]
	s_setprio 0
	s_setprio 1
	v_mfma_f32_16x16x32_bf16 v[52:55], v[144:147], v[176:179], v[52:55]
	v_mfma_f32_16x16x32_bf16 v[48:51], v[168:171], v[176:179], v[48:51]
	v_mfma_f32_16x16x32_bf16 v[36:39], v[144:147], v[192:195], v[36:39]
	v_mfma_f32_16x16x32_bf16 v[32:35], v[168:171], v[192:195], v[32:35]
	v_mfma_f32_16x16x32_bf16 v[20:23], v[144:147], v[200:203], v[20:23]
	v_mfma_f32_16x16x32_bf16 v[16:19], v[168:171], v[200:203], v[16:19]
	v_mfma_f32_16x16x32_bf16 v[4:7], v[144:147], v[208:211], v[4:7]
	v_mfma_f32_16x16x32_bf16 v[0:3], v[168:171], v[208:211], v[0:3]
	v_mfma_f32_16x16x32_bf16 v[52:55], v[148:151], v[188:191], v[52:55]
	v_mfma_f32_16x16x32_bf16 v[48:51], v[172:175], v[188:191], v[48:51]
	v_mfma_f32_16x16x32_bf16 v[36:39], v[148:151], v[196:199], v[36:39]
	v_mfma_f32_16x16x32_bf16 v[32:35], v[172:175], v[196:199], v[32:35]
	v_mfma_f32_16x16x32_bf16 v[20:23], v[148:151], v[204:207], v[20:23]
	v_mfma_f32_16x16x32_bf16 v[16:19], v[172:175], v[204:207], v[16:19]
	v_mfma_f32_16x16x32_bf16 v[4:7], v[148:151], v[212:215], v[4:7]
	v_mfma_f32_16x16x32_bf16 v[0:3], v[172:175], v[212:215], v[0:3]
	s_setprio 0
	s_barrier
	s_add_i32 s81, s81, 2
	s_add_u32 s79, s79, 0x100
	s_addc_u32 s80, s80, 0
	s_add_u32 s28, s28, 0x100
	s_addc_u32 s29, s29, 0
	s_cmp_gt_u32 s81, 13
	s_cbranch_scc0 .LBB0_665
; #define PG8_BAR __builtin_amdgcn_s_barrier()
; template <class Epi>
; __device__ __forceinline__ void gemm_phase(LAS unsigned char* lds, const Gemm g, const StaticOrder& S, const Epi& E, const int wid) {
;     ...
;         if (wr == 0) PG8_BAR;
;         E(acc, cur, wid);
;     __device__ __forceinline__ void operator()(const Acc& acc, const pg8::Unit& u, int wid) const {
;         const int lane_ = lane_id_asm(), wr = wid >> 2, wc = wid & 3, fr = lane_ & 15, fq = lane_ >> 4;
;         const int row0 = u.pm * 256 + wr * 64 + fr, col0 = u.pn * 256 + wc * 32 + 8 * fq;
; #pragma unroll
;         for (int ai = 0; ai < 2; ++ai)
; #pragma unroll
;             for (int mp = 0; mp < 2; ++mp) {
;                 u32x4 hv[2][2], pw[2][2]; float scv[2];
; #pragma unroll
;                 for (int mm = 0; mm < 2; ++mm) {
;                     const int row = row0 + ai * 128 + (2 * mp + mm) * 16;
;                     scv[mm] = ssq[row];
; #pragma unroll
;                     for (int bj = 0; bj < 2; ++bj) { const size_t off = (size_t)row * 1024 + col0 + bj * 128; hv[mm][bj] = *(const u32x4*)(hbase + off); pw[mm][bj] = *(const u32x4*)(pp + off); }
;                 }
; #pragma unroll
;                 for (int mm = 0; mm < 2; ++mm) {
;                     const int m = 2 * mp + mm, row = row0 + ai * 128 + m * 16; float sq = 0.f;
;                     const float sc = __builtin_amdgcn_rsqf(scv[mm] * (1.f / 1024.f) + EPS);
; #pragma unroll
;                     for (int bj = 0; bj < 2; ++bj) {
;                         const size_t off = (size_t)row * 1024 + col0 + bj * 128;
;                         const u32x4 pwv = pw[mm][bj], hw = hv[mm][bj];
;                         const f32x4 p0 = (f32x4){bflo(pwv.x), bfhi(pwv.x), bflo(pwv.y), bfhi(pwv.y)}, p1 = (f32x4){bflo(pwv.z), bfhi(pwv.z), bflo(pwv.w), bfhi(pwv.w)};
;                         f32x4 g0 = acc[ai][bj][m][0] * sc, g1 = acc[ai][bj][m][1] * sc;
; #pragma unroll
;                         for (int e = 0; e < 4; ++e) { g0[e] = __builtin_amdgcn_rcpf(1.f + __builtin_amdgcn_exp2f(-1.4426950408889634f * g0[e])); g1[e] = __builtin_amdgcn_rcpf(1.f + __builtin_amdgcn_exp2f(-1.4426950408889634f * g1[e])); }
;                         const f32x4 o0 = (f32x4){bflo(hw.x), bfhi(hw.x), bflo(hw.y), bfhi(hw.y)} + g0 * p0;
;                         const f32x4 o1 = (f32x4){bflo(hw.z), bfhi(hw.z), bflo(hw.w), bfhi(hw.w)} + g1 * p1;
.LBB0_668:
	s_lshl_b32 s4, s10, 8
	s_add_i32 s4, s4, s67
	v_mbcnt_lo_u32_b32 v188, -1, 0
	v_mbcnt_hi_u32_b32 v188, -1, v188
	v_cndmask_b32_e64 v181, 0, 1, s[40:41]
	v_and_or_b32 v172, v188, 15, s4
	v_ashrrev_i32_e32 v173, 31, v172
	v_lshl_add_u64 v[170:171], v[172:173], 2, s[60:61]
	flat_load_dword v180, v[170:171]
	s_lshl_b32 s4, s8, 8
	v_ashrrev_i32_e32 v128, 1, v188
	s_or_b32 s4, s4, s69
	v_and_b32_e32 v128, -8, v128
	v_add_u32_e32 v168, s4, v128
	v_or_b32_e32 v174, 16, v172
	v_ashrrev_i32_e32 v169, 31, v168
	v_lshlrev_b64 v[128:129], 10, v[172:173]
	v_ashrrev_i32_e32 v175, 31, v174
	v_lshl_add_u64 v[178:179], v[128:129], 0, v[168:169]
	v_lshlrev_b64 v[134:135], 10, v[174:175]
	v_lshlrev_b64 v[128:129], 1, v[178:179]
	v_lshl_add_u64 v[176:177], v[134:135], 0, v[168:169]
	v_lshl_add_u64 v[130:131], s[48:49], 0, v[128:129]
	v_lshl_add_u64 v[128:129], s[42:43], 0, v[128:129]
	v_lshl_add_u64 v[132:133], v[174:175], 2, s[60:61]
	v_lshlrev_b64 v[134:135], 1, v[176:177]
	flat_load_dwordx4 v[190:193], v[130:131]
	flat_load_dwordx4 v[194:197], v[128:129]
	flat_load_dwordx4 v[144:147], v[128:129] offset:256
	flat_load_dwordx4 v[148:151], v[130:131] offset:256
	flat_load_dword v189, v[132:133]
	v_lshl_add_u64 v[128:129], s[42:43], 0, v[134:135]
	v_lshl_add_u64 v[132:133], s[48:49], 0, v[134:135]
	flat_load_dwordx4 v[136:139], v[128:129]
	s_nop 0
	flat_load_dwordx4 v[128:131], v[128:129] offset:256
	s_nop 0
	flat_load_dwordx4 v[140:143], v[132:133]
	s_nop 0
	flat_load_dwordx4 v[132:135], v[132:133] offset:256
	v_cmp_ne_u32_e64 s[8:9], 1, v181
	s_andn2_b64 vcc, exec, s[40:41]
	v_lshl_add_u64 v[178:179], v[178:179], 1, s[52:53]
	s_waitcnt vmcnt(0) lgkmcnt(0)
	v_fmamk_f32 v180, v180, 0x3a800000, v186
	v_rsq_f32_e32 v180, v180
	v_lshlrev_b32_e32 v198, 16, v190
	v_pk_mul_f32 v[126:127], v[126:127], v[180:181] op_sel_hi:[1,0]
	v_pk_mul_f32 v[124:125], v[124:125], v[180:181] op_sel_hi:[1,0]
	v_pk_mul_f32 v[122:123], v[122:123], v[180:181] op_sel_hi:[1,0]
	v_pk_mul_f32 v[120:121], v[120:121], v[180:181] op_sel_hi:[1,0]
	v_mul_f32_e32 v124, 0xbfb8aa3b, v124
	v_mul_f32_e32 v120, 0xbfb8aa3b, v120
	v_mul_f32_e32 v125, 0xbfb8aa3b, v125
	v_mul_f32_e32 v121, 0xbfb8aa3b, v121
	v_mul_f32_e32 v126, 0xbfb8aa3b, v126
	v_mul_f32_e32 v122, 0xbfb8aa3b, v122
	v_mul_f32_e32 v127, 0xbfb8aa3b, v127
	v_mul_f32_e32 v123, 0xbfb8aa3b, v123
	v_exp_f32_e32 v124, v124
	v_exp_f32_e32 v120, v120
	v_exp_f32_e32 v125, v125
	v_exp_f32_e32 v121, v121
	v_exp_f32_e32 v126, v126
	v_exp_f32_e32 v122, v122
	v_exp_f32_e32 v127, v127
	v_exp_f32_e32 v123, v123
	v_add_f32_e32 v124, 1.0, v124
	v_add_f32_e32 v181, 1.0, v120
	v_add_f32_e32 v125, 1.0, v125
	v_add_f32_e32 v208, 1.0, v121
	v_add_f32_e32 v126, 1.0, v126
	v_add_f32_e32 v206, 1.0, v122
	v_add_f32_e32 v127, 1.0, v127
	v_add_f32_e32 v123, 1.0, v123
	v_rcp_f32_e32 v120, v124
	v_rcp_f32_e32 v122, v181
	v_rcp_f32_e32 v121, v125
	v_rcp_f32_e32 v124, v126
	v_rcp_f32_e32 v125, v127
	v_rcp_f32_e32 v206, v206
	v_rcp_f32_e32 v207, v123
	v_rcp_f32_e32 v123, v208
	v_and_b32_e32 v199, 0xffff0000, v190
	v_lshlrev_b32_e32 v190, 16, v191
	v_and_b32_e32 v191, 0xffff0000, v191
	v_lshlrev_b32_e32 v200, 16, v192
	v_and_b32_e32 v201, 0xffff0000, v192
	v_lshlrev_b32_e32 v192, 16, v193
	v_and_b32_e32 v193, 0xffff0000, v193
	v_lshlrev_b32_e32 v202, 16, v194
	v_and_b32_e32 v203, 0xffff0000, v194
	v_lshlrev_b32_e32 v194, 16, v195
	v_and_b32_e32 v195, 0xffff0000, v195
	v_lshlrev_b32_e32 v204, 16, v196
	v_and_b32_e32 v205, 0xffff0000, v196
	v_lshlrev_b32_e32 v196, 16, v197
	v_and_b32_e32 v197, 0xffff0000, v197
	v_pk_fma_f32 v[124:125], v[124:125], v[190:191], v[194:195]
	v_pk_fma_f32 v[126:127], v[120:121], v[198:199], v[202:203]
	v_pk_fma_f32 v[120:121], v[206:207], v[192:193], v[196:197]
	v_pk_fma_f32 v[122:123], v[122:123], v[200:201], v[204:205]
	s_cbranch_vccnz .LBB0_670
	v_cvt_pk_bf16_f32 v190, v126, v127
	v_cvt_pk_bf16_f32 v191, v124, v125
	v_cvt_pk_bf16_f32 v192, v122, v123
	v_cvt_pk_bf16_f32 v193, v120, v121
	global_store_dwordx4 v[178:179], v[190:193], off

; #define PG8_WAIT_V(n) asm volatile("s_waitcnt vmcnt(" #n ")" ::: "memory")
; #define PG8_BAR __builtin_amdgcn_s_barrier()
; template <class Epi>
; __device__ __forceinline__ void gemm_phase(LAS unsigned char* lds, const Gemm g, const StaticOrder& S, const Epi& E, const int wid) {
;     ...
;         if (!has_next) break;
; #pragma unroll
;         for (int a = 0; a < 2; ++a)
; #pragma unroll
;             for (int b = 0; b < 2; ++b)
; #pragma unroll
;                 for (int m = 0; m < 4; ++m)
; #pragma unroll
;                     for (int n = 0; n < 2; ++n) acc[a][b][m][n] = (f32x4){0.f, 0.f, 0.f, 0.f};
;         cur = nxt; cA = nA; cB = nB; ++ui;
;         if (wr == 1) PG8_BAR;
;     }
;     PG8_WAIT_V(0);
;     PG8_BAR;
.LBB0_716:
	s_or_b64 exec, exec, s[8:9]
	s_andn2_b64 vcc, exec, s[6:7]
	s_mov_b64 s[6:7], -1
	s_cbranch_vccnz .LBB0_657
	s_branch .LBB0_656
.LBB0_719:
	s_and_b64 vcc, exec, s[18:19]
	s_cbranch_vccz .Lna_6
	s_barrier

; #define PG8_STAGE(bufoff, gbase, voff) do { _Pragma("unroll") for (int _i = 0; _i < 2; ++_i) \
;         __builtin_amdgcn_global_load_lds((const unsigned*)((const char*)(gbase) + (voff)[_i]), (LAS unsigned*)(lds + (bufoff) + ldsw + _i * 8192), 16, 0, 0); } while (0)
; #define PG8_LDA(dst, b, h) do { _Pragma("unroll") for (int m = 0; m < 4; ++m) _Pragma("unroll") for (int k = 0; k < 2; ++k) dst[m][k] = *(const LAS bf16x8*)(lds + PG8_SA(b, h) + aoff + m * 2048 + k * 1024); } while (0)
; #define PG8_LDB(dst, b, h) do { _Pragma("unroll") for (int n = 0; n < 2; ++n) _Pragma("unroll") for (int k = 0; k < 2; ++k) dst[n][k] = *(const LAS bf16x8*)(lds + PG8_SB(b, h) + boff + n * 2048 + k * 1024); } while (0)
; #define PG8_MMA(ai, bj, At, Bt) do { __builtin_amdgcn_s_setprio(1); _Pragma("unroll") for (int m = 0; m < 4; ++m) _Pragma("unroll") for (int n = 0; n < 2; ++n) _Pragma("unroll") for (int k = 0; k < 2; ++k) \
;         acc[ai][bj][m][n] = __builtin_amdgcn_mfma_f32_16x16x32_bf16(Bt[n][k], At[m][k], acc[ai][bj][m][n], 0, 0, 0); __builtin_amdgcn_s_setprio(0); } while (0)
; #define PG8_WAIT_V(n) asm volatile("s_waitcnt vmcnt(" #n ")" ::: "memory")
; #define PG8_WAIT_L(n) asm volatile("s_waitcnt lgkmcnt(" #n ")" ::: "memory")
; template <class Epi>
; __device__ __forceinline__ void gemm_phase(LAS unsigned char* lds, const Gemm g, const StaticOrder& S, const Epi& E, const int wid) {
;     ...
;         const bool has_next = S.next(ui + 1, nxt);
;         const char* nA = has_next ? (const char*)g.A + (size_t)nxt.pm * tsA : cA; const char* nB = has_next ? (const char*)g.Bt + (size_t)nxt.pn * tsB : cB;
; #pragma unroll 1
;         for (int t = 0; t < nt; t += 2) {
;             const bool last = (t == nt - 2);
;             const char* a1 = cA + (size_t)(t + 1) * kstep;
;             const char* a2 = last ? nA : cA + (size_t)(t + 2) * kstep; const char* b2 = last ? nB : cB + (size_t)(t + 2) * kstep;
;             const char* a3 = a2 + kstep; const char* b3 = b2 + kstep;
;             PG8_LDB(B0, 0, 0); PG8_LDB(B1, 0, 1); PG8_SCHED; PG8_LDA(At, 0, 0); PG8_STAGE(PG8_SA(1, 1), a1 + hsA, voffA);
;             PG8_WAIT_V(8); PG8_WAIT_L(0); PG8_BAR; PG8_MMA(0, 0, At, B0); PG8_MMA(0, 1, At, B1); PG8_BAR; PG8_SCHED;
;             PG8_LDA(At, 0, 1); PG8_STAGE(PG8_SB(0, 0), b2, voffB); PG8_STAGE(PG8_SB(0, 1), b2 + hsB, voffB); PG8_STAGE(PG8_SA(0, 0), a2, voffA);
.LBB0_775:
	ds_read_b128 v[144:147], v151
	ds_read_b128 v[156:159], v151 offset:1024
	ds_read_b128 v[160:163], v151 offset:2048
	ds_read_b128 v[164:167], v151 offset:3072
	ds_read_b128 v[168:171], v152
	ds_read_b128 v[172:175], v152 offset:1024
	ds_read_b128 v[176:179], v152 offset:2048
	ds_read_b128 v[180:183], v152 offset:3072
	s_add_u32 s4, s30, 0xfffc0080
	s_addc_u32 s5, s31, -1
	s_cmp_eq_u32 s91, 12
	s_cselect_b32 s37, s1, s5
	s_cselect_b32 s36, s25, s4
	s_cselect_b32 s35, s23, s90
	s_cselect_b32 s34, s83, s89
	v_lshl_add_u64 v[148:149], s[30:31], 0, v[136:137]
	s_add_i32 m0, s9, 0xc000
	ds_read_b128 v[184:187], v153
	ds_read_b128 v[188:191], v153 offset:1024
	ds_read_b128 v[192:195], v153 offset:2048
	ds_read_b128 v[196:199], v153 offset:3072
	ds_read_b128 v[200:203], v153 offset:4096
	ds_read_b128 v[204:207], v153 offset:5120
	ds_read_b128 v[208:211], v153 offset:6144
	ds_read_b128 v[212:215], v153 offset:7168
	global_load_lds_dwordx4 v[148:149], off
	v_lshl_add_u64 v[148:149], s[30:31], 0, v[138:139]
	s_add_i32 m0, s9, 0xe000
	s_nop 0
	global_load_lds_dwordx4 v[148:149], off
	s_waitcnt vmcnt(8)
	s_waitcnt lgkmcnt(0)
	s_barrier
	s_setprio 1
	s_waitcnt lgkmcnt(0)
	v_mfma_f32_16x16x32_bf16 v[124:127], v[144:147], v[184:187], v[124:127]
	v_mfma_f32_16x16x32_bf16 v[120:123], v[160:163], v[184:187], v[120:123]
	v_mfma_f32_16x16x32_bf16 v[108:111], v[144:147], v[192:195], v[108:111]
	v_mfma_f32_16x16x32_bf16 v[104:107], v[160:163], v[192:195], v[104:107]
	v_mfma_f32_16x16x32_bf16 v[92:95], v[144:147], v[200:203], v[92:95]
	v_mfma_f32_16x16x32_bf16 v[88:91], v[160:163], v[200:203], v[88:91]
	v_mfma_f32_16x16x32_bf16 v[76:79], v[144:147], v[208:211], v[76:79]
	v_mfma_f32_16x16x32_bf16 v[72:75], v[160:163], v[208:211], v[72:75]
	v_mfma_f32_16x16x32_bf16 v[124:127], v[156:159], v[188:191], v[124:127]
	v_mfma_f32_16x16x32_bf16 v[120:123], v[164:167], v[188:191], v[120:123]
	v_mfma_f32_16x16x32_bf16 v[108:111], v[156:159], v[196:199], v[108:111]
	v_mfma_f32_16x16x32_bf16 v[104:107], v[164:167], v[196:199], v[104:107]
	v_mfma_f32_16x16x32_bf16 v[92:95], v[156:159], v[204:207], v[92:95]
	v_mfma_f32_16x16x32_bf16 v[88:91], v[164:167], v[204:207], v[88:91]
	v_mfma_f32_16x16x32_bf16 v[76:79], v[156:159], v[212:215], v[76:79]
	v_mfma_f32_16x16x32_bf16 v[72:75], v[164:167], v[212:215], v[72:75]
	s_setprio 0
	s_setprio 1
	v_mfma_f32_16x16x32_bf16 v[116:119], v[168:171], v[184:187], v[116:119]
	v_mfma_f32_16x16x32_bf16 v[112:115], v[176:179], v[184:187], v[112:115]
	v_mfma_f32_16x16x32_bf16 v[100:103], v[168:171], v[192:195], v[100:103]
	v_mfma_f32_16x16x32_bf16 v[96:99], v[176:179], v[192:195], v[96:99]
	v_mfma_f32_16x16x32_bf16 v[84:87], v[168:171], v[200:203], v[84:87]
	v_mfma_f32_16x16x32_bf16 v[80:83], v[176:179], v[200:203], v[80:83]
	v_mfma_f32_16x16x32_bf16 v[68:71], v[168:171], v[208:211], v[68:71]
	v_mfma_f32_16x16x32_bf16 v[64:67], v[176:179], v[208:211], v[64:67]
	v_mfma_f32_16x16x32_bf16 v[116:119], v[172:175], v[188:191], v[116:119]
	v_mfma_f32_16x16x32_bf16 v[112:115], v[180:183], v[188:191], v[112:115]
	v_mfma_f32_16x16x32_bf16 v[100:103], v[172:175], v[196:199], v[100:103]
	v_mfma_f32_16x16x32_bf16 v[96:99], v[180:183], v[196:199], v[96:99]
	v_mfma_f32_16x16x32_bf16 v[84:87], v[172:175], v[204:207], v[84:87]
	v_mfma_f32_16x16x32_bf16 v[80:83], v[180:183], v[204:207], v[80:83]
	v_mfma_f32_16x16x32_bf16 v[68:71], v[172:175], v[212:215], v[68:71]
	v_mfma_f32_16x16x32_bf16 v[64:67], v[180:183], v[212:215], v[64:67]
	s_setprio 0
	s_barrier
	s_add_i32 s4, s80, s68
	v_lshl_add_u64 v[148:149], s[34:35], 0, v[130:131]
	s_mov_b32 m0, s4
	ds_read_b128 v[184:187], v153 offset:16384
	ds_read_b128 v[188:191], v153 offset:17408
	ds_read_b128 v[192:195], v153 offset:18432
	ds_read_b128 v[196:199], v153 offset:19456
	ds_read_b128 v[200:203], v153 offset:20480
	ds_read_b128 v[204:207], v153 offset:21504
	ds_read_b128 v[208:211], v153 offset:22528
	ds_read_b128 v[212:215], v153 offset:23552
	global_load_lds_dwordx4 v[148:149], off
	s_add_i32 m0, s4, 0x2000
	s_add_u32 s4, s34, 0x40000
	v_lshl_add_u64 v[216:217], s[34:35], 0, v[134:135]
	s_addc_u32 s5, s35, 0
	s_add_i32 s47, s81, s68
	global_load_lds_dwordx4 v[216:217], off
	v_lshl_add_u64 v[218:219], s[4:5], 0, v[130:131]
	s_mov_b32 m0, s47
	v_lshl_add_u64 v[220:221], s[36:37], 0, v[132:133]
	global_load_lds_dwordx4 v[218:219], off
	v_lshl_add_u64 v[218:219], s[4:5], 0, v[134:135]
	s_add_i32 m0, s47, 0x2000
	s_nop 0
	global_load_lds_dwordx4 v[218:219], off
	v_lshl_add_u64 v[218:219], s[36:37], 0, v[128:129]
	s_mov_b32 m0, s9
	s_nop 0
	global_load_lds_dwordx4 v[218:219], off
	s_mov_b32 m0, s62
	s_nop 0
	global_load_lds_dwordx4 v[220:221], off
	s_waitcnt vmcnt(8)
	s_waitcnt lgkmcnt(0)
	s_barrier
; #define PG8_STAGE(bufoff, gbase, voff) do { _Pragma("unroll") for (int _i = 0; _i < 2; ++_i) \
;         __builtin_amdgcn_global_load_lds((const unsigned*)((const char*)(gbase) + (voff)[_i]), (LAS unsigned*)(lds + (bufoff) + ldsw + _i * 8192), 16, 0, 0); } while (0)
; #define PG8_LDA(dst, b, h) do { _Pragma("unroll") for (int m = 0; m < 4; ++m) _Pragma("unroll") for (int k = 0; k < 2; ++k) dst[m][k] = *(const LAS bf16x8*)(lds + PG8_SA(b, h) + aoff + m * 2048 + k * 1024); } while (0)
; #define PG8_LDB(dst, b, h) do { _Pragma("unroll") for (int n = 0; n < 2; ++n) _Pragma("unroll") for (int k = 0; k < 2; ++k) dst[n][k] = *(const LAS bf16x8*)(lds + PG8_SB(b, h) + boff + n * 2048 + k * 1024); } while (0)
; #define PG8_MMA(ai, bj, At, Bt) do { __builtin_amdgcn_s_setprio(1); _Pragma("unroll") for (int m = 0; m < 4; ++m) _Pragma("unroll") for (int n = 0; n < 2; ++n) _Pragma("unroll") for (int k = 0; k < 2; ++k) \
;         acc[ai][bj][m][n] = __builtin_amdgcn_mfma_f32_16x16x32_bf16(Bt[n][k], At[m][k], acc[ai][bj][m][n], 0, 0, 0); __builtin_amdgcn_s_setprio(0); } while (0)
; #define PG8_WAIT_V(n) asm volatile("s_waitcnt vmcnt(" #n ")" ::: "memory")
; #define PG8_WAIT_L(n) asm volatile("s_waitcnt lgkmcnt(" #n ")" ::: "memory")
; #define PG8_BAR __builtin_amdgcn_s_barrier()
; #define PG8_SCHED __builtin_amdgcn_sched_barrier(0)
; template <class Epi>
; __device__ __forceinline__ void gemm_phase(LAS unsigned char* lds, const Gemm g, const StaticOrder& S, const Epi& E, const int wid) {
;     ...
;             PG8_WAIT_V(8); PG8_WAIT_L(0); PG8_BAR; PG8_MMA(1, 0, At, B0); PG8_MMA(1, 1, At, B1); PG8_BAR; PG8_SCHED;
;             PG8_LDB(B0, 1, 0); PG8_LDB(B1, 1, 1); PG8_SCHED; PG8_LDA(At, 1, 0); PG8_STAGE(PG8_SA(0, 1), a2 + hsA, voffA);
;             PG8_WAIT_V(8); PG8_WAIT_L(0); PG8_BAR; PG8_MMA(0, 0, At, B0); PG8_MMA(0, 1, At, B1); PG8_BAR; PG8_SCHED;
;             PG8_LDA(At, 1, 1); PG8_STAGE(PG8_SB(1, 0), b3, voffB); PG8_STAGE(PG8_SB(1, 1), b3 + hsB, voffB); PG8_STAGE(PG8_SA(1, 0), a3, voffA);
;             PG8_WAIT_V(8); PG8_WAIT_L(0); PG8_BAR; PG8_MMA(1, 0, At, B0); PG8_MMA(1, 1, At, B1); PG8_BAR; PG8_SCHED;
	s_setprio 1
	s_waitcnt lgkmcnt(0)
	v_mfma_f32_16x16x32_bf16 v[60:63], v[144:147], v[184:187], v[60:63]
	v_mfma_f32_16x16x32_bf16 v[56:59], v[160:163], v[184:187], v[56:59]
	v_mfma_f32_16x16x32_bf16 v[44:47], v[144:147], v[192:195], v[44:47]
	v_mfma_f32_16x16x32_bf16 v[40:43], v[160:163], v[192:195], v[40:43]
	v_mfma_f32_16x16x32_bf16 v[28:31], v[144:147], v[200:203], v[28:31]
	v_mfma_f32_16x16x32_bf16 v[24:27], v[160:163], v[200:203], v[24:27]
	v_mfma_f32_16x16x32_bf16 v[12:15], v[144:147], v[208:211], v[12:15]
	v_mfma_f32_16x16x32_bf16 v[8:11], v[160:163], v[208:211], v[8:11]
	v_mfma_f32_16x16x32_bf16 v[60:63], v[156:159], v[188:191], v[60:63]
	v_mfma_f32_16x16x32_bf16 v[56:59], v[164:167], v[188:191], v[56:59]
	v_mfma_f32_16x16x32_bf16 v[44:47], v[156:159], v[196:199], v[44:47]
	v_mfma_f32_16x16x32_bf16 v[40:43], v[164:167], v[196:199], v[40:43]
	v_mfma_f32_16x16x32_bf16 v[28:31], v[156:159], v[204:207], v[28:31]
	v_mfma_f32_16x16x32_bf16 v[24:27], v[164:167], v[204:207], v[24:27]
	v_mfma_f32_16x16x32_bf16 v[12:15], v[156:159], v[212:215], v[12:15]
	v_mfma_f32_16x16x32_bf16 v[8:11], v[164:167], v[212:215], v[8:11]
	s_setprio 0
	s_setprio 1
	v_mfma_f32_16x16x32_bf16 v[52:55], v[168:171], v[184:187], v[52:55]
	v_mfma_f32_16x16x32_bf16 v[48:51], v[176:179], v[184:187], v[48:51]
	v_mfma_f32_16x16x32_bf16 v[36:39], v[168:171], v[192:195], v[36:39]
	v_mfma_f32_16x16x32_bf16 v[32:35], v[176:179], v[192:195], v[32:35]
	v_mfma_f32_16x16x32_bf16 v[20:23], v[168:171], v[200:203], v[20:23]
	v_mfma_f32_16x16x32_bf16 v[16:19], v[176:179], v[200:203], v[16:19]
	v_mfma_f32_16x16x32_bf16 v[4:7], v[168:171], v[208:211], v[4:7]
	v_mfma_f32_16x16x32_bf16 v[0:3], v[176:179], v[208:211], v[0:3]
	v_mfma_f32_16x16x32_bf16 v[52:55], v[172:175], v[188:191], v[52:55]
	v_mfma_f32_16x16x32_bf16 v[48:51], v[180:183], v[188:191], v[48:51]
	v_mfma_f32_16x16x32_bf16 v[36:39], v[172:175], v[196:199], v[36:39]
	v_mfma_f32_16x16x32_bf16 v[32:35], v[180:183], v[196:199], v[32:35]
	v_mfma_f32_16x16x32_bf16 v[20:23], v[172:175], v[204:207], v[20:23]
	v_mfma_f32_16x16x32_bf16 v[16:19], v[180:183], v[204:207], v[16:19]
	v_mfma_f32_16x16x32_bf16 v[4:7], v[172:175], v[212:215], v[4:7]
	v_mfma_f32_16x16x32_bf16 v[0:3], v[180:183], v[212:215], v[0:3]
	s_setprio 0
	s_barrier
	s_add_i32 s47, 0, 0x18000
	s_add_i32 s50, 0, 0x1c000
	v_add_u32_e32 v164, s47, v150
	v_add_u32_e32 v180, s50, v150
	ds_read_b128 v[144:147], v164
	ds_read_b128 v[156:159], v164 offset:1024
	ds_read_b128 v[160:163], v164 offset:2048
	ds_read_b128 v[164:167], v164 offset:3072
	ds_read_b128 v[168:171], v180
	ds_read_b128 v[172:175], v180 offset:1024
	ds_read_b128 v[176:179], v180 offset:2048
	ds_read_b128 v[180:183], v180 offset:3072
	s_add_u32 s4, s36, 0x40000
	s_addc_u32 s5, s37, 0
	s_mov_b32 m0, s63
	v_lshl_add_u64 v[222:223], s[4:5], 0, v[128:129]
	ds_read_b128 v[184:187], v153 offset:32768
	ds_read_b128 v[188:191], v153 offset:33792
	ds_read_b128 v[192:195], v153 offset:34816
	ds_read_b128 v[196:199], v153 offset:35840
	ds_read_b128 v[200:203], v153 offset:36864
	ds_read_b128 v[204:207], v153 offset:37888
	ds_read_b128 v[208:211], v153 offset:38912
	ds_read_b128 v[212:215], v153 offset:39936
	global_load_lds_dwordx4 v[222:223], off
	v_lshl_add_u64 v[222:223], s[4:5], 0, v[132:133]
	s_mov_b32 m0, s64
	s_nop 0
	global_load_lds_dwordx4 v[222:223], off
	s_waitcnt vmcnt(8)
	s_waitcnt lgkmcnt(0)
	s_barrier
	s_setprio 1
	s_waitcnt lgkmcnt(0)
	v_mfma_f32_16x16x32_bf16 v[124:127], v[144:147], v[184:187], v[124:127]
	v_mfma_f32_16x16x32_bf16 v[120:123], v[160:163], v[184:187], v[120:123]
	v_mfma_f32_16x16x32_bf16 v[108:111], v[144:147], v[192:195], v[108:111]
	v_mfma_f32_16x16x32_bf16 v[104:107], v[160:163], v[192:195], v[104:107]
	v_mfma_f32_16x16x32_bf16 v[92:95], v[144:147], v[200:203], v[92:95]
	v_mfma_f32_16x16x32_bf16 v[88:91], v[160:163], v[200:203], v[88:91]
	v_mfma_f32_16x16x32_bf16 v[76:79], v[144:147], v[208:211], v[76:79]
	v_mfma_f32_16x16x32_bf16 v[72:75], v[160:163], v[208:211], v[72:75]
	v_mfma_f32_16x16x32_bf16 v[124:127], v[156:159], v[188:191], v[124:127]
	v_mfma_f32_16x16x32_bf16 v[120:123], v[164:167], v[188:191], v[120:123]
	v_mfma_f32_16x16x32_bf16 v[108:111], v[156:159], v[196:199], v[108:111]
	v_mfma_f32_16x16x32_bf16 v[104:107], v[164:167], v[196:199], v[104:107]
	v_mfma_f32_16x16x32_bf16 v[92:95], v[156:159], v[204:207], v[92:95]
	v_mfma_f32_16x16x32_bf16 v[88:91], v[164:167], v[204:207], v[88:91]
	v_mfma_f32_16x16x32_bf16 v[76:79], v[156:159], v[212:215], v[76:79]
	v_mfma_f32_16x16x32_bf16 v[72:75], v[164:167], v[212:215], v[72:75]
	s_setprio 0
	s_setprio 1
	v_mfma_f32_16x16x32_bf16 v[116:119], v[168:171], v[184:187], v[116:119]
	v_mfma_f32_16x16x32_bf16 v[112:115], v[176:179], v[184:187], v[112:115]
	v_mfma_f32_16x16x32_bf16 v[100:103], v[168:171], v[192:195], v[100:103]
	v_mfma_f32_16x16x32_bf16 v[96:99], v[176:179], v[192:195], v[96:99]
	v_mfma_f32_16x16x32_bf16 v[84:87], v[168:171], v[200:203], v[84:87]
	v_mfma_f32_16x16x32_bf16 v[80:83], v[176:179], v[200:203], v[80:83]
	v_mfma_f32_16x16x32_bf16 v[68:71], v[168:171], v[208:211], v[68:71]
	v_mfma_f32_16x16x32_bf16 v[64:67], v[176:179], v[208:211], v[64:67]
	v_mfma_f32_16x16x32_bf16 v[116:119], v[172:175], v[188:191], v[116:119]
	v_mfma_f32_16x16x32_bf16 v[112:115], v[180:183], v[188:191], v[112:115]
	v_mfma_f32_16x16x32_bf16 v[100:103], v[172:175], v[196:199], v[100:103]
	v_mfma_f32_16x16x32_bf16 v[96:99], v[180:183], v[196:199], v[96:99]
	v_mfma_f32_16x16x32_bf16 v[84:87], v[172:175], v[204:207], v[84:87]
	v_mfma_f32_16x16x32_bf16 v[80:83], v[180:183], v[204:207], v[80:83]
	v_mfma_f32_16x16x32_bf16 v[68:71], v[172:175], v[212:215], v[68:71]
	v_mfma_f32_16x16x32_bf16 v[64:67], v[180:183], v[212:215], v[64:67]
	s_setprio 0
	s_barrier
; __device__ __forceinline__ int lane_id_asm() { int l; asm volatile("v_mbcnt_lo_u32_b32 %0, -1, 0\n\tv_mbcnt_hi_u32_b32 %0, -1, %0" : "=v"(l)); return l; }
; #define PG8_WAIT_V(n) asm volatile("s_waitcnt vmcnt(" #n ")" ::: "memory")
; #define PG8_WAIT_L(n) asm volatile("s_waitcnt lgkmcnt(" #n ")" ::: "memory")
; template <class Epi>
; __device__ __forceinline__ void gemm_phase(LAS unsigned char* lds, const Gemm g, const StaticOrder& S, const Epi& E, const int wid) {
;     ...
;             PG8_LDA(At, 1, 1); PG8_STAGE(PG8_SB(1, 0), b3, voffB); PG8_STAGE(PG8_SB(1, 1), b3 + hsB, voffB); PG8_STAGE(PG8_SA(1, 0), a3, voffA);
;             PG8_WAIT_V(8); PG8_WAIT_L(0); PG8_BAR; PG8_MMA(1, 0, At, B0); PG8_MMA(1, 1, At, B1); PG8_BAR; PG8_SCHED;
;         }
;         if (wr == 0) PG8_BAR;
;     __device__ __forceinline__ void operator()(const Acc& acc, const pg8::Unit& u, int wid) const {
;         const int lane_ = lane_id_asm(), wr = wid >> 2, wc = wid & 3, fr = lane_ & 15, fq = lane_ >> 4;
;         const int row0 = u.pm * 256 + wr * 64 + fr, col0 = u.pn * 256 + wc * 32 + 8 * fq;
;         float scv[8];
; #pragma unroll
;         for (int i = 0; i < 8; ++i) scv[i] = ssq ? ssq[row0 + (i >> 2) * 128 + (i & 3) * 16] : 0.f;
; #pragma unroll
;         for (int ai = 0; ai < 2; ++ai)
; #pragma unroll
;             for (int m = 0; m < 4; ++m) {
;                 const int row = row0 + ai * 128 + m * 16;
;                 const float sc = ssq ? __builtin_amdgcn_rsqf(scv[ai * 4 + m] * inv_n + EPS) : 1.f;
; #pragma unroll
;                 for (int bj = 0; bj < 2; ++bj) {
;                     f32x4 v0 = acc[ai][bj][m][0] * sc, v1 = acc[ai][bj][m][1] * sc;
;                     if (ACT == 1) {
; #pragma unroll
;                         for (int e = 0; e < 4; ++e) { float a = fmaxf(v0[e], 0.f), b = fmaxf(v1[e], 0.f); v0[e] = a * a; v1[e] = b * b; }
;                     }
;                     *(u32x4*)(O + (size_t)row * ldc + col0 + bj * 128) = pack8(v0, v1);
;                     if (SSQP) {
;                         float s = 0.f;
; #pragma unroll
;                         for (int e = 0; e < 4; ++e) s += v0[e] * v0[e] + v1[e] * v1[e];
;                         s += __shfl_xor(s, 16); s += __shfl_xor(s, 32);
;                         const int hidx = 2 * u.pn + bj;
;                         if (fq == 0 && hidx < 5) atomicAdd((hidx < 3 ? ssqA : ssqB) + row, s);
	s_add_i32 s4, s47, s68
	v_lshl_add_u64 v[148:149], v[148:149], 0, s[16:17]
	s_mov_b32 m0, s4
	ds_read_b128 v[184:187], v153 offset:49152
	ds_read_b128 v[188:191], v153 offset:50176
	ds_read_b128 v[192:195], v153 offset:51200
	ds_read_b128 v[196:199], v153 offset:52224
	ds_read_b128 v[200:203], v153 offset:53248
	ds_read_b128 v[204:207], v153 offset:54272
	ds_read_b128 v[208:211], v153 offset:55296
	ds_read_b128 v[212:215], v153 offset:56320
	global_load_lds_dwordx4 v[148:149], off
	s_add_i32 m0, s4, 0x2000
	s_add_u32 s4, s34, 0x40080
	v_lshl_add_u64 v[148:149], v[216:217], 0, s[16:17]
	s_addc_u32 s5, s35, 0
	s_add_i32 s34, s50, s68
	global_load_lds_dwordx4 v[148:149], off
	v_lshl_add_u64 v[148:149], s[4:5], 0, v[130:131]
	s_mov_b32 m0, s34
	s_nop 0
	global_load_lds_dwordx4 v[148:149], off
	v_lshl_add_u64 v[148:149], s[4:5], 0, v[134:135]
	s_add_i32 m0, s34, 0x2000
	s_nop 0
	global_load_lds_dwordx4 v[148:149], off
	v_lshl_add_u64 v[148:149], v[218:219], 0, s[16:17]
	s_mov_b32 m0, s74
	s_nop 0
	global_load_lds_dwordx4 v[148:149], off
	v_lshl_add_u64 v[148:149], v[220:221], 0, s[16:17]
	s_mov_b32 m0, s75
	s_nop 0
	global_load_lds_dwordx4 v[148:149], off
	s_waitcnt vmcnt(8)
	s_waitcnt lgkmcnt(0)
	s_barrier
	s_setprio 1
	s_waitcnt lgkmcnt(0)
	v_mfma_f32_16x16x32_bf16 v[60:63], v[144:147], v[184:187], v[60:63]
	v_mfma_f32_16x16x32_bf16 v[56:59], v[160:163], v[184:187], v[56:59]
	v_mfma_f32_16x16x32_bf16 v[44:47], v[144:147], v[192:195], v[44:47]
	v_mfma_f32_16x16x32_bf16 v[40:43], v[160:163], v[192:195], v[40:43]
	v_mfma_f32_16x16x32_bf16 v[28:31], v[144:147], v[200:203], v[28:31]
	v_mfma_f32_16x16x32_bf16 v[24:27], v[160:163], v[200:203], v[24:27]
	v_mfma_f32_16x16x32_bf16 v[12:15], v[144:147], v[208:211], v[12:15]
	v_mfma_f32_16x16x32_bf16 v[8:11], v[160:163], v[208:211], v[8:11]
	v_mfma_f32_16x16x32_bf16 v[60:63], v[156:159], v[188:191], v[60:63]
	v_mfma_f32_16x16x32_bf16 v[56:59], v[164:167], v[188:191], v[56:59]
	v_mfma_f32_16x16x32_bf16 v[44:47], v[156:159], v[196:199], v[44:47]
	v_mfma_f32_16x16x32_bf16 v[40:43], v[164:167], v[196:199], v[40:43]
	v_mfma_f32_16x16x32_bf16 v[28:31], v[156:159], v[204:207], v[28:31]
	v_mfma_f32_16x16x32_bf16 v[24:27], v[164:167], v[204:207], v[24:27]
	v_mfma_f32_16x16x32_bf16 v[12:15], v[156:159], v[212:215], v[12:15]
	v_mfma_f32_16x16x32_bf16 v[8:11], v[164:167], v[212:215], v[8:11]
	s_setprio 0
	s_setprio 1
	v_mfma_f32_16x16x32_bf16 v[52:55], v[168:171], v[184:187], v[52:55]
	v_mfma_f32_16x16x32_bf16 v[48:51], v[176:179], v[184:187], v[48:51]
	v_mfma_f32_16x16x32_bf16 v[36:39], v[168:171], v[192:195], v[36:39]
	v_mfma_f32_16x16x32_bf16 v[32:35], v[176:179], v[192:195], v[32:35]
	v_mfma_f32_16x16x32_bf16 v[20:23], v[168:171], v[200:203], v[20:23]
	v_mfma_f32_16x16x32_bf16 v[16:19], v[176:179], v[200:203], v[16:19]
	v_mfma_f32_16x16x32_bf16 v[4:7], v[168:171], v[208:211], v[4:7]
	v_mfma_f32_16x16x32_bf16 v[0:3], v[176:179], v[208:211], v[0:3]
	v_mfma_f32_16x16x32_bf16 v[52:55], v[172:175], v[188:191], v[52:55]
	v_mfma_f32_16x16x32_bf16 v[48:51], v[180:183], v[188:191], v[48:51]
	v_mfma_f32_16x16x32_bf16 v[36:39], v[172:175], v[196:199], v[36:39]
	v_mfma_f32_16x16x32_bf16 v[32:35], v[180:183], v[196:199], v[32:35]
	v_mfma_f32_16x16x32_bf16 v[20:23], v[172:175], v[204:207], v[20:23]
	v_mfma_f32_16x16x32_bf16 v[16:19], v[180:183], v[204:207], v[16:19]
	v_mfma_f32_16x16x32_bf16 v[4:7], v[172:175], v[212:215], v[4:7]
	v_mfma_f32_16x16x32_bf16 v[0:3], v[180:183], v[212:215], v[0:3]
	s_setprio 0
	s_barrier
	s_add_i32 s91, s91, 2
	s_add_u32 s30, s30, 0x100
	s_addc_u32 s31, s31, 0
	s_add_u32 s89, s89, 0x100
	s_addc_u32 s90, s90, 0
	s_cmp_gt_u32 s91, 13
	s_cbranch_scc0 .LBB0_775
.LBB0_778:
	s_lshl_b32 s0, s0, 8
	s_add_i32 s0, s0, s76
	v_mbcnt_lo_u32_b32 v148, -1, 0
	v_mbcnt_hi_u32_b32 v148, -1, v148
	v_xor_b32_e32 v156, 32, v154
	v_and_or_b32 v144, v148, 15, s0
	v_ashrrev_i32_e32 v145, 31, v144
	v_lshl_add_u64 v[146:147], v[144:145], 2, s[58:59]
	flat_load_dword v149, v[146:147]
	flat_load_dword v164, v[146:147] offset:64
	flat_load_dword v163, v[146:147] offset:128
	flat_load_dword v162, v[146:147] offset:192
	flat_load_dword v161, v[146:147] offset:512
	flat_load_dword v160, v[146:147] offset:576
	flat_load_dword v159, v[146:147] offset:640
	flat_load_dword v158, v[146:147] offset:704
	v_and_b32_e32 v147, 64, v154
	s_lshl_b32 s0, s8, 8
	v_xor_b32_e32 v146, 16, v154
	v_ashrrev_i32_e32 v157, 1, v148
	v_add_u32_e32 v147, 64, v147
	s_or_b32 s4, s0, s69
	v_cmp_gt_u32_e32 vcc, 16, v148
	v_and_b32_e32 v148, -8, v157
	v_cmp_lt_i32_e64 s[0:1], v146, v147
	s_cmp_lt_i32 s8, 3
	s_nop 0
	v_cndmask_b32_e64 v157, v154, v146, s[0:1]
	v_add_u32_e32 v146, s4, v148
	v_lshlrev_b32_e32 v157, 2, v157
	v_cmp_lt_i32_e64 s[0:1], v156, v147
	s_waitcnt vmcnt(0) lgkmcnt(0)
	v_fmamk_f32 v148, v149, 0x3a800000, v155
	v_rsq_f32_e32 v148, v148
	v_cndmask_b32_e64 v147, v154, v156, s[0:1]
	v_lshlrev_b32_e32 v156, 2, v147
	v_ashrrev_i32_e32 v147, 31, v146
	v_pk_mul_f32 v[120:121], v[120:121], v[148:149] op_sel_hi:[1,0]
	v_pk_mul_f32 v[166:167], v[126:127], v[148:149] op_sel_hi:[1,0]
	v_pk_mul_f32 v[168:169], v[124:125], v[148:149] op_sel_hi:[1,0]
	v_pk_mul_f32 v[122:123], v[122:123], v[148:149] op_sel_hi:[1,0]
	v_cvt_pk_bf16_f32 v126, v120, v121
	v_mul_f32_e32 v120, v120, v120
	v_mul_f32_e32 v121, v121, v121
	v_cvt_pk_bf16_f32 v127, v122, v123
	v_mul_f32_e32 v122, v122, v122
	v_fmac_f32_e32 v120, v168, v168
	v_fmac_f32_e32 v121, v169, v169
	v_mul_f32_e32 v123, v123, v123
	v_fmac_f32_e32 v122, v166, v166
	v_add_f32_e32 v120, v120, v121
	v_add_f32_e32 v120, v122, v120
	v_fmac_f32_e32 v123, v167, v167
	v_add_f32_e32 v122, v123, v120
	ds_bpermute_b32 v123, v157, v122
	v_mov_b64_e32 v[120:121], s[44:45]
	v_mad_i64_i32 v[120:121], s[0:1], v144, s82, v[120:121]
	s_cselect_b64 s[0:1], -1, 0
	s_waitcnt lgkmcnt(0)
	v_add_f32_e32 v122, v122, v123
	ds_bpermute_b32 v123, v156, v122
	v_cvt_pk_bf16_f32 v124, v168, v169
	v_cvt_pk_bf16_f32 v125, v166, v167
	v_lshl_add_u64 v[120:121], v[146:147], 1, v[120:121]
	s_and_b64 s[0:1], vcc, s[0:1]
	flat_store_dwordx4 v[120:121], v[124:127]
	s_and_saveexec_b64 s[30:31], s[0:1]
	s_cbranch_execz .LBB0_780
	s_cmp_lt_i32 s8, 2
	s_cselect_b32 s4, s67, s61
	s_cselect_b32 s5, s66, s60
	v_mov_b32_e32 v124, s5
	v_mov_b32_e32 v125, s4
	v_lshl_add_u64 v[124:125], v[144:145], 2, v[124:125]
	s_waitcnt lgkmcnt(0)
	v_add_f32_e32 v122, v122, v123
	flat_atomic_add_f32 v[124:125], v122

; #define PG8_BAR __builtin_amdgcn_s_barrier()
; __device__ __forceinline__ u32x4 pack8(f32x4 a, f32x4 b) { u32x4 w; w.x = pk2(a[0], a[1]); w.y = pk2(a[2], a[3]); w.z = pk2(b[0], b[1]); w.w = pk2(b[2], b[3]); return w; }
; template <class Epi>
; __device__ __forceinline__ void gemm_phase(LAS unsigned char* lds, const Gemm g, const StaticOrder& S, const Epi& E, const int wid) {
;     ...
;         if (wr == 0) PG8_BAR;
;         E(acc, cur, wid);
;         if (!has_next) break;
; #pragma unroll
;         for (int a = 0; a < 2; ++a)
; #pragma unroll
;             for (int b = 0; b < 2; ++b)
; #pragma unroll
;                 for (int m = 0; m < 4; ++m)
; #pragma unroll
;                     for (int n = 0; n < 2; ++n) acc[a][b][m][n] = (f32x4){0.f, 0.f, 0.f, 0.f};
;         cur = nxt; cA = nA; cB = nB; ++ui;
;         if (wr == 1) PG8_BAR;
;     }
;     __device__ __forceinline__ void operator()(const Acc& acc, const pg8::Unit& u, int wid) const {
;     ...
;         const int row0 = u.pm * 256 + wr * 64 + fr, col0 = u.pn * 256 + wc * 32 + 8 * fq;
;         float scv[8];
; #pragma unroll
;         for (int i = 0; i < 8; ++i) scv[i] = ssq ? ssq[row0 + (i >> 2) * 128 + (i & 3) * 16] : 0.f;
; #pragma unroll
;         for (int ai = 0; ai < 2; ++ai)
; #pragma unroll
;             for (int m = 0; m < 4; ++m) {
;                 const int row = row0 + ai * 128 + m * 16;
;                 const float sc = ssq ? __builtin_amdgcn_rsqf(scv[ai * 4 + m] * inv_n + EPS) : 1.f;
; #pragma unroll
;                 for (int bj = 0; bj < 2; ++bj) {
;                     f32x4 v0 = acc[ai][bj][m][0] * sc, v1 = acc[ai][bj][m][1] * sc;
;                     if (ACT == 1) {
; #pragma unroll
;                         for (int e = 0; e < 4; ++e) { float a = fmaxf(v0[e], 0.f), b = fmaxf(v1[e], 0.f); v0[e] = a * a; v1[e] = b * b; }
;                     }
;                     *(u32x4*)(O + (size_t)row * ldc + col0 + bj * 128) = pack8(v0, v1);
.LBB0_874:
	s_lshl_b32 s4, s75, 8
	v_mbcnt_lo_u32_b32 v148, -1, 0
	v_mbcnt_hi_u32_b32 v148, -1, v148
	s_add_i32 s4, s4, s63
	v_and_or_b32 v150, v148, 15, s4
	v_ashrrev_i32_e32 v148, 1, v148
	s_lshl_b32 s4, s78, 8
	v_and_b32_e32 v148, -8, v148
	s_or_b32 s4, s4, s69
	v_add_u32_e32 v148, s4, v148
	v_add_u32_e32 v151, 0x80, v150
	v_ashrrev_i32_e32 v149, 31, v148
	v_cvt_pk_bf16_f32 v124, v124, v125
	v_cvt_pk_bf16_f32 v125, v126, v127
	v_cvt_pk_bf16_f32 v126, v120, v121
	v_mov_b64_e32 v[120:121], s[58:59]
	v_cvt_pk_bf16_f32 v127, v122, v123
	v_mad_i64_i32 v[122:123], s[4:5], v150, s74, v[120:121]
	v_lshlrev_b64 v[148:149], 1, v[148:149]
	v_cvt_pk_bf16_f32 v60, v60, v61
	v_cvt_pk_bf16_f32 v61, v62, v63
	v_cvt_pk_bf16_f32 v62, v56, v57
	v_mad_i64_i32 v[56:57], s[4:5], v151, s74, v[120:121]
	v_lshl_add_u64 v[122:123], v[122:123], 0, v[148:149]
	v_cvt_pk_bf16_f32 v108, v108, v109
	v_cvt_pk_bf16_f32 v109, v110, v111
	v_cvt_pk_bf16_f32 v110, v104, v105
	v_cvt_pk_bf16_f32 v111, v106, v107
	v_lshl_add_u64 v[56:57], v[56:57], 0, v[148:149]
	v_cvt_pk_bf16_f32 v44, v44, v45
	v_cvt_pk_bf16_f32 v45, v46, v47
	v_cvt_pk_bf16_f32 v46, v40, v41
	v_cvt_pk_bf16_f32 v47, v42, v43
	flat_store_dwordx4 v[122:123], v[108:111] offset:256
	flat_store_dwordx4 v[56:57], v[44:47] offset:256
	v_cvt_pk_bf16_f32 v92, v92, v93
	v_or_b32_e32 v108, 16, v150
	v_add_u32_e32 v44, 0x90, v150
	v_mad_i64_i32 v[108:109], s[4:5], v108, s74, v[120:121]
	v_mad_i64_i32 v[44:45], s[4:5], v44, s74, v[120:121]
	v_lshl_add_u64 v[108:109], v[108:109], 0, v[148:149]
	v_cvt_pk_bf16_f32 v93, v94, v95
	v_cvt_pk_bf16_f32 v94, v88, v89
	v_cvt_pk_bf16_f32 v95, v90, v91
	v_lshl_add_u64 v[44:45], v[44:45], 0, v[148:149]
	v_cvt_pk_bf16_f32 v28, v28, v29
	v_cvt_pk_bf16_f32 v29, v30, v31
	v_cvt_pk_bf16_f32 v30, v24, v25
	v_cvt_pk_bf16_f32 v31, v26, v27
	flat_store_dwordx4 v[108:109], v[92:95] offset:256
	flat_store_dwordx4 v[44:45], v[28:31] offset:256
	v_cvt_pk_bf16_f32 v76, v76, v77
	v_or_b32_e32 v92, 32, v150
	v_add_u32_e32 v28, 0xa0, v150
	v_mad_i64_i32 v[92:93], s[4:5], v92, s74, v[120:121]
	v_mad_i64_i32 v[28:29], s[4:5], v28, s74, v[120:121]
	v_lshl_add_u64 v[92:93], v[92:93], 0, v[148:149]
	v_cvt_pk_bf16_f32 v77, v78, v79
	v_cvt_pk_bf16_f32 v78, v72, v73
	v_cvt_pk_bf16_f32 v79, v74, v75
	v_lshl_add_u64 v[28:29], v[28:29], 0, v[148:149]
	v_cvt_pk_bf16_f32 v12, v12, v13
	v_cvt_pk_bf16_f32 v13, v14, v15
	v_cvt_pk_bf16_f32 v14, v8, v9
	v_cvt_pk_bf16_f32 v15, v10, v11
	flat_store_dwordx4 v[92:93], v[76:79] offset:256
	flat_store_dwordx4 v[28:29], v[12:15] offset:256
	v_cvt_pk_bf16_f32 v104, v116, v117
	v_or_b32_e32 v76, 48, v150
	v_add_u32_e32 v12, 0xb0, v150
	v_mad_i64_i32 v[76:77], s[4:5], v76, s74, v[120:121]
	v_mad_i64_i32 v[12:13], s[4:5], v12, s74, v[120:121]
	v_cvt_pk_bf16_f32 v105, v118, v119
	v_cvt_pk_bf16_f32 v106, v112, v113
	v_cvt_pk_bf16_f32 v107, v114, v115
	v_cvt_pk_bf16_f32 v88, v100, v101
	v_cvt_pk_bf16_f32 v89, v102, v103
	v_cvt_pk_bf16_f32 v90, v96, v97
	v_cvt_pk_bf16_f32 v91, v98, v99
	v_cvt_pk_bf16_f32 v72, v84, v85
	v_cvt_pk_bf16_f32 v73, v86, v87
	v_cvt_pk_bf16_f32 v74, v80, v81
	v_cvt_pk_bf16_f32 v75, v82, v83
	v_lshl_add_u64 v[76:77], v[76:77], 0, v[148:149]
	v_cvt_pk_bf16_f32 v68, v68, v69
	v_cvt_pk_bf16_f32 v69, v70, v71
	v_cvt_pk_bf16_f32 v70, v64, v65
	v_cvt_pk_bf16_f32 v71, v66, v67
	v_cvt_pk_bf16_f32 v63, v58, v59
	v_cvt_pk_bf16_f32 v40, v52, v53
	v_cvt_pk_bf16_f32 v41, v54, v55
	v_cvt_pk_bf16_f32 v42, v48, v49
	v_cvt_pk_bf16_f32 v43, v50, v51
	v_cvt_pk_bf16_f32 v24, v36, v37
	v_cvt_pk_bf16_f32 v25, v38, v39
	v_cvt_pk_bf16_f32 v26, v32, v33
	v_cvt_pk_bf16_f32 v27, v34, v35
	v_cvt_pk_bf16_f32 v8, v20, v21
	v_cvt_pk_bf16_f32 v9, v22, v23
	v_cvt_pk_bf16_f32 v10, v16, v17
	v_cvt_pk_bf16_f32 v11, v18, v19
	v_lshl_add_u64 v[12:13], v[12:13], 0, v[148:149]
	v_cvt_pk_bf16_f32 v4, v4, v5
	v_cvt_pk_bf16_f32 v5, v6, v7
	v_cvt_pk_bf16_f32 v6, v0, v1
	v_cvt_pk_bf16_f32 v7, v2, v3
	s_and_b64 vcc, exec, s[6:7]
	s_mov_b64 s[6:7], -1
	flat_store_dwordx4 v[122:123], v[124:127]
	flat_store_dwordx4 v[108:109], v[104:107]
	flat_store_dwordx4 v[92:93], v[88:91]
	flat_store_dwordx4 v[76:77], v[72:75]
	flat_store_dwordx4 v[76:77], v[68:71] offset:256
	flat_store_dwordx4 v[56:57], v[60:63]
	flat_store_dwordx4 v[44:45], v[40:43]
	flat_store_dwordx4 v[28:29], v[24:27]
	flat_store_dwordx4 v[12:13], v[8:11]
	flat_store_dwordx4 v[12:13], v[4:7] offset:256
	s_cbranch_vccnz .LBB0_863
	s_branch .LBB0_862

; __device__ __forceinline__ int lane_id_asm() { int l; asm volatile("v_mbcnt_lo_u32_b32 %0, -1, 0\n\tv_mbcnt_hi_u32_b32 %0, -1, %0" : "=v"(l)); return l; }
; #define PG8_BAR __builtin_amdgcn_s_barrier()
; __device__ __forceinline__ u32x4 pack8(f32x4 a, f32x4 b) { u32x4 w; w.x = pk2(a[0], a[1]); w.y = pk2(a[2], a[3]); w.z = pk2(b[0], b[1]); w.w = pk2(b[2], b[3]); return w; }
; template <class Epi>
; __device__ __forceinline__ void gemm_phase(LAS unsigned char* lds, const Gemm g, const StaticOrder& S, const Epi& E, const int wid) {
;     ...
;         if (wr == 0) PG8_BAR;
;         E(acc, cur, wid);
;     __device__ __forceinline__ void operator()(const Acc& acc, const pg8::Unit& u, int wid) const {
;         const int lane_ = lane_id_asm(), wr = wid >> 2, wc = wid & 3, fr = lane_ & 15, fq = lane_ >> 4;
;         const int row0 = u.pm * 256 + wr * 64 + fr, col0 = u.pn * 256 + wc * 32 + 8 * fq;
;         float scv[8];
; #pragma unroll
;         for (int i = 0; i < 8; ++i) scv[i] = ssq ? ssq[row0 + (i >> 2) * 128 + (i & 3) * 16] : 0.f;
; #pragma unroll
;         for (int ai = 0; ai < 2; ++ai)
; #pragma unroll
;             for (int m = 0; m < 4; ++m) {
;                 const int row = row0 + ai * 128 + m * 16;
;                 const float sc = ssq ? __builtin_amdgcn_rsqf(scv[ai * 4 + m] * inv_n + EPS) : 1.f;
; #pragma unroll
;                 for (int bj = 0; bj < 2; ++bj) {
;                     f32x4 v0 = acc[ai][bj][m][0] * sc, v1 = acc[ai][bj][m][1] * sc;
;                     if (ACT == 1) {
; #pragma unroll
;                         for (int e = 0; e < 4; ++e) { float a = fmaxf(v0[e], 0.f), b = fmaxf(v1[e], 0.f); v0[e] = a * a; v1[e] = b * b; }
;                     }
;                     *(u32x4*)(O + (size_t)row * ldc + col0 + bj * 128) = pack8(v0, v1);
.LBB0_892:
	s_lshl_b32 s4, s89, 8
	s_add_i32 s4, s4, s83
	v_mbcnt_lo_u32_b32 v151, -1, 0
	v_mbcnt_hi_u32_b32 v151, -1, v151
	v_mov_b64_e32 v[142:143], s[48:49]
	v_and_or_b32 v140, v151, 15, s4
	v_ashrrev_i32_e32 v141, 31, v140
	v_lshl_add_u64 v[144:145], v[140:141], 2, s[60:61]
	s_lshl_b32 s4, s96, 8
	v_ashrrev_i32_e32 v151, 1, v151
	s_or_b32 s4, s4, s69
	v_and_b32_e32 v151, -8, v151
	v_add_u32_e32 v152, s4, v151
	v_or_b32_e32 v151, 16, v140
	v_mad_i64_i32 v[156:157], s[4:5], v151, s94, v[142:143]
	v_or_b32_e32 v158, 32, v140
	v_ashrrev_i32_e32 v153, 31, v152
	v_mad_i64_i32 v[154:155], s[4:5], v140, s94, v[142:143]
	v_mad_i64_i32 v[158:159], s[4:5], v158, s94, v[142:143]
	v_lshlrev_b64 v[144:145], 1, v[152:153]
	v_lshl_add_u64 v[152:153], v[154:155], 0, v[144:145]
	v_lshl_add_u64 v[154:155], v[156:157], 0, v[144:145]
	v_lshl_add_u64 v[156:157], v[158:159], 0, v[144:145]
	v_add_u32_e32 v170, 0x80, v140
	s_and_b64 vcc, exec, s[6:7]
	s_mov_b64 s[6:7], -1
	s_waitcnt lgkmcnt(0)
	v_fmamk_f32 v141, v228, 0x3b800000, v150
	v_fmamk_f32 v159, v229, 0x3b800000, v150
	v_fmamk_f32 v161, v230, 0x3b800000, v150
	v_rsq_f32_e32 v158, v141
	v_fmamk_f32 v141, v231, 0x3b800000, v150
	v_rsq_f32_e32 v160, v159
	v_rsq_f32_e32 v162, v161
	v_pk_mul_f32 v[126:127], v[126:127], v[158:159] op_sel_hi:[1,0]
	v_pk_mul_f32 v[124:125], v[124:125], v[158:159] op_sel_hi:[1,0]
	v_pk_mul_f32 v[122:123], v[122:123], v[158:159] op_sel_hi:[1,0]
	v_pk_mul_f32 v[120:121], v[120:121], v[158:159] op_sel_hi:[1,0]
	v_pk_mul_f32 v[106:107], v[106:107], v[158:159] op_sel_hi:[1,0]
	v_pk_mul_f32 v[104:105], v[104:105], v[158:159] op_sel_hi:[1,0]
	v_pk_mul_f32 v[98:99], v[98:99], v[158:159] op_sel_hi:[1,0]
	v_pk_mul_f32 v[96:97], v[96:97], v[158:159] op_sel_hi:[1,0]
	v_pk_mul_f32 v[118:119], v[118:119], v[160:161] op_sel_hi:[1,0]
	v_pk_mul_f32 v[116:117], v[116:117], v[160:161] op_sel_hi:[1,0]
	v_pk_mul_f32 v[114:115], v[114:115], v[160:161] op_sel_hi:[1,0]
	v_pk_mul_f32 v[112:113], v[112:113], v[160:161] op_sel_hi:[1,0]
	v_pk_mul_f32 v[94:95], v[94:95], v[160:161] op_sel_hi:[1,0]
	v_pk_mul_f32 v[92:93], v[92:93], v[160:161] op_sel_hi:[1,0]
	v_pk_mul_f32 v[158:159], v[90:91], v[160:161] op_sel_hi:[1,0]
	v_pk_mul_f32 v[160:161], v[88:89], v[160:161] op_sel_hi:[1,0]
	v_pk_mul_f32 v[110:111], v[110:111], v[162:163] op_sel_hi:[1,0]
	v_pk_mul_f32 v[108:109], v[108:109], v[162:163] op_sel_hi:[1,0]
	v_pk_mul_f32 v[102:103], v[102:103], v[162:163] op_sel_hi:[1,0]
	v_pk_mul_f32 v[100:101], v[100:101], v[162:163] op_sel_hi:[1,0]
	v_pk_mul_f32 v[164:165], v[86:87], v[162:163] op_sel_hi:[1,0]
	v_pk_mul_f32 v[166:167], v[84:85], v[162:163] op_sel_hi:[1,0]
	v_pk_mul_f32 v[168:169], v[82:83], v[162:163] op_sel_hi:[1,0]
	v_pk_mul_f32 v[162:163], v[80:81], v[162:163] op_sel_hi:[1,0]
	v_cvt_pk_bf16_f32 v80, v124, v125
	v_cvt_pk_bf16_f32 v81, v126, v127
	v_cvt_pk_bf16_f32 v82, v120, v121
	v_cvt_pk_bf16_f32 v83, v122, v123
	v_cvt_pk_bf16_f32 v84, v104, v105
	v_cvt_pk_bf16_f32 v85, v106, v107
	v_cvt_pk_bf16_f32 v86, v96, v97
	v_cvt_pk_bf16_f32 v87, v98, v99
	v_cvt_pk_bf16_f32 v88, v116, v117
	v_cvt_pk_bf16_f32 v89, v118, v119
	v_cvt_pk_bf16_f32 v90, v112, v113
	v_cvt_pk_bf16_f32 v91, v114, v115
	v_cvt_pk_bf16_f32 v92, v92, v93
	v_cvt_pk_bf16_f32 v93, v94, v95
	v_cvt_pk_bf16_f32 v94, v160, v161
	v_cvt_pk_bf16_f32 v95, v158, v159
	v_cvt_pk_bf16_f32 v96, v108, v109
	v_cvt_pk_bf16_f32 v97, v110, v111
	v_cvt_pk_bf16_f32 v98, v100, v101
	v_cvt_pk_bf16_f32 v99, v102, v103
	flat_store_dwordx4 v[152:153], v[80:83]
	flat_store_dwordx4 v[152:153], v[84:87] offset:256
	flat_store_dwordx4 v[154:155], v[88:91]
	flat_store_dwordx4 v[154:155], v[92:95] offset:256
	flat_store_dwordx4 v[156:157], v[96:99]
	v_rsq_f32_e32 v80, v141
	v_or_b32_e32 v81, 48, v140
	v_cvt_pk_bf16_f32 v100, v166, v167
	v_cvt_pk_bf16_f32 v101, v164, v165
	v_pk_mul_f32 v[76:77], v[76:77], v[80:81] op_sel_hi:[1,0]
	v_pk_mul_f32 v[78:79], v[78:79], v[80:81] op_sel_hi:[1,0]
	v_pk_mul_f32 v[82:83], v[74:75], v[80:81] op_sel_hi:[1,0]
	v_pk_mul_f32 v[74:75], v[72:73], v[80:81] op_sel_hi:[1,0]
	v_cvt_pk_bf16_f32 v72, v76, v77
	v_mad_i64_i32 v[76:77], s[4:5], v81, s94, v[142:143]
	v_cvt_pk_bf16_f32 v73, v78, v79
	v_cvt_pk_bf16_f32 v74, v74, v75
	v_cvt_pk_bf16_f32 v75, v82, v83
	v_lshl_add_u64 v[76:77], v[76:77], 0, v[144:145]
	v_pk_mul_f32 v[68:69], v[68:69], v[80:81] op_sel_hi:[1,0]
	flat_store_dwordx4 v[76:77], v[72:75]
	v_pk_mul_f32 v[70:71], v[70:71], v[80:81] op_sel_hi:[1,0]
	v_cvt_pk_bf16_f32 v102, v162, v163
	v_pk_mul_f32 v[72:73], v[66:67], v[80:81] op_sel_hi:[1,0]
	v_pk_mul_f32 v[66:67], v[64:65], v[80:81] op_sel_hi:[1,0]
	v_cvt_pk_bf16_f32 v64, v68, v69
	v_fmamk_f32 v68, v232, 0x3b800000, v150
	v_rsq_f32_e32 v68, v68
	v_cvt_pk_bf16_f32 v65, v70, v71
	v_cvt_pk_bf16_f32 v66, v66, v67
	v_cvt_pk_bf16_f32 v67, v72, v73
; #define PG8_BAR __builtin_amdgcn_s_barrier()
; __device__ __forceinline__ u32x4 pack8(f32x4 a, f32x4 b) { u32x4 w; w.x = pk2(a[0], a[1]); w.y = pk2(a[2], a[3]); w.z = pk2(b[0], b[1]); w.w = pk2(b[2], b[3]); return w; }
; template <class Epi>
; __device__ __forceinline__ void gemm_phase(LAS unsigned char* lds, const Gemm g, const StaticOrder& S, const Epi& E, const int wid) {
;     ...
;         if (!has_next) break;
; #pragma unroll
;         for (int a = 0; a < 2; ++a)
; #pragma unroll
;             for (int b = 0; b < 2; ++b)
; #pragma unroll
;                 for (int m = 0; m < 4; ++m)
; #pragma unroll
;                     for (int n = 0; n < 2; ++n) acc[a][b][m][n] = (f32x4){0.f, 0.f, 0.f, 0.f};
;         cur = nxt; cA = nA; cB = nB; ++ui;
;         if (wr == 1) PG8_BAR;
;     }
;     __device__ __forceinline__ void operator()(const Acc& acc, const pg8::Unit& u, int wid) const {
;     ...
;         const int row0 = u.pm * 256 + wr * 64 + fr, col0 = u.pn * 256 + wc * 32 + 8 * fq;
;         float scv[8];
; #pragma unroll
;         for (int i = 0; i < 8; ++i) scv[i] = ssq ? ssq[row0 + (i >> 2) * 128 + (i & 3) * 16] : 0.f;
; #pragma unroll
;         for (int ai = 0; ai < 2; ++ai)
; #pragma unroll
;             for (int m = 0; m < 4; ++m) {
;                 const int row = row0 + ai * 128 + m * 16;
;                 const float sc = ssq ? __builtin_amdgcn_rsqf(scv[ai * 4 + m] * inv_n + EPS) : 1.f;
; #pragma unroll
;                 for (int bj = 0; bj < 2; ++bj) {
;                     f32x4 v0 = acc[ai][bj][m][0] * sc, v1 = acc[ai][bj][m][1] * sc;
;                     if (ACT == 1) {
; #pragma unroll
;                         for (int e = 0; e < 4; ++e) { float a = fmaxf(v0[e], 0.f), b = fmaxf(v1[e], 0.f); v0[e] = a * a; v1[e] = b * b; }
;                     }
;                     *(u32x4*)(O + (size_t)row * ldc + col0 + bj * 128) = pack8(v0, v1);
	v_pk_mul_f32 v[60:61], v[60:61], v[68:69] op_sel_hi:[1,0]
	flat_store_dwordx4 v[76:77], v[64:67] offset:256
	v_pk_mul_f32 v[62:63], v[62:63], v[68:69] op_sel_hi:[1,0]
	v_pk_mul_f32 v[48:49], v[48:49], v[68:69] op_sel_hi:[1,0]
	v_pk_mul_f32 v[64:65], v[58:59], v[68:69] op_sel_hi:[1,0]
	v_pk_mul_f32 v[58:59], v[56:57], v[68:69] op_sel_hi:[1,0]
	v_cvt_pk_bf16_f32 v56, v60, v61
	v_mad_i64_i32 v[60:61], s[4:5], v170, s94, v[142:143]
	v_cvt_pk_bf16_f32 v57, v62, v63
	v_cvt_pk_bf16_f32 v58, v58, v59
	v_cvt_pk_bf16_f32 v59, v64, v65
	v_lshl_add_u64 v[60:61], v[60:61], 0, v[144:145]
	flat_store_dwordx4 v[60:61], v[56:59]
	v_pk_mul_f32 v[50:51], v[50:51], v[68:69] op_sel_hi:[1,0]
	v_cvt_pk_bf16_f32 v103, v168, v169
	v_pk_mul_f32 v[56:57], v[42:43], v[68:69] op_sel_hi:[1,0]
	v_pk_mul_f32 v[42:43], v[40:41], v[68:69] op_sel_hi:[1,0]
	v_cvt_pk_bf16_f32 v40, v48, v49
	v_cvt_pk_bf16_f32 v42, v42, v43
	v_fmamk_f32 v43, v233, 0x3b800000, v150
	v_rsq_f32_e32 v48, v43
	v_cvt_pk_bf16_f32 v41, v50, v51
	v_cvt_pk_bf16_f32 v43, v56, v57
	v_add_u32_e32 v49, 0x90, v140
	flat_store_dwordx4 v[60:61], v[40:43] offset:256
	v_pk_mul_f32 v[44:45], v[44:45], v[48:49] op_sel_hi:[1,0]
	v_pk_mul_f32 v[46:47], v[46:47], v[48:49] op_sel_hi:[1,0]
	v_pk_mul_f32 v[42:43], v[54:55], v[48:49] op_sel_hi:[1,0]
	v_pk_mul_f32 v[40:41], v[52:53], v[48:49] op_sel_hi:[1,0]
	v_pk_mul_f32 v[32:33], v[32:33], v[48:49] op_sel_hi:[1,0]
	v_cvt_pk_bf16_f32 v40, v40, v41
	v_cvt_pk_bf16_f32 v41, v42, v43
	v_cvt_pk_bf16_f32 v42, v44, v45
	v_mad_i64_i32 v[44:45], s[4:5], v49, s94, v[142:143]
	v_cvt_pk_bf16_f32 v43, v46, v47
	v_lshl_add_u64 v[44:45], v[44:45], 0, v[144:145]
	flat_store_dwordx4 v[44:45], v[40:43]
	v_pk_mul_f32 v[34:35], v[34:35], v[48:49] op_sel_hi:[1,0]
	flat_store_dwordx4 v[156:157], v[100:103] offset:256
	v_pk_mul_f32 v[40:41], v[26:27], v[48:49] op_sel_hi:[1,0]
	v_pk_mul_f32 v[26:27], v[24:25], v[48:49] op_sel_hi:[1,0]
	v_cvt_pk_bf16_f32 v24, v32, v33
	v_cvt_pk_bf16_f32 v26, v26, v27
	v_fmamk_f32 v27, v234, 0x3b800000, v150
	v_rsq_f32_e32 v32, v27
	v_cvt_pk_bf16_f32 v25, v34, v35
	v_cvt_pk_bf16_f32 v27, v40, v41
	v_add_u32_e32 v33, 0xa0, v140
	flat_store_dwordx4 v[44:45], v[24:27] offset:256
	v_pk_mul_f32 v[28:29], v[28:29], v[32:33] op_sel_hi:[1,0]
	v_pk_mul_f32 v[30:31], v[30:31], v[32:33] op_sel_hi:[1,0]
	v_pk_mul_f32 v[26:27], v[38:39], v[32:33] op_sel_hi:[1,0]
	v_pk_mul_f32 v[24:25], v[36:37], v[32:33] op_sel_hi:[1,0]
	v_pk_mul_f32 v[16:17], v[16:17], v[32:33] op_sel_hi:[1,0]
	v_cvt_pk_bf16_f32 v24, v24, v25
	v_cvt_pk_bf16_f32 v25, v26, v27
	v_cvt_pk_bf16_f32 v26, v28, v29
	v_mad_i64_i32 v[28:29], s[4:5], v33, s94, v[142:143]
	v_cvt_pk_bf16_f32 v27, v30, v31
	v_lshl_add_u64 v[28:29], v[28:29], 0, v[144:145]
	flat_store_dwordx4 v[28:29], v[24:27]
	v_pk_mul_f32 v[18:19], v[18:19], v[32:33] op_sel_hi:[1,0]
	s_nop 0
	v_pk_mul_f32 v[24:25], v[10:11], v[32:33] op_sel_hi:[1,0]
	v_pk_mul_f32 v[10:11], v[8:9], v[32:33] op_sel_hi:[1,0]
	v_cvt_pk_bf16_f32 v8, v16, v17
	v_cvt_pk_bf16_f32 v10, v10, v11
	v_fmamk_f32 v11, v235, 0x3b800000, v150
	s_min_u32 s4, s95, 0x7f
	s_lshl_b32 s4, s4, 8
	s_add_i32 s4, s4, s83
	v_mbcnt_lo_u32_b32 v238, -1, 0
	v_mbcnt_hi_u32_b32 v238, -1, v238
	v_and_or_b32 v238, v238, 15, s4
	v_ashrrev_i32_e32 v239, 31, v238
	v_lshl_add_u64 v[238:239], v[238:239], 2, s[60:61]
	global_load_dword v228, v[238:239], off
	global_load_dword v229, v[238:239], off offset:64
	global_load_dword v230, v[238:239], off offset:128
	global_load_dword v231, v[238:239], off offset:192
	global_load_dword v232, v[238:239], off offset:512
	global_load_dword v233, v[238:239], off offset:576
	global_load_dword v234, v[238:239], off offset:640
	global_load_dword v235, v[238:239], off offset:704
	v_rsq_f32_e32 v16, v11
	v_cvt_pk_bf16_f32 v9, v18, v19
	v_cvt_pk_bf16_f32 v11, v24, v25
	v_add_u32_e32 v17, 0xb0, v140
	flat_store_dwordx4 v[28:29], v[8:11] offset:256
	v_pk_mul_f32 v[12:13], v[12:13], v[16:17] op_sel_hi:[1,0]
	v_pk_mul_f32 v[14:15], v[14:15], v[16:17] op_sel_hi:[1,0]
	v_pk_mul_f32 v[10:11], v[22:23], v[16:17] op_sel_hi:[1,0]
	v_pk_mul_f32 v[8:9], v[20:21], v[16:17] op_sel_hi:[1,0]
	v_pk_mul_f32 v[6:7], v[6:7], v[16:17] op_sel_hi:[1,0]
	v_cvt_pk_bf16_f32 v8, v8, v9
	v_cvt_pk_bf16_f32 v9, v10, v11
	v_cvt_pk_bf16_f32 v10, v12, v13
	v_mad_i64_i32 v[12:13], s[4:5], v17, s94, v[142:143]
	v_cvt_pk_bf16_f32 v11, v14, v15
	v_lshl_add_u64 v[12:13], v[12:13], 0, v[144:145]
	flat_store_dwordx4 v[12:13], v[8:11]
	v_pk_mul_f32 v[4:5], v[4:5], v[16:17] op_sel_hi:[1,0]
	s_nop 0
	v_pk_mul_f32 v[8:9], v[2:3], v[16:17] op_sel_hi:[1,0]
	v_pk_mul_f32 v[2:3], v[0:1], v[16:17] op_sel_hi:[1,0]
	v_cvt_pk_bf16_f32 v0, v4, v5
	v_cvt_pk_bf16_f32 v1, v6, v7
	v_cvt_pk_bf16_f32 v2, v2, v3
	v_cvt_pk_bf16_f32 v3, v8, v9
	flat_store_dwordx4 v[12:13], v[0:3] offset:256
	s_cbranch_vccnz .LBB0_883
	s_branch .LBB0_882

; #define PG8_STAGE(bufoff, gbase, voff) do { _Pragma("unroll") for (int _i = 0; _i < 2; ++_i) \
;         __builtin_amdgcn_global_load_lds((const unsigned*)((const char*)(gbase) + (voff)[_i]), (LAS unsigned*)(lds + (bufoff) + ldsw + _i * 8192), 16, 0, 0); } while (0)
; #define PG8_LDA(dst, b, h) do { _Pragma("unroll") for (int m = 0; m < 4; ++m) _Pragma("unroll") for (int k = 0; k < 2; ++k) dst[m][k] = *(const LAS bf16x8*)(lds + PG8_SA(b, h) + aoff + m * 2048 + k * 1024); } while (0)
; #define PG8_LDB(dst, b, h) do { _Pragma("unroll") for (int n = 0; n < 2; ++n) _Pragma("unroll") for (int k = 0; k < 2; ++k) dst[n][k] = *(const LAS bf16x8*)(lds + PG8_SB(b, h) + boff + n * 2048 + k * 1024); } while (0)
; #define PG8_MMA(ai, bj, At, Bt) do { __builtin_amdgcn_s_setprio(1); _Pragma("unroll") for (int m = 0; m < 4; ++m) _Pragma("unroll") for (int n = 0; n < 2; ++n) _Pragma("unroll") for (int k = 0; k < 2; ++k) \
;         acc[ai][bj][m][n] = __builtin_amdgcn_mfma_f32_16x16x32_bf16(Bt[n][k], At[m][k], acc[ai][bj][m][n], 0, 0, 0); __builtin_amdgcn_s_setprio(0); } while (0)
; #define PG8_WAIT_V(n) asm volatile("s_waitcnt vmcnt(" #n ")" ::: "memory")
; #define PG8_WAIT_L(n) asm volatile("s_waitcnt lgkmcnt(" #n ")" ::: "memory")
; template <class Epi>
; __device__ __forceinline__ void gemm_phase(LAS unsigned char* lds, const Gemm g, const StaticOrder& S, const Epi& E, const int wid) {
;     ...
;         const bool has_next = S.next(ui + 1, nxt);
;         const char* nA = has_next ? (const char*)g.A + (size_t)nxt.pm * tsA : cA; const char* nB = has_next ? (const char*)g.Bt + (size_t)nxt.pn * tsB : cB;
; #pragma unroll 1
;         for (int t = 0; t < nt; t += 2) {
;             const bool last = (t == nt - 2);
;             const char* a1 = cA + (size_t)(t + 1) * kstep;
;             const char* a2 = last ? nA : cA + (size_t)(t + 2) * kstep; const char* b2 = last ? nB : cB + (size_t)(t + 2) * kstep;
;             const char* a3 = a2 + kstep; const char* b3 = b2 + kstep;
;             PG8_LDB(B0, 0, 0); PG8_LDB(B1, 0, 1); PG8_SCHED; PG8_LDA(At, 0, 0); PG8_STAGE(PG8_SA(1, 1), a1 + hsA, voffA);
;             PG8_WAIT_V(8); PG8_WAIT_L(0); PG8_BAR; PG8_MMA(0, 0, At, B0); PG8_MMA(0, 1, At, B1); PG8_BAR; PG8_SCHED;
;             PG8_LDA(At, 0, 1); PG8_STAGE(PG8_SB(0, 0), b2, voffB); PG8_STAGE(PG8_SB(0, 1), b2 + hsB, voffB); PG8_STAGE(PG8_SA(0, 0), a2, voffA);
.LBB0_1091:
	ds_read_b128 v[120:123], v246
	ds_read_b128 v[124:127], v246 offset:1024
	ds_read_b128 v[132:135], v246 offset:2048
	ds_read_b128 v[136:139], v246 offset:3072
	ds_read_b128 v[144:147], v247
	ds_read_b128 v[148:151], v247 offset:1024
	ds_read_b128 v[152:155], v247 offset:2048
	ds_read_b128 v[156:159], v247 offset:3072
	s_add_u32 s4, s28, 0xfffc0080
	s_addc_u32 s5, s29, -1
	s_cmp_eq_u32 s74, 12
	s_cselect_b32 s35, s1, s5
	s_cselect_b32 s34, s21, s4
	s_cselect_b32 s31, s19, s73
	s_cselect_b32 s30, s66, s67
	v_lshl_add_u64 v[208:209], s[28:29], 0, v[202:203]
	s_add_i32 m0, s27, 0xc000
	ds_read_b128 v[160:163], v248
	ds_read_b128 v[164:167], v248 offset:1024
	ds_read_b128 v[168:171], v248 offset:2048
	ds_read_b128 v[172:175], v248 offset:3072
	ds_read_b128 v[176:179], v248 offset:4096
	ds_read_b128 v[180:183], v248 offset:5120
	ds_read_b128 v[184:187], v248 offset:6144
	ds_read_b128 v[188:191], v248 offset:7168
	global_load_lds_dwordx4 v[208:209], off
	v_lshl_add_u64 v[208:209], s[28:29], 0, v[200:201]
	s_add_i32 m0, s27, 0xe000
	s_nop 0
	global_load_lds_dwordx4 v[208:209], off
	s_waitcnt vmcnt(8)
	s_waitcnt lgkmcnt(0)
	s_barrier
	s_setprio 1
	s_waitcnt lgkmcnt(0)
	v_mfma_f32_16x16x32_bf16 v[140:143], v[120:123], v[160:163], v[140:143]
	v_mfma_f32_16x16x32_bf16 v[128:131], v[132:135], v[160:163], v[128:131]
	v_mfma_f32_16x16x32_bf16 v[108:111], v[120:123], v[168:171], v[108:111]
	v_mfma_f32_16x16x32_bf16 v[104:107], v[132:135], v[168:171], v[104:107]
	v_mfma_f32_16x16x32_bf16 v[92:95], v[120:123], v[176:179], v[92:95]
	v_mfma_f32_16x16x32_bf16 v[88:91], v[132:135], v[176:179], v[88:91]
	v_mfma_f32_16x16x32_bf16 v[76:79], v[120:123], v[184:187], v[76:79]
	v_mfma_f32_16x16x32_bf16 v[72:75], v[132:135], v[184:187], v[72:75]
	v_mfma_f32_16x16x32_bf16 v[140:143], v[124:127], v[164:167], v[140:143]
	v_mfma_f32_16x16x32_bf16 v[128:131], v[136:139], v[164:167], v[128:131]
	v_mfma_f32_16x16x32_bf16 v[108:111], v[124:127], v[172:175], v[108:111]
	v_mfma_f32_16x16x32_bf16 v[104:107], v[136:139], v[172:175], v[104:107]
	v_mfma_f32_16x16x32_bf16 v[92:95], v[124:127], v[180:183], v[92:95]
	v_mfma_f32_16x16x32_bf16 v[88:91], v[136:139], v[180:183], v[88:91]
	v_mfma_f32_16x16x32_bf16 v[76:79], v[124:127], v[188:191], v[76:79]
	v_mfma_f32_16x16x32_bf16 v[72:75], v[136:139], v[188:191], v[72:75]
	s_setprio 0
	s_setprio 1
	v_mfma_f32_16x16x32_bf16 v[116:119], v[144:147], v[160:163], v[116:119]
	v_mfma_f32_16x16x32_bf16 v[112:115], v[152:155], v[160:163], v[112:115]
	v_mfma_f32_16x16x32_bf16 v[100:103], v[144:147], v[168:171], v[100:103]
	v_mfma_f32_16x16x32_bf16 v[96:99], v[152:155], v[168:171], v[96:99]
	v_mfma_f32_16x16x32_bf16 v[84:87], v[144:147], v[176:179], v[84:87]
	v_mfma_f32_16x16x32_bf16 v[80:83], v[152:155], v[176:179], v[80:83]
	v_mfma_f32_16x16x32_bf16 v[68:71], v[144:147], v[184:187], v[68:71]
	v_mfma_f32_16x16x32_bf16 v[64:67], v[152:155], v[184:187], v[64:67]
	v_mfma_f32_16x16x32_bf16 v[116:119], v[148:151], v[164:167], v[116:119]
	v_mfma_f32_16x16x32_bf16 v[112:115], v[156:159], v[164:167], v[112:115]
	v_mfma_f32_16x16x32_bf16 v[100:103], v[148:151], v[172:175], v[100:103]
	v_mfma_f32_16x16x32_bf16 v[96:99], v[156:159], v[172:175], v[96:99]
	v_mfma_f32_16x16x32_bf16 v[84:87], v[148:151], v[180:183], v[84:87]
	v_mfma_f32_16x16x32_bf16 v[80:83], v[156:159], v[180:183], v[80:83]
	v_mfma_f32_16x16x32_bf16 v[68:71], v[148:151], v[188:191], v[68:71]
	v_mfma_f32_16x16x32_bf16 v[64:67], v[156:159], v[188:191], v[64:67]
	s_setprio 0
	s_barrier
	s_add_i32 s4, s64, s68
	v_lshl_add_u64 v[208:209], s[30:31], 0, v[194:195]
	s_mov_b32 m0, s4
	ds_read_b128 v[160:163], v248 offset:16384
	ds_read_b128 v[164:167], v248 offset:17408
	ds_read_b128 v[168:171], v248 offset:18432
	ds_read_b128 v[172:175], v248 offset:19456
	ds_read_b128 v[176:179], v248 offset:20480
	ds_read_b128 v[180:183], v248 offset:21504
	ds_read_b128 v[184:187], v248 offset:22528
	ds_read_b128 v[188:191], v248 offset:23552
	global_load_lds_dwordx4 v[208:209], off
	s_add_i32 m0, s4, 0x2000
	s_add_u32 s4, s30, 0x40000
	v_lshl_add_u64 v[210:211], s[30:31], 0, v[198:199]
	s_addc_u32 s5, s31, 0
	s_add_i32 s70, s65, s68
	global_load_lds_dwordx4 v[210:211], off
	v_lshl_add_u64 v[212:213], s[4:5], 0, v[194:195]
	s_mov_b32 m0, s70
	v_lshl_add_u64 v[214:215], s[34:35], 0, v[196:197]
	global_load_lds_dwordx4 v[212:213], off
	v_lshl_add_u64 v[212:213], s[4:5], 0, v[198:199]
	s_add_i32 m0, s70, 0x2000
	s_nop 0
	global_load_lds_dwordx4 v[212:213], off
	v_lshl_add_u64 v[212:213], s[34:35], 0, v[192:193]
	s_mov_b32 m0, s27
	s_nop 0
	global_load_lds_dwordx4 v[212:213], off
	s_mov_b32 m0, s38
	s_nop 0
	global_load_lds_dwordx4 v[214:215], off
	s_waitcnt vmcnt(8)
	s_waitcnt lgkmcnt(0)
	s_barrier
; #define PG8_STAGE(bufoff, gbase, voff) do { _Pragma("unroll") for (int _i = 0; _i < 2; ++_i) \
;         __builtin_amdgcn_global_load_lds((const unsigned*)((const char*)(gbase) + (voff)[_i]), (LAS unsigned*)(lds + (bufoff) + ldsw + _i * 8192), 16, 0, 0); } while (0)
; #define PG8_LDA(dst, b, h) do { _Pragma("unroll") for (int m = 0; m < 4; ++m) _Pragma("unroll") for (int k = 0; k < 2; ++k) dst[m][k] = *(const LAS bf16x8*)(lds + PG8_SA(b, h) + aoff + m * 2048 + k * 1024); } while (0)
; #define PG8_LDB(dst, b, h) do { _Pragma("unroll") for (int n = 0; n < 2; ++n) _Pragma("unroll") for (int k = 0; k < 2; ++k) dst[n][k] = *(const LAS bf16x8*)(lds + PG8_SB(b, h) + boff + n * 2048 + k * 1024); } while (0)
; #define PG8_MMA(ai, bj, At, Bt) do { __builtin_amdgcn_s_setprio(1); _Pragma("unroll") for (int m = 0; m < 4; ++m) _Pragma("unroll") for (int n = 0; n < 2; ++n) _Pragma("unroll") for (int k = 0; k < 2; ++k) \
;         acc[ai][bj][m][n] = __builtin_amdgcn_mfma_f32_16x16x32_bf16(Bt[n][k], At[m][k], acc[ai][bj][m][n], 0, 0, 0); __builtin_amdgcn_s_setprio(0); } while (0)
; #define PG8_WAIT_V(n) asm volatile("s_waitcnt vmcnt(" #n ")" ::: "memory")
; #define PG8_WAIT_L(n) asm volatile("s_waitcnt lgkmcnt(" #n ")" ::: "memory")
; #define PG8_BAR __builtin_amdgcn_s_barrier()
; #define PG8_SCHED __builtin_amdgcn_sched_barrier(0)
; template <class Epi>
; __device__ __forceinline__ void gemm_phase(LAS unsigned char* lds, const Gemm g, const StaticOrder& S, const Epi& E, const int wid) {
;     ...
;             PG8_WAIT_V(8); PG8_WAIT_L(0); PG8_BAR; PG8_MMA(1, 0, At, B0); PG8_MMA(1, 1, At, B1); PG8_BAR; PG8_SCHED;
;             PG8_LDB(B0, 1, 0); PG8_LDB(B1, 1, 1); PG8_SCHED; PG8_LDA(At, 1, 0); PG8_STAGE(PG8_SA(0, 1), a2 + hsA, voffA);
;             PG8_WAIT_V(8); PG8_WAIT_L(0); PG8_BAR; PG8_MMA(0, 0, At, B0); PG8_MMA(0, 1, At, B1); PG8_BAR; PG8_SCHED;
;             PG8_LDA(At, 1, 1); PG8_STAGE(PG8_SB(1, 0), b3, voffB); PG8_STAGE(PG8_SB(1, 1), b3 + hsB, voffB); PG8_STAGE(PG8_SA(1, 0), a3, voffA);
;             PG8_WAIT_V(8); PG8_WAIT_L(0); PG8_BAR; PG8_MMA(1, 0, At, B0); PG8_MMA(1, 1, At, B1); PG8_BAR; PG8_SCHED;
	s_setprio 1
	s_waitcnt lgkmcnt(0)
	v_mfma_f32_16x16x32_bf16 v[60:63], v[120:123], v[160:163], v[60:63]
	v_mfma_f32_16x16x32_bf16 v[56:59], v[132:135], v[160:163], v[56:59]
	v_mfma_f32_16x16x32_bf16 v[44:47], v[120:123], v[168:171], v[44:47]
	v_mfma_f32_16x16x32_bf16 v[40:43], v[132:135], v[168:171], v[40:43]
	v_mfma_f32_16x16x32_bf16 v[28:31], v[120:123], v[176:179], v[28:31]
	v_mfma_f32_16x16x32_bf16 v[24:27], v[132:135], v[176:179], v[24:27]
	v_mfma_f32_16x16x32_bf16 v[12:15], v[120:123], v[184:187], v[12:15]
	v_mfma_f32_16x16x32_bf16 v[8:11], v[132:135], v[184:187], v[8:11]
	v_mfma_f32_16x16x32_bf16 v[60:63], v[124:127], v[164:167], v[60:63]
	v_mfma_f32_16x16x32_bf16 v[56:59], v[136:139], v[164:167], v[56:59]
	v_mfma_f32_16x16x32_bf16 v[44:47], v[124:127], v[172:175], v[44:47]
	v_mfma_f32_16x16x32_bf16 v[40:43], v[136:139], v[172:175], v[40:43]
	v_mfma_f32_16x16x32_bf16 v[28:31], v[124:127], v[180:183], v[28:31]
	v_mfma_f32_16x16x32_bf16 v[24:27], v[136:139], v[180:183], v[24:27]
	v_mfma_f32_16x16x32_bf16 v[12:15], v[124:127], v[188:191], v[12:15]
	v_mfma_f32_16x16x32_bf16 v[8:11], v[136:139], v[188:191], v[8:11]
	s_setprio 0
	s_setprio 1
	v_mfma_f32_16x16x32_bf16 v[52:55], v[144:147], v[160:163], v[52:55]
	v_mfma_f32_16x16x32_bf16 v[48:51], v[152:155], v[160:163], v[48:51]
	v_mfma_f32_16x16x32_bf16 v[36:39], v[144:147], v[168:171], v[36:39]
	v_mfma_f32_16x16x32_bf16 v[32:35], v[152:155], v[168:171], v[32:35]
	v_mfma_f32_16x16x32_bf16 v[20:23], v[144:147], v[176:179], v[20:23]
	v_mfma_f32_16x16x32_bf16 v[16:19], v[152:155], v[176:179], v[16:19]
	v_mfma_f32_16x16x32_bf16 v[4:7], v[144:147], v[184:187], v[4:7]
	v_mfma_f32_16x16x32_bf16 v[0:3], v[152:155], v[184:187], v[0:3]
	v_mfma_f32_16x16x32_bf16 v[52:55], v[148:151], v[164:167], v[52:55]
	v_mfma_f32_16x16x32_bf16 v[48:51], v[156:159], v[164:167], v[48:51]
	v_mfma_f32_16x16x32_bf16 v[36:39], v[148:151], v[172:175], v[36:39]
	v_mfma_f32_16x16x32_bf16 v[32:35], v[156:159], v[172:175], v[32:35]
	v_mfma_f32_16x16x32_bf16 v[20:23], v[148:151], v[180:183], v[20:23]
	v_mfma_f32_16x16x32_bf16 v[16:19], v[156:159], v[180:183], v[16:19]
	v_mfma_f32_16x16x32_bf16 v[4:7], v[148:151], v[188:191], v[4:7]
	v_mfma_f32_16x16x32_bf16 v[0:3], v[156:159], v[188:191], v[0:3]
	s_setprio 0
	s_barrier
	s_add_i32 s70, 0, 0x18000
	s_add_i32 s71, 0, 0x1c000
	v_add_u32_e32 v136, s70, v245
	v_add_u32_e32 v156, s71, v245
	ds_read_b128 v[120:123], v136
	ds_read_b128 v[124:127], v136 offset:1024
	ds_read_b128 v[132:135], v136 offset:2048
	ds_read_b128 v[136:139], v136 offset:3072
	ds_read_b128 v[144:147], v156
	ds_read_b128 v[148:151], v156 offset:1024
	ds_read_b128 v[152:155], v156 offset:2048
	ds_read_b128 v[156:159], v156 offset:3072
	s_add_u32 s4, s34, 0x40000
	s_addc_u32 s5, s35, 0
	s_mov_b32 m0, s39
	v_lshl_add_u64 v[216:217], s[4:5], 0, v[192:193]
	ds_read_b128 v[160:163], v248 offset:32768
	ds_read_b128 v[164:167], v248 offset:33792
	ds_read_b128 v[168:171], v248 offset:34816
	ds_read_b128 v[172:175], v248 offset:35840
	ds_read_b128 v[176:179], v248 offset:36864
	ds_read_b128 v[180:183], v248 offset:37888
	ds_read_b128 v[184:187], v248 offset:38912
	ds_read_b128 v[188:191], v248 offset:39936
	global_load_lds_dwordx4 v[216:217], off
	v_lshl_add_u64 v[216:217], s[4:5], 0, v[196:197]
	s_mov_b32 m0, s50
	s_nop 0
	global_load_lds_dwordx4 v[216:217], off
	s_waitcnt vmcnt(8)
	s_waitcnt lgkmcnt(0)
	s_barrier
	s_setprio 1
	s_waitcnt lgkmcnt(0)
	v_mfma_f32_16x16x32_bf16 v[140:143], v[120:123], v[160:163], v[140:143]
	v_mfma_f32_16x16x32_bf16 v[128:131], v[132:135], v[160:163], v[128:131]
	v_mfma_f32_16x16x32_bf16 v[108:111], v[120:123], v[168:171], v[108:111]
	v_mfma_f32_16x16x32_bf16 v[104:107], v[132:135], v[168:171], v[104:107]
	v_mfma_f32_16x16x32_bf16 v[92:95], v[120:123], v[176:179], v[92:95]
	v_mfma_f32_16x16x32_bf16 v[88:91], v[132:135], v[176:179], v[88:91]
	v_mfma_f32_16x16x32_bf16 v[76:79], v[120:123], v[184:187], v[76:79]
	v_mfma_f32_16x16x32_bf16 v[72:75], v[132:135], v[184:187], v[72:75]
	v_mfma_f32_16x16x32_bf16 v[140:143], v[124:127], v[164:167], v[140:143]
	v_mfma_f32_16x16x32_bf16 v[128:131], v[136:139], v[164:167], v[128:131]
	v_mfma_f32_16x16x32_bf16 v[108:111], v[124:127], v[172:175], v[108:111]
	v_mfma_f32_16x16x32_bf16 v[104:107], v[136:139], v[172:175], v[104:107]
	v_mfma_f32_16x16x32_bf16 v[92:95], v[124:127], v[180:183], v[92:95]
	v_mfma_f32_16x16x32_bf16 v[88:91], v[136:139], v[180:183], v[88:91]
	v_mfma_f32_16x16x32_bf16 v[76:79], v[124:127], v[188:191], v[76:79]
	v_mfma_f32_16x16x32_bf16 v[72:75], v[136:139], v[188:191], v[72:75]
	s_setprio 0
	s_setprio 1
	v_mfma_f32_16x16x32_bf16 v[116:119], v[144:147], v[160:163], v[116:119]
	v_mfma_f32_16x16x32_bf16 v[112:115], v[152:155], v[160:163], v[112:115]
	v_mfma_f32_16x16x32_bf16 v[100:103], v[144:147], v[168:171], v[100:103]
	v_mfma_f32_16x16x32_bf16 v[96:99], v[152:155], v[168:171], v[96:99]
	v_mfma_f32_16x16x32_bf16 v[84:87], v[144:147], v[176:179], v[84:87]
	v_mfma_f32_16x16x32_bf16 v[80:83], v[152:155], v[176:179], v[80:83]
	v_mfma_f32_16x16x32_bf16 v[68:71], v[144:147], v[184:187], v[68:71]
	v_mfma_f32_16x16x32_bf16 v[64:67], v[152:155], v[184:187], v[64:67]
	v_mfma_f32_16x16x32_bf16 v[116:119], v[148:151], v[164:167], v[116:119]
	v_mfma_f32_16x16x32_bf16 v[112:115], v[156:159], v[164:167], v[112:115]
	v_mfma_f32_16x16x32_bf16 v[100:103], v[148:151], v[172:175], v[100:103]
	v_mfma_f32_16x16x32_bf16 v[96:99], v[156:159], v[172:175], v[96:99]
	v_mfma_f32_16x16x32_bf16 v[84:87], v[148:151], v[180:183], v[84:87]
	v_mfma_f32_16x16x32_bf16 v[80:83], v[156:159], v[180:183], v[80:83]
	v_mfma_f32_16x16x32_bf16 v[68:71], v[148:151], v[188:191], v[68:71]
	v_mfma_f32_16x16x32_bf16 v[64:67], v[156:159], v[188:191], v[64:67]
	s_setprio 0
	s_barrier
; #define PG8_STAGE(bufoff, gbase, voff) do { _Pragma("unroll") for (int _i = 0; _i < 2; ++_i) \
;         __builtin_amdgcn_global_load_lds((const unsigned*)((const char*)(gbase) + (voff)[_i]), (LAS unsigned*)(lds + (bufoff) + ldsw + _i * 8192), 16, 0, 0); } while (0)
; #define PG8_LDA(dst, b, h) do { _Pragma("unroll") for (int m = 0; m < 4; ++m) _Pragma("unroll") for (int k = 0; k < 2; ++k) dst[m][k] = *(const LAS bf16x8*)(lds + PG8_SA(b, h) + aoff + m * 2048 + k * 1024); } while (0)
; #define PG8_MMA(ai, bj, At, Bt) do { __builtin_amdgcn_s_setprio(1); _Pragma("unroll") for (int m = 0; m < 4; ++m) _Pragma("unroll") for (int n = 0; n < 2; ++n) _Pragma("unroll") for (int k = 0; k < 2; ++k) \
;         acc[ai][bj][m][n] = __builtin_amdgcn_mfma_f32_16x16x32_bf16(Bt[n][k], At[m][k], acc[ai][bj][m][n], 0, 0, 0); __builtin_amdgcn_s_setprio(0); } while (0)
; #define PG8_WAIT_V(n) asm volatile("s_waitcnt vmcnt(" #n ")" ::: "memory")
; #define PG8_WAIT_L(n) asm volatile("s_waitcnt lgkmcnt(" #n ")" ::: "memory")
; #define PG8_BAR __builtin_amdgcn_s_barrier()
; #define PG8_SCHED __builtin_amdgcn_sched_barrier(0)
; template <class Epi>
; __device__ __forceinline__ void gemm_phase(LAS unsigned char* lds, const Gemm g, const StaticOrder& S, const Epi& E, const int wid) {
;     ...
;             PG8_LDA(At, 1, 1); PG8_STAGE(PG8_SB(1, 0), b3, voffB); PG8_STAGE(PG8_SB(1, 1), b3 + hsB, voffB); PG8_STAGE(PG8_SA(1, 0), a3, voffA);
;             PG8_WAIT_V(8); PG8_WAIT_L(0); PG8_BAR; PG8_MMA(1, 0, At, B0); PG8_MMA(1, 1, At, B1); PG8_BAR; PG8_SCHED;
;         }
	s_add_i32 s4, s70, s68
	v_lshl_add_u64 v[208:209], v[208:209], 0, s[10:11]
	s_mov_b32 m0, s4
	ds_read_b128 v[160:163], v248 offset:49152
	ds_read_b128 v[164:167], v248 offset:50176
	ds_read_b128 v[168:171], v248 offset:51200
	ds_read_b128 v[172:175], v248 offset:52224
	ds_read_b128 v[176:179], v248 offset:53248
	ds_read_b128 v[180:183], v248 offset:54272
	ds_read_b128 v[184:187], v248 offset:55296
	ds_read_b128 v[188:191], v248 offset:56320
	global_load_lds_dwordx4 v[208:209], off
	s_add_i32 m0, s4, 0x2000
	s_add_u32 s4, s30, 0x40080
	v_lshl_add_u64 v[208:209], v[210:211], 0, s[10:11]
	s_addc_u32 s5, s31, 0
	s_add_i32 s30, s71, s68
	global_load_lds_dwordx4 v[208:209], off
	v_lshl_add_u64 v[208:209], s[4:5], 0, v[194:195]
	s_mov_b32 m0, s30
	s_nop 0
	global_load_lds_dwordx4 v[208:209], off
	v_lshl_add_u64 v[208:209], s[4:5], 0, v[198:199]
	s_add_i32 m0, s30, 0x2000
	s_nop 0
	global_load_lds_dwordx4 v[208:209], off
	v_lshl_add_u64 v[208:209], v[212:213], 0, s[10:11]
	s_mov_b32 m0, s58
	s_nop 0
	global_load_lds_dwordx4 v[208:209], off
	v_lshl_add_u64 v[208:209], v[214:215], 0, s[10:11]
	s_mov_b32 m0, s59
	s_nop 0
	global_load_lds_dwordx4 v[208:209], off
	s_waitcnt vmcnt(8)
	s_waitcnt lgkmcnt(0)
	s_barrier
	s_setprio 1
	s_waitcnt lgkmcnt(0)
	v_mfma_f32_16x16x32_bf16 v[60:63], v[120:123], v[160:163], v[60:63]
	v_mfma_f32_16x16x32_bf16 v[56:59], v[132:135], v[160:163], v[56:59]
	v_mfma_f32_16x16x32_bf16 v[44:47], v[120:123], v[168:171], v[44:47]
	v_mfma_f32_16x16x32_bf16 v[40:43], v[132:135], v[168:171], v[40:43]
	v_mfma_f32_16x16x32_bf16 v[28:31], v[120:123], v[176:179], v[28:31]
	v_mfma_f32_16x16x32_bf16 v[24:27], v[132:135], v[176:179], v[24:27]
	v_mfma_f32_16x16x32_bf16 v[12:15], v[120:123], v[184:187], v[12:15]
	v_mfma_f32_16x16x32_bf16 v[8:11], v[132:135], v[184:187], v[8:11]
	v_mfma_f32_16x16x32_bf16 v[60:63], v[124:127], v[164:167], v[60:63]
	v_mfma_f32_16x16x32_bf16 v[56:59], v[136:139], v[164:167], v[56:59]
	v_mfma_f32_16x16x32_bf16 v[44:47], v[124:127], v[172:175], v[44:47]
	v_mfma_f32_16x16x32_bf16 v[40:43], v[136:139], v[172:175], v[40:43]
	v_mfma_f32_16x16x32_bf16 v[28:31], v[124:127], v[180:183], v[28:31]
	v_mfma_f32_16x16x32_bf16 v[24:27], v[136:139], v[180:183], v[24:27]
	v_mfma_f32_16x16x32_bf16 v[12:15], v[124:127], v[188:191], v[12:15]
	v_mfma_f32_16x16x32_bf16 v[8:11], v[136:139], v[188:191], v[8:11]
	s_setprio 0
	s_setprio 1
	v_mfma_f32_16x16x32_bf16 v[52:55], v[144:147], v[160:163], v[52:55]
	v_mfma_f32_16x16x32_bf16 v[48:51], v[152:155], v[160:163], v[48:51]
	v_mfma_f32_16x16x32_bf16 v[36:39], v[144:147], v[168:171], v[36:39]
	v_mfma_f32_16x16x32_bf16 v[32:35], v[152:155], v[168:171], v[32:35]
	v_mfma_f32_16x16x32_bf16 v[20:23], v[144:147], v[176:179], v[20:23]
	v_mfma_f32_16x16x32_bf16 v[16:19], v[152:155], v[176:179], v[16:19]
	v_mfma_f32_16x16x32_bf16 v[4:7], v[144:147], v[184:187], v[4:7]
	v_mfma_f32_16x16x32_bf16 v[0:3], v[152:155], v[184:187], v[0:3]
	v_mfma_f32_16x16x32_bf16 v[52:55], v[148:151], v[164:167], v[52:55]
	v_mfma_f32_16x16x32_bf16 v[48:51], v[156:159], v[164:167], v[48:51]
	v_mfma_f32_16x16x32_bf16 v[36:39], v[148:151], v[172:175], v[36:39]
	v_mfma_f32_16x16x32_bf16 v[32:35], v[156:159], v[172:175], v[32:35]
	v_mfma_f32_16x16x32_bf16 v[20:23], v[148:151], v[180:183], v[20:23]
	v_mfma_f32_16x16x32_bf16 v[16:19], v[156:159], v[180:183], v[16:19]
	v_mfma_f32_16x16x32_bf16 v[4:7], v[148:151], v[188:191], v[4:7]
	v_mfma_f32_16x16x32_bf16 v[0:3], v[156:159], v[188:191], v[0:3]
	s_setprio 0
	s_barrier
	s_add_i32 s74, s74, 2
	s_add_u32 s67, s67, 0x100
	s_addc_u32 s73, s73, 0
	s_add_u32 s28, s28, 0x100
	s_addc_u32 s29, s29, 0
	s_cmp_gt_u32 s74, 13
	s_cbranch_scc0 .LBB0_1091
; __device__ __forceinline__ int lane_id_asm() { int l; asm volatile("v_mbcnt_lo_u32_b32 %0, -1, 0\n\tv_mbcnt_hi_u32_b32 %0, -1, %0" : "=v"(l)); return l; }
; #define PG8_BAR __builtin_amdgcn_s_barrier()
; template <class Epi>
; __device__ __forceinline__ void gemm_phase(LAS unsigned char* lds, const Gemm g, const StaticOrder& S, const Epi& E, const int wid) {
;     ...
;         if (wr == 0) PG8_BAR;
;         E(acc, cur, wid);
;     __device__ __forceinline__ void operator()(const Acc& acc, const pg8::Unit& u, int wid) const {
;         const int lane_ = lane_id_asm(), wr = wid >> 2, wc = wid & 3, fr = lane_ & 15, fq = lane_ >> 4;
;         const int row0 = u.pm * 256 + wr * 64 + fr, col0 = u.pn * 256 + wc * 32 + 8 * fq;
;         float r2[8];
; #pragma unroll
;         for (int i = 0; i < 8; ++i) r2[i] = ssq2 ? ssq2[row0 + (i >> 2) * 128 + (i & 3) * 16] : 0.f;
;         u32x4 bv[2][4][2];
; #pragma unroll
;         for (int ai = 0; ai < 2; ++ai)
; #pragma unroll
;             for (int m = 0; m < 4; ++m)
; #pragma unroll
;                 for (int bj = 0; bj < 2; ++bj) bv[ai][m][bj] = *(const u32x4*)(base + (size_t)(row0 + ai * 128 + m * 16) * 1024 + col0 + bj * 128);
; #pragma unroll
;         for (int ai = 0; ai < 2; ++ai) {
; #pragma unroll
;             for (int m = 0; m < 4; ++m) {
;                 const int row = row0 + ai * 128 + m * 16; float sq = 0.f;
;                 const float rr = ssq2 ? __builtin_amdgcn_rcpf(r2[ai * 4 + m] * (1.f / 1024.f) + EPS) : 1.f;
; #pragma unroll
;                 for (int bj = 0; bj < 2; ++bj) {
;                     const u32x4 b4 = bv[ai][m][bj];
;                     const f32x4 o0 = (f32x4){bflo(b4.x), bfhi(b4.x), bflo(b4.y), bfhi(b4.y)} + acc[ai][bj][m][0] * rr;
;                     const f32x4 o1 = (f32x4){bflo(b4.z), bfhi(b4.z), bflo(b4.w), bfhi(b4.w)} + acc[ai][bj][m][1] * rr;
;                     *(u32x4*)(hb + (size_t)row * 1024 + col0 + bj * 128) = pack8(o0, o1);
;                     sq += (o0[0] * o0[0] + o0[1] * o0[1]) + (o0[2] * o0[2] + o0[3] * o0[3]) + (o1[0] * o1[0] + o1[1] * o1[1]) + (o1[2] * o1[2] + o1[3] * o1[3]);
;                 }
;                 if (ssq_out) { sq += __shfl_xor(sq, 16); sq += __shfl_xor(sq, 32); if (fq == 0) atomicAdd(ssq_out + row, sq); }
.LBB0_1094:
	v_mbcnt_lo_u32_b32 v250, -1, 0
	v_mbcnt_hi_u32_b32 v250, -1, v250
	s_lshl_b32 s0, s0, 8
	v_ashrrev_i32_e32 v120, 1, v250
	s_lshl_b32 s1, s26, 8
	v_and_b32_e32 v120, -8, v120
	s_or_b32 s0, s0, s69
	s_add_i32 s1, s1, s60
	v_add_u32_e32 v208, s0, v120
	v_and_or_b32 v238, v250, 15, s1
	v_ashrrev_i32_e32 v209, 31, v208
	v_lshlrev_b64 v[240:241], 1, v[208:209]
	v_ashrrev_i32_e32 v239, 31, v238
	v_lshl_add_u64 v[120:121], s[52:53], 0, v[240:241]
	v_lshlrev_b64 v[242:243], 11, v[238:239]
	v_lshl_add_u64 v[122:123], v[120:121], 0, v[242:243]
	global_load_dwordx4 v[188:191], v[122:123], off
	global_load_dwordx4 v[184:187], v[122:123], off offset:256
	v_or_b32_e32 v234, 16, v238
	v_ashrrev_i32_e32 v235, 31, v234
	v_or_b32_e32 v230, 32, v238
	v_lshlrev_b64 v[236:237], 11, v[234:235]
	v_ashrrev_i32_e32 v231, 31, v230
	v_or_b32_e32 v226, 48, v238
	v_add_u32_e32 v220, 0x80, v238
	v_lshl_add_u64 v[122:123], v[120:121], 0, v[236:237]
	v_lshlrev_b64 v[232:233], 11, v[230:231]
	v_ashrrev_i32_e32 v227, 31, v226
	v_ashrrev_i32_e32 v221, 31, v220
	global_load_dwordx4 v[180:183], v[122:123], off
	global_load_dwordx4 v[176:179], v[122:123], off offset:256
	v_lshl_add_u64 v[122:123], v[120:121], 0, v[232:233]
	v_lshlrev_b64 v[228:229], 11, v[226:227]
	v_add_u32_e32 v218, 0x90, v238
	global_load_dwordx4 v[172:175], v[122:123], off
	global_load_dwordx4 v[168:171], v[122:123], off offset:256
	v_lshl_add_u64 v[122:123], v[120:121], 0, v[228:229]
	v_lshlrev_b64 v[224:225], 11, v[220:221]
	v_ashrrev_i32_e32 v219, 31, v218
	v_add_u32_e32 v214, 0xa0, v238
	v_add_u32_e32 v210, 0xb0, v238
	global_load_dwordx4 v[164:167], v[122:123], off
	global_load_dwordx4 v[160:163], v[122:123], off offset:256
	v_lshl_add_u64 v[122:123], v[120:121], 0, v[224:225]
	v_lshlrev_b64 v[222:223], 11, v[218:219]
	v_ashrrev_i32_e32 v215, 31, v214
	v_ashrrev_i32_e32 v211, 31, v210
	global_load_dwordx4 v[156:159], v[122:123], off
	global_load_dwordx4 v[152:155], v[122:123], off offset:256
	v_lshl_add_u64 v[122:123], v[120:121], 0, v[222:223]
	v_lshlrev_b64 v[216:217], 11, v[214:215]
	v_lshlrev_b64 v[212:213], 11, v[210:211]
	global_load_dwordx4 v[148:151], v[122:123], off
	global_load_dwordx4 v[144:147], v[122:123], off offset:256
	v_lshl_add_u64 v[122:123], v[120:121], 0, v[216:217]
	v_lshl_add_u64 v[120:121], v[120:121], 0, v[212:213]
	global_load_dwordx4 v[136:139], v[122:123], off
	global_load_dwordx4 v[124:127], v[122:123], off offset:256
	global_load_dwordx4 v[132:135], v[120:121], off
	s_nop 0
	global_load_dwordx4 v[120:123], v[120:121], off offset:256
	v_cmp_gt_u32_e32 vcc, 16, v250
	v_lshl_add_u64 v[242:243], s[42:43], 0, v[242:243]
	v_lshl_add_u64 v[240:241], v[242:243], 0, v[240:241]
	s_waitcnt vmcnt(0)
	v_lshlrev_b32_e32 v250, 16, v188
	v_and_b32_e32 v251, 0xffff0000, v188
	v_lshlrev_b32_e32 v188, 16, v189
	v_and_b32_e32 v189, 0xffff0000, v189
	v_pk_add_f32 v[142:143], v[142:143], v[188:189]
	v_lshlrev_b32_e32 v188, 16, v190
	v_and_b32_e32 v189, 0xffff0000, v190
	v_lshlrev_b32_e32 v190, 16, v191
	v_and_b32_e32 v191, 0xffff0000, v191
	v_pk_add_f32 v[140:141], v[140:141], v[250:251]
	v_pk_add_f32 v[190:191], v[130:131], v[190:191]
	v_pk_add_f32 v[188:189], v[128:129], v[188:189]
	v_cvt_pk_bf16_f32 v128, v140, v141
	v_cvt_pk_bf16_f32 v129, v142, v143
	v_cvt_pk_bf16_f32 v130, v188, v189
	v_cvt_pk_bf16_f32 v131, v190, v191
	flat_store_dwordx4 v[240:241], v[128:131]
	s_nop 1
	v_lshlrev_b32_e32 v128, 16, v184
	v_and_b32_e32 v129, 0xffff0000, v184
	v_lshlrev_b32_e32 v130, 16, v185
	v_and_b32_e32 v131, 0xffff0000, v185
	v_pk_add_f32 v[118:119], v[118:119], v[130:131]
	v_pk_add_f32 v[116:117], v[116:117], v[128:129]
	v_lshlrev_b32_e32 v128, 16, v186
	v_and_b32_e32 v129, 0xffff0000, v186
	v_lshlrev_b32_e32 v130, 16, v187
	v_and_b32_e32 v131, 0xffff0000, v187
	v_pk_add_f32 v[130:131], v[114:115], v[130:131]
	v_pk_add_f32 v[128:129], v[112:113], v[128:129]
	v_cvt_pk_bf16_f32 v112, v116, v117
	v_cvt_pk_bf16_f32 v113, v118, v119
	v_cvt_pk_bf16_f32 v114, v128, v129
	v_cvt_pk_bf16_f32 v115, v130, v131
	flat_store_dwordx4 v[240:241], v[112:115] offset:256
	s_nop 1
	v_mul_f32_e32 v114, v141, v141
	v_mul_f32_e32 v115, v143, v143
	v_fmac_f32_e32 v114, v140, v140
	v_fmac_f32_e32 v115, v142, v142
	v_mul_f32_e32 v113, v189, v189
	v_add_f32_e32 v114, v114, v115
	v_mul_f32_e32 v115, v117, v117
	v_mul_f32_e32 v112, v191, v191
	v_fmac_f32_e32 v113, v188, v188
	v_fmac_f32_e32 v115, v116, v116
	v_mul_f32_e32 v116, v119, v119
	v_fmac_f32_e32 v112, v190, v190
	v_add_f32_e32 v113, v113, v114
	v_mul_f32_e32 v114, v129, v129
	v_fmac_f32_e32 v116, v118, v118
	v_add_f32_e32 v112, v112, v113
	v_mul_f32_e32 v113, v131, v131
	v_fmac_f32_e32 v114, v128, v128
	v_add_f32_e32 v115, v115, v116
	v_fmac_f32_e32 v113, v130, v130
	v_add_f32_e32 v114, v114, v115
	v_add_f32_e32 v113, v113, v114
	v_and_b32_e32 v114, 64, v249
	v_add_f32_e32 v113, v112, v113
	v_xor_b32_e32 v112, 16, v249
	v_add_u32_e32 v115, 64, v114
	v_cmp_lt_i32_e64 s[0:1], v112, v115
	s_nop 1
	v_cndmask_b32_e64 v112, v249, v112, s[0:1]
	v_lshlrev_b32_e32 v112, 2, v112
	ds_bpermute_b32 v114, v112, v113
	s_waitcnt lgkmcnt(0)
	v_add_f32_e32 v114, v113, v114
	v_xor_b32_e32 v113, 32, v249
	v_cmp_lt_i32_e64 s[0:1], v113, v115
	s_nop 1
	v_cndmask_b32_e64 v113, v249, v113, s[0:1]
	v_lshlrev_b32_e32 v113, 2, v113
	ds_bpermute_b32 v115, v113, v114
	s_and_saveexec_b64 s[0:1], vcc
	s_cbranch_execz .LBB0_1096
	v_lshl_add_u64 v[116:117], v[238:239], 2, s[46:47]
	s_waitcnt lgkmcnt(0)
	v_add_f32_e32 v114, v114, v115
	flat_atomic_add_f32 v[116:117], v114

; __device__ __forceinline__ int lane_id_asm() { int l; asm volatile("v_mbcnt_lo_u32_b32 %0, -1, 0\n\tv_mbcnt_hi_u32_b32 %0, -1, %0" : "=v"(l)); return l; }
; #define PG8_BAR __builtin_amdgcn_s_barrier()
; __device__ __forceinline__ u32x4 pack8(f32x4 a, f32x4 b) { u32x4 w; w.x = pk2(a[0], a[1]); w.y = pk2(a[2], a[3]); w.z = pk2(b[0], b[1]); w.w = pk2(b[2], b[3]); return w; }
; template <class Epi>
; __device__ __forceinline__ void gemm_phase(LAS unsigned char* lds, const Gemm g, const StaticOrder& S, const Epi& E, const int wid) {
;     ...
;         if (wr == 0) PG8_BAR;
;         E(acc, cur, wid);
;     __device__ __forceinline__ void operator()(const Acc& acc, const pg8::Unit& u, int wid) const {
;         const int lane_ = lane_id_asm(), wr = wid >> 2, wc = wid & 3, fr = lane_ & 15, fq = lane_ >> 4;
;         const int row0 = u.pm * 256 + wr * 64 + fr, col0 = u.pn * 256 + wc * 32 + 8 * fq;
;         float scv[8];
; #pragma unroll
;         for (int i = 0; i < 8; ++i) scv[i] = ssq ? ssq[row0 + (i >> 2) * 128 + (i & 3) * 16] : 0.f;
; #pragma unroll
;         for (int ai = 0; ai < 2; ++ai)
; #pragma unroll
;             for (int m = 0; m < 4; ++m) {
;                 const int row = row0 + ai * 128 + m * 16;
;                 const float sc = ssq ? __builtin_amdgcn_rsqf(scv[ai * 4 + m] * inv_n + EPS) : 1.f;
; #pragma unroll
;                 for (int bj = 0; bj < 2; ++bj) {
;                     f32x4 v0 = acc[ai][bj][m][0] * sc, v1 = acc[ai][bj][m][1] * sc;
;                     if (ACT == 1) {
; #pragma unroll
;                         for (int e = 0; e < 4; ++e) { float a = fmaxf(v0[e], 0.f), b = fmaxf(v1[e], 0.f); v0[e] = a * a; v1[e] = b * b; }
;                     }
;                     *(u32x4*)(O + (size_t)row * ldc + col0 + bj * 128) = pack8(v0, v1);
.LBB0_1178:
	s_lshl_b32 s23, s30, 8
	v_mbcnt_lo_u32_b32 v149, -1, 0
	v_mbcnt_hi_u32_b32 v149, -1, v149
	s_add_i32 s23, s23, s65
	v_and_or_b32 v148, v149, 15, s23
	v_ashrrev_i32_e32 v149, 1, v149
	s_lshl_b32 s23, s79, 8
	v_and_b32_e32 v149, -8, v149
	s_or_b32 s23, s23, s69
	v_add_u32_e32 v150, s23, v149
	v_mov_b32_e32 v149, 0
	v_mov_b32_e32 v151, 0
	v_lshlrev_b64 v[152:153], 13, v[148:149]
	v_lshl_add_u64 v[152:153], s[44:45], 0, v[152:153]
	v_lshlrev_b64 v[150:151], 1, v[150:151]
	v_lshl_add_u64 v[152:153], v[152:153], 0, v[150:151]
	v_max_f32_e32 v124, 0, v124
	v_max_f32_e32 v125, 0, v125
	v_max_f32_e32 v126, 0, v126
	v_max_f32_e32 v127, 0, v127
	v_max_f32_e32 v120, 0, v120
	v_max_f32_e32 v121, 0, v121
	v_max_f32_e32 v122, 0, v122
	v_max_f32_e32 v123, 0, v123
	v_pk_mul_f32 v[124:125], v[124:125], v[124:125]
	v_pk_mul_f32 v[126:127], v[126:127], v[126:127]
	v_pk_mul_f32 v[120:121], v[120:121], v[120:121]
	v_pk_mul_f32 v[122:123], v[122:123], v[122:123]
	v_cvt_pk_bf16_f32 v124, v124, v125
	v_cvt_pk_bf16_f32 v125, v126, v127
	v_cvt_pk_bf16_f32 v126, v120, v121
	v_cvt_pk_bf16_f32 v127, v122, v123
	flat_store_dwordx4 v[152:153], v[124:127]
	v_max_f32_e32 v116, 0, v116
	v_max_f32_e32 v117, 0, v117
	v_max_f32_e32 v118, 0, v118
	v_max_f32_e32 v119, 0, v119
	v_max_f32_e32 v112, 0, v112
	v_max_f32_e32 v113, 0, v113
	v_max_f32_e32 v114, 0, v114
	v_max_f32_e32 v115, 0, v115
	v_pk_mul_f32 v[116:117], v[116:117], v[116:117]
	v_pk_mul_f32 v[118:119], v[118:119], v[118:119]
	v_pk_mul_f32 v[112:113], v[112:113], v[112:113]
	v_pk_mul_f32 v[114:115], v[114:115], v[114:115]
	v_cvt_pk_bf16_f32 v116, v116, v117
	v_cvt_pk_bf16_f32 v117, v118, v119
	v_cvt_pk_bf16_f32 v118, v112, v113
	v_cvt_pk_bf16_f32 v119, v114, v115
	flat_store_dwordx4 v[152:153], v[116:119] offset:256
	v_add_co_u32_e32 v150, vcc, 0x20000, v152
	s_nop 1
	v_addc_co_u32_e32 v151, vcc, 0, v153, vcc
	v_max_f32_e32 v108, 0, v108
	v_max_f32_e32 v109, 0, v109
	v_max_f32_e32 v110, 0, v110
	v_max_f32_e32 v111, 0, v111
	v_max_f32_e32 v104, 0, v104
	v_max_f32_e32 v105, 0, v105
	v_max_f32_e32 v106, 0, v106
	v_max_f32_e32 v107, 0, v107
	v_pk_mul_f32 v[108:109], v[108:109], v[108:109]
	v_pk_mul_f32 v[110:111], v[110:111], v[110:111]
	v_pk_mul_f32 v[104:105], v[104:105], v[104:105]
	v_pk_mul_f32 v[106:107], v[106:107], v[106:107]
	v_cvt_pk_bf16_f32 v108, v108, v109
	v_cvt_pk_bf16_f32 v109, v110, v111
	v_cvt_pk_bf16_f32 v110, v104, v105
	v_cvt_pk_bf16_f32 v111, v106, v107
	flat_store_dwordx4 v[150:151], v[108:111]
	v_max_f32_e32 v100, 0, v100
	v_max_f32_e32 v101, 0, v101
	v_max_f32_e32 v102, 0, v102
	v_max_f32_e32 v103, 0, v103
	v_max_f32_e32 v96, 0, v96
	v_max_f32_e32 v97, 0, v97
	v_max_f32_e32 v98, 0, v98
	v_max_f32_e32 v99, 0, v99
	v_pk_mul_f32 v[100:101], v[100:101], v[100:101]
	v_pk_mul_f32 v[102:103], v[102:103], v[102:103]
	v_pk_mul_f32 v[96:97], v[96:97], v[96:97]
	v_pk_mul_f32 v[98:99], v[98:99], v[98:99]
	v_cvt_pk_bf16_f32 v100, v100, v101
	v_cvt_pk_bf16_f32 v101, v102, v103
	v_cvt_pk_bf16_f32 v102, v96, v97
	v_cvt_pk_bf16_f32 v103, v98, v99
	flat_store_dwordx4 v[150:151], v[100:103] offset:256
	v_add_co_u32_e32 v150, vcc, 0x40000, v152
	s_nop 1
	v_addc_co_u32_e32 v151, vcc, 0, v153, vcc
	v_max_f32_e32 v92, 0, v92
	v_max_f32_e32 v93, 0, v93
	v_max_f32_e32 v94, 0, v94
	v_max_f32_e32 v95, 0, v95
	v_max_f32_e32 v88, 0, v88
	v_max_f32_e32 v89, 0, v89
	v_max_f32_e32 v90, 0, v90
	v_max_f32_e32 v91, 0, v91
	v_pk_mul_f32 v[92:93], v[92:93], v[92:93]
	v_pk_mul_f32 v[94:95], v[94:95], v[94:95]
	v_pk_mul_f32 v[88:89], v[88:89], v[88:89]
	v_pk_mul_f32 v[90:91], v[90:91], v[90:91]
	v_cvt_pk_bf16_f32 v92, v92, v93
	v_cvt_pk_bf16_f32 v93, v94, v95
	v_cvt_pk_bf16_f32 v94, v88, v89
	v_cvt_pk_bf16_f32 v95, v90, v91
	flat_store_dwordx4 v[150:151], v[92:95]
	v_max_f32_e32 v84, 0, v84
	v_max_f32_e32 v85, 0, v85
	v_max_f32_e32 v86, 0, v86
	v_max_f32_e32 v87, 0, v87
	v_max_f32_e32 v80, 0, v80
	v_max_f32_e32 v81, 0, v81
	v_max_f32_e32 v82, 0, v82
	v_max_f32_e32 v83, 0, v83
	v_pk_mul_f32 v[84:85], v[84:85], v[84:85]
	v_pk_mul_f32 v[86:87], v[86:87], v[86:87]
	v_pk_mul_f32 v[80:81], v[80:81], v[80:81]
	v_pk_mul_f32 v[82:83], v[82:83], v[82:83]
	v_cvt_pk_bf16_f32 v84, v84, v85
	v_cvt_pk_bf16_f32 v85, v86, v87
	v_cvt_pk_bf16_f32 v86, v80, v81
	v_cvt_pk_bf16_f32 v87, v82, v83
	flat_store_dwordx4 v[150:151], v[84:87] offset:256
	v_add_co_u32_e32 v150, vcc, 0x60000, v152
	s_nop 1
	v_addc_co_u32_e32 v151, vcc, 0, v153, vcc
	v_max_f32_e32 v76, 0, v76
	v_max_f32_e32 v77, 0, v77
	v_max_f32_e32 v78, 0, v78
	v_max_f32_e32 v79, 0, v79
	v_max_f32_e32 v72, 0, v72
	v_max_f32_e32 v73, 0, v73
	v_max_f32_e32 v74, 0, v74
	v_max_f32_e32 v75, 0, v75
	v_pk_mul_f32 v[76:77], v[76:77], v[76:77]
	v_pk_mul_f32 v[78:79], v[78:79], v[78:79]
	v_pk_mul_f32 v[72:73], v[72:73], v[72:73]
	v_pk_mul_f32 v[74:75], v[74:75], v[74:75]
	v_cvt_pk_bf16_f32 v76, v76, v77
	v_cvt_pk_bf16_f32 v77, v78, v79
	v_cvt_pk_bf16_f32 v78, v72, v73
	v_cvt_pk_bf16_f32 v79, v74, v75
	flat_store_dwordx4 v[150:151], v[76:79]
	v_max_f32_e32 v68, 0, v68
	v_max_f32_e32 v69, 0, v69
	v_max_f32_e32 v70, 0, v70
	v_max_f32_e32 v71, 0, v71
	v_max_f32_e32 v64, 0, v64
	v_max_f32_e32 v65, 0, v65
	v_max_f32_e32 v66, 0, v66
	v_max_f32_e32 v67, 0, v67
	v_pk_mul_f32 v[68:69], v[68:69], v[68:69]
; #define PG8_BAR __builtin_amdgcn_s_barrier()
; __device__ __forceinline__ u32x4 pack8(f32x4 a, f32x4 b) { u32x4 w; w.x = pk2(a[0], a[1]); w.y = pk2(a[2], a[3]); w.z = pk2(b[0], b[1]); w.w = pk2(b[2], b[3]); return w; }
; template <class Epi>
; __device__ __forceinline__ void gemm_phase(LAS unsigned char* lds, const Gemm g, const StaticOrder& S, const Epi& E, const int wid) {
;     ...
;         if (!has_next) break;
; #pragma unroll
;         for (int a = 0; a < 2; ++a)
; #pragma unroll
;             for (int b = 0; b < 2; ++b)
; #pragma unroll
;                 for (int m = 0; m < 4; ++m)
; #pragma unroll
;                     for (int n = 0; n < 2; ++n) acc[a][b][m][n] = (f32x4){0.f, 0.f, 0.f, 0.f};
;         cur = nxt; cA = nA; cB = nB; ++ui;
;         if (wr == 1) PG8_BAR;
;     }
;     __device__ __forceinline__ void operator()(const Acc& acc, const pg8::Unit& u, int wid) const {
;     ...
;         for (int ai = 0; ai < 2; ++ai)
; #pragma unroll
;             for (int m = 0; m < 4; ++m) {
;                 const int row = row0 + ai * 128 + m * 16;
;                 const float sc = ssq ? __builtin_amdgcn_rsqf(scv[ai * 4 + m] * inv_n + EPS) : 1.f;
; #pragma unroll
;                 for (int bj = 0; bj < 2; ++bj) {
;                     f32x4 v0 = acc[ai][bj][m][0] * sc, v1 = acc[ai][bj][m][1] * sc;
;                     if (ACT == 1) {
; #pragma unroll
;                         for (int e = 0; e < 4; ++e) { float a = fmaxf(v0[e], 0.f), b = fmaxf(v1[e], 0.f); v0[e] = a * a; v1[e] = b * b; }
;                     }
;                     *(u32x4*)(O + (size_t)row * ldc + col0 + bj * 128) = pack8(v0, v1);
	v_pk_mul_f32 v[70:71], v[70:71], v[70:71]
	v_pk_mul_f32 v[64:65], v[64:65], v[64:65]
	v_pk_mul_f32 v[66:67], v[66:67], v[66:67]
	v_cvt_pk_bf16_f32 v68, v68, v69
	v_cvt_pk_bf16_f32 v69, v70, v71
	v_cvt_pk_bf16_f32 v70, v64, v65
	v_cvt_pk_bf16_f32 v71, v66, v67
	flat_store_dwordx4 v[150:151], v[68:71] offset:256
	v_add_co_u32_e32 v150, vcc, 0x100000, v152
	s_nop 1
	v_addc_co_u32_e32 v151, vcc, 0, v153, vcc
	v_max_f32_e32 v60, 0, v60
	v_max_f32_e32 v61, 0, v61
	v_max_f32_e32 v62, 0, v62
	v_max_f32_e32 v63, 0, v63
	v_max_f32_e32 v56, 0, v56
	v_max_f32_e32 v57, 0, v57
	v_max_f32_e32 v58, 0, v58
	v_max_f32_e32 v59, 0, v59
	v_pk_mul_f32 v[60:61], v[60:61], v[60:61]
	v_pk_mul_f32 v[62:63], v[62:63], v[62:63]
	v_pk_mul_f32 v[56:57], v[56:57], v[56:57]
	v_pk_mul_f32 v[58:59], v[58:59], v[58:59]
	v_cvt_pk_bf16_f32 v60, v60, v61
	v_cvt_pk_bf16_f32 v61, v62, v63
	v_cvt_pk_bf16_f32 v62, v56, v57
	v_cvt_pk_bf16_f32 v63, v58, v59
	flat_store_dwordx4 v[150:151], v[60:63]
	v_max_f32_e32 v52, 0, v52
	v_max_f32_e32 v53, 0, v53
	v_max_f32_e32 v54, 0, v54
	v_max_f32_e32 v55, 0, v55
	v_max_f32_e32 v48, 0, v48
	v_max_f32_e32 v49, 0, v49
	v_max_f32_e32 v50, 0, v50
	v_max_f32_e32 v51, 0, v51
	v_pk_mul_f32 v[52:53], v[52:53], v[52:53]
	v_pk_mul_f32 v[54:55], v[54:55], v[54:55]
	v_pk_mul_f32 v[48:49], v[48:49], v[48:49]
	v_pk_mul_f32 v[50:51], v[50:51], v[50:51]
	v_cvt_pk_bf16_f32 v52, v52, v53
	v_cvt_pk_bf16_f32 v53, v54, v55
	v_cvt_pk_bf16_f32 v54, v48, v49
	v_cvt_pk_bf16_f32 v55, v50, v51
	flat_store_dwordx4 v[150:151], v[52:55] offset:256
	v_add_co_u32_e32 v150, vcc, 0x120000, v152
	s_nop 1
	v_addc_co_u32_e32 v151, vcc, 0, v153, vcc
	v_max_f32_e32 v44, 0, v44
	v_max_f32_e32 v45, 0, v45
	v_max_f32_e32 v46, 0, v46
	v_max_f32_e32 v47, 0, v47
	v_max_f32_e32 v40, 0, v40
	v_max_f32_e32 v41, 0, v41
	v_max_f32_e32 v42, 0, v42
	v_max_f32_e32 v43, 0, v43
	v_pk_mul_f32 v[44:45], v[44:45], v[44:45]
	v_pk_mul_f32 v[46:47], v[46:47], v[46:47]
	v_pk_mul_f32 v[40:41], v[40:41], v[40:41]
	v_pk_mul_f32 v[42:43], v[42:43], v[42:43]
	v_cvt_pk_bf16_f32 v44, v44, v45
	v_cvt_pk_bf16_f32 v45, v46, v47
	v_cvt_pk_bf16_f32 v46, v40, v41
	v_cvt_pk_bf16_f32 v47, v42, v43
	flat_store_dwordx4 v[150:151], v[44:47]
	v_max_f32_e32 v36, 0, v36
	v_max_f32_e32 v37, 0, v37
	v_max_f32_e32 v38, 0, v38
	v_max_f32_e32 v39, 0, v39
	v_max_f32_e32 v32, 0, v32
	v_max_f32_e32 v33, 0, v33
	v_max_f32_e32 v34, 0, v34
	v_max_f32_e32 v35, 0, v35
	v_pk_mul_f32 v[36:37], v[36:37], v[36:37]
	v_pk_mul_f32 v[38:39], v[38:39], v[38:39]
	v_pk_mul_f32 v[32:33], v[32:33], v[32:33]
	v_pk_mul_f32 v[34:35], v[34:35], v[34:35]
	v_cvt_pk_bf16_f32 v36, v36, v37
	v_cvt_pk_bf16_f32 v37, v38, v39
	v_cvt_pk_bf16_f32 v38, v32, v33
	v_cvt_pk_bf16_f32 v39, v34, v35
	flat_store_dwordx4 v[150:151], v[36:39] offset:256
	v_add_co_u32_e32 v150, vcc, 0x140000, v152
	s_nop 1
	v_addc_co_u32_e32 v151, vcc, 0, v153, vcc
	v_max_f32_e32 v28, 0, v28
	v_max_f32_e32 v29, 0, v29
	v_max_f32_e32 v30, 0, v30
	v_max_f32_e32 v31, 0, v31
	v_max_f32_e32 v24, 0, v24
	v_max_f32_e32 v25, 0, v25
	v_max_f32_e32 v26, 0, v26
	v_max_f32_e32 v27, 0, v27
	v_pk_mul_f32 v[28:29], v[28:29], v[28:29]
	v_pk_mul_f32 v[30:31], v[30:31], v[30:31]
	v_pk_mul_f32 v[24:25], v[24:25], v[24:25]
	v_pk_mul_f32 v[26:27], v[26:27], v[26:27]
	v_cvt_pk_bf16_f32 v28, v28, v29
	v_cvt_pk_bf16_f32 v29, v30, v31
	v_cvt_pk_bf16_f32 v30, v24, v25
	v_cvt_pk_bf16_f32 v31, v26, v27
	flat_store_dwordx4 v[150:151], v[28:31]
	v_max_f32_e32 v20, 0, v20
	v_max_f32_e32 v21, 0, v21
	v_max_f32_e32 v22, 0, v22
	v_max_f32_e32 v23, 0, v23
	v_max_f32_e32 v16, 0, v16
	v_max_f32_e32 v17, 0, v17
	v_max_f32_e32 v18, 0, v18
	v_max_f32_e32 v19, 0, v19
	v_pk_mul_f32 v[20:21], v[20:21], v[20:21]
	v_pk_mul_f32 v[22:23], v[22:23], v[22:23]
	v_pk_mul_f32 v[16:17], v[16:17], v[16:17]
	v_pk_mul_f32 v[18:19], v[18:19], v[18:19]
	v_cvt_pk_bf16_f32 v20, v20, v21
	v_cvt_pk_bf16_f32 v21, v22, v23
	v_cvt_pk_bf16_f32 v22, v16, v17
	v_cvt_pk_bf16_f32 v23, v18, v19
	flat_store_dwordx4 v[150:151], v[20:23] offset:256
	v_add_co_u32_e32 v150, vcc, 0x160000, v152
	s_nop 1
	v_addc_co_u32_e32 v151, vcc, 0, v153, vcc
	v_max_f32_e32 v12, 0, v12
	v_max_f32_e32 v13, 0, v13
	v_max_f32_e32 v14, 0, v14
	v_max_f32_e32 v15, 0, v15
	v_max_f32_e32 v8, 0, v8
	v_max_f32_e32 v9, 0, v9
	v_max_f32_e32 v10, 0, v10
	v_max_f32_e32 v11, 0, v11
	v_pk_mul_f32 v[12:13], v[12:13], v[12:13]
	v_pk_mul_f32 v[14:15], v[14:15], v[14:15]
	v_pk_mul_f32 v[8:9], v[8:9], v[8:9]
	v_pk_mul_f32 v[10:11], v[10:11], v[10:11]
	v_cvt_pk_bf16_f32 v12, v12, v13
	v_cvt_pk_bf16_f32 v13, v14, v15
	v_cvt_pk_bf16_f32 v14, v8, v9
	v_cvt_pk_bf16_f32 v15, v10, v11
	flat_store_dwordx4 v[150:151], v[12:15]
	v_max_f32_e32 v4, 0, v4
	v_max_f32_e32 v5, 0, v5
	v_max_f32_e32 v6, 0, v6
	v_max_f32_e32 v7, 0, v7
	v_max_f32_e32 v0, 0, v0
	v_max_f32_e32 v1, 0, v1
	v_max_f32_e32 v2, 0, v2
	v_max_f32_e32 v3, 0, v3
	v_pk_mul_f32 v[4:5], v[4:5], v[4:5]
	v_pk_mul_f32 v[6:7], v[6:7], v[6:7]
	v_pk_mul_f32 v[0:1], v[0:1], v[0:1]
	v_pk_mul_f32 v[2:3], v[2:3], v[2:3]
	v_cvt_pk_bf16_f32 v4, v4, v5
	v_cvt_pk_bf16_f32 v5, v6, v7
	v_cvt_pk_bf16_f32 v6, v0, v1
	v_cvt_pk_bf16_f32 v7, v2, v3
	s_andn2_b64 vcc, exec, s[4:5]
	s_mov_b64 s[4:5], -1
	flat_store_dwordx4 v[150:151], v[4:7] offset:256
	s_cbranch_vccnz .LBB0_1167
	s_branch .LBB0_1166

; #define PG8_STAGE(bufoff, gbase, voff) do { _Pragma("unroll") for (int _i = 0; _i < 2; ++_i) \
;         __builtin_amdgcn_global_load_lds((const unsigned*)((const char*)(gbase) + (voff)[_i]), (LAS unsigned*)(lds + (bufoff) + ldsw + _i * 8192), 16, 0, 0); } while (0)
; #define PG8_LDA(dst, b, h) do { _Pragma("unroll") for (int m = 0; m < 4; ++m) _Pragma("unroll") for (int k = 0; k < 2; ++k) dst[m][k] = *(const LAS bf16x8*)(lds + PG8_SA(b, h) + aoff + m * 2048 + k * 1024); } while (0)
; #define PG8_LDB(dst, b, h) do { _Pragma("unroll") for (int n = 0; n < 2; ++n) _Pragma("unroll") for (int k = 0; k < 2; ++k) dst[n][k] = *(const LAS bf16x8*)(lds + PG8_SB(b, h) + boff + n * 2048 + k * 1024); } while (0)
; #define PG8_MMA(ai, bj, At, Bt) do { __builtin_amdgcn_s_setprio(1); _Pragma("unroll") for (int m = 0; m < 4; ++m) _Pragma("unroll") for (int n = 0; n < 2; ++n) _Pragma("unroll") for (int k = 0; k < 2; ++k) \
;         acc[ai][bj][m][n] = __builtin_amdgcn_mfma_f32_16x16x32_bf16(Bt[n][k], At[m][k], acc[ai][bj][m][n], 0, 0, 0); __builtin_amdgcn_s_setprio(0); } while (0)
; #define PG8_WAIT_V(n) asm volatile("s_waitcnt vmcnt(" #n ")" ::: "memory")
; #define PG8_WAIT_L(n) asm volatile("s_waitcnt lgkmcnt(" #n ")" ::: "memory")
; template <class Epi>
; __device__ __forceinline__ void gemm_phase(LAS unsigned char* lds, const Gemm g, const StaticOrder& S, const Epi& E, const int wid) {
;     ...
;         const bool has_next = S.next(ui + 1, nxt);
;         const char* nA = has_next ? (const char*)g.A + (size_t)nxt.pm * tsA : cA; const char* nB = has_next ? (const char*)g.Bt + (size_t)nxt.pn * tsB : cB;
; #pragma unroll 1
;         for (int t = 0; t < nt; t += 2) {
;             const bool last = (t == nt - 2);
;             const char* a1 = cA + (size_t)(t + 1) * kstep;
;             const char* a2 = last ? nA : cA + (size_t)(t + 2) * kstep; const char* b2 = last ? nB : cB + (size_t)(t + 2) * kstep;
;             const char* a3 = a2 + kstep; const char* b3 = b2 + kstep;
;             PG8_LDB(B0, 0, 0); PG8_LDB(B1, 0, 1); PG8_SCHED; PG8_LDA(At, 0, 0); PG8_STAGE(PG8_SA(1, 1), a1 + hsA, voffA);
;             PG8_WAIT_V(8); PG8_WAIT_L(0); PG8_BAR; PG8_MMA(0, 0, At, B0); PG8_MMA(0, 1, At, B1); PG8_BAR; PG8_SCHED;
;             PG8_LDA(At, 0, 1); PG8_STAGE(PG8_SB(0, 0), b2, voffB); PG8_STAGE(PG8_SB(0, 1), b2 + hsB, voffB); PG8_STAGE(PG8_SA(0, 0), a2, voffA);
.LBB0_1245:
	ds_read_b128 v[124:127], v241
	ds_read_b128 v[132:135], v241 offset:1024
	ds_read_b128 v[136:139], v241 offset:2048
	ds_read_b128 v[140:143], v241 offset:3072
	ds_read_b128 v[144:147], v242
	ds_read_b128 v[148:151], v242 offset:1024
	ds_read_b128 v[152:155], v242 offset:2048
	ds_read_b128 v[156:159], v242 offset:3072
	s_add_u32 s28, s26, 0xfff00080
	s_addc_u32 s29, s27, -1
	s_cmp_eq_u32 s74, 60
	s_cselect_b32 s31, s1, s29
	s_cselect_b32 s30, s19, s28
	s_cselect_b32 s29, s17, s73
	s_cselect_b32 s28, s66, s67
	v_lshl_add_u64 v[204:205], s[26:27], 0, v[202:203]
	s_add_i32 m0, s25, 0xc000
	ds_read_b128 v[160:163], v243
	ds_read_b128 v[164:167], v243 offset:1024
	ds_read_b128 v[168:171], v243 offset:2048
	ds_read_b128 v[172:175], v243 offset:3072
	ds_read_b128 v[176:179], v243 offset:4096
	ds_read_b128 v[180:183], v243 offset:5120
	ds_read_b128 v[184:187], v243 offset:6144
	ds_read_b128 v[188:191], v243 offset:7168
	global_load_lds_dwordx4 v[204:205], off
	v_lshl_add_u64 v[204:205], s[26:27], 0, v[200:201]
	s_add_i32 m0, s25, 0xe000
	s_nop 0
	global_load_lds_dwordx4 v[204:205], off
	s_waitcnt vmcnt(8)
	s_waitcnt lgkmcnt(0)
	s_barrier
	s_setprio 1
	s_waitcnt lgkmcnt(0)
	v_mfma_f32_16x16x32_bf16 v[128:131], v[124:127], v[160:163], v[128:131]
	v_mfma_f32_16x16x32_bf16 v[120:123], v[136:139], v[160:163], v[120:123]
	v_mfma_f32_16x16x32_bf16 v[108:111], v[124:127], v[168:171], v[108:111]
	v_mfma_f32_16x16x32_bf16 v[104:107], v[136:139], v[168:171], v[104:107]
	v_mfma_f32_16x16x32_bf16 v[92:95], v[124:127], v[176:179], v[92:95]
	v_mfma_f32_16x16x32_bf16 v[88:91], v[136:139], v[176:179], v[88:91]
	v_mfma_f32_16x16x32_bf16 v[76:79], v[124:127], v[184:187], v[76:79]
	v_mfma_f32_16x16x32_bf16 v[72:75], v[136:139], v[184:187], v[72:75]
	v_mfma_f32_16x16x32_bf16 v[128:131], v[132:135], v[164:167], v[128:131]
	v_mfma_f32_16x16x32_bf16 v[120:123], v[140:143], v[164:167], v[120:123]
	v_mfma_f32_16x16x32_bf16 v[108:111], v[132:135], v[172:175], v[108:111]
	v_mfma_f32_16x16x32_bf16 v[104:107], v[140:143], v[172:175], v[104:107]
	v_mfma_f32_16x16x32_bf16 v[92:95], v[132:135], v[180:183], v[92:95]
	v_mfma_f32_16x16x32_bf16 v[88:91], v[140:143], v[180:183], v[88:91]
	v_mfma_f32_16x16x32_bf16 v[76:79], v[132:135], v[188:191], v[76:79]
	v_mfma_f32_16x16x32_bf16 v[72:75], v[140:143], v[188:191], v[72:75]
	s_setprio 0
	s_setprio 1
	v_mfma_f32_16x16x32_bf16 v[116:119], v[144:147], v[160:163], v[116:119]
	v_mfma_f32_16x16x32_bf16 v[112:115], v[152:155], v[160:163], v[112:115]
	v_mfma_f32_16x16x32_bf16 v[100:103], v[144:147], v[168:171], v[100:103]
	v_mfma_f32_16x16x32_bf16 v[96:99], v[152:155], v[168:171], v[96:99]
	v_mfma_f32_16x16x32_bf16 v[84:87], v[144:147], v[176:179], v[84:87]
	v_mfma_f32_16x16x32_bf16 v[80:83], v[152:155], v[176:179], v[80:83]
	v_mfma_f32_16x16x32_bf16 v[68:71], v[144:147], v[184:187], v[68:71]
	v_mfma_f32_16x16x32_bf16 v[64:67], v[152:155], v[184:187], v[64:67]
	v_mfma_f32_16x16x32_bf16 v[116:119], v[148:151], v[164:167], v[116:119]
	v_mfma_f32_16x16x32_bf16 v[112:115], v[156:159], v[164:167], v[112:115]
	v_mfma_f32_16x16x32_bf16 v[100:103], v[148:151], v[172:175], v[100:103]
	v_mfma_f32_16x16x32_bf16 v[96:99], v[156:159], v[172:175], v[96:99]
	v_mfma_f32_16x16x32_bf16 v[84:87], v[148:151], v[180:183], v[84:87]
	v_mfma_f32_16x16x32_bf16 v[80:83], v[156:159], v[180:183], v[80:83]
	v_mfma_f32_16x16x32_bf16 v[68:71], v[148:151], v[188:191], v[68:71]
	v_mfma_f32_16x16x32_bf16 v[64:67], v[156:159], v[188:191], v[64:67]
	s_setprio 0
	s_barrier
	s_add_i32 s70, s64, s68
	v_lshl_add_u64 v[204:205], s[28:29], 0, v[194:195]
	s_mov_b32 m0, s70
	ds_read_b128 v[160:163], v243 offset:16384
	ds_read_b128 v[164:167], v243 offset:17408
	ds_read_b128 v[168:171], v243 offset:18432
	ds_read_b128 v[172:175], v243 offset:19456
	ds_read_b128 v[176:179], v243 offset:20480
	ds_read_b128 v[180:183], v243 offset:21504
	ds_read_b128 v[184:187], v243 offset:22528
	ds_read_b128 v[188:191], v243 offset:23552
	global_load_lds_dwordx4 v[204:205], off
	s_add_i32 m0, s70, 0x2000
	s_add_u32 s70, s28, 0x100000
	v_lshl_add_u64 v[206:207], s[28:29], 0, v[198:199]
	s_addc_u32 s71, s29, 0
	s_add_i32 s75, s65, s68
	global_load_lds_dwordx4 v[206:207], off
	v_lshl_add_u64 v[208:209], s[70:71], 0, v[194:195]
	s_mov_b32 m0, s75
	v_lshl_add_u64 v[210:211], s[30:31], 0, v[196:197]
	global_load_lds_dwordx4 v[208:209], off
	v_lshl_add_u64 v[208:209], s[70:71], 0, v[198:199]
	s_add_i32 m0, s75, 0x2000
	s_nop 0
	global_load_lds_dwordx4 v[208:209], off
	v_lshl_add_u64 v[208:209], s[30:31], 0, v[192:193]
	s_mov_b32 m0, s25
	s_nop 0
	global_load_lds_dwordx4 v[208:209], off
	s_mov_b32 m0, s38
	s_nop 0
	global_load_lds_dwordx4 v[210:211], off
	s_waitcnt vmcnt(8)
	s_waitcnt lgkmcnt(0)
	s_barrier
; #define PG8_STAGE(bufoff, gbase, voff) do { _Pragma("unroll") for (int _i = 0; _i < 2; ++_i) \
;         __builtin_amdgcn_global_load_lds((const unsigned*)((const char*)(gbase) + (voff)[_i]), (LAS unsigned*)(lds + (bufoff) + ldsw + _i * 8192), 16, 0, 0); } while (0)
; #define PG8_LDA(dst, b, h) do { _Pragma("unroll") for (int m = 0; m < 4; ++m) _Pragma("unroll") for (int k = 0; k < 2; ++k) dst[m][k] = *(const LAS bf16x8*)(lds + PG8_SA(b, h) + aoff + m * 2048 + k * 1024); } while (0)
; #define PG8_LDB(dst, b, h) do { _Pragma("unroll") for (int n = 0; n < 2; ++n) _Pragma("unroll") for (int k = 0; k < 2; ++k) dst[n][k] = *(const LAS bf16x8*)(lds + PG8_SB(b, h) + boff + n * 2048 + k * 1024); } while (0)
; #define PG8_MMA(ai, bj, At, Bt) do { __builtin_amdgcn_s_setprio(1); _Pragma("unroll") for (int m = 0; m < 4; ++m) _Pragma("unroll") for (int n = 0; n < 2; ++n) _Pragma("unroll") for (int k = 0; k < 2; ++k) \
;         acc[ai][bj][m][n] = __builtin_amdgcn_mfma_f32_16x16x32_bf16(Bt[n][k], At[m][k], acc[ai][bj][m][n], 0, 0, 0); __builtin_amdgcn_s_setprio(0); } while (0)
; #define PG8_WAIT_V(n) asm volatile("s_waitcnt vmcnt(" #n ")" ::: "memory")
; #define PG8_WAIT_L(n) asm volatile("s_waitcnt lgkmcnt(" #n ")" ::: "memory")
; #define PG8_BAR __builtin_amdgcn_s_barrier()
; #define PG8_SCHED __builtin_amdgcn_sched_barrier(0)
; template <class Epi>
; __device__ __forceinline__ void gemm_phase(LAS unsigned char* lds, const Gemm g, const StaticOrder& S, const Epi& E, const int wid) {
;     ...
;             PG8_WAIT_V(8); PG8_WAIT_L(0); PG8_BAR; PG8_MMA(1, 0, At, B0); PG8_MMA(1, 1, At, B1); PG8_BAR; PG8_SCHED;
;             PG8_LDB(B0, 1, 0); PG8_LDB(B1, 1, 1); PG8_SCHED; PG8_LDA(At, 1, 0); PG8_STAGE(PG8_SA(0, 1), a2 + hsA, voffA);
;             PG8_WAIT_V(8); PG8_WAIT_L(0); PG8_BAR; PG8_MMA(0, 0, At, B0); PG8_MMA(0, 1, At, B1); PG8_BAR; PG8_SCHED;
;             PG8_LDA(At, 1, 1); PG8_STAGE(PG8_SB(1, 0), b3, voffB); PG8_STAGE(PG8_SB(1, 1), b3 + hsB, voffB); PG8_STAGE(PG8_SA(1, 0), a3, voffA);
;             PG8_WAIT_V(8); PG8_WAIT_L(0); PG8_BAR; PG8_MMA(1, 0, At, B0); PG8_MMA(1, 1, At, B1); PG8_BAR; PG8_SCHED;
	s_setprio 1
	s_waitcnt lgkmcnt(0)
	v_mfma_f32_16x16x32_bf16 v[60:63], v[124:127], v[160:163], v[60:63]
	v_mfma_f32_16x16x32_bf16 v[56:59], v[136:139], v[160:163], v[56:59]
	v_mfma_f32_16x16x32_bf16 v[44:47], v[124:127], v[168:171], v[44:47]
	v_mfma_f32_16x16x32_bf16 v[40:43], v[136:139], v[168:171], v[40:43]
	v_mfma_f32_16x16x32_bf16 v[28:31], v[124:127], v[176:179], v[28:31]
	v_mfma_f32_16x16x32_bf16 v[24:27], v[136:139], v[176:179], v[24:27]
	v_mfma_f32_16x16x32_bf16 v[12:15], v[124:127], v[184:187], v[12:15]
	v_mfma_f32_16x16x32_bf16 v[8:11], v[136:139], v[184:187], v[8:11]
	v_mfma_f32_16x16x32_bf16 v[60:63], v[132:135], v[164:167], v[60:63]
	v_mfma_f32_16x16x32_bf16 v[56:59], v[140:143], v[164:167], v[56:59]
	v_mfma_f32_16x16x32_bf16 v[44:47], v[132:135], v[172:175], v[44:47]
	v_mfma_f32_16x16x32_bf16 v[40:43], v[140:143], v[172:175], v[40:43]
	v_mfma_f32_16x16x32_bf16 v[28:31], v[132:135], v[180:183], v[28:31]
	v_mfma_f32_16x16x32_bf16 v[24:27], v[140:143], v[180:183], v[24:27]
	v_mfma_f32_16x16x32_bf16 v[12:15], v[132:135], v[188:191], v[12:15]
	v_mfma_f32_16x16x32_bf16 v[8:11], v[140:143], v[188:191], v[8:11]
	s_setprio 0
	s_setprio 1
	v_mfma_f32_16x16x32_bf16 v[52:55], v[144:147], v[160:163], v[52:55]
	v_mfma_f32_16x16x32_bf16 v[48:51], v[152:155], v[160:163], v[48:51]
	v_mfma_f32_16x16x32_bf16 v[36:39], v[144:147], v[168:171], v[36:39]
	v_mfma_f32_16x16x32_bf16 v[32:35], v[152:155], v[168:171], v[32:35]
	v_mfma_f32_16x16x32_bf16 v[20:23], v[144:147], v[176:179], v[20:23]
	v_mfma_f32_16x16x32_bf16 v[16:19], v[152:155], v[176:179], v[16:19]
	v_mfma_f32_16x16x32_bf16 v[4:7], v[144:147], v[184:187], v[4:7]
	v_mfma_f32_16x16x32_bf16 v[0:3], v[152:155], v[184:187], v[0:3]
	v_mfma_f32_16x16x32_bf16 v[52:55], v[148:151], v[164:167], v[52:55]
	v_mfma_f32_16x16x32_bf16 v[48:51], v[156:159], v[164:167], v[48:51]
	v_mfma_f32_16x16x32_bf16 v[36:39], v[148:151], v[172:175], v[36:39]
	v_mfma_f32_16x16x32_bf16 v[32:35], v[156:159], v[172:175], v[32:35]
	v_mfma_f32_16x16x32_bf16 v[20:23], v[148:151], v[180:183], v[20:23]
	v_mfma_f32_16x16x32_bf16 v[16:19], v[156:159], v[180:183], v[16:19]
	v_mfma_f32_16x16x32_bf16 v[4:7], v[148:151], v[188:191], v[4:7]
	v_mfma_f32_16x16x32_bf16 v[0:3], v[156:159], v[188:191], v[0:3]
	s_setprio 0
	s_barrier
	s_add_i32 s70, 0, 0x18000
	s_add_i32 s71, 0, 0x1c000
	v_add_u32_e32 v140, s70, v240
	v_add_u32_e32 v156, s71, v240
	ds_read_b128 v[124:127], v140
	ds_read_b128 v[132:135], v140 offset:1024
	ds_read_b128 v[136:139], v140 offset:2048
	ds_read_b128 v[140:143], v140 offset:3072
	ds_read_b128 v[144:147], v156
	ds_read_b128 v[148:151], v156 offset:1024
	ds_read_b128 v[152:155], v156 offset:2048
	ds_read_b128 v[156:159], v156 offset:3072
	s_add_u32 s30, s30, 0x100000
	s_addc_u32 s31, s31, 0
	s_mov_b32 m0, s39
	v_lshl_add_u64 v[212:213], s[30:31], 0, v[192:193]
	ds_read_b128 v[160:163], v243 offset:32768
	ds_read_b128 v[164:167], v243 offset:33792
	ds_read_b128 v[168:171], v243 offset:34816
	ds_read_b128 v[172:175], v243 offset:35840
	ds_read_b128 v[176:179], v243 offset:36864
	ds_read_b128 v[180:183], v243 offset:37888
	ds_read_b128 v[184:187], v243 offset:38912
	ds_read_b128 v[188:191], v243 offset:39936
	global_load_lds_dwordx4 v[212:213], off
	v_lshl_add_u64 v[212:213], s[30:31], 0, v[196:197]
	s_mov_b32 m0, s50
	s_nop 0
	global_load_lds_dwordx4 v[212:213], off
	s_waitcnt vmcnt(8)
	s_waitcnt lgkmcnt(0)
	s_barrier
	s_setprio 1
	s_waitcnt lgkmcnt(0)
	v_mfma_f32_16x16x32_bf16 v[128:131], v[124:127], v[160:163], v[128:131]
	v_mfma_f32_16x16x32_bf16 v[120:123], v[136:139], v[160:163], v[120:123]
	v_mfma_f32_16x16x32_bf16 v[108:111], v[124:127], v[168:171], v[108:111]
	v_mfma_f32_16x16x32_bf16 v[104:107], v[136:139], v[168:171], v[104:107]
	v_mfma_f32_16x16x32_bf16 v[92:95], v[124:127], v[176:179], v[92:95]
	v_mfma_f32_16x16x32_bf16 v[88:91], v[136:139], v[176:179], v[88:91]
	v_mfma_f32_16x16x32_bf16 v[76:79], v[124:127], v[184:187], v[76:79]
	v_mfma_f32_16x16x32_bf16 v[72:75], v[136:139], v[184:187], v[72:75]
	v_mfma_f32_16x16x32_bf16 v[128:131], v[132:135], v[164:167], v[128:131]
	v_mfma_f32_16x16x32_bf16 v[120:123], v[140:143], v[164:167], v[120:123]
	v_mfma_f32_16x16x32_bf16 v[108:111], v[132:135], v[172:175], v[108:111]
	v_mfma_f32_16x16x32_bf16 v[104:107], v[140:143], v[172:175], v[104:107]
	v_mfma_f32_16x16x32_bf16 v[92:95], v[132:135], v[180:183], v[92:95]
	v_mfma_f32_16x16x32_bf16 v[88:91], v[140:143], v[180:183], v[88:91]
	v_mfma_f32_16x16x32_bf16 v[76:79], v[132:135], v[188:191], v[76:79]
	v_mfma_f32_16x16x32_bf16 v[72:75], v[140:143], v[188:191], v[72:75]
	s_setprio 0
	s_setprio 1
	v_mfma_f32_16x16x32_bf16 v[116:119], v[144:147], v[160:163], v[116:119]
	v_mfma_f32_16x16x32_bf16 v[112:115], v[152:155], v[160:163], v[112:115]
	v_mfma_f32_16x16x32_bf16 v[100:103], v[144:147], v[168:171], v[100:103]
	v_mfma_f32_16x16x32_bf16 v[96:99], v[152:155], v[168:171], v[96:99]
	v_mfma_f32_16x16x32_bf16 v[84:87], v[144:147], v[176:179], v[84:87]
	v_mfma_f32_16x16x32_bf16 v[80:83], v[152:155], v[176:179], v[80:83]
	v_mfma_f32_16x16x32_bf16 v[68:71], v[144:147], v[184:187], v[68:71]
	v_mfma_f32_16x16x32_bf16 v[64:67], v[152:155], v[184:187], v[64:67]
	v_mfma_f32_16x16x32_bf16 v[116:119], v[148:151], v[164:167], v[116:119]
	v_mfma_f32_16x16x32_bf16 v[112:115], v[156:159], v[164:167], v[112:115]
	v_mfma_f32_16x16x32_bf16 v[100:103], v[148:151], v[172:175], v[100:103]
	v_mfma_f32_16x16x32_bf16 v[96:99], v[156:159], v[172:175], v[96:99]
	v_mfma_f32_16x16x32_bf16 v[84:87], v[148:151], v[180:183], v[84:87]
	v_mfma_f32_16x16x32_bf16 v[80:83], v[156:159], v[180:183], v[80:83]
	v_mfma_f32_16x16x32_bf16 v[68:71], v[148:151], v[188:191], v[68:71]
	v_mfma_f32_16x16x32_bf16 v[64:67], v[156:159], v[188:191], v[64:67]
	s_setprio 0
	s_barrier
; #define PG8_STAGE(bufoff, gbase, voff) do { _Pragma("unroll") for (int _i = 0; _i < 2; ++_i) \
;         __builtin_amdgcn_global_load_lds((const unsigned*)((const char*)(gbase) + (voff)[_i]), (LAS unsigned*)(lds + (bufoff) + ldsw + _i * 8192), 16, 0, 0); } while (0)
; #define PG8_LDA(dst, b, h) do { _Pragma("unroll") for (int m = 0; m < 4; ++m) _Pragma("unroll") for (int k = 0; k < 2; ++k) dst[m][k] = *(const LAS bf16x8*)(lds + PG8_SA(b, h) + aoff + m * 2048 + k * 1024); } while (0)
; #define PG8_MMA(ai, bj, At, Bt) do { __builtin_amdgcn_s_setprio(1); _Pragma("unroll") for (int m = 0; m < 4; ++m) _Pragma("unroll") for (int n = 0; n < 2; ++n) _Pragma("unroll") for (int k = 0; k < 2; ++k) \
;         acc[ai][bj][m][n] = __builtin_amdgcn_mfma_f32_16x16x32_bf16(Bt[n][k], At[m][k], acc[ai][bj][m][n], 0, 0, 0); __builtin_amdgcn_s_setprio(0); } while (0)
; #define PG8_WAIT_V(n) asm volatile("s_waitcnt vmcnt(" #n ")" ::: "memory")
; #define PG8_WAIT_L(n) asm volatile("s_waitcnt lgkmcnt(" #n ")" ::: "memory")
; #define PG8_BAR __builtin_amdgcn_s_barrier()
; #define PG8_SCHED __builtin_amdgcn_sched_barrier(0)
; template <class Epi>
; __device__ __forceinline__ void gemm_phase(LAS unsigned char* lds, const Gemm g, const StaticOrder& S, const Epi& E, const int wid) {
;     ...
;             PG8_LDA(At, 1, 1); PG8_STAGE(PG8_SB(1, 0), b3, voffB); PG8_STAGE(PG8_SB(1, 1), b3 + hsB, voffB); PG8_STAGE(PG8_SA(1, 0), a3, voffA);
;             PG8_WAIT_V(8); PG8_WAIT_L(0); PG8_BAR; PG8_MMA(1, 0, At, B0); PG8_MMA(1, 1, At, B1); PG8_BAR; PG8_SCHED;
;         }
	s_add_i32 s30, s70, s68
	v_lshl_add_u64 v[204:205], v[204:205], 0, s[8:9]
	s_mov_b32 m0, s30
	ds_read_b128 v[160:163], v243 offset:49152
	ds_read_b128 v[164:167], v243 offset:50176
	ds_read_b128 v[168:171], v243 offset:51200
	ds_read_b128 v[172:175], v243 offset:52224
	ds_read_b128 v[176:179], v243 offset:53248
	ds_read_b128 v[180:183], v243 offset:54272
	ds_read_b128 v[184:187], v243 offset:55296
	ds_read_b128 v[188:191], v243 offset:56320
	global_load_lds_dwordx4 v[204:205], off
	s_add_i32 m0, s30, 0x2000
	s_add_u32 s28, s28, 0x100080
	v_lshl_add_u64 v[204:205], v[206:207], 0, s[8:9]
	s_addc_u32 s29, s29, 0
	s_add_i32 s30, s71, s68
	global_load_lds_dwordx4 v[204:205], off
	v_lshl_add_u64 v[204:205], s[28:29], 0, v[194:195]
	s_mov_b32 m0, s30
	s_nop 0
	global_load_lds_dwordx4 v[204:205], off
	v_lshl_add_u64 v[204:205], s[28:29], 0, v[198:199]
	s_add_i32 m0, s30, 0x2000
	s_nop 0
	global_load_lds_dwordx4 v[204:205], off
	v_lshl_add_u64 v[204:205], v[208:209], 0, s[8:9]
	s_mov_b32 m0, s58
	s_nop 0
	global_load_lds_dwordx4 v[204:205], off
	v_lshl_add_u64 v[204:205], v[210:211], 0, s[8:9]
	s_mov_b32 m0, s59
	s_nop 0
	global_load_lds_dwordx4 v[204:205], off
	s_waitcnt vmcnt(8)
	s_waitcnt lgkmcnt(0)
	s_barrier
	s_setprio 1
	s_waitcnt lgkmcnt(0)
	v_mfma_f32_16x16x32_bf16 v[60:63], v[124:127], v[160:163], v[60:63]
	v_mfma_f32_16x16x32_bf16 v[56:59], v[136:139], v[160:163], v[56:59]
	v_mfma_f32_16x16x32_bf16 v[44:47], v[124:127], v[168:171], v[44:47]
	v_mfma_f32_16x16x32_bf16 v[40:43], v[136:139], v[168:171], v[40:43]
	v_mfma_f32_16x16x32_bf16 v[28:31], v[124:127], v[176:179], v[28:31]
	v_mfma_f32_16x16x32_bf16 v[24:27], v[136:139], v[176:179], v[24:27]
	v_mfma_f32_16x16x32_bf16 v[12:15], v[124:127], v[184:187], v[12:15]
	v_mfma_f32_16x16x32_bf16 v[8:11], v[136:139], v[184:187], v[8:11]
	v_mfma_f32_16x16x32_bf16 v[60:63], v[132:135], v[164:167], v[60:63]
	v_mfma_f32_16x16x32_bf16 v[56:59], v[140:143], v[164:167], v[56:59]
	v_mfma_f32_16x16x32_bf16 v[44:47], v[132:135], v[172:175], v[44:47]
	v_mfma_f32_16x16x32_bf16 v[40:43], v[140:143], v[172:175], v[40:43]
	v_mfma_f32_16x16x32_bf16 v[28:31], v[132:135], v[180:183], v[28:31]
	v_mfma_f32_16x16x32_bf16 v[24:27], v[140:143], v[180:183], v[24:27]
	v_mfma_f32_16x16x32_bf16 v[12:15], v[132:135], v[188:191], v[12:15]
	v_mfma_f32_16x16x32_bf16 v[8:11], v[140:143], v[188:191], v[8:11]
	s_setprio 0
	s_setprio 1
	v_mfma_f32_16x16x32_bf16 v[52:55], v[144:147], v[160:163], v[52:55]
	v_mfma_f32_16x16x32_bf16 v[48:51], v[152:155], v[160:163], v[48:51]
	v_mfma_f32_16x16x32_bf16 v[36:39], v[144:147], v[168:171], v[36:39]
	v_mfma_f32_16x16x32_bf16 v[32:35], v[152:155], v[168:171], v[32:35]
	v_mfma_f32_16x16x32_bf16 v[20:23], v[144:147], v[176:179], v[20:23]
	v_mfma_f32_16x16x32_bf16 v[16:19], v[152:155], v[176:179], v[16:19]
	v_mfma_f32_16x16x32_bf16 v[4:7], v[144:147], v[184:187], v[4:7]
	v_mfma_f32_16x16x32_bf16 v[0:3], v[152:155], v[184:187], v[0:3]
	v_mfma_f32_16x16x32_bf16 v[52:55], v[148:151], v[164:167], v[52:55]
	v_mfma_f32_16x16x32_bf16 v[48:51], v[156:159], v[164:167], v[48:51]
	v_mfma_f32_16x16x32_bf16 v[36:39], v[148:151], v[172:175], v[36:39]
	v_mfma_f32_16x16x32_bf16 v[32:35], v[156:159], v[172:175], v[32:35]
	v_mfma_f32_16x16x32_bf16 v[20:23], v[148:151], v[180:183], v[20:23]
	v_mfma_f32_16x16x32_bf16 v[16:19], v[156:159], v[180:183], v[16:19]
	v_mfma_f32_16x16x32_bf16 v[4:7], v[148:151], v[188:191], v[4:7]
	v_mfma_f32_16x16x32_bf16 v[0:3], v[156:159], v[188:191], v[0:3]
	s_setprio 0
	s_barrier
	s_add_i32 s74, s74, 2
	s_add_u32 s67, s67, 0x100
	s_addc_u32 s73, s73, 0
	s_add_u32 s26, s26, 0x100
	s_addc_u32 s27, s27, 0
	s_cmp_gt_u32 s74, 61
	s_cbranch_scc0 .LBB0_1245
; #define PG8_BAR __builtin_amdgcn_s_barrier()
; __device__ __forceinline__ u32x4 pack8(f32x4 a, f32x4 b) { u32x4 w; w.x = pk2(a[0], a[1]); w.y = pk2(a[2], a[3]); w.z = pk2(b[0], b[1]); w.w = pk2(b[2], b[3]); return w; }
; template <class Epi>
; __device__ __forceinline__ void gemm_phase(LAS unsigned char* lds, const Gemm g, const StaticOrder& S, const Epi& E, const int wid) {
;     ...
;         if (wr == 0) PG8_BAR;
;         E(acc, cur, wid);
;     __device__ __forceinline__ void operator()(const Acc& acc, const pg8::Unit& u, int wid) const {
;     ...
;         float r2[8];
; #pragma unroll
;         for (int i = 0; i < 8; ++i) r2[i] = ssq2 ? ssq2[row0 + (i >> 2) * 128 + (i & 3) * 16] : 0.f;
;         u32x4 bv[2][4][2];
; #pragma unroll
;         for (int ai = 0; ai < 2; ++ai)
; #pragma unroll
;             for (int m = 0; m < 4; ++m)
; #pragma unroll
;                 for (int bj = 0; bj < 2; ++bj) bv[ai][m][bj] = *(const u32x4*)(base + (size_t)(row0 + ai * 128 + m * 16) * 1024 + col0 + bj * 128);
; #pragma unroll
;         for (int ai = 0; ai < 2; ++ai) {
; #pragma unroll
;             for (int m = 0; m < 4; ++m) {
;                 const int row = row0 + ai * 128 + m * 16; float sq = 0.f;
;                 const float rr = ssq2 ? __builtin_amdgcn_rcpf(r2[ai * 4 + m] * (1.f / 1024.f) + EPS) : 1.f;
; #pragma unroll
;                 for (int bj = 0; bj < 2; ++bj) {
;                     const u32x4 b4 = bv[ai][m][bj];
;                     const f32x4 o0 = (f32x4){bflo(b4.x), bfhi(b4.x), bflo(b4.y), bfhi(b4.y)} + acc[ai][bj][m][0] * rr;
;                     const f32x4 o1 = (f32x4){bflo(b4.z), bfhi(b4.z), bflo(b4.w), bfhi(b4.w)} + acc[ai][bj][m][1] * rr;
;                     *(u32x4*)(hb + (size_t)row * 1024 + col0 + bj * 128) = pack8(o0, o1);
;                     sq += (o0[0] * o0[0] + o0[1] * o0[1]) + (o0[2] * o0[2] + o0[3] * o0[3]) + (o1[0] * o1[0] + o1[1] * o1[1]) + (o1[2] * o1[2] + o1[3] * o1[3]);
;                 }
;                 if (ssq_out) { sq += __shfl_xor(sq, 16); sq += __shfl_xor(sq, 32); if (fq == 0) atomicAdd(ssq_out + row, sq); }
.LBB0_1248:
	s_lshl_b32 s1, s24, 8
	s_add_i32 s1, s1, s60
	v_mbcnt_lo_u32_b32 v208, -1, 0
	v_mbcnt_hi_u32_b32 v208, -1, v208
	s_lshl_b32 s0, s0, 8
	v_and_or_b32 v234, v208, 15, s1
	v_ashrrev_i32_e32 v124, 1, v208
	v_ashrrev_i32_e32 v235, 31, v234
	v_and_b32_e32 v126, -8, v124
	v_lshl_add_u64 v[124:125], v[234:235], 2, s[46:47]
	flat_load_dword v127, v[124:125]
	s_or_b32 s0, s0, s69
	v_add_u32_e32 v204, s0, v126
	v_ashrrev_i32_e32 v205, 31, v204
	v_lshlrev_b64 v[236:237], 1, v[204:205]
	v_lshl_add_u64 v[136:137], s[42:43], 0, v[236:237]
	v_lshlrev_b64 v[238:239], 11, v[234:235]
	flat_load_dword v252, v[124:125] offset:64
	flat_load_dword v251, v[124:125] offset:128
	flat_load_dword v250, v[124:125] offset:192
	flat_load_dword v249, v[124:125] offset:512
	flat_load_dword v248, v[124:125] offset:576
	flat_load_dword v247, v[124:125] offset:640
	flat_load_dword v246, v[124:125] offset:704
	v_lshl_add_u64 v[124:125], v[136:137], 0, v[238:239]
	flat_load_dwordx4 v[188:191], v[124:125]
	flat_load_dwordx4 v[184:187], v[124:125] offset:256
	v_or_b32_e32 v230, 16, v234
	v_ashrrev_i32_e32 v231, 31, v230
	v_or_b32_e32 v226, 32, v234
	v_lshlrev_b64 v[232:233], 11, v[230:231]
	v_ashrrev_i32_e32 v227, 31, v226
	v_or_b32_e32 v222, 48, v234
	v_add_u32_e32 v214, 0x80, v234
	v_lshl_add_u64 v[124:125], v[136:137], 0, v[232:233]
	v_lshlrev_b64 v[228:229], 11, v[226:227]
	v_ashrrev_i32_e32 v223, 31, v222
	v_ashrrev_i32_e32 v215, 31, v214
	flat_load_dwordx4 v[180:183], v[124:125]
	flat_load_dwordx4 v[176:179], v[124:125] offset:256
	v_lshl_add_u64 v[124:125], v[136:137], 0, v[228:229]
	v_lshlrev_b64 v[224:225], 11, v[222:223]
	v_add_u32_e32 v216, 0x90, v234
	flat_load_dwordx4 v[172:175], v[124:125]
	flat_load_dwordx4 v[168:171], v[124:125] offset:256
	v_lshl_add_u64 v[124:125], v[136:137], 0, v[224:225]
	v_lshlrev_b64 v[220:221], 11, v[214:215]
	v_ashrrev_i32_e32 v217, 31, v216
	flat_load_dwordx4 v[164:167], v[124:125]
	flat_load_dwordx4 v[160:163], v[124:125] offset:256
	v_lshl_add_u64 v[124:125], v[136:137], 0, v[220:221]
	v_lshlrev_b64 v[218:219], 11, v[216:217]
	v_add_u32_e32 v210, 0xa0, v234
	v_add_u32_e32 v206, 0xb0, v234
	flat_load_dwordx4 v[156:159], v[124:125]
	flat_load_dwordx4 v[152:155], v[124:125] offset:256
	v_lshl_add_u64 v[124:125], v[136:137], 0, v[218:219]
	v_ashrrev_i32_e32 v211, 31, v210
	v_ashrrev_i32_e32 v207, 31, v206
	flat_load_dwordx4 v[148:151], v[124:125]
	flat_load_dwordx4 v[144:147], v[124:125] offset:256
	v_lshlrev_b64 v[124:125], 11, v[210:211]
	v_lshlrev_b64 v[138:139], 11, v[206:207]
	v_lshl_add_u64 v[124:125], v[136:137], 0, v[124:125]
	v_lshl_add_u64 v[136:137], v[136:137], 0, v[138:139]
	v_cmp_gt_u32_e32 vcc, 16, v208
	s_waitcnt vmcnt(0) lgkmcnt(0)
	v_fmamk_f32 v209, v127, 0x3a800000, v245
	flat_load_dwordx4 v[132:135], v[124:125]
	s_nop 0
	flat_load_dwordx4 v[124:127], v[124:125] offset:256
	s_nop 0
	flat_load_dwordx4 v[140:143], v[136:137]
	s_nop 0
	flat_load_dwordx4 v[136:139], v[136:137] offset:256
	v_rcp_f32_e32 v208, v209
	v_lshlrev_b32_e32 v212, 16, v188
	v_and_b32_e32 v213, 0xffff0000, v188
	v_lshlrev_b32_e32 v188, 16, v189
	v_and_b32_e32 v189, 0xffff0000, v189
	v_pk_fma_f32 v[130:131], v[130:131], v[208:209], v[188:189] op_sel_hi:[1,0,1]
	v_lshlrev_b32_e32 v188, 16, v190
	v_and_b32_e32 v189, 0xffff0000, v190
	v_lshlrev_b32_e32 v190, 16, v191
	v_and_b32_e32 v191, 0xffff0000, v191
	v_pk_fma_f32 v[128:129], v[128:129], v[208:209], v[212:213] op_sel_hi:[1,0,1]
	v_pk_fma_f32 v[190:191], v[122:123], v[208:209], v[190:191] op_sel_hi:[1,0,1]
	v_pk_fma_f32 v[188:189], v[120:121], v[208:209], v[188:189] op_sel_hi:[1,0,1]
	v_lshl_add_u64 v[212:213], s[42:43], 0, v[238:239]
	v_cvt_pk_bf16_f32 v120, v128, v129
	v_cvt_pk_bf16_f32 v121, v130, v131
	v_cvt_pk_bf16_f32 v122, v188, v189
	v_cvt_pk_bf16_f32 v123, v190, v191
	v_lshl_add_u64 v[212:213], v[212:213], 0, v[236:237]
	flat_store_dwordx4 v[212:213], v[120:123]
	s_nop 1
	v_lshlrev_b32_e32 v120, 16, v184
	v_and_b32_e32 v121, 0xffff0000, v184
	v_lshlrev_b32_e32 v122, 16, v185
	v_and_b32_e32 v123, 0xffff0000, v185
	v_pk_fma_f32 v[118:119], v[118:119], v[208:209], v[122:123] op_sel_hi:[1,0,1]
	v_pk_fma_f32 v[116:117], v[116:117], v[208:209], v[120:121] op_sel_hi:[1,0,1]
	v_lshlrev_b32_e32 v120, 16, v186
	v_and_b32_e32 v121, 0xffff0000, v186
	v_lshlrev_b32_e32 v122, 16, v187
	v_and_b32_e32 v123, 0xffff0000, v187
	v_pk_fma_f32 v[122:123], v[114:115], v[208:209], v[122:123] op_sel_hi:[1,0,1]
	v_pk_fma_f32 v[120:121], v[112:113], v[208:209], v[120:121] op_sel_hi:[1,0,1]
	v_cvt_pk_bf16_f32 v112, v116, v117
	v_cvt_pk_bf16_f32 v113, v118, v119
	v_cvt_pk_bf16_f32 v114, v120, v121
	v_cvt_pk_bf16_f32 v115, v122, v123
	flat_store_dwordx4 v[212:213], v[112:115] offset:256
	s_nop 1
	v_mul_f32_e32 v114, v129, v129
	v_mul_f32_e32 v115, v131, v131
	v_fmac_f32_e32 v114, v128, v128
	v_fmac_f32_e32 v115, v130, v130
	v_mul_f32_e32 v113, v189, v189
	v_add_f32_e32 v114, v114, v115
	v_mul_f32_e32 v115, v117, v117
	v_mul_f32_e32 v112, v191, v191
	v_fmac_f32_e32 v113, v188, v188
	v_fmac_f32_e32 v115, v116, v116
	v_mul_f32_e32 v116, v119, v119
	v_fmac_f32_e32 v112, v190, v190
	v_add_f32_e32 v113, v113, v114
	v_mul_f32_e32 v114, v121, v121
	v_fmac_f32_e32 v116, v118, v118
	v_add_f32_e32 v112, v112, v113
	v_mul_f32_e32 v113, v123, v123
	v_fmac_f32_e32 v114, v120, v120
	v_add_f32_e32 v115, v115, v116
	v_fmac_f32_e32 v113, v122, v122
	v_add_f32_e32 v114, v114, v115
	v_add_f32_e32 v113, v113, v114
	v_and_b32_e32 v114, 64, v244
	v_add_f32_e32 v113, v112, v113
	v_xor_b32_e32 v112, 16, v244
	v_add_u32_e32 v115, 64, v114
	v_cmp_lt_i32_e64 s[0:1], v112, v115
	s_nop 1
	v_cndmask_b32_e64 v112, v244, v112, s[0:1]
	v_lshlrev_b32_e32 v112, 2, v112
	ds_bpermute_b32 v114, v112, v113
	s_waitcnt lgkmcnt(0)
	v_add_f32_e32 v114, v113, v114
	v_xor_b32_e32 v113, 32, v244
	v_cmp_lt_i32_e64 s[0:1], v113, v115
	s_nop 1
	v_cndmask_b32_e64 v113, v244, v113, s[0:1]
	v_lshlrev_b32_e32 v113, 2, v113
	ds_bpermute_b32 v115, v113, v114
	s_and_saveexec_b64 s[0:1], vcc
	s_cbranch_execz .LBB0_1250
	v_lshl_add_u64 v[116:117], v[234:235], 2, s[36:37]
	s_waitcnt lgkmcnt(0)
	v_add_f32_e32 v114, v114, v115
	flat_atomic_add_f32 v[116:117], v114

; __device__ __forceinline__ int lane_id_asm() { int l; asm volatile("v_mbcnt_lo_u32_b32 %0, -1, 0\n\tv_mbcnt_hi_u32_b32 %0, -1, %0" : "=v"(l)); return l; }
; #define PG8_BAR __builtin_amdgcn_s_barrier()
; __device__ __forceinline__ u32x4 pack8(f32x4 a, f32x4 b) { u32x4 w; w.x = pk2(a[0], a[1]); w.y = pk2(a[2], a[3]); w.z = pk2(b[0], b[1]); w.w = pk2(b[2], b[3]); return w; }
; template <class Epi>
; __device__ __forceinline__ void gemm_phase(LAS unsigned char* lds, const Gemm g, const StaticOrder& S, const Epi& E, const int wid) {
;     ...
;         if (wr == 0) PG8_BAR;
;         E(acc, cur, wid);
;         if (!has_next) break;
; #pragma unroll
;         for (int a = 0; a < 2; ++a)
; #pragma unroll
;             for (int b = 0; b < 2; ++b)
; #pragma unroll
;                 for (int m = 0; m < 4; ++m)
; #pragma unroll
;                     for (int n = 0; n < 2; ++n) acc[a][b][m][n] = (f32x4){0.f, 0.f, 0.f, 0.f};
;         cur = nxt; cA = nA; cB = nB; ++ui;
;         if (wr == 1) PG8_BAR;
;     }
;     __device__ __forceinline__ void operator()(const Acc& acc, const pg8::Unit& u, int wid) const {
;         const int lane_ = lane_id_asm(), wr = wid >> 2, wc = wid & 3, fr = lane_ & 15, fq = lane_ >> 4;
;         const int row0 = u.pm * 256 + wr * 64 + fr, col0 = u.pn * 256 + wc * 32 + 8 * fq;
; #pragma unroll
;         for (int ai = 0; ai < 2; ++ai)
; #pragma unroll
;             for (int m = 0; m < 4; ++m)
; #pragma unroll
;                 for (int bj = 0; bj < 2; ++bj) *(u32x4*)(O + (size_t)(row0 + ai * 128 + m * 16) * 1024 + col0 + bj * 128) = pack8(acc[ai][bj][m][0], acc[ai][bj][m][1]);
;     }
.LBB0_1332:
	s_lshl_b32 s20, s20, 8
	v_mbcnt_lo_u32_b32 v145, -1, 0
	v_mbcnt_hi_u32_b32 v145, -1, v145
	s_add_i32 s20, s20, s79
	v_and_or_b32 v144, v145, 15, s20
	s_lshl_b32 s20, s87, 8
	v_ashrrev_i32_e32 v145, 1, v145
	s_or_b32 s20, s20, s69
	v_and_b32_e32 v145, -8, v145
	v_add_u32_e32 v146, s20, v145
	v_ashrrev_i32_e32 v145, 31, v144
	v_ashrrev_i32_e32 v147, 31, v146
	v_lshlrev_b64 v[148:149], 11, v[144:145]
	v_cvt_pk_bf16_f32 v124, v124, v125
	v_cvt_pk_bf16_f32 v125, v126, v127
	v_cvt_pk_bf16_f32 v126, v120, v121
	v_cvt_pk_bf16_f32 v127, v122, v123
	v_lshl_add_u64 v[120:121], s[48:49], 0, v[148:149]
	v_lshlrev_b64 v[122:123], 1, v[146:147]
	v_cvt_pk_bf16_f32 v108, v108, v109
	v_cvt_pk_bf16_f32 v109, v110, v111
	v_cvt_pk_bf16_f32 v110, v104, v105
	v_or_b32_e32 v104, 16, v144
	v_lshl_add_u64 v[120:121], v[120:121], 0, v[122:123]
	v_cvt_pk_bf16_f32 v111, v106, v107
	v_ashrrev_i32_e32 v105, 31, v104
	flat_store_dwordx4 v[120:121], v[108:111] offset:256
	v_cvt_pk_bf16_f32 v60, v60, v61
	v_cvt_pk_bf16_f32 v61, v62, v63
	v_lshlrev_b64 v[108:109], 11, v[104:105]
	v_cvt_pk_bf16_f32 v63, v58, v59
	v_add_co_u32_e32 v58, vcc, s83, v120
	v_lshl_add_u64 v[108:109], s[48:49], 0, v[108:109]
	v_cvt_pk_bf16_f32 v92, v92, v93
	v_cvt_pk_bf16_f32 v93, v94, v95
	v_cvt_pk_bf16_f32 v94, v88, v89
	v_or_b32_e32 v88, 32, v144
	v_cvt_pk_bf16_f32 v62, v56, v57
	v_lshl_add_u64 v[56:57], v[120:121], 0, s[10:11]
	v_addc_co_u32_e32 v59, vcc, 0, v121, vcc
	v_cvt_pk_bf16_f32 v44, v44, v45
	v_cvt_pk_bf16_f32 v45, v46, v47
	v_cvt_pk_bf16_f32 v46, v40, v41
	v_cvt_pk_bf16_f32 v47, v42, v43
	v_lshl_add_u64 v[108:109], v[108:109], 0, v[122:123]
	v_cvt_pk_bf16_f32 v95, v90, v91
	v_ashrrev_i32_e32 v89, 31, v88
	flat_store_dwordx4 v[56:57], v[44:47] offset:256
	flat_store_dwordx4 v[108:109], v[92:95] offset:256
	v_cvt_pk_bf16_f32 v28, v28, v29
	v_add_co_u32_e32 v46, vcc, s84, v120
	v_lshlrev_b64 v[92:93], 11, v[88:89]
	v_lshl_add_u64 v[44:45], v[120:121], 0, s[12:13]
	v_addc_co_u32_e32 v47, vcc, 0, v121, vcc
	v_cvt_pk_bf16_f32 v29, v30, v31
	v_cvt_pk_bf16_f32 v30, v24, v25
	v_cvt_pk_bf16_f32 v31, v26, v27
	v_lshl_add_u64 v[92:93], s[48:49], 0, v[92:93]
	v_cvt_pk_bf16_f32 v76, v76, v77
	v_cvt_pk_bf16_f32 v77, v78, v79
	v_cvt_pk_bf16_f32 v78, v72, v73
	v_or_b32_e32 v72, 48, v144
	flat_store_dwordx4 v[44:45], v[28:31] offset:256
	v_lshl_add_u64 v[92:93], v[92:93], 0, v[122:123]
	v_cvt_pk_bf16_f32 v79, v74, v75
	v_add_co_u32_e32 v30, vcc, s85, v120
	v_ashrrev_i32_e32 v73, 31, v72
	v_lshl_add_u64 v[28:29], v[120:121], 0, s[16:17]
	v_addc_co_u32_e32 v31, vcc, 0, v121, vcc
	v_cvt_pk_bf16_f32 v12, v12, v13
	v_cvt_pk_bf16_f32 v13, v14, v15
	v_cvt_pk_bf16_f32 v14, v8, v9
	v_cvt_pk_bf16_f32 v15, v10, v11
	flat_store_dwordx4 v[92:93], v[76:79] offset:256
	flat_store_dwordx4 v[28:29], v[12:15] offset:256
	v_cvt_pk_bf16_f32 v104, v116, v117
	v_lshlrev_b64 v[76:77], 11, v[72:73]
	v_add_co_u32_e32 v14, vcc, s86, v120
	v_lshl_add_u64 v[76:77], s[48:49], 0, v[76:77]
	s_nop 0
	v_addc_co_u32_e32 v15, vcc, 0, v121, vcc
	v_cvt_pk_bf16_f32 v105, v118, v119
	v_cvt_pk_bf16_f32 v106, v112, v113
	v_cvt_pk_bf16_f32 v107, v114, v115
	v_cvt_pk_bf16_f32 v88, v100, v101
	v_cvt_pk_bf16_f32 v89, v102, v103
	v_cvt_pk_bf16_f32 v90, v96, v97
	v_cvt_pk_bf16_f32 v91, v98, v99
	v_cvt_pk_bf16_f32 v72, v84, v85
	v_cvt_pk_bf16_f32 v73, v86, v87
	v_cvt_pk_bf16_f32 v74, v80, v81
	v_cvt_pk_bf16_f32 v75, v82, v83
	v_lshl_add_u64 v[76:77], v[76:77], 0, v[122:123]
	v_cvt_pk_bf16_f32 v68, v68, v69
	v_cvt_pk_bf16_f32 v69, v70, v71
	v_cvt_pk_bf16_f32 v70, v64, v65
	v_cvt_pk_bf16_f32 v71, v66, v67
	v_cvt_pk_bf16_f32 v40, v52, v53
	v_cvt_pk_bf16_f32 v41, v54, v55
	v_cvt_pk_bf16_f32 v42, v48, v49
	v_cvt_pk_bf16_f32 v43, v50, v51
	v_cvt_pk_bf16_f32 v24, v36, v37
	v_cvt_pk_bf16_f32 v25, v38, v39
	v_cvt_pk_bf16_f32 v26, v32, v33
	v_cvt_pk_bf16_f32 v27, v34, v35
	v_cvt_pk_bf16_f32 v8, v20, v21
	v_cvt_pk_bf16_f32 v9, v22, v23
	v_cvt_pk_bf16_f32 v10, v16, v17
	v_cvt_pk_bf16_f32 v11, v18, v19
	v_lshl_add_u64 v[12:13], v[120:121], 0, s[18:19]
	v_cvt_pk_bf16_f32 v4, v4, v5
	v_cvt_pk_bf16_f32 v5, v6, v7
	v_cvt_pk_bf16_f32 v6, v0, v1
	v_cvt_pk_bf16_f32 v7, v2, v3
	s_andn2_b64 vcc, exec, s[0:1]
	s_mov_b64 s[0:1], -1
	flat_store_dwordx4 v[120:121], v[124:127]
	flat_store_dwordx4 v[108:109], v[104:107]
	flat_store_dwordx4 v[92:93], v[88:91]
	flat_store_dwordx4 v[76:77], v[72:75]
	flat_store_dwordx4 v[76:77], v[68:71] offset:256
	flat_store_dwordx4 v[58:59], v[60:63]
	flat_store_dwordx4 v[46:47], v[40:43]
	flat_store_dwordx4 v[30:31], v[24:27]
	flat_store_dwordx4 v[14:15], v[8:11]
	flat_store_dwordx4 v[12:13], v[4:7] offset:256
	s_cbranch_vccnz .LBB0_1321
	s_branch .LBB0_1320

; #define PG8_STAGE(bufoff, gbase, voff) do { _Pragma("unroll") for (int _i = 0; _i < 2; ++_i) \
;         __builtin_amdgcn_global_load_lds((const unsigned*)((const char*)(gbase) + (voff)[_i]), (LAS unsigned*)(lds + (bufoff) + ldsw + _i * 8192), 16, 0, 0); } while (0)
; #define PG8_LDA(dst, b, h) do { _Pragma("unroll") for (int m = 0; m < 4; ++m) _Pragma("unroll") for (int k = 0; k < 2; ++k) dst[m][k] = *(const LAS bf16x8*)(lds + PG8_SA(b, h) + aoff + m * 2048 + k * 1024); } while (0)
; #define PG8_LDB(dst, b, h) do { _Pragma("unroll") for (int n = 0; n < 2; ++n) _Pragma("unroll") for (int k = 0; k < 2; ++k) dst[n][k] = *(const LAS bf16x8*)(lds + PG8_SB(b, h) + boff + n * 2048 + k * 1024); } while (0)
; #define PG8_MMA(ai, bj, At, Bt) do { __builtin_amdgcn_s_setprio(1); _Pragma("unroll") for (int m = 0; m < 4; ++m) _Pragma("unroll") for (int n = 0; n < 2; ++n) _Pragma("unroll") for (int k = 0; k < 2; ++k) \
;         acc[ai][bj][m][n] = __builtin_amdgcn_mfma_f32_16x16x32_bf16(Bt[n][k], At[m][k], acc[ai][bj][m][n], 0, 0, 0); __builtin_amdgcn_s_setprio(0); } while (0)
; #define PG8_WAIT_V(n) asm volatile("s_waitcnt vmcnt(" #n ")" ::: "memory")
; #define PG8_WAIT_L(n) asm volatile("s_waitcnt lgkmcnt(" #n ")" ::: "memory")
; #define PG8_BAR __builtin_amdgcn_s_barrier()
; #define PG8_SCHED __builtin_amdgcn_sched_barrier(0)
; template <class Epi>
; __device__ __forceinline__ void gemm_phase(LAS unsigned char* lds, const Gemm g, const StaticOrder& S, const Epi& E, const int wid) {
;     ...
;             PG8_LDB(B0, 0, 0); PG8_LDB(B1, 0, 1); PG8_SCHED; PG8_LDA(At, 0, 0); PG8_STAGE(PG8_SA(1, 1), a1 + hsA, voffA);
;             PG8_WAIT_V(8); PG8_WAIT_L(0); PG8_BAR; PG8_MMA(0, 0, At, B0); PG8_MMA(0, 1, At, B1); PG8_BAR; PG8_SCHED;
;             PG8_LDA(At, 0, 1); PG8_STAGE(PG8_SB(0, 0), b2, voffB); PG8_STAGE(PG8_SB(0, 1), b2 + hsB, voffB); PG8_STAGE(PG8_SA(0, 0), a2, voffA);
;             PG8_WAIT_V(8); PG8_WAIT_L(0); PG8_BAR; PG8_MMA(1, 0, At, B0); PG8_MMA(1, 1, At, B1); PG8_BAR; PG8_SCHED;
.LBB0_1353:
	ds_read_b128 v[128:131], v169
	ds_read_b128 v[132:135], v169 offset:1024
	ds_read_b128 v[136:139], v169 offset:2048
	ds_read_b128 v[140:143], v169 offset:3072
	ds_read_b128 v[160:163], v170
	ds_read_b128 v[164:167], v170 offset:1024
	ds_read_b128 v[174:177], v170 offset:2048
	ds_read_b128 v[178:181], v170 offset:3072
	s_add_u32 s34, s30, 0xfffc0080
	s_addc_u32 s35, s31, -1
	s_cmp_eq_u32 s65, 12
	s_cselect_b32 s39, s23, s35
	s_cselect_b32 s38, s61, s34
	s_cselect_b32 s35, s21, s64
	s_cselect_b32 s34, s62, s63
	v_lshl_add_u64 v[214:215], s[30:31], 0, v[154:155]
	s_add_i32 m0, s29, 0xc000
	ds_read_b128 v[182:185], v171
	ds_read_b128 v[186:189], v171 offset:1024
	ds_read_b128 v[190:193], v171 offset:2048
	ds_read_b128 v[194:197], v171 offset:3072
	ds_read_b128 v[198:201], v171 offset:4096
	ds_read_b128 v[202:205], v171 offset:5120
	ds_read_b128 v[206:209], v171 offset:6144
	ds_read_b128 v[210:213], v171 offset:7168
	global_load_lds_dwordx4 v[214:215], off
	v_lshl_add_u64 v[214:215], s[30:31], 0, v[152:153]
	s_add_i32 m0, s29, 0xe000
	s_nop 0
	global_load_lds_dwordx4 v[214:215], off
	s_waitcnt vmcnt(8)
	s_waitcnt lgkmcnt(0)
	s_barrier
	s_setprio 1
	s_waitcnt lgkmcnt(0)
	v_mfma_f32_16x16x32_bf16 v[124:127], v[128:131], v[182:185], v[124:127]
	v_mfma_f32_16x16x32_bf16 v[120:123], v[136:139], v[182:185], v[120:123]
	v_mfma_f32_16x16x32_bf16 v[104:107], v[128:131], v[190:193], v[104:107]
	v_mfma_f32_16x16x32_bf16 v[108:111], v[136:139], v[190:193], v[108:111]
	v_mfma_f32_16x16x32_bf16 v[88:91], v[128:131], v[198:201], v[88:91]
	v_mfma_f32_16x16x32_bf16 v[92:95], v[136:139], v[198:201], v[92:95]
	v_mfma_f32_16x16x32_bf16 v[72:75], v[128:131], v[206:209], v[72:75]
	v_mfma_f32_16x16x32_bf16 v[76:79], v[136:139], v[206:209], v[76:79]
	v_mfma_f32_16x16x32_bf16 v[124:127], v[132:135], v[186:189], v[124:127]
	v_mfma_f32_16x16x32_bf16 v[120:123], v[140:143], v[186:189], v[120:123]
	v_mfma_f32_16x16x32_bf16 v[104:107], v[132:135], v[194:197], v[104:107]
	v_mfma_f32_16x16x32_bf16 v[108:111], v[140:143], v[194:197], v[108:111]
	v_mfma_f32_16x16x32_bf16 v[88:91], v[132:135], v[202:205], v[88:91]
	v_mfma_f32_16x16x32_bf16 v[92:95], v[140:143], v[202:205], v[92:95]
	v_mfma_f32_16x16x32_bf16 v[72:75], v[132:135], v[210:213], v[72:75]
	v_mfma_f32_16x16x32_bf16 v[76:79], v[140:143], v[210:213], v[76:79]
	s_setprio 0
	s_setprio 1
	v_mfma_f32_16x16x32_bf16 v[112:115], v[160:163], v[182:185], v[112:115]
	v_mfma_f32_16x16x32_bf16 v[116:119], v[174:177], v[182:185], v[116:119]
	v_mfma_f32_16x16x32_bf16 v[96:99], v[160:163], v[190:193], v[96:99]
	v_mfma_f32_16x16x32_bf16 v[100:103], v[174:177], v[190:193], v[100:103]
	v_mfma_f32_16x16x32_bf16 v[80:83], v[160:163], v[198:201], v[80:83]
	v_mfma_f32_16x16x32_bf16 v[84:87], v[174:177], v[198:201], v[84:87]
	v_mfma_f32_16x16x32_bf16 v[64:67], v[160:163], v[206:209], v[64:67]
	v_mfma_f32_16x16x32_bf16 v[68:71], v[174:177], v[206:209], v[68:71]
	v_mfma_f32_16x16x32_bf16 v[112:115], v[164:167], v[186:189], v[112:115]
	v_mfma_f32_16x16x32_bf16 v[116:119], v[178:181], v[186:189], v[116:119]
	v_mfma_f32_16x16x32_bf16 v[96:99], v[164:167], v[194:197], v[96:99]
	v_mfma_f32_16x16x32_bf16 v[100:103], v[178:181], v[194:197], v[100:103]
	v_mfma_f32_16x16x32_bf16 v[80:83], v[164:167], v[202:205], v[80:83]
	v_mfma_f32_16x16x32_bf16 v[84:87], v[178:181], v[202:205], v[84:87]
	v_mfma_f32_16x16x32_bf16 v[64:67], v[164:167], v[210:213], v[64:67]
	v_mfma_f32_16x16x32_bf16 v[68:71], v[178:181], v[210:213], v[68:71]
	s_setprio 0
	s_barrier
	s_add_i32 s66, s58, s68
	v_lshl_add_u64 v[214:215], s[34:35], 0, v[146:147]
	s_mov_b32 m0, s66
	ds_read_b128 v[182:185], v171 offset:16384
	ds_read_b128 v[186:189], v171 offset:17408
	ds_read_b128 v[190:193], v171 offset:18432
	ds_read_b128 v[194:197], v171 offset:19456
	ds_read_b128 v[198:201], v171 offset:20480
	ds_read_b128 v[202:205], v171 offset:21504
	ds_read_b128 v[206:209], v171 offset:22528
	ds_read_b128 v[210:213], v171 offset:23552
	global_load_lds_dwordx4 v[214:215], off
	s_add_i32 m0, s66, 0x2000
	s_add_u32 s66, s34, 0x40000
	v_lshl_add_u64 v[216:217], s[34:35], 0, v[150:151]
	s_addc_u32 s67, s35, 0
	s_add_i32 s70, s59, s68
	global_load_lds_dwordx4 v[216:217], off
	v_lshl_add_u64 v[218:219], s[66:67], 0, v[146:147]
	s_mov_b32 m0, s70
	v_lshl_add_u64 v[220:221], s[38:39], 0, v[148:149]
	global_load_lds_dwordx4 v[218:219], off
	v_lshl_add_u64 v[218:219], s[66:67], 0, v[150:151]
	s_add_i32 m0, s70, 0x2000
	s_nop 0
	global_load_lds_dwordx4 v[218:219], off
	v_lshl_add_u64 v[218:219], s[38:39], 0, v[144:145]
	s_mov_b32 m0, s29
	s_nop 0
	global_load_lds_dwordx4 v[218:219], off
	s_mov_b32 m0, s47
	s_nop 0
	global_load_lds_dwordx4 v[220:221], off
	s_waitcnt vmcnt(8)
	s_waitcnt lgkmcnt(0)
	s_barrier
; #define PG8_STAGE(bufoff, gbase, voff) do { _Pragma("unroll") for (int _i = 0; _i < 2; ++_i) \
;         __builtin_amdgcn_global_load_lds((const unsigned*)((const char*)(gbase) + (voff)[_i]), (LAS unsigned*)(lds + (bufoff) + ldsw + _i * 8192), 16, 0, 0); } while (0)
; #define PG8_LDA(dst, b, h) do { _Pragma("unroll") for (int m = 0; m < 4; ++m) _Pragma("unroll") for (int k = 0; k < 2; ++k) dst[m][k] = *(const LAS bf16x8*)(lds + PG8_SA(b, h) + aoff + m * 2048 + k * 1024); } while (0)
; #define PG8_LDB(dst, b, h) do { _Pragma("unroll") for (int n = 0; n < 2; ++n) _Pragma("unroll") for (int k = 0; k < 2; ++k) dst[n][k] = *(const LAS bf16x8*)(lds + PG8_SB(b, h) + boff + n * 2048 + k * 1024); } while (0)
; #define PG8_MMA(ai, bj, At, Bt) do { __builtin_amdgcn_s_setprio(1); _Pragma("unroll") for (int m = 0; m < 4; ++m) _Pragma("unroll") for (int n = 0; n < 2; ++n) _Pragma("unroll") for (int k = 0; k < 2; ++k) \
;         acc[ai][bj][m][n] = __builtin_amdgcn_mfma_f32_16x16x32_bf16(Bt[n][k], At[m][k], acc[ai][bj][m][n], 0, 0, 0); __builtin_amdgcn_s_setprio(0); } while (0)
; #define PG8_WAIT_V(n) asm volatile("s_waitcnt vmcnt(" #n ")" ::: "memory")
; #define PG8_WAIT_L(n) asm volatile("s_waitcnt lgkmcnt(" #n ")" ::: "memory")
; #define PG8_BAR __builtin_amdgcn_s_barrier()
; #define PG8_SCHED __builtin_amdgcn_sched_barrier(0)
; template <class Epi>
; __device__ __forceinline__ void gemm_phase(LAS unsigned char* lds, const Gemm g, const StaticOrder& S, const Epi& E, const int wid) {
;     ...
;             PG8_WAIT_V(8); PG8_WAIT_L(0); PG8_BAR; PG8_MMA(1, 0, At, B0); PG8_MMA(1, 1, At, B1); PG8_BAR; PG8_SCHED;
;             PG8_LDB(B0, 1, 0); PG8_LDB(B1, 1, 1); PG8_SCHED; PG8_LDA(At, 1, 0); PG8_STAGE(PG8_SA(0, 1), a2 + hsA, voffA);
;             PG8_WAIT_V(8); PG8_WAIT_L(0); PG8_BAR; PG8_MMA(0, 0, At, B0); PG8_MMA(0, 1, At, B1); PG8_BAR; PG8_SCHED;
	s_setprio 1
	s_waitcnt lgkmcnt(0)
	v_mfma_f32_16x16x32_bf16 v[56:59], v[128:131], v[182:185], v[56:59]
	v_mfma_f32_16x16x32_bf16 v[60:63], v[136:139], v[182:185], v[60:63]
	v_mfma_f32_16x16x32_bf16 v[40:43], v[128:131], v[190:193], v[40:43]
	v_mfma_f32_16x16x32_bf16 v[44:47], v[136:139], v[190:193], v[44:47]
	v_mfma_f32_16x16x32_bf16 v[24:27], v[128:131], v[198:201], v[24:27]
	v_mfma_f32_16x16x32_bf16 v[28:31], v[136:139], v[198:201], v[28:31]
	v_mfma_f32_16x16x32_bf16 v[8:11], v[128:131], v[206:209], v[8:11]
	v_mfma_f32_16x16x32_bf16 v[12:15], v[136:139], v[206:209], v[12:15]
	v_mfma_f32_16x16x32_bf16 v[56:59], v[132:135], v[186:189], v[56:59]
	v_mfma_f32_16x16x32_bf16 v[60:63], v[140:143], v[186:189], v[60:63]
	v_mfma_f32_16x16x32_bf16 v[40:43], v[132:135], v[194:197], v[40:43]
	v_mfma_f32_16x16x32_bf16 v[44:47], v[140:143], v[194:197], v[44:47]
	v_mfma_f32_16x16x32_bf16 v[24:27], v[132:135], v[202:205], v[24:27]
	v_mfma_f32_16x16x32_bf16 v[28:31], v[140:143], v[202:205], v[28:31]
	v_mfma_f32_16x16x32_bf16 v[8:11], v[132:135], v[210:213], v[8:11]
	v_mfma_f32_16x16x32_bf16 v[12:15], v[140:143], v[210:213], v[12:15]
	s_setprio 0
	s_setprio 1
	v_mfma_f32_16x16x32_bf16 v[48:51], v[160:163], v[182:185], v[48:51]
	v_mfma_f32_16x16x32_bf16 v[52:55], v[174:177], v[182:185], v[52:55]
	v_mfma_f32_16x16x32_bf16 v[32:35], v[160:163], v[190:193], v[32:35]
	v_mfma_f32_16x16x32_bf16 v[36:39], v[174:177], v[190:193], v[36:39]
	v_mfma_f32_16x16x32_bf16 v[16:19], v[160:163], v[198:201], v[16:19]
	v_mfma_f32_16x16x32_bf16 v[20:23], v[174:177], v[198:201], v[20:23]
	v_mfma_f32_16x16x32_bf16 v[0:3], v[160:163], v[206:209], v[0:3]
	v_mfma_f32_16x16x32_bf16 v[4:7], v[174:177], v[206:209], v[4:7]
	v_mfma_f32_16x16x32_bf16 v[48:51], v[164:167], v[186:189], v[48:51]
	v_mfma_f32_16x16x32_bf16 v[52:55], v[178:181], v[186:189], v[52:55]
	v_mfma_f32_16x16x32_bf16 v[32:35], v[164:167], v[194:197], v[32:35]
	v_mfma_f32_16x16x32_bf16 v[36:39], v[178:181], v[194:197], v[36:39]
	v_mfma_f32_16x16x32_bf16 v[16:19], v[164:167], v[202:205], v[16:19]
	v_mfma_f32_16x16x32_bf16 v[20:23], v[178:181], v[202:205], v[20:23]
	v_mfma_f32_16x16x32_bf16 v[0:3], v[164:167], v[210:213], v[0:3]
	v_mfma_f32_16x16x32_bf16 v[4:7], v[178:181], v[210:213], v[4:7]
	s_setprio 0
	s_barrier
	s_add_i32 s66, 0, 0x18000
	s_add_i32 s67, 0, 0x1c000
	v_add_u32_e32 v140, s66, v168
	v_add_u32_e32 v173, s67, v168
	ds_read_b128 v[128:131], v140
	ds_read_b128 v[132:135], v140 offset:1024
	ds_read_b128 v[136:139], v140 offset:2048
	ds_read_b128 v[140:143], v140 offset:3072
	ds_read_b128 v[160:163], v173
	ds_read_b128 v[164:167], v173 offset:1024
	ds_read_b128 v[174:177], v173 offset:2048
	ds_read_b128 v[178:181], v173 offset:3072
	s_add_u32 s38, s38, 0x40000
	s_addc_u32 s39, s39, 0
	s_mov_b32 m0, s50
	v_lshl_add_u64 v[222:223], s[38:39], 0, v[144:145]
	ds_read_b128 v[182:185], v171 offset:32768
	ds_read_b128 v[186:189], v171 offset:33792
	ds_read_b128 v[190:193], v171 offset:34816
	ds_read_b128 v[194:197], v171 offset:35840
	ds_read_b128 v[198:201], v171 offset:36864
	ds_read_b128 v[202:205], v171 offset:37888
	ds_read_b128 v[206:209], v171 offset:38912
	ds_read_b128 v[210:213], v171 offset:39936
	global_load_lds_dwordx4 v[222:223], off
	v_lshl_add_u64 v[222:223], s[38:39], 0, v[148:149]
	s_mov_b32 m0, s51
	s_nop 0
	global_load_lds_dwordx4 v[222:223], off
	s_waitcnt vmcnt(8)
	s_waitcnt lgkmcnt(0)
	s_barrier
	s_setprio 1
	s_waitcnt lgkmcnt(0)
	v_mfma_f32_16x16x32_bf16 v[124:127], v[128:131], v[182:185], v[124:127]
	v_mfma_f32_16x16x32_bf16 v[120:123], v[136:139], v[182:185], v[120:123]
	v_mfma_f32_16x16x32_bf16 v[104:107], v[128:131], v[190:193], v[104:107]
	v_mfma_f32_16x16x32_bf16 v[108:111], v[136:139], v[190:193], v[108:111]
	v_mfma_f32_16x16x32_bf16 v[88:91], v[128:131], v[198:201], v[88:91]
	v_mfma_f32_16x16x32_bf16 v[92:95], v[136:139], v[198:201], v[92:95]
	v_mfma_f32_16x16x32_bf16 v[72:75], v[128:131], v[206:209], v[72:75]
	v_mfma_f32_16x16x32_bf16 v[76:79], v[136:139], v[206:209], v[76:79]
	v_mfma_f32_16x16x32_bf16 v[124:127], v[132:135], v[186:189], v[124:127]
	v_mfma_f32_16x16x32_bf16 v[120:123], v[140:143], v[186:189], v[120:123]
	v_mfma_f32_16x16x32_bf16 v[104:107], v[132:135], v[194:197], v[104:107]
	v_mfma_f32_16x16x32_bf16 v[108:111], v[140:143], v[194:197], v[108:111]
	v_mfma_f32_16x16x32_bf16 v[88:91], v[132:135], v[202:205], v[88:91]
	v_mfma_f32_16x16x32_bf16 v[92:95], v[140:143], v[202:205], v[92:95]
	v_mfma_f32_16x16x32_bf16 v[72:75], v[132:135], v[210:213], v[72:75]
	v_mfma_f32_16x16x32_bf16 v[76:79], v[140:143], v[210:213], v[76:79]
	s_setprio 0
	s_setprio 1
	v_mfma_f32_16x16x32_bf16 v[112:115], v[160:163], v[182:185], v[112:115]
	v_mfma_f32_16x16x32_bf16 v[116:119], v[174:177], v[182:185], v[116:119]
	v_mfma_f32_16x16x32_bf16 v[96:99], v[160:163], v[190:193], v[96:99]
	v_mfma_f32_16x16x32_bf16 v[100:103], v[174:177], v[190:193], v[100:103]
	v_mfma_f32_16x16x32_bf16 v[80:83], v[160:163], v[198:201], v[80:83]
	v_mfma_f32_16x16x32_bf16 v[84:87], v[174:177], v[198:201], v[84:87]
	v_mfma_f32_16x16x32_bf16 v[64:67], v[160:163], v[206:209], v[64:67]
	v_mfma_f32_16x16x32_bf16 v[68:71], v[174:177], v[206:209], v[68:71]
	v_mfma_f32_16x16x32_bf16 v[112:115], v[164:167], v[186:189], v[112:115]
	v_mfma_f32_16x16x32_bf16 v[116:119], v[178:181], v[186:189], v[116:119]
	v_mfma_f32_16x16x32_bf16 v[96:99], v[164:167], v[194:197], v[96:99]
	v_mfma_f32_16x16x32_bf16 v[100:103], v[178:181], v[194:197], v[100:103]
	v_mfma_f32_16x16x32_bf16 v[80:83], v[164:167], v[202:205], v[80:83]
	v_mfma_f32_16x16x32_bf16 v[84:87], v[178:181], v[202:205], v[84:87]
	v_mfma_f32_16x16x32_bf16 v[64:67], v[164:167], v[210:213], v[64:67]
	v_mfma_f32_16x16x32_bf16 v[68:71], v[178:181], v[210:213], v[68:71]
	s_setprio 0
	s_barrier
; #define PG8_STAGE(bufoff, gbase, voff) do { _Pragma("unroll") for (int _i = 0; _i < 2; ++_i) \
;         __builtin_amdgcn_global_load_lds((const unsigned*)((const char*)(gbase) + (voff)[_i]), (LAS unsigned*)(lds + (bufoff) + ldsw + _i * 8192), 16, 0, 0); } while (0)
; #define PG8_LDA(dst, b, h) do { _Pragma("unroll") for (int m = 0; m < 4; ++m) _Pragma("unroll") for (int k = 0; k < 2; ++k) dst[m][k] = *(const LAS bf16x8*)(lds + PG8_SA(b, h) + aoff + m * 2048 + k * 1024); } while (0)
; #define PG8_MMA(ai, bj, At, Bt) do { __builtin_amdgcn_s_setprio(1); _Pragma("unroll") for (int m = 0; m < 4; ++m) _Pragma("unroll") for (int n = 0; n < 2; ++n) _Pragma("unroll") for (int k = 0; k < 2; ++k) \
;         acc[ai][bj][m][n] = __builtin_amdgcn_mfma_f32_16x16x32_bf16(Bt[n][k], At[m][k], acc[ai][bj][m][n], 0, 0, 0); __builtin_amdgcn_s_setprio(0); } while (0)
; #define PG8_WAIT_V(n) asm volatile("s_waitcnt vmcnt(" #n ")" ::: "memory")
; #define PG8_WAIT_L(n) asm volatile("s_waitcnt lgkmcnt(" #n ")" ::: "memory")
; #define PG8_BAR __builtin_amdgcn_s_barrier()
; #define PG8_SCHED __builtin_amdgcn_sched_barrier(0)
; template <class Epi>
; __device__ __forceinline__ void gemm_phase(LAS unsigned char* lds, const Gemm g, const StaticOrder& S, const Epi& E, const int wid) {
;     ...
;             PG8_LDA(At, 1, 1); PG8_STAGE(PG8_SB(1, 0), b3, voffB); PG8_STAGE(PG8_SB(1, 1), b3 + hsB, voffB); PG8_STAGE(PG8_SA(1, 0), a3, voffA);
;             PG8_WAIT_V(8); PG8_WAIT_L(0); PG8_BAR; PG8_MMA(1, 0, At, B0); PG8_MMA(1, 1, At, B1); PG8_BAR; PG8_SCHED;
;         }
;         if (wr == 0) PG8_BAR;
;     __device__ __forceinline__ void operator()(const Acc& acc, const pg8::Unit& u, int wid) const {
;     ...
; #pragma unroll
;         for (int ai = 0; ai < 2; ++ai)
; #pragma unroll
;             for (int mp = 0; mp < 2; ++mp) {
;                 u32x4 hv[2][2], pw[2][2]; float scv[2];
; #pragma unroll
;                 for (int mm = 0; mm < 2; ++mm) {
;                     const int row = row0 + ai * 128 + (2 * mp + mm) * 16;
;                     scv[mm] = ssq[row];
; #pragma unroll
;                     for (int bj = 0; bj < 2; ++bj) { const size_t off = (size_t)row * 1024 + col0 + bj * 128; hv[mm][bj] = *(const u32x4*)(hbase + off); pw[mm][bj] = *(const u32x4*)(pp + off); }
	s_add_i32 s38, s66, s68
	v_lshl_add_u64 v[214:215], v[214:215], 0, s[6:7]
	s_mov_b32 m0, s38
	ds_read_b128 v[182:185], v171 offset:49152
	ds_read_b128 v[186:189], v171 offset:50176
	ds_read_b128 v[190:193], v171 offset:51200
	ds_read_b128 v[194:197], v171 offset:52224
	ds_read_b128 v[198:201], v171 offset:53248
	ds_read_b128 v[202:205], v171 offset:54272
	ds_read_b128 v[206:209], v171 offset:55296
	ds_read_b128 v[210:213], v171 offset:56320
	global_load_lds_dwordx4 v[214:215], off
	s_add_i32 m0, s38, 0x2000
	s_add_u32 s34, s34, 0x40080
	v_lshl_add_u64 v[214:215], v[216:217], 0, s[6:7]
	s_addc_u32 s35, s35, 0
	s_add_i32 s38, s67, s68
	global_load_lds_dwordx4 v[214:215], off
	v_lshl_add_u64 v[214:215], s[34:35], 0, v[146:147]
	s_mov_b32 m0, s38
	s_nop 0
	global_load_lds_dwordx4 v[214:215], off
	v_lshl_add_u64 v[214:215], s[34:35], 0, v[150:151]
	s_add_i32 m0, s38, 0x2000
	s_nop 0
	global_load_lds_dwordx4 v[214:215], off
	v_lshl_add_u64 v[214:215], v[218:219], 0, s[6:7]
	s_mov_b32 m0, s55
	s_nop 0
	global_load_lds_dwordx4 v[214:215], off
	v_lshl_add_u64 v[214:215], v[220:221], 0, s[6:7]
	s_mov_b32 m0, s57
	s_nop 0
	global_load_lds_dwordx4 v[214:215], off
	s_waitcnt vmcnt(8)
	s_waitcnt lgkmcnt(0)
	s_barrier
	s_setprio 1
	s_waitcnt lgkmcnt(0)
	v_mfma_f32_16x16x32_bf16 v[56:59], v[128:131], v[182:185], v[56:59]
	v_mfma_f32_16x16x32_bf16 v[60:63], v[136:139], v[182:185], v[60:63]
	v_mfma_f32_16x16x32_bf16 v[40:43], v[128:131], v[190:193], v[40:43]
	v_mfma_f32_16x16x32_bf16 v[44:47], v[136:139], v[190:193], v[44:47]
	v_mfma_f32_16x16x32_bf16 v[24:27], v[128:131], v[198:201], v[24:27]
	v_mfma_f32_16x16x32_bf16 v[28:31], v[136:139], v[198:201], v[28:31]
	v_mfma_f32_16x16x32_bf16 v[8:11], v[128:131], v[206:209], v[8:11]
	v_mfma_f32_16x16x32_bf16 v[12:15], v[136:139], v[206:209], v[12:15]
	v_mfma_f32_16x16x32_bf16 v[56:59], v[132:135], v[186:189], v[56:59]
	v_mfma_f32_16x16x32_bf16 v[60:63], v[140:143], v[186:189], v[60:63]
	v_mfma_f32_16x16x32_bf16 v[40:43], v[132:135], v[194:197], v[40:43]
	v_mfma_f32_16x16x32_bf16 v[44:47], v[140:143], v[194:197], v[44:47]
	v_mfma_f32_16x16x32_bf16 v[24:27], v[132:135], v[202:205], v[24:27]
	v_mfma_f32_16x16x32_bf16 v[28:31], v[140:143], v[202:205], v[28:31]
	v_mfma_f32_16x16x32_bf16 v[8:11], v[132:135], v[210:213], v[8:11]
	v_mfma_f32_16x16x32_bf16 v[12:15], v[140:143], v[210:213], v[12:15]
	s_setprio 0
	s_setprio 1
	v_mfma_f32_16x16x32_bf16 v[48:51], v[160:163], v[182:185], v[48:51]
	v_mfma_f32_16x16x32_bf16 v[52:55], v[174:177], v[182:185], v[52:55]
	v_mfma_f32_16x16x32_bf16 v[32:35], v[160:163], v[190:193], v[32:35]
	v_mfma_f32_16x16x32_bf16 v[36:39], v[174:177], v[190:193], v[36:39]
	v_mfma_f32_16x16x32_bf16 v[16:19], v[160:163], v[198:201], v[16:19]
	v_mfma_f32_16x16x32_bf16 v[20:23], v[174:177], v[198:201], v[20:23]
	v_mfma_f32_16x16x32_bf16 v[0:3], v[160:163], v[206:209], v[0:3]
	v_mfma_f32_16x16x32_bf16 v[4:7], v[174:177], v[206:209], v[4:7]
	v_mfma_f32_16x16x32_bf16 v[48:51], v[164:167], v[186:189], v[48:51]
	v_mfma_f32_16x16x32_bf16 v[52:55], v[178:181], v[186:189], v[52:55]
	v_mfma_f32_16x16x32_bf16 v[32:35], v[164:167], v[194:197], v[32:35]
	v_mfma_f32_16x16x32_bf16 v[36:39], v[178:181], v[194:197], v[36:39]
	v_mfma_f32_16x16x32_bf16 v[16:19], v[164:167], v[202:205], v[16:19]
	v_mfma_f32_16x16x32_bf16 v[20:23], v[178:181], v[202:205], v[20:23]
	v_mfma_f32_16x16x32_bf16 v[0:3], v[164:167], v[210:213], v[0:3]
	v_mfma_f32_16x16x32_bf16 v[4:7], v[178:181], v[210:213], v[4:7]
	s_setprio 0
	s_barrier
	s_add_i32 s65, s65, 2
	s_add_u32 s63, s63, 0x100
	s_addc_u32 s64, s64, 0
	s_add_u32 s30, s30, 0x100
	s_addc_u32 s31, s31, 0
	s_cmp_gt_u32 s65, 13
	s_cbranch_scc0 .LBB0_1353
.LBB0_1356:
	s_andn2_b64 vcc, exec, s[40:41]
	v_mbcnt_lo_u32_b32 v128, -1, 0
	v_mbcnt_hi_u32_b32 v128, -1, v128
	s_cbranch_vccnz .LBB0_1358
	s_lshl_b32 s21, s60, 8
	v_ashrrev_i32_e32 v129, 1, v128
	s_or_b32 s21, s21, s69
	v_and_b32_e32 v129, -8, v129
	v_add_u32_e32 v164, s21, v129
	s_lshl_b32 s21, s28, 8
	s_add_i32 s21, s21, s3
	v_and_or_b32 v166, v128, 15, s21
	v_ashrrev_i32_e32 v167, 31, v166
	v_lshl_add_u64 v[160:161], v[166:167], 2, s[36:37]
	flat_load_dword v173, v[160:161]
	v_ashrrev_i32_e32 v165, 31, v164
	v_lshlrev_b64 v[128:129], 10, v[166:167]
	v_lshl_add_u64 v[162:163], v[128:129], 0, v[164:165]
	v_lshlrev_b64 v[128:129], 1, v[162:163]
	v_lshl_add_u64 v[130:131], s[48:49], 0, v[128:129]
	flat_load_dwordx4 v[174:177], v[130:131]
	v_lshl_add_u64 v[130:131], s[42:43], 0, v[128:129]
	flat_load_dwordx4 v[178:181], v[130:131]
	v_or_b32_e32 v130, 16, v166
	v_ashrrev_i32_e32 v131, 31, v130
	v_lshlrev_b64 v[132:133], 10, v[130:131]
	v_lshl_add_u64 v[190:191], v[132:133], 0, v[164:165]
	v_lshlrev_b64 v[132:133], 1, v[190:191]
	v_lshl_add_u64 v[128:129], v[128:129], 0, s[10:11]
	v_lshl_add_u64 v[130:131], v[130:131], 2, s[36:37]
	v_lshl_add_u64 v[134:135], v[132:133], 0, s[10:11]
	v_lshl_add_u64 v[140:141], s[48:49], 0, v[132:133]
	v_lshl_add_u64 v[132:133], s[42:43], 0, v[132:133]
	v_lshl_add_u64 v[142:143], s[48:49], 0, v[128:129]
	v_lshl_add_u64 v[128:129], s[42:43], 0, v[128:129]
	v_lshl_add_u64 v[194:195], s[48:49], 0, v[134:135]
	v_lshl_add_u64 v[196:197], s[42:43], 0, v[134:135]
	flat_load_dwordx4 v[136:139], v[132:133]
	flat_load_dword v167, v[130:131]
	flat_load_dwordx4 v[182:185], v[142:143]
	flat_load_dwordx4 v[186:189], v[128:129]
	s_nop 0
	flat_load_dwordx4 v[132:135], v[194:195]
	flat_load_dwordx4 v[128:131], v[196:197]
	s_nop 0
	flat_load_dwordx4 v[140:143], v[140:141]
	v_lshl_add_u64 v[192:193], v[162:163], 2, s[52:53]
	s_waitcnt vmcnt(0) lgkmcnt(0)
; __device__ __forceinline__ u32x4 pack8(f32x4 a, f32x4 b) { u32x4 w; w.x = pk2(a[0], a[1]); w.y = pk2(a[2], a[3]); w.z = pk2(b[0], b[1]); w.w = pk2(b[2], b[3]); return w; }
;     __device__ __forceinline__ void operator()(const Acc& acc, const pg8::Unit& u, int wid) const {
;     ...
;                 for (int mm = 0; mm < 2; ++mm) {
;                     const int m = 2 * mp + mm, row = row0 + ai * 128 + m * 16; float sq = 0.f;
;                     const float sc = __builtin_amdgcn_rsqf(scv[mm] * (1.f / 1024.f) + EPS);
; #pragma unroll
;                     for (int bj = 0; bj < 2; ++bj) {
;                         const size_t off = (size_t)row * 1024 + col0 + bj * 128;
;                         const u32x4 pwv = pw[mm][bj], hw = hv[mm][bj];
;                         const f32x4 p0 = (f32x4){bflo(pwv.x), bfhi(pwv.x), bflo(pwv.y), bfhi(pwv.y)}, p1 = (f32x4){bflo(pwv.z), bfhi(pwv.z), bflo(pwv.w), bfhi(pwv.w)};
;                         f32x4 g0 = acc[ai][bj][m][0] * sc, g1 = acc[ai][bj][m][1] * sc;
; #pragma unroll
;                         for (int e = 0; e < 4; ++e) { g0[e] = __builtin_amdgcn_rcpf(1.f + __builtin_amdgcn_exp2f(-1.4426950408889634f * g0[e])); g1[e] = __builtin_amdgcn_rcpf(1.f + __builtin_amdgcn_exp2f(-1.4426950408889634f * g1[e])); }
;                         const f32x4 o0 = (f32x4){bflo(hw.x), bfhi(hw.x), bflo(hw.y), bfhi(hw.y)} + g0 * p0;
;                         const f32x4 o1 = (f32x4){bflo(hw.z), bfhi(hw.z), bflo(hw.w), bfhi(hw.w)} + g1 * p1;
;                         if (fout) { *(f32x4*)(fout + off) = o0; *(f32x4*)(fout + off + 4) = o1; }
;                         if (hb_out) *(u32x4*)(hb_out + off) = pack8(o0, o1);
;                         sq += (o0[0] * o0[0] + o0[1] * o0[1]) + (o0[2] * o0[2] + o0[3] * o0[3]) + (o1[0] * o1[0] + o1[1] * o1[1]) + (o1[2] * o1[2] + o1[3] * o1[3]);
;                     }
	v_fmamk_f32 v173, v173, 0x3a800000, v172
	v_rsq_f32_e32 v194, v173
	v_lshlrev_b32_e32 v196, 16, v176
	v_pk_mul_f32 v[120:121], v[120:121], v[194:195] op_sel_hi:[1,0]
	v_pk_mul_f32 v[126:127], v[126:127], v[194:195] op_sel_hi:[1,0]
	v_pk_mul_f32 v[124:125], v[124:125], v[194:195] op_sel_hi:[1,0]
	v_pk_mul_f32 v[122:123], v[122:123], v[194:195] op_sel_hi:[1,0]
	v_mul_f32_e32 v120, 0xbfb8aa3b, v120
	v_mul_f32_e32 v121, 0xbfb8aa3b, v121
	v_mul_f32_e32 v124, 0xbfb8aa3b, v124
	v_mul_f32_e32 v125, 0xbfb8aa3b, v125
	v_mul_f32_e32 v126, 0xbfb8aa3b, v126
	v_mul_f32_e32 v127, 0xbfb8aa3b, v127
	v_mul_f32_e32 v122, 0xbfb8aa3b, v122
	v_mul_f32_e32 v123, 0xbfb8aa3b, v123
	v_exp_f32_e32 v120, v120
	v_exp_f32_e32 v121, v121
	v_exp_f32_e32 v124, v124
	v_exp_f32_e32 v125, v125
	v_exp_f32_e32 v126, v126
	v_exp_f32_e32 v127, v127
	v_exp_f32_e32 v122, v122
	v_exp_f32_e32 v123, v123
	v_add_f32_e32 v120, 1.0, v120
	v_add_f32_e32 v121, 1.0, v121
	v_add_f32_e32 v124, 1.0, v124
	v_add_f32_e32 v125, 1.0, v125
	v_add_f32_e32 v126, 1.0, v126
	v_add_f32_e32 v127, 1.0, v127
	v_add_f32_e32 v122, 1.0, v122
	v_add_f32_e32 v123, 1.0, v123
	v_rcp_f32_e32 v120, v120
	v_rcp_f32_e32 v121, v121
	v_rcp_f32_e32 v124, v124
	v_rcp_f32_e32 v126, v126
	v_rcp_f32_e32 v127, v127
	v_rcp_f32_e32 v125, v125
	v_rcp_f32_e32 v122, v122
	v_rcp_f32_e32 v123, v123
	v_and_b32_e32 v197, 0xffff0000, v176
	v_lshlrev_b32_e32 v198, 16, v180
	v_and_b32_e32 v199, 0xffff0000, v180
	v_lshlrev_b32_e32 v200, 16, v174
	v_and_b32_e32 v201, 0xffff0000, v174
	v_lshlrev_b32_e32 v174, 16, v175
	v_and_b32_e32 v175, 0xffff0000, v175
	v_lshlrev_b32_e32 v202, 16, v178
	v_and_b32_e32 v203, 0xffff0000, v178
	v_lshlrev_b32_e32 v178, 16, v179
	v_and_b32_e32 v179, 0xffff0000, v179
	v_pk_mul_f32 v[116:117], v[116:117], v[194:195] op_sel_hi:[1,0]
	v_lshlrev_b32_e32 v176, 16, v177
	v_and_b32_e32 v177, 0xffff0000, v177
	v_lshlrev_b32_e32 v180, 16, v181
	v_and_b32_e32 v181, 0xffff0000, v181
	v_mul_f32_e32 v116, 0xbfb8aa3b, v116
	v_pk_fma_f32 v[120:121], v[120:121], v[196:197], v[198:199]
	v_pk_fma_f32 v[126:127], v[126:127], v[174:175], v[178:179]
	v_pk_fma_f32 v[124:125], v[124:125], v[200:201], v[202:203]
	v_pk_fma_f32 v[122:123], v[122:123], v[176:177], v[180:181]
	global_store_dwordx4 v[192:193], v[124:127], off
	global_store_dwordx4 v[192:193], v[120:123], off offset:16
	v_pk_mul_f32 v[112:113], v[112:113], v[194:195] op_sel_hi:[1,0]
	v_lshlrev_b32_e32 v124, 16, v188
	v_exp_f32_e32 v120, v116
	v_mul_f32_e32 v116, 0xbfb8aa3b, v117
	v_exp_f32_e32 v121, v116
	v_pk_mul_f32 v[116:117], v[118:119], v[194:195] op_sel_hi:[1,0]
	v_add_f32_e32 v118, 1.0, v120
	v_mul_f32_e32 v116, 0xbfb8aa3b, v116
	v_mul_f32_e32 v117, 0xbfb8aa3b, v117
	v_exp_f32_e32 v116, v116
	v_exp_f32_e32 v117, v117
	v_rcp_f32_e32 v120, v118
	v_add_f32_e32 v118, 1.0, v121
	v_add_f32_e32 v116, 1.0, v116
	v_add_f32_e32 v117, 1.0, v117
	v_rcp_f32_e32 v121, v118
	v_rcp_f32_e32 v116, v116
	v_rcp_f32_e32 v117, v117
	v_lshlrev_b32_e32 v122, 16, v184
	v_and_b32_e32 v123, 0xffff0000, v184
	v_lshlrev_b32_e32 v118, 16, v185
	v_and_b32_e32 v119, 0xffff0000, v185
	v_and_b32_e32 v125, 0xffff0000, v188
	v_lshlrev_b32_e32 v126, 16, v189
	v_and_b32_e32 v127, 0xffff0000, v189
	v_mul_f32_e32 v112, 0xbfb8aa3b, v112
	v_pk_fma_f32 v[118:119], v[116:117], v[118:119], v[126:127]
	v_pk_fma_f32 v[116:117], v[120:121], v[122:123], v[124:125]
	v_exp_f32_e32 v120, v112
	v_mul_f32_e32 v112, 0xbfb8aa3b, v113
	v_exp_f32_e32 v121, v112
	v_pk_mul_f32 v[112:113], v[114:115], v[194:195] op_sel_hi:[1,0]
	v_add_f32_e32 v114, 1.0, v120
	v_mul_f32_e32 v112, 0xbfb8aa3b, v112
	v_mul_f32_e32 v113, 0xbfb8aa3b, v113
	v_exp_f32_e32 v112, v112
	v_exp_f32_e32 v113, v113
	v_rcp_f32_e32 v120, v114
	v_add_f32_e32 v114, 1.0, v121
	v_add_f32_e32 v112, 1.0, v112
	v_add_f32_e32 v113, 1.0, v113
	v_rcp_f32_e32 v121, v114
	v_rcp_f32_e32 v112, v112
	v_rcp_f32_e32 v113, v113
	v_lshlrev_b32_e32 v122, 16, v182
	v_and_b32_e32 v123, 0xffff0000, v182
	v_lshlrev_b32_e32 v114, 16, v183
	v_and_b32_e32 v115, 0xffff0000, v183
	v_lshlrev_b32_e32 v124, 16, v186
	v_and_b32_e32 v125, 0xffff0000, v186
	v_lshlrev_b32_e32 v126, 16, v187
	v_and_b32_e32 v127, 0xffff0000, v187
	v_pk_fma_f32 v[114:115], v[112:113], v[114:115], v[126:127]
	v_pk_fma_f32 v[112:113], v[120:121], v[122:123], v[124:125]
	v_fmamk_f32 v120, v167, 0x3a800000, v172
	v_rsq_f32_e32 v120, v120
	global_store_dwordx4 v[192:193], v[112:115], off offset:512
	global_store_dwordx4 v[192:193], v[116:119], off offset:528
	v_lshlrev_b32_e32 v122, 16, v139
	v_and_b32_e32 v123, 0xffff0000, v139
	v_pk_mul_f32 v[108:109], v[108:109], v[120:121] op_sel_hi:[1,0]
	v_pk_mul_f32 v[104:105], v[104:105], v[120:121] op_sel_hi:[1,0]
	v_mul_f32_e32 v108, 0xbfb8aa3b, v108
	v_exp_f32_e32 v114, v108
	v_mul_f32_e32 v108, 0xbfb8aa3b, v109
	v_exp_f32_e32 v115, v108
	v_pk_mul_f32 v[108:109], v[110:111], v[120:121] op_sel_hi:[1,0]
	v_add_f32_e32 v110, 1.0, v114
	v_mul_f32_e32 v108, 0xbfb8aa3b, v108
	v_mul_f32_e32 v109, 0xbfb8aa3b, v109
	v_exp_f32_e32 v108, v108
	v_exp_f32_e32 v109, v109
	v_rcp_f32_e32 v114, v110
	v_add_f32_e32 v110, 1.0, v115
	v_add_f32_e32 v108, 1.0, v108
	v_add_f32_e32 v109, 1.0, v109
	v_rcp_f32_e32 v115, v110
	v_rcp_f32_e32 v108, v108
	v_rcp_f32_e32 v109, v109
	v_lshlrev_b32_e32 v116, 16, v142
	v_and_b32_e32 v117, 0xffff0000, v142
	v_lshlrev_b32_e32 v110, 16, v143
	v_and_b32_e32 v111, 0xffff0000, v143
	v_lshlrev_b32_e32 v118, 16, v138
	v_and_b32_e32 v119, 0xffff0000, v138
	v_mul_f32_e32 v104, 0xbfb8aa3b, v104
	v_pk_fma_f32 v[110:111], v[108:109], v[110:111], v[122:123]
	v_pk_fma_f32 v[108:109], v[114:115], v[116:117], v[118:119]
	v_exp_f32_e32 v114, v104
	v_mul_f32_e32 v104, 0xbfb8aa3b, v105
; __device__ __forceinline__ u32x4 pack8(f32x4 a, f32x4 b) { u32x4 w; w.x = pk2(a[0], a[1]); w.y = pk2(a[2], a[3]); w.z = pk2(b[0], b[1]); w.w = pk2(b[2], b[3]); return w; }
;     __device__ __forceinline__ void operator()(const Acc& acc, const pg8::Unit& u, int wid) const {
;     ...
;                 for (int mm = 0; mm < 2; ++mm) {
;                     const int m = 2 * mp + mm, row = row0 + ai * 128 + m * 16; float sq = 0.f;
;                     const float sc = __builtin_amdgcn_rsqf(scv[mm] * (1.f / 1024.f) + EPS);
; #pragma unroll
;                     for (int bj = 0; bj < 2; ++bj) {
;                         const size_t off = (size_t)row * 1024 + col0 + bj * 128;
;                         const u32x4 pwv = pw[mm][bj], hw = hv[mm][bj];
;                         const f32x4 p0 = (f32x4){bflo(pwv.x), bfhi(pwv.x), bflo(pwv.y), bfhi(pwv.y)}, p1 = (f32x4){bflo(pwv.z), bfhi(pwv.z), bflo(pwv.w), bfhi(pwv.w)};
;                         f32x4 g0 = acc[ai][bj][m][0] * sc, g1 = acc[ai][bj][m][1] * sc;
; #pragma unroll
;                         for (int e = 0; e < 4; ++e) { g0[e] = __builtin_amdgcn_rcpf(1.f + __builtin_amdgcn_exp2f(-1.4426950408889634f * g0[e])); g1[e] = __builtin_amdgcn_rcpf(1.f + __builtin_amdgcn_exp2f(-1.4426950408889634f * g1[e])); }
;                         const f32x4 o0 = (f32x4){bflo(hw.x), bfhi(hw.x), bflo(hw.y), bfhi(hw.y)} + g0 * p0;
;                         const f32x4 o1 = (f32x4){bflo(hw.z), bfhi(hw.z), bflo(hw.w), bfhi(hw.w)} + g1 * p1;
;                         if (fout) { *(f32x4*)(fout + off) = o0; *(f32x4*)(fout + off + 4) = o1; }
;                         if (hb_out) *(u32x4*)(hb_out + off) = pack8(o0, o1);
;                         sq += (o0[0] * o0[0] + o0[1] * o0[1]) + (o0[2] * o0[2] + o0[3] * o0[3]) + (o1[0] * o1[0] + o1[1] * o1[1]) + (o1[2] * o1[2] + o1[3] * o1[3]);
;                     }
	v_exp_f32_e32 v115, v104
	v_pk_mul_f32 v[104:105], v[106:107], v[120:121] op_sel_hi:[1,0]
	v_add_f32_e32 v106, 1.0, v114
	v_mul_f32_e32 v104, 0xbfb8aa3b, v104
	v_mul_f32_e32 v105, 0xbfb8aa3b, v105
	v_exp_f32_e32 v104, v104
	v_exp_f32_e32 v105, v105
	v_rcp_f32_e32 v114, v106
	v_add_f32_e32 v106, 1.0, v115
	v_add_f32_e32 v104, 1.0, v104
	v_add_f32_e32 v105, 1.0, v105
	v_rcp_f32_e32 v115, v106
	v_rcp_f32_e32 v104, v104
	v_rcp_f32_e32 v105, v105
	v_lshlrev_b32_e32 v116, 16, v140
	v_and_b32_e32 v117, 0xffff0000, v140
	v_lshlrev_b32_e32 v106, 16, v141
	v_and_b32_e32 v107, 0xffff0000, v141
	v_lshlrev_b32_e32 v118, 16, v136
	v_and_b32_e32 v119, 0xffff0000, v136
	v_lshlrev_b32_e32 v122, 16, v137
	v_and_b32_e32 v123, 0xffff0000, v137
	v_pk_mul_f32 v[100:101], v[100:101], v[120:121] op_sel_hi:[1,0]
	v_lshl_add_u64 v[112:113], v[190:191], 2, s[52:53]
	v_pk_fma_f32 v[106:107], v[104:105], v[106:107], v[122:123]
	v_pk_fma_f32 v[104:105], v[114:115], v[116:117], v[118:119]
	v_mul_f32_e32 v100, 0xbfb8aa3b, v100
	global_store_dwordx4 v[112:113], v[104:107], off
	global_store_dwordx4 v[112:113], v[108:111], off offset:16
	v_pk_mul_f32 v[96:97], v[96:97], v[120:121] op_sel_hi:[1,0]
	v_exp_f32_e32 v104, v100
	v_mul_f32_e32 v100, 0xbfb8aa3b, v101
	v_exp_f32_e32 v105, v100
	v_pk_mul_f32 v[100:101], v[102:103], v[120:121] op_sel_hi:[1,0]
	v_add_f32_e32 v102, 1.0, v104
	v_mul_f32_e32 v100, 0xbfb8aa3b, v100
	v_mul_f32_e32 v101, 0xbfb8aa3b, v101
	v_exp_f32_e32 v100, v100
	v_exp_f32_e32 v101, v101
	v_rcp_f32_e32 v104, v102
	v_add_f32_e32 v102, 1.0, v105
	v_add_f32_e32 v100, 1.0, v100
	v_add_f32_e32 v101, 1.0, v101
	v_rcp_f32_e32 v105, v102
	v_rcp_f32_e32 v100, v100
	v_rcp_f32_e32 v101, v101
	v_lshlrev_b32_e32 v106, 16, v134
	v_and_b32_e32 v107, 0xffff0000, v134
	v_lshlrev_b32_e32 v102, 16, v135
	v_and_b32_e32 v103, 0xffff0000, v135
	v_lshlrev_b32_e32 v108, 16, v130
	v_and_b32_e32 v109, 0xffff0000, v130
	v_lshlrev_b32_e32 v110, 16, v131
	v_and_b32_e32 v111, 0xffff0000, v131
	v_mul_f32_e32 v96, 0xbfb8aa3b, v96
	v_pk_fma_f32 v[102:103], v[100:101], v[102:103], v[110:111]
	v_pk_fma_f32 v[100:101], v[104:105], v[106:107], v[108:109]
	v_exp_f32_e32 v104, v96
	v_mul_f32_e32 v96, 0xbfb8aa3b, v97
	v_exp_f32_e32 v105, v96
	v_pk_mul_f32 v[96:97], v[98:99], v[120:121] op_sel_hi:[1,0]
	v_add_f32_e32 v98, 1.0, v104
	v_mul_f32_e32 v96, 0xbfb8aa3b, v96
	v_mul_f32_e32 v97, 0xbfb8aa3b, v97
	v_exp_f32_e32 v96, v96
	v_exp_f32_e32 v97, v97
	v_rcp_f32_e32 v104, v98
	v_add_f32_e32 v98, 1.0, v105
	v_add_f32_e32 v96, 1.0, v96
	v_add_f32_e32 v97, 1.0, v97
	v_rcp_f32_e32 v105, v98
	v_rcp_f32_e32 v96, v96
	v_rcp_f32_e32 v97, v97
	v_lshlrev_b32_e32 v106, 16, v132
	v_and_b32_e32 v107, 0xffff0000, v132
	v_lshlrev_b32_e32 v98, 16, v133
	v_and_b32_e32 v99, 0xffff0000, v133
	v_lshlrev_b32_e32 v108, 16, v128
	v_and_b32_e32 v109, 0xffff0000, v128
	v_lshlrev_b32_e32 v110, 16, v129
	v_and_b32_e32 v111, 0xffff0000, v129
	v_pk_fma_f32 v[98:99], v[96:97], v[98:99], v[110:111]
	v_pk_fma_f32 v[96:97], v[104:105], v[106:107], v[108:109]
	global_store_dwordx4 v[112:113], v[96:99], off offset:512
	global_store_dwordx4 v[112:113], v[100:103], off offset:528
	v_or_b32_e32 v104, 48, v166
	v_or_b32_e32 v96, 32, v166
	v_ashrrev_i32_e32 v97, 31, v96
	v_lshl_add_u64 v[98:99], v[96:97], 2, s[36:37]
	flat_load_dword v102, v[98:99]
	v_lshlrev_b64 v[96:97], 10, v[96:97]
	v_lshl_add_u64 v[128:129], v[96:97], 0, v[164:165]
	v_lshlrev_b64 v[120:121], 1, v[128:129]
	v_lshl_add_u64 v[96:97], s[48:49], 0, v[120:121]
	flat_load_dwordx4 v[112:115], v[96:97]
	v_lshl_add_u64 v[96:97], s[42:43], 0, v[120:121]
	v_ashrrev_i32_e32 v105, 31, v104
	flat_load_dwordx4 v[116:119], v[96:97]
	v_lshlrev_b64 v[96:97], 10, v[104:105]
	v_lshl_add_u64 v[130:131], v[96:97], 0, v[164:165]
	v_lshlrev_b64 v[106:107], 1, v[130:131]
	v_lshl_add_u64 v[100:101], v[106:107], 0, s[10:11]
	v_lshl_add_u64 v[96:97], s[48:49], 0, v[100:101]
	v_lshl_add_u64 v[100:101], s[42:43], 0, v[100:101]
	v_lshl_add_u64 v[108:109], s[48:49], 0, v[106:107]
	v_lshl_add_u64 v[106:107], s[42:43], 0, v[106:107]
	flat_load_dwordx4 v[96:99], v[96:97]
	v_lshl_add_u64 v[122:123], v[104:105], 2, s[36:37]
	v_lshl_add_u64 v[124:125], v[120:121], 0, s[10:11]
	v_lshl_add_u64 v[120:121], s[48:49], 0, v[124:125]
	v_lshl_add_u64 v[124:125], s[42:43], 0, v[124:125]
	v_lshl_add_u64 v[128:129], v[128:129], 2, s[52:53]
	s_waitcnt vmcnt(0) lgkmcnt(0)
	v_fmamk_f32 v102, v102, 0x3a800000, v172
	v_rsq_f32_e32 v132, v102
	flat_load_dwordx4 v[100:103], v[100:101]
	s_nop 0
	flat_load_dwordx4 v[108:111], v[108:109]
	s_nop 0
	flat_load_dwordx4 v[104:107], v[106:107]
	s_nop 0
	flat_load_dword v133, v[122:123]
	v_lshlrev_b32_e32 v136, 16, v114
	flat_load_dwordx4 v[120:123], v[120:121]
	v_and_b32_e32 v137, 0xffff0000, v114
	flat_load_dwordx4 v[124:127], v[124:125]
	v_lshlrev_b32_e32 v114, 16, v118
	s_waitcnt vmcnt(0) lgkmcnt(0)
; __device__ __forceinline__ u32x4 pack8(f32x4 a, f32x4 b) { u32x4 w; w.x = pk2(a[0], a[1]); w.y = pk2(a[2], a[3]); w.z = pk2(b[0], b[1]); w.w = pk2(b[2], b[3]); return w; }
;     __device__ __forceinline__ void operator()(const Acc& acc, const pg8::Unit& u, int wid) const {
;     ...
;                 for (int mm = 0; mm < 2; ++mm) {
;                     const int m = 2 * mp + mm, row = row0 + ai * 128 + m * 16; float sq = 0.f;
;                     const float sc = __builtin_amdgcn_rsqf(scv[mm] * (1.f / 1024.f) + EPS);
; #pragma unroll
;                     for (int bj = 0; bj < 2; ++bj) {
;                         const size_t off = (size_t)row * 1024 + col0 + bj * 128;
;                         const u32x4 pwv = pw[mm][bj], hw = hv[mm][bj];
;                         const f32x4 p0 = (f32x4){bflo(pwv.x), bfhi(pwv.x), bflo(pwv.y), bfhi(pwv.y)}, p1 = (f32x4){bflo(pwv.z), bfhi(pwv.z), bflo(pwv.w), bfhi(pwv.w)};
;                         f32x4 g0 = acc[ai][bj][m][0] * sc, g1 = acc[ai][bj][m][1] * sc;
; #pragma unroll
;                         for (int e = 0; e < 4; ++e) { g0[e] = __builtin_amdgcn_rcpf(1.f + __builtin_amdgcn_exp2f(-1.4426950408889634f * g0[e])); g1[e] = __builtin_amdgcn_rcpf(1.f + __builtin_amdgcn_exp2f(-1.4426950408889634f * g1[e])); }
;                         const f32x4 o0 = (f32x4){bflo(hw.x), bfhi(hw.x), bflo(hw.y), bfhi(hw.y)} + g0 * p0;
;                         const f32x4 o1 = (f32x4){bflo(hw.z), bfhi(hw.z), bflo(hw.w), bfhi(hw.w)} + g1 * p1;
;                         if (fout) { *(f32x4*)(fout + off) = o0; *(f32x4*)(fout + off + 4) = o1; }
;                         if (hb_out) *(u32x4*)(hb_out + off) = pack8(o0, o1);
;                         sq += (o0[0] * o0[0] + o0[1] * o0[1]) + (o0[2] * o0[2] + o0[3] * o0[3]) + (o1[0] * o1[0] + o1[1] * o1[1]) + (o1[2] * o1[2] + o1[3] * o1[3]);
;                     }
	v_pk_mul_f32 v[92:93], v[92:93], v[132:133] op_sel_hi:[1,0]
	s_nop 0
	v_mul_f32_e32 v92, 0xbfb8aa3b, v92
	v_exp_f32_e32 v134, v92
	v_mul_f32_e32 v92, 0xbfb8aa3b, v93
	v_exp_f32_e32 v135, v92
	v_pk_mul_f32 v[92:93], v[94:95], v[132:133] op_sel_hi:[1,0]
	v_add_f32_e32 v94, 1.0, v134
	v_mul_f32_e32 v92, 0xbfb8aa3b, v92
	v_mul_f32_e32 v93, 0xbfb8aa3b, v93
	v_exp_f32_e32 v92, v92
	v_exp_f32_e32 v93, v93
	v_rcp_f32_e32 v134, v94
	v_add_f32_e32 v94, 1.0, v135
	v_add_f32_e32 v92, 1.0, v92
	v_add_f32_e32 v93, 1.0, v93
	v_rcp_f32_e32 v135, v94
	v_rcp_f32_e32 v92, v92
	v_rcp_f32_e32 v93, v93
	v_pk_mul_f32 v[88:89], v[88:89], v[132:133] op_sel_hi:[1,0]
	v_lshlrev_b32_e32 v94, 16, v115
	v_and_b32_e32 v95, 0xffff0000, v115
	v_and_b32_e32 v115, 0xffff0000, v118
	v_lshlrev_b32_e32 v118, 16, v119
	v_and_b32_e32 v119, 0xffff0000, v119
	v_mul_f32_e32 v88, 0xbfb8aa3b, v88
	v_pk_fma_f32 v[94:95], v[92:93], v[94:95], v[118:119]
	v_pk_fma_f32 v[92:93], v[134:135], v[136:137], v[114:115]
	v_exp_f32_e32 v114, v88
	v_mul_f32_e32 v88, 0xbfb8aa3b, v89
	v_exp_f32_e32 v115, v88
	v_pk_mul_f32 v[88:89], v[90:91], v[132:133] op_sel_hi:[1,0]
	v_add_f32_e32 v90, 1.0, v114
	v_mul_f32_e32 v88, 0xbfb8aa3b, v88
	v_mul_f32_e32 v89, 0xbfb8aa3b, v89
	v_exp_f32_e32 v88, v88
	v_exp_f32_e32 v89, v89
	v_rcp_f32_e32 v114, v90
	v_add_f32_e32 v90, 1.0, v115
	v_add_f32_e32 v88, 1.0, v88
	v_add_f32_e32 v89, 1.0, v89
	v_rcp_f32_e32 v115, v90
	v_rcp_f32_e32 v88, v88
	v_rcp_f32_e32 v89, v89
	v_lshlrev_b32_e32 v118, 16, v112
	v_and_b32_e32 v119, 0xffff0000, v112
	v_lshlrev_b32_e32 v90, 16, v113
	v_and_b32_e32 v91, 0xffff0000, v113
	v_lshlrev_b32_e32 v112, 16, v116
	v_and_b32_e32 v113, 0xffff0000, v116
	v_lshlrev_b32_e32 v116, 16, v117
	v_and_b32_e32 v117, 0xffff0000, v117
	v_pk_mul_f32 v[84:85], v[84:85], v[132:133] op_sel_hi:[1,0]
	v_pk_fma_f32 v[90:91], v[88:89], v[90:91], v[116:117]
	v_pk_fma_f32 v[88:89], v[114:115], v[118:119], v[112:113]
	v_mul_f32_e32 v84, 0xbfb8aa3b, v84
	global_store_dwordx4 v[128:129], v[88:91], off
	global_store_dwordx4 v[128:129], v[92:95], off offset:16
	v_pk_mul_f32 v[80:81], v[80:81], v[132:133] op_sel_hi:[1,0]
	v_exp_f32_e32 v88, v84
	v_mul_f32_e32 v84, 0xbfb8aa3b, v85
	v_exp_f32_e32 v89, v84
	v_pk_mul_f32 v[84:85], v[86:87], v[132:133] op_sel_hi:[1,0]
	v_add_f32_e32 v86, 1.0, v88
	v_mul_f32_e32 v84, 0xbfb8aa3b, v84
	v_mul_f32_e32 v85, 0xbfb8aa3b, v85
	v_exp_f32_e32 v84, v84
	v_exp_f32_e32 v85, v85
	v_rcp_f32_e32 v88, v86
	v_add_f32_e32 v86, 1.0, v89
	v_add_f32_e32 v84, 1.0, v84
	v_add_f32_e32 v85, 1.0, v85
	v_rcp_f32_e32 v89, v86
	v_rcp_f32_e32 v84, v84
	v_rcp_f32_e32 v85, v85
	v_lshlrev_b32_e32 v90, 16, v122
	v_and_b32_e32 v91, 0xffff0000, v122
	v_lshlrev_b32_e32 v86, 16, v123
	v_and_b32_e32 v87, 0xffff0000, v123
	v_lshlrev_b32_e32 v92, 16, v126
	v_and_b32_e32 v93, 0xffff0000, v126
	v_lshlrev_b32_e32 v94, 16, v127
	v_and_b32_e32 v95, 0xffff0000, v127
	v_mul_f32_e32 v80, 0xbfb8aa3b, v80
	v_pk_fma_f32 v[86:87], v[84:85], v[86:87], v[94:95]
	v_pk_fma_f32 v[84:85], v[88:89], v[90:91], v[92:93]
	v_exp_f32_e32 v88, v80
	v_mul_f32_e32 v80, 0xbfb8aa3b, v81
	v_exp_f32_e32 v89, v80
	v_pk_mul_f32 v[80:81], v[82:83], v[132:133] op_sel_hi:[1,0]
	v_add_f32_e32 v82, 1.0, v88
	v_mul_f32_e32 v80, 0xbfb8aa3b, v80
	v_mul_f32_e32 v81, 0xbfb8aa3b, v81
	v_exp_f32_e32 v80, v80
	v_exp_f32_e32 v81, v81
	v_rcp_f32_e32 v88, v82
	v_add_f32_e32 v82, 1.0, v89
	v_add_f32_e32 v80, 1.0, v80
	v_add_f32_e32 v81, 1.0, v81
	v_rcp_f32_e32 v89, v82
	v_rcp_f32_e32 v80, v80
	v_rcp_f32_e32 v81, v81
	v_lshlrev_b32_e32 v90, 16, v120
	v_and_b32_e32 v91, 0xffff0000, v120
	v_lshlrev_b32_e32 v82, 16, v121
	v_and_b32_e32 v83, 0xffff0000, v121
	v_lshlrev_b32_e32 v92, 16, v124
	v_and_b32_e32 v93, 0xffff0000, v124
	v_lshlrev_b32_e32 v94, 16, v125
	v_and_b32_e32 v95, 0xffff0000, v125
	v_pk_fma_f32 v[82:83], v[80:81], v[82:83], v[94:95]
	v_pk_fma_f32 v[80:81], v[88:89], v[90:91], v[92:93]
	v_fmamk_f32 v88, v133, 0x3a800000, v172
	v_rsq_f32_e32 v88, v88
	global_store_dwordx4 v[128:129], v[80:83], off offset:512
	global_store_dwordx4 v[128:129], v[84:87], off offset:528
	v_lshlrev_b32_e32 v90, 16, v107
	v_and_b32_e32 v91, 0xffff0000, v107
	v_pk_mul_f32 v[76:77], v[76:77], v[88:89] op_sel_hi:[1,0]
	v_pk_mul_f32 v[72:73], v[72:73], v[88:89] op_sel_hi:[1,0]
	v_mul_f32_e32 v76, 0xbfb8aa3b, v76
	v_exp_f32_e32 v82, v76
	v_mul_f32_e32 v76, 0xbfb8aa3b, v77
	v_exp_f32_e32 v83, v76
	v_pk_mul_f32 v[76:77], v[78:79], v[88:89] op_sel_hi:[1,0]
	v_add_f32_e32 v78, 1.0, v82
	v_mul_f32_e32 v76, 0xbfb8aa3b, v76
	v_mul_f32_e32 v77, 0xbfb8aa3b, v77
	v_exp_f32_e32 v76, v76
	v_exp_f32_e32 v77, v77
	v_rcp_f32_e32 v82, v78
	v_add_f32_e32 v78, 1.0, v83
	v_add_f32_e32 v76, 1.0, v76
	v_add_f32_e32 v77, 1.0, v77
	v_rcp_f32_e32 v83, v78
	v_rcp_f32_e32 v76, v76
	v_rcp_f32_e32 v77, v77
	v_lshlrev_b32_e32 v84, 16, v110
	v_and_b32_e32 v85, 0xffff0000, v110
	v_lshlrev_b32_e32 v78, 16, v111
	v_and_b32_e32 v79, 0xffff0000, v111
	v_lshlrev_b32_e32 v86, 16, v106
	v_and_b32_e32 v87, 0xffff0000, v106
	v_mul_f32_e32 v72, 0xbfb8aa3b, v72
	v_pk_fma_f32 v[78:79], v[76:77], v[78:79], v[90:91]
	v_pk_fma_f32 v[76:77], v[82:83], v[84:85], v[86:87]
	v_exp_f32_e32 v82, v72
	v_mul_f32_e32 v72, 0xbfb8aa3b, v73
	v_exp_f32_e32 v83, v72
	v_pk_mul_f32 v[72:73], v[74:75], v[88:89] op_sel_hi:[1,0]
	v_add_f32_e32 v74, 1.0, v82
	v_mul_f32_e32 v72, 0xbfb8aa3b, v72
	v_mul_f32_e32 v73, 0xbfb8aa3b, v73
	v_exp_f32_e32 v72, v72
	v_exp_f32_e32 v73, v73
	v_rcp_f32_e32 v82, v74
	v_add_f32_e32 v74, 1.0, v83
	v_add_f32_e32 v72, 1.0, v72
	v_add_f32_e32 v73, 1.0, v73
	v_rcp_f32_e32 v83, v74
	v_rcp_f32_e32 v72, v72
	v_rcp_f32_e32 v73, v73
	v_lshlrev_b32_e32 v84, 16, v108
; __device__ __forceinline__ u32x4 pack8(f32x4 a, f32x4 b) { u32x4 w; w.x = pk2(a[0], a[1]); w.y = pk2(a[2], a[3]); w.z = pk2(b[0], b[1]); w.w = pk2(b[2], b[3]); return w; }
;     __device__ __forceinline__ void operator()(const Acc& acc, const pg8::Unit& u, int wid) const {
;     ...
;                     const int row = row0 + ai * 128 + (2 * mp + mm) * 16;
;                     scv[mm] = ssq[row];
; #pragma unroll
;                     for (int bj = 0; bj < 2; ++bj) { const size_t off = (size_t)row * 1024 + col0 + bj * 128; hv[mm][bj] = *(const u32x4*)(hbase + off); pw[mm][bj] = *(const u32x4*)(pp + off); }
;     ...
;                 for (int mm = 0; mm < 2; ++mm) {
;                     const int m = 2 * mp + mm, row = row0 + ai * 128 + m * 16; float sq = 0.f;
;                     const float sc = __builtin_amdgcn_rsqf(scv[mm] * (1.f / 1024.f) + EPS);
; #pragma unroll
;                     for (int bj = 0; bj < 2; ++bj) {
;                         const size_t off = (size_t)row * 1024 + col0 + bj * 128;
;                         const u32x4 pwv = pw[mm][bj], hw = hv[mm][bj];
;                         const f32x4 p0 = (f32x4){bflo(pwv.x), bfhi(pwv.x), bflo(pwv.y), bfhi(pwv.y)}, p1 = (f32x4){bflo(pwv.z), bfhi(pwv.z), bflo(pwv.w), bfhi(pwv.w)};
;                         f32x4 g0 = acc[ai][bj][m][0] * sc, g1 = acc[ai][bj][m][1] * sc;
; #pragma unroll
;                         for (int e = 0; e < 4; ++e) { g0[e] = __builtin_amdgcn_rcpf(1.f + __builtin_amdgcn_exp2f(-1.4426950408889634f * g0[e])); g1[e] = __builtin_amdgcn_rcpf(1.f + __builtin_amdgcn_exp2f(-1.4426950408889634f * g1[e])); }
;                         const f32x4 o0 = (f32x4){bflo(hw.x), bfhi(hw.x), bflo(hw.y), bfhi(hw.y)} + g0 * p0;
;                         const f32x4 o1 = (f32x4){bflo(hw.z), bfhi(hw.z), bflo(hw.w), bfhi(hw.w)} + g1 * p1;
;                         if (fout) { *(f32x4*)(fout + off) = o0; *(f32x4*)(fout + off + 4) = o1; }
;                         if (hb_out) *(u32x4*)(hb_out + off) = pack8(o0, o1);
;                         sq += (o0[0] * o0[0] + o0[1] * o0[1]) + (o0[2] * o0[2] + o0[3] * o0[3]) + (o1[0] * o1[0] + o1[1] * o1[1]) + (o1[2] * o1[2] + o1[3] * o1[3]);
;                     }
	v_and_b32_e32 v85, 0xffff0000, v108
	v_lshlrev_b32_e32 v74, 16, v109
	v_and_b32_e32 v75, 0xffff0000, v109
	v_lshlrev_b32_e32 v86, 16, v104
	v_and_b32_e32 v87, 0xffff0000, v104
	v_lshlrev_b32_e32 v90, 16, v105
	v_and_b32_e32 v91, 0xffff0000, v105
	v_pk_mul_f32 v[68:69], v[68:69], v[88:89] op_sel_hi:[1,0]
	v_lshl_add_u64 v[80:81], v[130:131], 2, s[52:53]
	v_pk_fma_f32 v[74:75], v[72:73], v[74:75], v[90:91]
	v_pk_fma_f32 v[72:73], v[82:83], v[84:85], v[86:87]
	v_mul_f32_e32 v68, 0xbfb8aa3b, v68
	global_store_dwordx4 v[80:81], v[72:75], off
	global_store_dwordx4 v[80:81], v[76:79], off offset:16
	v_pk_mul_f32 v[64:65], v[64:65], v[88:89] op_sel_hi:[1,0]
	v_exp_f32_e32 v72, v68
	v_mul_f32_e32 v68, 0xbfb8aa3b, v69
	v_exp_f32_e32 v73, v68
	v_pk_mul_f32 v[68:69], v[70:71], v[88:89] op_sel_hi:[1,0]
	v_add_f32_e32 v70, 1.0, v72
	v_mul_f32_e32 v68, 0xbfb8aa3b, v68
	v_mul_f32_e32 v69, 0xbfb8aa3b, v69
	v_exp_f32_e32 v68, v68
	v_exp_f32_e32 v69, v69
	v_rcp_f32_e32 v72, v70
	v_add_f32_e32 v70, 1.0, v73
	v_add_f32_e32 v68, 1.0, v68
	v_add_f32_e32 v69, 1.0, v69
	v_rcp_f32_e32 v73, v70
	v_rcp_f32_e32 v68, v68
	v_rcp_f32_e32 v69, v69
	v_lshlrev_b32_e32 v74, 16, v98
	v_and_b32_e32 v75, 0xffff0000, v98
	v_lshlrev_b32_e32 v70, 16, v99
	v_and_b32_e32 v71, 0xffff0000, v99
	v_lshlrev_b32_e32 v76, 16, v102
	v_and_b32_e32 v77, 0xffff0000, v102
	v_lshlrev_b32_e32 v78, 16, v103
	v_and_b32_e32 v79, 0xffff0000, v103
	v_mul_f32_e32 v64, 0xbfb8aa3b, v64
	v_pk_fma_f32 v[70:71], v[68:69], v[70:71], v[78:79]
	v_pk_fma_f32 v[68:69], v[72:73], v[74:75], v[76:77]
	v_exp_f32_e32 v72, v64
	v_mul_f32_e32 v64, 0xbfb8aa3b, v65
	v_exp_f32_e32 v73, v64
	v_pk_mul_f32 v[64:65], v[66:67], v[88:89] op_sel_hi:[1,0]
	v_add_f32_e32 v66, 1.0, v72
	v_mul_f32_e32 v64, 0xbfb8aa3b, v64
	v_mul_f32_e32 v65, 0xbfb8aa3b, v65
	v_exp_f32_e32 v64, v64
	v_exp_f32_e32 v65, v65
	v_rcp_f32_e32 v72, v66
	v_add_f32_e32 v66, 1.0, v73
	v_add_f32_e32 v64, 1.0, v64
	v_add_f32_e32 v65, 1.0, v65
	v_rcp_f32_e32 v73, v66
	v_rcp_f32_e32 v64, v64
	v_rcp_f32_e32 v65, v65
	v_lshlrev_b32_e32 v74, 16, v96
	v_and_b32_e32 v75, 0xffff0000, v96
	v_lshlrev_b32_e32 v66, 16, v97
	v_and_b32_e32 v67, 0xffff0000, v97
	v_lshlrev_b32_e32 v76, 16, v100
	v_and_b32_e32 v77, 0xffff0000, v100
	v_lshlrev_b32_e32 v78, 16, v101
	v_and_b32_e32 v79, 0xffff0000, v101
	v_pk_fma_f32 v[66:67], v[64:65], v[66:67], v[78:79]
	v_pk_fma_f32 v[64:65], v[72:73], v[74:75], v[76:77]
	global_store_dwordx4 v[80:81], v[64:67], off offset:512
	global_store_dwordx4 v[80:81], v[68:71], off offset:528
	flat_load_dword v74, v[160:161] offset:512
	v_lshl_add_u64 v[96:97], v[162:163], 0, s[14:15]
	v_lshlrev_b64 v[64:65], 1, v[96:97]
	v_lshl_add_u64 v[98:99], v[162:163], 0, s[12:13]
	v_lshl_add_u64 v[66:67], s[48:49], 0, v[64:65]
	v_lshl_add_u64 v[68:69], v[64:65], 0, s[10:11]
	v_lshlrev_b64 v[70:71], 1, v[98:99]
	flat_load_dwordx4 v[80:83], v[66:67]
	v_lshl_add_u64 v[66:67], s[42:43], 0, v[64:65]
	v_lshl_add_u64 v[64:65], s[42:43], 0, v[68:69]
	v_lshl_add_u64 v[72:73], v[70:71], 0, s[10:11]
	flat_load_dwordx4 v[84:87], v[66:67]
	flat_load_dwordx4 v[88:91], v[64:65]
	v_lshl_add_u64 v[64:65], s[48:49], 0, v[72:73]
	flat_load_dwordx4 v[64:67], v[64:65]
	s_nop 0
	flat_load_dword v101, v[160:161] offset:576
	v_lshl_add_u64 v[76:77], s[42:43], 0, v[72:73]
	v_lshl_add_u64 v[78:79], s[48:49], 0, v[70:71]
	v_lshl_add_u64 v[70:71], s[42:43], 0, v[70:71]
	v_lshl_add_u64 v[68:69], s[48:49], 0, v[68:69]
	v_lshl_add_u64 v[96:97], v[96:97], 2, s[52:53]
	s_waitcnt vmcnt(0) lgkmcnt(0)
	v_fmamk_f32 v74, v74, 0x3a800000, v172
	v_rsq_f32_e32 v100, v74
	flat_load_dwordx4 v[72:75], v[70:71]
	flat_load_dwordx4 v[92:95], v[68:69]
	s_nop 0
	flat_load_dwordx4 v[68:71], v[76:77]
	s_nop 0
	flat_load_dwordx4 v[76:79], v[78:79]
	v_lshlrev_b32_e32 v104, 16, v82
	v_and_b32_e32 v105, 0xffff0000, v82
	v_lshlrev_b32_e32 v82, 16, v86
	v_pk_mul_f32 v[60:61], v[60:61], v[100:101] op_sel_hi:[1,0]
	s_nop 0
	v_mul_f32_e32 v60, 0xbfb8aa3b, v60
	v_exp_f32_e32 v102, v60
	v_mul_f32_e32 v60, 0xbfb8aa3b, v61
	v_exp_f32_e32 v103, v60
	v_pk_mul_f32 v[60:61], v[62:63], v[100:101] op_sel_hi:[1,0]
	v_add_f32_e32 v62, 1.0, v102
	v_mul_f32_e32 v60, 0xbfb8aa3b, v60
	v_mul_f32_e32 v61, 0xbfb8aa3b, v61
	v_exp_f32_e32 v60, v60
	v_exp_f32_e32 v61, v61
	v_rcp_f32_e32 v102, v62
	v_add_f32_e32 v62, 1.0, v103
	v_add_f32_e32 v60, 1.0, v60
	v_add_f32_e32 v61, 1.0, v61
	v_rcp_f32_e32 v103, v62
	v_rcp_f32_e32 v60, v60
	v_rcp_f32_e32 v61, v61
	v_pk_mul_f32 v[56:57], v[56:57], v[100:101] op_sel_hi:[1,0]
	v_lshlrev_b32_e32 v62, 16, v83
	v_and_b32_e32 v63, 0xffff0000, v83
	v_and_b32_e32 v83, 0xffff0000, v86
	v_lshlrev_b32_e32 v86, 16, v87
	v_and_b32_e32 v87, 0xffff0000, v87
	v_mul_f32_e32 v56, 0xbfb8aa3b, v56
	v_pk_fma_f32 v[62:63], v[60:61], v[62:63], v[86:87]
	v_pk_fma_f32 v[60:61], v[102:103], v[104:105], v[82:83]
	v_exp_f32_e32 v82, v56
	v_mul_f32_e32 v56, 0xbfb8aa3b, v57
	v_exp_f32_e32 v83, v56
	v_pk_mul_f32 v[56:57], v[58:59], v[100:101] op_sel_hi:[1,0]
	v_add_f32_e32 v58, 1.0, v82
	v_mul_f32_e32 v56, 0xbfb8aa3b, v56
	v_mul_f32_e32 v57, 0xbfb8aa3b, v57
	v_exp_f32_e32 v56, v56
	v_exp_f32_e32 v57, v57
	v_rcp_f32_e32 v82, v58
	v_add_f32_e32 v58, 1.0, v83
	v_add_f32_e32 v56, 1.0, v56
	v_add_f32_e32 v57, 1.0, v57
	v_rcp_f32_e32 v83, v58
	v_rcp_f32_e32 v56, v56
	v_rcp_f32_e32 v57, v57
	v_lshlrev_b32_e32 v86, 16, v80
	v_and_b32_e32 v87, 0xffff0000, v80
	v_lshlrev_b32_e32 v58, 16, v81
	v_and_b32_e32 v59, 0xffff0000, v81
	v_lshlrev_b32_e32 v80, 16, v84
	v_and_b32_e32 v81, 0xffff0000, v84
	v_lshlrev_b32_e32 v84, 16, v85
	v_and_b32_e32 v85, 0xffff0000, v85
	v_pk_mul_f32 v[52:53], v[52:53], v[100:101] op_sel_hi:[1,0]
	v_pk_fma_f32 v[58:59], v[56:57], v[58:59], v[84:85]
	v_pk_fma_f32 v[56:57], v[82:83], v[86:87], v[80:81]
	v_mul_f32_e32 v52, 0xbfb8aa3b, v52
	global_store_dwordx4 v[96:97], v[56:59], off
	global_store_dwordx4 v[96:97], v[60:63], off offset:16
	v_pk_mul_f32 v[48:49], v[48:49], v[100:101] op_sel_hi:[1,0]
	v_exp_f32_e32 v56, v52
	v_mul_f32_e32 v52, 0xbfb8aa3b, v53
	v_exp_f32_e32 v57, v52
	v_pk_mul_f32 v[52:53], v[54:55], v[100:101] op_sel_hi:[1,0]
	v_add_f32_e32 v54, 1.0, v56
	v_mul_f32_e32 v52, 0xbfb8aa3b, v52
	v_mul_f32_e32 v53, 0xbfb8aa3b, v53
	v_exp_f32_e32 v52, v52
	v_exp_f32_e32 v53, v53
	v_rcp_f32_e32 v56, v54
	v_add_f32_e32 v54, 1.0, v57
	v_add_f32_e32 v52, 1.0, v52
	v_add_f32_e32 v53, 1.0, v53
	v_rcp_f32_e32 v57, v54
	v_rcp_f32_e32 v52, v52
	v_rcp_f32_e32 v53, v53
	s_waitcnt vmcnt(0) lgkmcnt(0)
; __device__ __forceinline__ u32x4 pack8(f32x4 a, f32x4 b) { u32x4 w; w.x = pk2(a[0], a[1]); w.y = pk2(a[2], a[3]); w.z = pk2(b[0], b[1]); w.w = pk2(b[2], b[3]); return w; }
;     __device__ __forceinline__ void operator()(const Acc& acc, const pg8::Unit& u, int wid) const {
;     ...
;                     const int row = row0 + ai * 128 + (2 * mp + mm) * 16;
;                     scv[mm] = ssq[row];
; #pragma unroll
;                     for (int bj = 0; bj < 2; ++bj) { const size_t off = (size_t)row * 1024 + col0 + bj * 128; hv[mm][bj] = *(const u32x4*)(hbase + off); pw[mm][bj] = *(const u32x4*)(pp + off); }
;     ...
;                 for (int mm = 0; mm < 2; ++mm) {
;                     const int m = 2 * mp + mm, row = row0 + ai * 128 + m * 16; float sq = 0.f;
;                     const float sc = __builtin_amdgcn_rsqf(scv[mm] * (1.f / 1024.f) + EPS);
; #pragma unroll
;                     for (int bj = 0; bj < 2; ++bj) {
;                         const size_t off = (size_t)row * 1024 + col0 + bj * 128;
;                         const u32x4 pwv = pw[mm][bj], hw = hv[mm][bj];
;                         const f32x4 p0 = (f32x4){bflo(pwv.x), bfhi(pwv.x), bflo(pwv.y), bfhi(pwv.y)}, p1 = (f32x4){bflo(pwv.z), bfhi(pwv.z), bflo(pwv.w), bfhi(pwv.w)};
;                         f32x4 g0 = acc[ai][bj][m][0] * sc, g1 = acc[ai][bj][m][1] * sc;
; #pragma unroll
;                         for (int e = 0; e < 4; ++e) { g0[e] = __builtin_amdgcn_rcpf(1.f + __builtin_amdgcn_exp2f(-1.4426950408889634f * g0[e])); g1[e] = __builtin_amdgcn_rcpf(1.f + __builtin_amdgcn_exp2f(-1.4426950408889634f * g1[e])); }
;                         const f32x4 o0 = (f32x4){bflo(hw.x), bfhi(hw.x), bflo(hw.y), bfhi(hw.y)} + g0 * p0;
;                         const f32x4 o1 = (f32x4){bflo(hw.z), bfhi(hw.z), bflo(hw.w), bfhi(hw.w)} + g1 * p1;
;                         if (fout) { *(f32x4*)(fout + off) = o0; *(f32x4*)(fout + off + 4) = o1; }
;                         if (hb_out) *(u32x4*)(hb_out + off) = pack8(o0, o1);
;                         sq += (o0[0] * o0[0] + o0[1] * o0[1]) + (o0[2] * o0[2] + o0[3] * o0[3]) + (o1[0] * o1[0] + o1[1] * o1[1]) + (o1[2] * o1[2] + o1[3] * o1[3]);
;                     }
	v_lshlrev_b32_e32 v58, 16, v94
	v_and_b32_e32 v59, 0xffff0000, v94
	v_lshlrev_b32_e32 v54, 16, v95
	v_and_b32_e32 v55, 0xffff0000, v95
	v_lshlrev_b32_e32 v60, 16, v90
	v_and_b32_e32 v61, 0xffff0000, v90
	v_lshlrev_b32_e32 v62, 16, v91
	v_and_b32_e32 v63, 0xffff0000, v91
	v_mul_f32_e32 v48, 0xbfb8aa3b, v48
	v_pk_fma_f32 v[54:55], v[52:53], v[54:55], v[62:63]
	v_pk_fma_f32 v[52:53], v[56:57], v[58:59], v[60:61]
	v_exp_f32_e32 v56, v48
	v_mul_f32_e32 v48, 0xbfb8aa3b, v49
	v_exp_f32_e32 v57, v48
	v_pk_mul_f32 v[48:49], v[50:51], v[100:101] op_sel_hi:[1,0]
	v_add_f32_e32 v50, 1.0, v56
	v_mul_f32_e32 v48, 0xbfb8aa3b, v48
	v_mul_f32_e32 v49, 0xbfb8aa3b, v49
	v_exp_f32_e32 v48, v48
	v_exp_f32_e32 v49, v49
	v_rcp_f32_e32 v56, v50
	v_add_f32_e32 v50, 1.0, v57
	v_add_f32_e32 v48, 1.0, v48
	v_add_f32_e32 v49, 1.0, v49
	v_rcp_f32_e32 v57, v50
	v_rcp_f32_e32 v48, v48
	v_rcp_f32_e32 v49, v49
	v_lshlrev_b32_e32 v58, 16, v92
	v_and_b32_e32 v59, 0xffff0000, v92
	v_lshlrev_b32_e32 v50, 16, v93
	v_and_b32_e32 v51, 0xffff0000, v93
	v_lshlrev_b32_e32 v60, 16, v88
	v_and_b32_e32 v61, 0xffff0000, v88
	v_lshlrev_b32_e32 v62, 16, v89
	v_and_b32_e32 v63, 0xffff0000, v89
	v_pk_fma_f32 v[50:51], v[48:49], v[50:51], v[62:63]
	v_pk_fma_f32 v[48:49], v[56:57], v[58:59], v[60:61]
	v_fmamk_f32 v56, v101, 0x3a800000, v172
	v_rsq_f32_e32 v56, v56
	global_store_dwordx4 v[96:97], v[48:51], off offset:512
	global_store_dwordx4 v[96:97], v[52:55], off offset:528
	v_lshlrev_b32_e32 v58, 16, v75
	v_and_b32_e32 v59, 0xffff0000, v75
	v_pk_mul_f32 v[44:45], v[44:45], v[56:57] op_sel_hi:[1,0]
	v_pk_mul_f32 v[40:41], v[40:41], v[56:57] op_sel_hi:[1,0]
	v_mul_f32_e32 v44, 0xbfb8aa3b, v44
	v_exp_f32_e32 v50, v44
	v_mul_f32_e32 v44, 0xbfb8aa3b, v45
	v_exp_f32_e32 v51, v44
	v_pk_mul_f32 v[44:45], v[46:47], v[56:57] op_sel_hi:[1,0]
	v_add_f32_e32 v46, 1.0, v50
	v_mul_f32_e32 v44, 0xbfb8aa3b, v44
	v_mul_f32_e32 v45, 0xbfb8aa3b, v45
	v_exp_f32_e32 v44, v44
	v_exp_f32_e32 v45, v45
	v_rcp_f32_e32 v50, v46
	v_add_f32_e32 v46, 1.0, v51
	v_add_f32_e32 v44, 1.0, v44
	v_add_f32_e32 v45, 1.0, v45
	v_rcp_f32_e32 v51, v46
	v_rcp_f32_e32 v44, v44
	v_rcp_f32_e32 v45, v45
	v_lshlrev_b32_e32 v52, 16, v78
	v_and_b32_e32 v53, 0xffff0000, v78
	v_lshlrev_b32_e32 v46, 16, v79
	v_and_b32_e32 v47, 0xffff0000, v79
	v_lshlrev_b32_e32 v54, 16, v74
	v_and_b32_e32 v55, 0xffff0000, v74
	v_mul_f32_e32 v40, 0xbfb8aa3b, v40
	v_pk_fma_f32 v[46:47], v[44:45], v[46:47], v[58:59]
	v_pk_fma_f32 v[44:45], v[50:51], v[52:53], v[54:55]
	v_exp_f32_e32 v50, v40
	v_mul_f32_e32 v40, 0xbfb8aa3b, v41
	v_exp_f32_e32 v51, v40
	v_pk_mul_f32 v[40:41], v[42:43], v[56:57] op_sel_hi:[1,0]
	v_add_f32_e32 v42, 1.0, v50
	v_mul_f32_e32 v40, 0xbfb8aa3b, v40
	v_mul_f32_e32 v41, 0xbfb8aa3b, v41
	v_exp_f32_e32 v40, v40
	v_exp_f32_e32 v41, v41
	v_rcp_f32_e32 v50, v42
	v_add_f32_e32 v42, 1.0, v51
	v_add_f32_e32 v40, 1.0, v40
	v_add_f32_e32 v41, 1.0, v41
	v_rcp_f32_e32 v51, v42
	v_rcp_f32_e32 v40, v40
	v_rcp_f32_e32 v41, v41
	v_lshlrev_b32_e32 v52, 16, v76
	v_and_b32_e32 v53, 0xffff0000, v76
	v_lshlrev_b32_e32 v42, 16, v77
	v_and_b32_e32 v43, 0xffff0000, v77
	v_lshlrev_b32_e32 v54, 16, v72
	v_and_b32_e32 v55, 0xffff0000, v72
	v_lshlrev_b32_e32 v58, 16, v73
	v_and_b32_e32 v59, 0xffff0000, v73
	v_pk_mul_f32 v[36:37], v[36:37], v[56:57] op_sel_hi:[1,0]
	v_lshl_add_u64 v[48:49], v[98:99], 2, s[52:53]
	v_pk_fma_f32 v[42:43], v[40:41], v[42:43], v[58:59]
	v_pk_fma_f32 v[40:41], v[50:51], v[52:53], v[54:55]
	v_mul_f32_e32 v36, 0xbfb8aa3b, v36
	global_store_dwordx4 v[48:49], v[40:43], off
	global_store_dwordx4 v[48:49], v[44:47], off offset:16
	v_pk_mul_f32 v[32:33], v[32:33], v[56:57] op_sel_hi:[1,0]
	v_exp_f32_e32 v40, v36
	v_mul_f32_e32 v36, 0xbfb8aa3b, v37
	v_exp_f32_e32 v41, v36
	v_pk_mul_f32 v[36:37], v[38:39], v[56:57] op_sel_hi:[1,0]
	v_add_f32_e32 v38, 1.0, v40
	v_mul_f32_e32 v36, 0xbfb8aa3b, v36
	v_mul_f32_e32 v37, 0xbfb8aa3b, v37
	v_exp_f32_e32 v36, v36
	v_exp_f32_e32 v37, v37
	v_rcp_f32_e32 v40, v38
	v_add_f32_e32 v38, 1.0, v41
	v_add_f32_e32 v36, 1.0, v36
	v_add_f32_e32 v37, 1.0, v37
	v_rcp_f32_e32 v41, v38
	v_rcp_f32_e32 v36, v36
	v_rcp_f32_e32 v37, v37
	v_lshlrev_b32_e32 v42, 16, v66
	v_and_b32_e32 v43, 0xffff0000, v66
	v_lshlrev_b32_e32 v38, 16, v67
	v_and_b32_e32 v39, 0xffff0000, v67
	v_lshlrev_b32_e32 v44, 16, v70
	v_and_b32_e32 v45, 0xffff0000, v70
	v_lshlrev_b32_e32 v46, 16, v71
	v_and_b32_e32 v47, 0xffff0000, v71
	v_mul_f32_e32 v32, 0xbfb8aa3b, v32
	v_pk_fma_f32 v[38:39], v[36:37], v[38:39], v[46:47]
	v_pk_fma_f32 v[36:37], v[40:41], v[42:43], v[44:45]
	v_exp_f32_e32 v40, v32
	v_mul_f32_e32 v32, 0xbfb8aa3b, v33
	v_exp_f32_e32 v41, v32
	v_pk_mul_f32 v[32:33], v[34:35], v[56:57] op_sel_hi:[1,0]
	v_add_f32_e32 v34, 1.0, v40
	v_mul_f32_e32 v32, 0xbfb8aa3b, v32
	v_mul_f32_e32 v33, 0xbfb8aa3b, v33
	v_exp_f32_e32 v32, v32
	v_exp_f32_e32 v33, v33
	v_rcp_f32_e32 v40, v34
	v_add_f32_e32 v34, 1.0, v41
	v_add_f32_e32 v32, 1.0, v32
	v_add_f32_e32 v33, 1.0, v33
	v_rcp_f32_e32 v41, v34
	v_rcp_f32_e32 v32, v32
	v_rcp_f32_e32 v33, v33
	v_lshlrev_b32_e32 v42, 16, v64
	v_and_b32_e32 v43, 0xffff0000, v64
	v_lshlrev_b32_e32 v34, 16, v65
	v_and_b32_e32 v35, 0xffff0000, v65
	v_lshlrev_b32_e32 v44, 16, v68
	v_and_b32_e32 v45, 0xffff0000, v68
	v_lshlrev_b32_e32 v46, 16, v69
	v_and_b32_e32 v47, 0xffff0000, v69
	v_pk_fma_f32 v[34:35], v[32:33], v[34:35], v[46:47]
	v_pk_fma_f32 v[32:33], v[40:41], v[42:43], v[44:45]
	global_store_dwordx4 v[48:49], v[32:35], off offset:512
	global_store_dwordx4 v[48:49], v[36:39], off offset:528
	flat_load_dword v42, v[160:161] offset:640
	v_lshl_add_u64 v[64:65], v[162:163], 0, s[18:19]
	v_lshlrev_b64 v[32:33], 1, v[64:65]
	v_lshl_add_u64 v[66:67], v[162:163], 0, s[16:17]
	v_lshl_add_u64 v[34:35], s[48:49], 0, v[32:33]
	v_lshl_add_u64 v[36:37], v[32:33], 0, s[10:11]
	v_lshlrev_b64 v[38:39], 1, v[66:67]
	flat_load_dwordx4 v[48:51], v[34:35]
	v_lshl_add_u64 v[34:35], s[42:43], 0, v[32:33]
	v_lshl_add_u64 v[32:33], s[42:43], 0, v[36:37]
	v_lshl_add_u64 v[40:41], v[38:39], 0, s[10:11]
	flat_load_dwordx4 v[52:55], v[34:35]
	flat_load_dwordx4 v[56:59], v[32:33]
	v_lshl_add_u64 v[32:33], s[48:49], 0, v[40:41]
	flat_load_dwordx4 v[32:35], v[32:33]
	s_nop 0
	flat_load_dword v69, v[160:161] offset:704
	v_lshl_add_u64 v[44:45], s[42:43], 0, v[40:41]
	v_lshl_add_u64 v[46:47], s[48:49], 0, v[38:39]
	v_lshl_add_u64 v[38:39], s[42:43], 0, v[38:39]
	v_lshl_add_u64 v[36:37], s[48:49], 0, v[36:37]
	v_lshl_add_u64 v[64:65], v[64:65], 2, s[52:53]
	s_waitcnt vmcnt(0) lgkmcnt(0)
; __device__ __forceinline__ u32x4 pack8(f32x4 a, f32x4 b) { u32x4 w; w.x = pk2(a[0], a[1]); w.y = pk2(a[2], a[3]); w.z = pk2(b[0], b[1]); w.w = pk2(b[2], b[3]); return w; }
;     __device__ __forceinline__ void operator()(const Acc& acc, const pg8::Unit& u, int wid) const {
;     ...
;                 for (int mm = 0; mm < 2; ++mm) {
;                     const int m = 2 * mp + mm, row = row0 + ai * 128 + m * 16; float sq = 0.f;
;                     const float sc = __builtin_amdgcn_rsqf(scv[mm] * (1.f / 1024.f) + EPS);
; #pragma unroll
;                     for (int bj = 0; bj < 2; ++bj) {
;                         const size_t off = (size_t)row * 1024 + col0 + bj * 128;
;                         const u32x4 pwv = pw[mm][bj], hw = hv[mm][bj];
;                         const f32x4 p0 = (f32x4){bflo(pwv.x), bfhi(pwv.x), bflo(pwv.y), bfhi(pwv.y)}, p1 = (f32x4){bflo(pwv.z), bfhi(pwv.z), bflo(pwv.w), bfhi(pwv.w)};
;                         f32x4 g0 = acc[ai][bj][m][0] * sc, g1 = acc[ai][bj][m][1] * sc;
; #pragma unroll
;                         for (int e = 0; e < 4; ++e) { g0[e] = __builtin_amdgcn_rcpf(1.f + __builtin_amdgcn_exp2f(-1.4426950408889634f * g0[e])); g1[e] = __builtin_amdgcn_rcpf(1.f + __builtin_amdgcn_exp2f(-1.4426950408889634f * g1[e])); }
;                         const f32x4 o0 = (f32x4){bflo(hw.x), bfhi(hw.x), bflo(hw.y), bfhi(hw.y)} + g0 * p0;
;                         const f32x4 o1 = (f32x4){bflo(hw.z), bfhi(hw.z), bflo(hw.w), bfhi(hw.w)} + g1 * p1;
;                         if (fout) { *(f32x4*)(fout + off) = o0; *(f32x4*)(fout + off + 4) = o1; }
;                         if (hb_out) *(u32x4*)(hb_out + off) = pack8(o0, o1);
;                         sq += (o0[0] * o0[0] + o0[1] * o0[1]) + (o0[2] * o0[2] + o0[3] * o0[3]) + (o1[0] * o1[0] + o1[1] * o1[1]) + (o1[2] * o1[2] + o1[3] * o1[3]);
;                     }
	v_fmamk_f32 v42, v42, 0x3a800000, v172
	v_rsq_f32_e32 v68, v42
	flat_load_dwordx4 v[40:43], v[38:39]
	flat_load_dwordx4 v[60:63], v[36:37]
	s_nop 0
	flat_load_dwordx4 v[36:39], v[44:45]
	s_nop 0
	flat_load_dwordx4 v[44:47], v[46:47]
	v_lshlrev_b32_e32 v72, 16, v50
	v_and_b32_e32 v73, 0xffff0000, v50
	v_lshlrev_b32_e32 v50, 16, v54
	v_pk_mul_f32 v[28:29], v[28:29], v[68:69] op_sel_hi:[1,0]
	s_nop 0
	v_mul_f32_e32 v28, 0xbfb8aa3b, v28
	v_exp_f32_e32 v70, v28
	v_mul_f32_e32 v28, 0xbfb8aa3b, v29
	v_exp_f32_e32 v71, v28
	v_pk_mul_f32 v[28:29], v[30:31], v[68:69] op_sel_hi:[1,0]
	v_add_f32_e32 v30, 1.0, v70
	v_mul_f32_e32 v28, 0xbfb8aa3b, v28
	v_mul_f32_e32 v29, 0xbfb8aa3b, v29
	v_exp_f32_e32 v28, v28
	v_exp_f32_e32 v29, v29
	v_rcp_f32_e32 v70, v30
	v_add_f32_e32 v30, 1.0, v71
	v_add_f32_e32 v28, 1.0, v28
	v_add_f32_e32 v29, 1.0, v29
	v_rcp_f32_e32 v71, v30
	v_rcp_f32_e32 v28, v28
	v_rcp_f32_e32 v29, v29
	v_pk_mul_f32 v[24:25], v[24:25], v[68:69] op_sel_hi:[1,0]
	v_lshlrev_b32_e32 v30, 16, v51
	v_and_b32_e32 v31, 0xffff0000, v51
	v_and_b32_e32 v51, 0xffff0000, v54
	v_lshlrev_b32_e32 v54, 16, v55
	v_and_b32_e32 v55, 0xffff0000, v55
	v_mul_f32_e32 v24, 0xbfb8aa3b, v24
	v_pk_fma_f32 v[30:31], v[28:29], v[30:31], v[54:55]
	v_pk_fma_f32 v[28:29], v[70:71], v[72:73], v[50:51]
	v_exp_f32_e32 v50, v24
	v_mul_f32_e32 v24, 0xbfb8aa3b, v25
	v_exp_f32_e32 v51, v24
	v_pk_mul_f32 v[24:25], v[26:27], v[68:69] op_sel_hi:[1,0]
	v_add_f32_e32 v26, 1.0, v50
	v_mul_f32_e32 v24, 0xbfb8aa3b, v24
	v_mul_f32_e32 v25, 0xbfb8aa3b, v25
	v_exp_f32_e32 v24, v24
	v_exp_f32_e32 v25, v25
	v_rcp_f32_e32 v50, v26
	v_add_f32_e32 v26, 1.0, v51
	v_add_f32_e32 v24, 1.0, v24
	v_add_f32_e32 v25, 1.0, v25
	v_rcp_f32_e32 v51, v26
	v_rcp_f32_e32 v24, v24
	v_rcp_f32_e32 v25, v25
	v_lshlrev_b32_e32 v54, 16, v48
	v_and_b32_e32 v55, 0xffff0000, v48
	v_lshlrev_b32_e32 v26, 16, v49
	v_and_b32_e32 v27, 0xffff0000, v49
	v_lshlrev_b32_e32 v48, 16, v52
	v_and_b32_e32 v49, 0xffff0000, v52
	v_lshlrev_b32_e32 v52, 16, v53
	v_and_b32_e32 v53, 0xffff0000, v53
	v_pk_mul_f32 v[20:21], v[20:21], v[68:69] op_sel_hi:[1,0]
	v_pk_fma_f32 v[26:27], v[24:25], v[26:27], v[52:53]
	v_pk_fma_f32 v[24:25], v[50:51], v[54:55], v[48:49]
	v_mul_f32_e32 v20, 0xbfb8aa3b, v20
	global_store_dwordx4 v[64:65], v[24:27], off
	global_store_dwordx4 v[64:65], v[28:31], off offset:16
	v_pk_mul_f32 v[16:17], v[16:17], v[68:69] op_sel_hi:[1,0]
	v_exp_f32_e32 v24, v20
	v_mul_f32_e32 v20, 0xbfb8aa3b, v21
	v_exp_f32_e32 v25, v20
	v_pk_mul_f32 v[20:21], v[22:23], v[68:69] op_sel_hi:[1,0]
	v_add_f32_e32 v22, 1.0, v24
	v_mul_f32_e32 v20, 0xbfb8aa3b, v20
	v_mul_f32_e32 v21, 0xbfb8aa3b, v21
	v_exp_f32_e32 v20, v20
	v_exp_f32_e32 v21, v21
	v_rcp_f32_e32 v24, v22
	v_add_f32_e32 v22, 1.0, v25
	v_add_f32_e32 v20, 1.0, v20
	v_add_f32_e32 v21, 1.0, v21
	v_rcp_f32_e32 v25, v22
	v_rcp_f32_e32 v20, v20
	v_rcp_f32_e32 v21, v21
	s_waitcnt vmcnt(0) lgkmcnt(0)
; #define PG8_BAR __builtin_amdgcn_s_barrier()
; template <class Epi>
; __device__ __forceinline__ void gemm_phase(LAS unsigned char* lds, const Gemm g, const StaticOrder& S, const Epi& E, const int wid) {
;     ...
;         if (!has_next) break;
; #pragma unroll
;         for (int a = 0; a < 2; ++a)
; #pragma unroll
;             for (int b = 0; b < 2; ++b)
; #pragma unroll
;                 for (int m = 0; m < 4; ++m)
; #pragma unroll
;                     for (int n = 0; n < 2; ++n) acc[a][b][m][n] = (f32x4){0.f, 0.f, 0.f, 0.f};
;         cur = nxt; cA = nA; cB = nB; ++ui;
;         if (wr == 1) PG8_BAR;
;     }
;     __device__ __forceinline__ void operator()(const Acc& acc, const pg8::Unit& u, int wid) const {
;     ...
;                 for (int mm = 0; mm < 2; ++mm) {
;                     const int m = 2 * mp + mm, row = row0 + ai * 128 + m * 16; float sq = 0.f;
;                     const float sc = __builtin_amdgcn_rsqf(scv[mm] * (1.f / 1024.f) + EPS);
; #pragma unroll
;                     for (int bj = 0; bj < 2; ++bj) {
;                         const size_t off = (size_t)row * 1024 + col0 + bj * 128;
;                         const u32x4 pwv = pw[mm][bj], hw = hv[mm][bj];
;                         const f32x4 p0 = (f32x4){bflo(pwv.x), bfhi(pwv.x), bflo(pwv.y), bfhi(pwv.y)}, p1 = (f32x4){bflo(pwv.z), bfhi(pwv.z), bflo(pwv.w), bfhi(pwv.w)};
;                         f32x4 g0 = acc[ai][bj][m][0] * sc, g1 = acc[ai][bj][m][1] * sc;
; #pragma unroll
;                         for (int e = 0; e < 4; ++e) { g0[e] = __builtin_amdgcn_rcpf(1.f + __builtin_amdgcn_exp2f(-1.4426950408889634f * g0[e])); g1[e] = __builtin_amdgcn_rcpf(1.f + __builtin_amdgcn_exp2f(-1.4426950408889634f * g1[e])); }
;                         const f32x4 o0 = (f32x4){bflo(hw.x), bfhi(hw.x), bflo(hw.y), bfhi(hw.y)} + g0 * p0;
;                         const f32x4 o1 = (f32x4){bflo(hw.z), bfhi(hw.z), bflo(hw.w), bfhi(hw.w)} + g1 * p1;
;                         if (fout) { *(f32x4*)(fout + off) = o0; *(f32x4*)(fout + off + 4) = o1; }
;                         if (hb_out) *(u32x4*)(hb_out + off) = pack8(o0, o1);
;                         sq += (o0[0] * o0[0] + o0[1] * o0[1]) + (o0[2] * o0[2] + o0[3] * o0[3]) + (o1[0] * o1[0] + o1[1] * o1[1]) + (o1[2] * o1[2] + o1[3] * o1[3]);
;                     }
	v_lshlrev_b32_e32 v26, 16, v62
	v_and_b32_e32 v27, 0xffff0000, v62
	v_lshlrev_b32_e32 v22, 16, v63
	v_and_b32_e32 v23, 0xffff0000, v63
	v_lshlrev_b32_e32 v28, 16, v58
	v_and_b32_e32 v29, 0xffff0000, v58
	v_lshlrev_b32_e32 v30, 16, v59
	v_and_b32_e32 v31, 0xffff0000, v59
	v_mul_f32_e32 v16, 0xbfb8aa3b, v16
	v_pk_fma_f32 v[22:23], v[20:21], v[22:23], v[30:31]
	v_pk_fma_f32 v[20:21], v[24:25], v[26:27], v[28:29]
	v_exp_f32_e32 v24, v16
	v_mul_f32_e32 v16, 0xbfb8aa3b, v17
	v_exp_f32_e32 v25, v16
	v_pk_mul_f32 v[16:17], v[18:19], v[68:69] op_sel_hi:[1,0]
	v_add_f32_e32 v18, 1.0, v24
	v_mul_f32_e32 v16, 0xbfb8aa3b, v16
	v_mul_f32_e32 v17, 0xbfb8aa3b, v17
	v_exp_f32_e32 v16, v16
	v_exp_f32_e32 v17, v17
	v_rcp_f32_e32 v24, v18
	v_add_f32_e32 v18, 1.0, v25
	v_add_f32_e32 v16, 1.0, v16
	v_add_f32_e32 v17, 1.0, v17
	v_rcp_f32_e32 v25, v18
	v_rcp_f32_e32 v16, v16
	v_rcp_f32_e32 v17, v17
	v_lshlrev_b32_e32 v26, 16, v60
	v_and_b32_e32 v27, 0xffff0000, v60
	v_lshlrev_b32_e32 v18, 16, v61
	v_and_b32_e32 v19, 0xffff0000, v61
	v_lshlrev_b32_e32 v28, 16, v56
	v_and_b32_e32 v29, 0xffff0000, v56
	v_lshlrev_b32_e32 v30, 16, v57
	v_and_b32_e32 v31, 0xffff0000, v57
	v_pk_fma_f32 v[18:19], v[16:17], v[18:19], v[30:31]
	v_pk_fma_f32 v[16:17], v[24:25], v[26:27], v[28:29]
	v_fmamk_f32 v24, v69, 0x3a800000, v172
	v_rsq_f32_e32 v24, v24
	global_store_dwordx4 v[64:65], v[16:19], off offset:512
	global_store_dwordx4 v[64:65], v[20:23], off offset:528
	v_lshlrev_b32_e32 v26, 16, v43
	v_and_b32_e32 v27, 0xffff0000, v43
	v_pk_mul_f32 v[12:13], v[12:13], v[24:25] op_sel_hi:[1,0]
	v_pk_mul_f32 v[8:9], v[8:9], v[24:25] op_sel_hi:[1,0]
	v_mul_f32_e32 v12, 0xbfb8aa3b, v12
	v_exp_f32_e32 v18, v12
	v_mul_f32_e32 v12, 0xbfb8aa3b, v13
	v_exp_f32_e32 v19, v12
	v_pk_mul_f32 v[12:13], v[14:15], v[24:25] op_sel_hi:[1,0]
	v_add_f32_e32 v14, 1.0, v18
	v_mul_f32_e32 v12, 0xbfb8aa3b, v12
	v_mul_f32_e32 v13, 0xbfb8aa3b, v13
	v_exp_f32_e32 v12, v12
	v_exp_f32_e32 v13, v13
	v_rcp_f32_e32 v18, v14
	v_add_f32_e32 v14, 1.0, v19
	v_add_f32_e32 v12, 1.0, v12
	v_add_f32_e32 v13, 1.0, v13
	v_rcp_f32_e32 v19, v14
	v_rcp_f32_e32 v12, v12
	v_rcp_f32_e32 v13, v13
	v_lshlrev_b32_e32 v20, 16, v46
	v_and_b32_e32 v21, 0xffff0000, v46
	v_lshlrev_b32_e32 v14, 16, v47
	v_and_b32_e32 v15, 0xffff0000, v47
	v_lshlrev_b32_e32 v22, 16, v42
	v_and_b32_e32 v23, 0xffff0000, v42
	v_mul_f32_e32 v8, 0xbfb8aa3b, v8
	v_pk_fma_f32 v[14:15], v[12:13], v[14:15], v[26:27]
	v_pk_fma_f32 v[12:13], v[18:19], v[20:21], v[22:23]
	v_exp_f32_e32 v18, v8
	v_mul_f32_e32 v8, 0xbfb8aa3b, v9
	v_exp_f32_e32 v19, v8
	v_pk_mul_f32 v[8:9], v[10:11], v[24:25] op_sel_hi:[1,0]
	v_add_f32_e32 v10, 1.0, v18
	v_mul_f32_e32 v8, 0xbfb8aa3b, v8
	v_mul_f32_e32 v9, 0xbfb8aa3b, v9
	v_exp_f32_e32 v8, v8
	v_exp_f32_e32 v9, v9
	v_rcp_f32_e32 v18, v10
	v_add_f32_e32 v10, 1.0, v19
	v_add_f32_e32 v8, 1.0, v8
	v_add_f32_e32 v9, 1.0, v9
	v_rcp_f32_e32 v19, v10
	v_rcp_f32_e32 v8, v8
	v_rcp_f32_e32 v9, v9
	v_lshlrev_b32_e32 v20, 16, v44
	v_and_b32_e32 v21, 0xffff0000, v44
	v_lshlrev_b32_e32 v10, 16, v45
	v_and_b32_e32 v11, 0xffff0000, v45
	v_lshlrev_b32_e32 v22, 16, v40
	v_and_b32_e32 v23, 0xffff0000, v40
	v_lshlrev_b32_e32 v26, 16, v41
	v_and_b32_e32 v27, 0xffff0000, v41
	v_pk_mul_f32 v[4:5], v[4:5], v[24:25] op_sel_hi:[1,0]
	v_lshl_add_u64 v[16:17], v[66:67], 2, s[52:53]
	v_pk_fma_f32 v[10:11], v[8:9], v[10:11], v[26:27]
	v_pk_fma_f32 v[8:9], v[18:19], v[20:21], v[22:23]
	v_mul_f32_e32 v4, 0xbfb8aa3b, v4
	global_store_dwordx4 v[16:17], v[8:11], off
	global_store_dwordx4 v[16:17], v[12:15], off offset:16
	v_pk_mul_f32 v[0:1], v[0:1], v[24:25] op_sel_hi:[1,0]
	v_exp_f32_e32 v8, v4
	v_mul_f32_e32 v4, 0xbfb8aa3b, v5
	v_exp_f32_e32 v9, v4
	v_pk_mul_f32 v[4:5], v[6:7], v[24:25] op_sel_hi:[1,0]
	v_add_f32_e32 v6, 1.0, v8
	v_mul_f32_e32 v4, 0xbfb8aa3b, v4
	v_mul_f32_e32 v5, 0xbfb8aa3b, v5
	v_exp_f32_e32 v4, v4
	v_exp_f32_e32 v5, v5
	v_rcp_f32_e32 v8, v6
	v_add_f32_e32 v6, 1.0, v9
	v_add_f32_e32 v4, 1.0, v4
	v_add_f32_e32 v5, 1.0, v5
	v_rcp_f32_e32 v9, v6
	v_rcp_f32_e32 v4, v4
	v_rcp_f32_e32 v5, v5
	v_lshlrev_b32_e32 v10, 16, v34
	v_and_b32_e32 v11, 0xffff0000, v34
	v_lshlrev_b32_e32 v6, 16, v35
	v_and_b32_e32 v7, 0xffff0000, v35
	v_lshlrev_b32_e32 v12, 16, v38
	v_and_b32_e32 v13, 0xffff0000, v38
	v_lshlrev_b32_e32 v14, 16, v39
	v_and_b32_e32 v15, 0xffff0000, v39
	v_mul_f32_e32 v0, 0xbfb8aa3b, v0
	v_pk_fma_f32 v[6:7], v[4:5], v[6:7], v[14:15]
	v_pk_fma_f32 v[4:5], v[8:9], v[10:11], v[12:13]
	v_exp_f32_e32 v8, v0
	v_mul_f32_e32 v0, 0xbfb8aa3b, v1
	v_exp_f32_e32 v9, v0
	v_pk_mul_f32 v[0:1], v[2:3], v[24:25] op_sel_hi:[1,0]
	v_add_f32_e32 v2, 1.0, v8
	v_mul_f32_e32 v0, 0xbfb8aa3b, v0
	v_mul_f32_e32 v1, 0xbfb8aa3b, v1
	v_exp_f32_e32 v0, v0
	v_exp_f32_e32 v1, v1
	v_rcp_f32_e32 v8, v2
	v_add_f32_e32 v2, 1.0, v9
	v_add_f32_e32 v0, 1.0, v0
	v_add_f32_e32 v1, 1.0, v1
	v_rcp_f32_e32 v9, v2
	v_rcp_f32_e32 v0, v0
	v_rcp_f32_e32 v1, v1
	v_lshlrev_b32_e32 v10, 16, v32
	v_and_b32_e32 v11, 0xffff0000, v32
	v_lshlrev_b32_e32 v2, 16, v33
	v_and_b32_e32 v3, 0xffff0000, v33
	v_lshlrev_b32_e32 v12, 16, v36
	v_and_b32_e32 v13, 0xffff0000, v36
	v_lshlrev_b32_e32 v14, 16, v37
	v_and_b32_e32 v15, 0xffff0000, v37
	v_pk_fma_f32 v[2:3], v[0:1], v[2:3], v[14:15]
	v_pk_fma_f32 v[0:1], v[8:9], v[10:11], v[12:13]
	global_store_dwordx4 v[16:17], v[0:3], off offset:512
	global_store_dwordx4 v[16:17], v[4:7], off offset:528
.LBB0_1358:
	s_andn2_b64 vcc, exec, s[0:1]
	s_mov_b64 s[0:1], -1
	s_cbranch_vccnz .LBB0_1345
	s_branch .LBB0_1344
